# all v_pk_mul/add/fma_f32 split into two scalar f32 ops (bit-identical results; packed f32 measured slower per op in the MLA loop)
# speedup vs baseline: 1.0344x; 1.0057x over previous
; DI void transpose_tile(const float* __restrict__ W, bf16_t* __restrict__ out, int K, int N, int k0, int n0, const float* __restrict__ scale, float* tile) {
;     ...
;   for (int i = 0; i < 16; ++i) {
;     const int kk = i * 4 + (tid >> 6), nn = tid & 63, n = n0 + nn;
;     tv[i] = (n < N) ? W[(size_t)(k0 + kk) * N + n] : 0.f;
;   }
; #pragma unroll
;   for (int i = 0; i < 16; ++i) {
;     const int kk = i * 4 + (tid >> 6), nn = tid & 63;
;     float v = tv[i];
;     if (scale) v *= scale[k0 + kk];
;     tile[kk * 65 + nn] = v;
.LBB0_41:
	s_andn2_b64 vcc, exec, s[6:7]
	s_cbranch_vccnz .LBB0_49
	s_add_i32 s6, s57, 0x100
	s_and_b32 s48, s6, 0x7fffffc0
	s_add_i32 s6, s55, 0x1000
	s_and_b32 s97, s6, 0x3c0
	v_or_b32_e32 v0, s97, v181
	v_or_b32_e32 v8, s48, v254
	v_lshl_or_b32 v38, v8, 10, v0
	v_add_u32_e32 v2, 0x1000, v38
	v_mov_b32_e32 v3, v39
	v_lshl_add_u64 v[0:1], v[38:39], 2, s[38:39]
	v_lshl_add_u64 v[2:3], v[2:3], 2, s[38:39]
	global_load_dword v15, v[0:1], off
	global_load_dword v17, v[2:3], off
	v_add_u32_e32 v2, 0x2000, v38
	v_mov_b32_e32 v3, v39
	v_lshl_add_u64 v[2:3], v[2:3], 2, s[38:39]
	global_load_dword v18, v[2:3], off
	v_add_u32_e32 v2, 0x3000, v38
	v_mov_b32_e32 v3, v39
	v_lshl_add_u64 v[2:3], v[2:3], 2, s[38:39]
	global_load_dword v19, v[2:3], off
	v_add_co_u32_e32 v2, vcc, s60, v0
	v_cmp_ne_u32_e64 s[6:7], 1, v177
	s_nop 0
	v_addc_co_u32_e32 v3, vcc, 0, v1, vcc
	global_load_dword v4, v[2:3], off
	v_add_u32_e32 v2, 0x5000, v38
	v_mov_b32_e32 v3, v39
	v_lshl_add_u64 v[2:3], v[2:3], 2, s[38:39]
	global_load_dword v5, v[2:3], off
	v_add_u32_e32 v2, 0x6000, v38
	v_mov_b32_e32 v3, v39
	v_lshl_add_u64 v[2:3], v[2:3], 2, s[38:39]
	global_load_dword v6, v[2:3], off
	v_add_u32_e32 v2, 0x7000, v38
	v_mov_b32_e32 v3, v39
	v_lshl_add_u64 v[2:3], v[2:3], 2, s[38:39]
	global_load_dword v7, v[2:3], off
	v_add_co_u32_e32 v2, vcc, s61, v0
	s_nop 1
	v_addc_co_u32_e32 v3, vcc, 0, v1, vcc
	v_add_co_u32_e32 v0, vcc, s3, v0
	global_load_dword v12, v[2:3], off
	s_nop 0
	v_addc_co_u32_e32 v1, vcc, 0, v1, vcc
	global_load_dword v0, v[0:1], off
	v_add_u32_e32 v2, 0x9000, v38
	v_mov_b32_e32 v3, v39
	v_lshl_add_u64 v[2:3], v[2:3], 2, s[38:39]
	global_load_dword v13, v[2:3], off
	v_add_u32_e32 v2, 0xa000, v38
	v_mov_b32_e32 v3, v39
	v_lshl_add_u64 v[2:3], v[2:3], 2, s[38:39]
	global_load_dword v14, v[2:3], off
	v_add_u32_e32 v2, 0xb000, v38
	v_mov_b32_e32 v3, v39
	v_lshl_add_u64 v[2:3], v[2:3], 2, s[38:39]
	global_load_dword v16, v[2:3], off
	v_add_u32_e32 v2, 0xd000, v38
	v_mov_b32_e32 v3, v39
	v_lshl_add_u64 v[2:3], v[2:3], 2, s[38:39]
	global_load_dword v1, v[2:3], off
	v_add_u32_e32 v2, 0xe000, v38
	v_mov_b32_e32 v3, v39
	v_add_u32_e32 v38, 0xf000, v38
	v_lshl_add_u64 v[2:3], v[2:3], 2, s[38:39]
	v_lshl_add_u64 v[10:11], v[38:39], 2, s[38:39]
	global_load_dword v2, v[2:3], off
	s_andn2_b64 vcc, exec, s[40:41]
	global_load_dword v3, v[10:11], off
	v_add_u32_e32 v38, s48, v254
	s_cbranch_vccnz .LBB0_99
	v_mov_b32_e32 v9, v39
	v_lshl_add_u64 v[8:9], v[8:9], 2, s[22:23]
	global_load_dword v8, v[8:9], off
	v_lshl_add_u64 v[10:11], v[38:39], 2, s[22:23]
	global_load_dword v20, v[10:11], off offset:32
	global_load_dword v9, v[10:11], off offset:16
	global_load_dword v21, v[10:11], off offset:48
	s_waitcnt vmcnt(3)
	v_mul_f32_e32 v8, v15, v8
	s_waitcnt vmcnt(2)
	v_mul_f32_e32 v20, v18, v20
	s_waitcnt vmcnt(1)
	v_mul_f32_e32 v9, v17, v9
	s_waitcnt vmcnt(0)
	v_mul_f32_e32 v21, v19, v21
	ds_write_b32 v175, v8
	ds_write_b32 v185, v9
	ds_write_b32 v185, v20 offset:1040
	ds_write_b32 v185, v21 offset:2080
	global_load_dword v8, v[10:11], off offset:64
	global_load_dword v9, v[10:11], off offset:80
	global_load_dword v20, v[10:11], off offset:96
	global_load_dword v21, v[10:11], off offset:112
	s_waitcnt vmcnt(2)
	v_mul_f32_e64 v8, v4, v8
	v_mul_f32_e64 v9, v5, v9
	s_waitcnt vmcnt(0)
	v_mul_f32_e64 v10, v6, v20
	v_mul_f32_e64 v11, v7, v21
	s_cbranch_execnz .LBB0_45

; DI void transpose_tile(const float* __restrict__ W, bf16_t* __restrict__ out, int K, int N, int k0, int n0, const float* __restrict__ scale, float* tile) {
;     ...
; #pragma unroll
;   for (int i = 0; i < 16; ++i) {
;     const int kk = i * 4 + (tid >> 6), nn = tid & 63;
;     float v = tv[i];
;     if (scale) v *= scale[k0 + kk];
;     tile[kk * 65 + nn] = v;
.LBB0_45:
	s_and_b64 vcc, exec, s[6:7]
	ds_write_b32 v185, v8 offset:3120
	ds_write_b32 v185, v9 offset:4160
	ds_write_b32 v185, v10 offset:5200
	ds_write_b32 v185, v11 offset:6240
	s_cbranch_vccnz .LBB0_100
	s_waitcnt vmcnt(10)
	v_lshl_add_u64 v[4:5], v[38:39], 2, s[22:23]
	global_load_dword v10, v[4:5], off offset:128
	global_load_dword v11, v[4:5], off offset:144
	global_load_dword v15, v[4:5], off offset:160
	global_load_dword v17, v[4:5], off offset:176
	global_load_dword v6, v[4:5], off offset:192
	global_load_dword v7, v[4:5], off offset:208
	global_load_dword v8, v[4:5], off offset:224
	global_load_dword v9, v[4:5], off offset:240
	s_waitcnt vmcnt(7)
	v_mul_f32_e32 v10, v12, v10
	s_waitcnt vmcnt(6)
	v_mul_f32_e32 v11, v13, v11
	s_waitcnt vmcnt(5)
	v_mul_f32_e32 v15, v14, v15
	s_waitcnt vmcnt(4)
	v_mul_f32_e32 v17, v16, v17
	ds_write_b32 v185, v10 offset:7280
	ds_write_b32 v185, v11 offset:8320
	ds_write_b32 v185, v15 offset:9360
	ds_write_b32 v185, v17 offset:10400
	s_waitcnt vmcnt(2)
	v_mul_f32_e64 v4, v0, v6
	v_mul_f32_e64 v5, v1, v7
	s_waitcnt vmcnt(0)
	v_mul_f32_e64 v6, v2, v8
	v_mul_f32_e64 v7, v3, v9
	s_cbranch_execnz .LBB0_48

; DI void transpose_tile(const float* __restrict__ W, bf16_t* __restrict__ out, int K, int N, int k0, int n0, const float* __restrict__ scale, float* tile) {
;     ...
;   for (int i = 0; i < 16; ++i) {
;     const int kk = i * 4 + (tid >> 6), nn = tid & 63, n = n0 + nn;
;     tv[i] = (n < N) ? W[(size_t)(k0 + kk) * N + n] : 0.f;
;   }
; #pragma unroll
;   for (int i = 0; i < 16; ++i) {
;     const int kk = i * 4 + (tid >> 6), nn = tid & 63;
;     float v = tv[i];
;     if (scale) v *= scale[k0 + kk];
;     tile[kk * 65 + nn] = v;
.LBB0_50:
	s_andn2_b64 vcc, exec, s[6:7]
	s_cbranch_vccnz .LBB0_58
	s_and_b32 s6, s2, 0xff
	s_mulk_i32 s6, 0xab
	s_lshr_b32 s6, s6, 11
	s_lshl_b32 s48, s6, 6
	s_mul_i32 s6, s6, 12
	s_sub_i32 s6, s2, s6
	s_and_b32 s6, s6, 0xff
	s_lshl_b32 s97, s6, 6
	v_or_b32_e32 v0, s97, v181
	v_or_b32_e32 v8, s48, v254
	v_mad_u32_u24 v38, v8, s62, v0
	v_add_u32_e32 v4, 0x1800, v38
	v_mov_b32_e32 v5, v39
	v_add_u32_e32 v6, 0x2400, v38
	v_mov_b32_e32 v7, v39
	v_add_u32_e32 v12, 0x3c00, v38
	v_mov_b32_e32 v13, v39
	v_lshl_add_u64 v[0:1], v[38:39], 2, s[20:21]
	v_add_u32_e32 v2, 0xc00, v38
	v_mov_b32_e32 v3, v39
	v_lshl_add_u64 v[4:5], v[4:5], 2, s[20:21]
	v_lshl_add_u64 v[6:7], v[6:7], 2, s[20:21]
	v_add_u32_e32 v10, 0x3000, v38
	v_mov_b32_e32 v11, v39
	v_lshl_add_u64 v[12:13], v[12:13], 2, s[20:21]
	v_add_u32_e32 v14, 0x4800, v38
	v_mov_b32_e32 v15, v39
	v_add_u32_e32 v16, 0x5400, v38
	v_mov_b32_e32 v17, v39
	v_lshl_add_u64 v[2:3], v[2:3], 2, s[20:21]
	v_lshl_add_u64 v[10:11], v[10:11], 2, s[20:21]
	v_lshl_add_u64 v[14:15], v[14:15], 2, s[20:21]
	v_lshl_add_u64 v[20:21], v[16:17], 2, s[20:21]
	global_load_dword v16, v[0:1], off
	global_load_dword v17, v[2:3], off
	global_load_dword v18, v[4:5], off
	global_load_dword v19, v[6:7], off
	s_nop 0
	global_load_dword v6, v[10:11], off
	global_load_dword v7, v[12:13], off
	global_load_dword v4, v[14:15], off
	global_load_dword v5, v[20:21], off
	v_add_u32_e32 v12, 0x8400, v38
	v_mov_b32_e32 v13, v39
	v_lshl_add_u64 v[20:21], v[12:13], 2, s[20:21]
	v_add_u32_e32 v12, 0x9000, v38
	v_add_u32_e32 v0, 0x6000, v38
	v_mov_b32_e32 v1, v39
	v_add_u32_e32 v2, 0x6c00, v38
	v_mov_b32_e32 v3, v39
	v_lshl_add_u64 v[22:23], v[12:13], 2, s[20:21]
	v_add_u32_e32 v12, 0x9c00, v38
	v_lshl_add_u64 v[0:1], v[0:1], 2, s[20:21]
	v_lshl_add_u64 v[2:3], v[2:3], 2, s[20:21]
	v_add_u32_e32 v10, 0x7800, v38
	v_mov_b32_e32 v11, v39
	v_lshl_add_u64 v[24:25], v[12:13], 2, s[20:21]
	v_add_u32_e32 v12, 0xa800, v38
	v_add_u32_e32 v38, 0xb400, v38
	v_lshl_add_u64 v[10:11], v[10:11], 2, s[20:21]
	v_lshl_add_u64 v[26:27], v[12:13], 2, s[20:21]
	v_lshl_add_u64 v[28:29], v[38:39], 2, s[20:21]
	global_load_dword v12, v[0:1], off
	global_load_dword v13, v[2:3], off
	global_load_dword v14, v[10:11], off
	global_load_dword v15, v[20:21], off
	s_nop 0
	global_load_dword v2, v[22:23], off
	global_load_dword v3, v[24:25], off
	global_load_dword v0, v[26:27], off
	global_load_dword v1, v[28:29], off
	v_cmp_ne_u32_e64 s[6:7], 1, v179
	s_andn2_b64 vcc, exec, s[36:37]
	v_add_lshl_u32 v20, s48, v254, 2
	s_cbranch_vccnz .LBB0_97
	v_lshlrev_b32_e32 v8, 2, v8
	global_load_dword v8, v8, s[18:19]
	s_nop 0
	global_load_dword v9, v20, s[18:19] offset:16
	global_load_dword v10, v20, s[18:19] offset:32
	global_load_dword v11, v20, s[18:19] offset:48
	s_waitcnt vmcnt(3)
	v_mul_f32_e32 v8, v16, v8
	s_waitcnt vmcnt(2)
	v_mul_f32_e32 v9, v17, v9
	s_waitcnt vmcnt(1)
	v_mul_f32_e32 v10, v18, v10
	s_waitcnt vmcnt(0)
	v_mul_f32_e32 v11, v19, v11
	ds_write_b32 v175, v8
	ds_write_b32 v185, v9
	ds_write_b32 v185, v10 offset:1040
	ds_write_b32 v185, v11 offset:2080
	global_load_dword v8, v20, s[18:19] offset:64
	global_load_dword v9, v20, s[18:19] offset:80
	global_load_dword v10, v20, s[18:19] offset:96
	global_load_dword v11, v20, s[18:19] offset:112
	s_waitcnt vmcnt(2)
	v_mul_f32_e64 v8, v6, v8
	v_mul_f32_e64 v9, v7, v9
	s_waitcnt vmcnt(0)
	v_mul_f32_e64 v10, v4, v10
	v_mul_f32_e64 v11, v5, v11
	s_cbranch_execnz .LBB0_54

; DI void transpose_tile(const float* __restrict__ W, bf16_t* __restrict__ out, int K, int N, int k0, int n0, const float* __restrict__ scale, float* tile) {
;     ...
; #pragma unroll
;   for (int i = 0; i < 16; ++i) {
;     const int kk = i * 4 + (tid >> 6), nn = tid & 63;
;     float v = tv[i];
;     if (scale) v *= scale[k0 + kk];
;     tile[kk * 65 + nn] = v;
.LBB0_54:
	s_and_b64 vcc, exec, s[6:7]
	ds_write_b32 v185, v8 offset:3120
	ds_write_b32 v185, v9 offset:4160
	ds_write_b32 v185, v10 offset:5200
	ds_write_b32 v185, v11 offset:6240
	s_cbranch_vccnz .LBB0_98
	global_load_dword v8, v20, s[18:19] offset:128
	global_load_dword v9, v20, s[18:19] offset:144
	global_load_dword v10, v20, s[18:19] offset:160
	global_load_dword v11, v20, s[18:19] offset:176
	global_load_dword v4, v20, s[18:19] offset:192
	global_load_dword v5, v20, s[18:19] offset:208
	global_load_dword v6, v20, s[18:19] offset:224
	global_load_dword v7, v20, s[18:19] offset:240
	s_waitcnt vmcnt(7)
	v_mul_f32_e32 v8, v12, v8
	s_waitcnt vmcnt(6)
	v_mul_f32_e32 v9, v13, v9
	s_waitcnt vmcnt(5)
	v_mul_f32_e32 v10, v14, v10
	s_waitcnt vmcnt(4)
	v_mul_f32_e32 v11, v15, v11
	ds_write_b32 v185, v8 offset:7280
	ds_write_b32 v185, v9 offset:8320
	ds_write_b32 v185, v10 offset:9360
	ds_write_b32 v185, v11 offset:10400
	s_waitcnt vmcnt(2)
	v_mul_f32_e64 v4, v2, v4
	v_mul_f32_e64 v5, v3, v5
	s_waitcnt vmcnt(0)
	v_mul_f32_e64 v6, v0, v6
	v_mul_f32_e64 v7, v1, v7
	s_cbranch_execnz .LBB0_57

; DI void ada_item(const Params& p, float* red, int item) {
;   const int tid = threadIdx.x, col = tid & 15, ks = tid >> 4, n = item * 16 + col;
;   float a0 = 0.f, a1 = 0.f;
; #pragma unroll
;   for (int kq = 0; kq < 2; ++kq) {
;     float wv[32];
; #pragma unroll
;     for (int j = 0; j < 32; ++j) wv[j] = p.w_ada[(size_t)(ks * 64 + kq * 32 + j) * 3072 + n];
; #pragma unroll
;     for (int j = 0; j < 32; ++j) {
;       const int k = ks * 64 + kq * 32 + j;
;       const float c0 = p.c[k], c1 = p.c[1024 + k];
;       a0 += (c0 / (1.f + __expf(-c0))) * wv[j];
;       a1 += (c1 / (1.f + __expf(-c1))) * wv[j];
;     }
.LBB0_94:
	s_andn2_b64 vcc, exec, s[6:7]
	s_cbranch_vccnz .LBB0_23
	v_ashrrev_i32_e32 v147, 31, v146
	v_lshl_add_u64 v[160:161], v[146:147], 2, s[12:13]
	v_lshl_add_u64 v[162:163], v[50:51], 2, v[160:161]
	v_add_co_u32_e32 v0, vcc, 0x3000, v162
	v_lshl_add_u64 v[2:3], v[52:53], 2, v[160:161]
	s_nop 0
	v_addc_co_u32_e32 v1, vcc, 0, v163, vcc
	v_add_co_u32_e32 v4, vcc, 0x9000, v162
	s_movk_i32 s6, 0x6000
	s_nop 0
	v_addc_co_u32_e32 v5, vcc, 0, v163, vcc
	v_add_co_u32_e32 v6, vcc, s6, v2
	s_mov_b32 s6, 0xf000
	s_nop 0
	v_addc_co_u32_e32 v7, vcc, 0, v3, vcc
	v_add_co_u32_e32 v8, vcc, s6, v162
	s_mov_b32 s6, 0x12000
	s_nop 0
	v_addc_co_u32_e32 v9, vcc, 0, v163, vcc
	v_add_co_u32_e32 v10, vcc, 0xc000, v2
	v_lshl_add_u64 v[36:37], v[54:55], 2, v[160:161]
	s_nop 0
	v_addc_co_u32_e32 v11, vcc, 0, v3, vcc
	v_add_co_u32_e32 v12, vcc, s52, v162
	v_lshl_add_u64 v[40:41], v[56:57], 2, v[160:161]
	s_nop 0
	v_addc_co_u32_e32 v13, vcc, 0, v163, vcc
	global_load_dword v212, v[162:163], off
	global_load_dword v34, v[0:1], off
	global_load_dword v30, v[2:3], off
	global_load_dword v28, v[4:5], off
	global_load_dword v26, v[6:7], off
	global_load_dword v24, v[8:9], off
	global_load_dword v22, v[10:11], off
	global_load_dword v20, v[12:13], off
	s_nop 0
	global_load_dwordx4 v[8:11], v[132:133], off offset:16
	global_load_dwordx4 v[12:15], v[132:133], off
	global_load_dwordx4 v[16:19], v[134:135], off
	v_add_co_u32_e32 v32, vcc, s6, v2
	global_load_dwordx4 v[4:7], v[134:135], off offset:32
	s_nop 0
	v_addc_co_u32_e32 v33, vcc, 0, v3, vcc
	global_load_dwordx4 v[0:3], v[132:133], off offset:32
	v_add_co_u32_e32 v186, vcc, s53, v162
	v_lshl_add_u64 v[44:45], v[58:59], 2, v[160:161]
	s_nop 0
	v_addc_co_u32_e32 v187, vcc, 0, v163, vcc
	v_add_co_u32_e32 v190, vcc, s79, v162
	v_lshl_add_u64 v[188:189], v[60:61], 2, v[160:161]
	s_nop 0
	v_addc_co_u32_e32 v191, vcc, 0, v163, vcc
	v_lshl_add_u64 v[192:193], v[62:63], 2, v[160:161]
	global_load_dword v32, v[32:33], off
	s_nop 0
	global_load_dword v208, v[36:37], off
	global_load_dword v210, v[40:41], off
	global_load_dword v206, v[44:45], off
	global_load_dword v204, v[186:187], off
	global_load_dword v202, v[188:189], off
	global_load_dword v200, v[190:191], off
	global_load_dword v198, v[192:193], off
	v_add_co_u32_e32 v36, vcc, s3, v162
	v_lshl_add_u64 v[40:41], v[64:65], 2, v[160:161]
	s_nop 0
	v_addc_co_u32_e32 v37, vcc, 0, v163, vcc
	v_add_co_u32_e32 v44, vcc, s80, v162
	v_lshl_add_u64 v[186:187], v[66:67], 2, v[160:161]
	s_nop 0
	v_addc_co_u32_e32 v45, vcc, 0, v163, vcc
	v_add_co_u32_e32 v218, vcc, s81, v162
	v_lshl_add_u64 v[188:189], v[68:69], 2, v[160:161]
	s_nop 0
	v_addc_co_u32_e32 v219, vcc, 0, v163, vcc
	v_lshl_add_u64 v[214:215], v[70:71], 2, v[160:161]
	v_lshl_add_u64 v[216:217], v[72:73], 2, v[160:161]
	global_load_dword v196, v[36:37], off
	global_load_dword v194, v[40:41], off
	global_load_dword v192, v[44:45], off
	global_load_dword v190, v[186:187], off
	s_nop 0
	global_load_dword v186, v[188:189], off
	s_nop 0
	global_load_dword v188, v[214:215], off
	global_load_dword v184, v[216:217], off
	global_load_dword v182, v[218:219], off
	v_add_co_u32_e32 v40, vcc, s82, v162
	v_lshl_add_u64 v[36:37], v[74:75], 2, v[160:161]
	s_nop 0
	v_addc_co_u32_e32 v41, vcc, 0, v163, vcc
	v_add_co_u32_e32 v214, vcc, s83, v162
	v_lshl_add_u64 v[44:45], v[76:77], 2, v[160:161]
	s_nop 0
	v_addc_co_u32_e32 v215, vcc, 0, v163, vcc
	v_add_co_u32_e32 v218, vcc, s84, v162
	v_lshl_add_u64 v[216:217], v[78:79], 2, v[160:161]
	s_nop 0
	v_addc_co_u32_e32 v219, vcc, 0, v163, vcc
	v_lshl_add_u64 v[220:221], v[80:81], 2, v[160:161]
	v_lshl_add_u64 v[222:223], v[82:83], 2, v[160:161]
	global_load_dword v180, v[36:37], off
	global_load_dword v178, v[40:41], off
	global_load_dword v174, v[44:45], off
	global_load_dword v172, v[214:215], off
	global_load_dword v170, v[216:217], off
	global_load_dword v168, v[218:219], off
	global_load_dword v166, v[220:221], off
	global_load_dword v164, v[222:223], off
	global_load_dwordx3 v[36:38], v[132:133], off offset:48
	global_load_dwordx3 v[40:42], v[132:133], off offset:244
	s_nop 0
	global_load_dwordx4 v[216:219], v[134:135], off offset:16
	global_load_dwordx3 v[44:46], v[134:135], off offset:48
	v_lshl_add_u64 v[224:225], v[122:123], 2, v[160:161]
	s_waitcnt vmcnt(31)
	v_mul_f32_e32 v21, 0xbfb8aa3b, v12
	v_exp_f32_e32 v214, v21
	s_waitcnt vmcnt(30)
	v_mul_f32_e32 v21, 0xbfb8aa3b, v16
	v_exp_f32_e32 v215, v21
	s_waitcnt vmcnt(28)
; DI void ada_item(const Params& p, float* red, int item) {
;     ...
;   for (int kq = 0; kq < 2; ++kq) {
;     float wv[32];
; #pragma unroll
;     for (int j = 0; j < 32; ++j) wv[j] = p.w_ada[(size_t)(ks * 64 + kq * 32 + j) * 3072 + n];
; #pragma unroll
;     for (int j = 0; j < 32; ++j) {
;       const int k = ks * 64 + kq * 32 + j;
;       const float c0 = p.c[k], c1 = p.c[1024 + k];
;       a0 += (c0 / (1.f + __expf(-c0))) * wv[j];
;       a1 += (c1 / (1.f + __expf(-c1))) * wv[j];
;     }
	v_mul_f32_e32 v21, 0xbfb8aa3b, v0
	v_add_f32_e64 v214, v214, 1.0
	v_add_f32_e64 v215, v215, 1.0
	v_exp_f32_e32 v220, v21
	v_div_scale_f32 v23, s[6:7], v215, v215, v16
	v_rcp_f32_e32 v25, v23
	v_mul_f32_e32 v21, 0xbfb8aa3b, v4
	v_exp_f32_e32 v221, v21
	v_fma_f32 v21, -v23, v25, 1.0
	v_fmac_f32_e32 v25, v21, v25
	v_div_scale_f32 v21, vcc, v16, v215, v16
	v_mul_f32_e32 v27, v21, v25
	v_fma_f32 v29, -v23, v27, v21
	v_fmac_f32_e32 v27, v29, v25
	v_fma_f32 v21, -v23, v27, v21
	v_div_scale_f32 v23, s[6:7], v214, v214, v12
	v_rcp_f32_e32 v29, v23
	v_div_fmas_f32 v21, v21, v25, v27
	v_mul_f32_e32 v25, 0xbfb8aa3b, v13
	v_exp_f32_e32 v222, v25
	v_mul_f32_e32 v25, 0xbfb8aa3b, v17
	v_div_fixup_f32 v215, v21, v215, v16
	v_fma_f32 v16, -v23, v29, 1.0
	v_exp_f32_e32 v223, v25
	v_fmac_f32_e32 v29, v16, v29
	v_div_scale_f32 v16, vcc, v12, v214, v12
	v_mul_f32_e32 v21, v16, v29
	v_fma_f32 v25, -v23, v21, v16
	v_fmac_f32_e32 v21, v25, v29
	v_add_f32_e64 v222, v222, 1.0
	v_add_f32_e64 v223, v223, 1.0
	v_fma_f32 v16, -v23, v21, v16
	v_div_scale_f32 v23, s[6:7], v223, v223, v17
	v_rcp_f32_e32 v25, v23
	v_div_fmas_f32 v16, v16, v29, v21
	v_div_fixup_f32 v214, v16, v214, v12
	v_fma_f32 v213, v212, v215, 0
	v_fma_f32 v212, v212, v214, 0
	v_fma_f32 v12, -v23, v25, 1.0
	v_fmac_f32_e32 v25, v12, v25
	v_div_scale_f32 v12, vcc, v17, v223, v17
	v_mul_f32_e32 v16, v12, v25
	v_fma_f32 v21, -v23, v16, v12
	v_fmac_f32_e32 v16, v21, v25
	v_div_scale_f32 v21, s[6:7], v222, v222, v13
	v_fma_f32 v12, -v23, v16, v12
	v_rcp_f32_e32 v23, v21
	v_div_fmas_f32 v12, v12, v25, v16
	v_mul_f32_e32 v25, 0xbfb8aa3b, v14
	v_exp_f32_e32 v214, v25
	v_mul_f32_e32 v25, 0xbfb8aa3b, v18
	v_div_fixup_f32 v17, v12, v223, v17
	v_fma_f32 v12, -v21, v23, 1.0
	v_exp_f32_e32 v215, v25
	v_fmac_f32_e32 v23, v12, v23
	v_div_scale_f32 v12, vcc, v13, v222, v13
	v_mul_f32_e32 v16, v12, v23
	v_fma_f32 v25, -v21, v16, v12
	v_fmac_f32_e32 v16, v25, v23
	v_add_f32_e64 v214, v214, 1.0
	v_add_f32_e64 v215, v215, 1.0
	v_fma_f32 v12, -v21, v16, v12
	v_div_scale_f32 v21, s[6:7], v215, v215, v18
	v_rcp_f32_e32 v25, v21
	v_div_fmas_f32 v12, v12, v23, v16
	v_div_fixup_f32 v16, v12, v222, v13
	v_fma_f32 v12, v34, v16, v212
	v_fma_f32 v13, v34, v17, v213
	v_fma_f32 v16, -v21, v25, 1.0
	v_fmac_f32_e32 v25, v16, v25
	v_div_scale_f32 v16, vcc, v18, v215, v18
	v_mul_f32_e32 v17, v16, v25
	v_fma_f32 v23, -v21, v17, v16
	v_fmac_f32_e32 v17, v23, v25
	v_fma_f32 v16, -v21, v17, v16
	v_div_scale_f32 v21, s[6:7], v214, v214, v14
	v_rcp_f32_e32 v23, v21
	v_div_fmas_f32 v16, v16, v25, v17
	v_mul_f32_e32 v25, 0xbfb8aa3b, v15
	v_exp_f32_e32 v34, v25
	v_mul_f32_e32 v25, 0xbfb8aa3b, v19
	v_div_fixup_f32 v17, v16, v215, v18
	v_fma_f32 v16, -v21, v23, 1.0
	v_exp_f32_e32 v35, v25
	v_fmac_f32_e32 v23, v16, v23
	v_div_scale_f32 v16, vcc, v14, v214, v14
	v_mul_f32_e32 v18, v16, v23
	v_fma_f32 v25, -v21, v18, v16
	v_fmac_f32_e32 v18, v25, v23
	v_add_f32_e64 v34, v34, 1.0
	v_add_f32_e64 v35, v35, 1.0
	v_fma_f32 v16, -v21, v18, v16
	v_div_scale_f32 v21, s[6:7], v35, v35, v19
	v_rcp_f32_e32 v25, v21
	v_div_fmas_f32 v16, v16, v23, v18
	v_div_fixup_f32 v16, v16, v214, v14
	v_fma_f32 v12, v30, v16, v12
	v_fma_f32 v13, v30, v17, v13
	v_fma_f32 v14, -v21, v25, 1.0
	v_fmac_f32_e32 v25, v14, v25
	v_div_scale_f32 v14, vcc, v19, v35, v19
	v_mul_f32_e32 v16, v14, v25
	v_fma_f32 v17, -v21, v16, v14
	v_fmac_f32_e32 v16, v17, v25
	v_fma_f32 v14, -v21, v16, v14
	v_div_scale_f32 v21, s[6:7], v34, v34, v15
	v_rcp_f32_e32 v23, v21
	v_div_fmas_f32 v14, v14, v25, v16
	v_div_fixup_f32 v17, v14, v35, v19
	v_mul_f32_e32 v18, 0xbfb8aa3b, v8
	s_waitcnt vmcnt(1)
	v_mul_f32_e32 v19, 0xbfb8aa3b, v216
	v_fma_f32 v14, -v21, v23, 1.0
	v_exp_f32_e32 v18, v18
	v_exp_f32_e32 v19, v19
	v_fmac_f32_e32 v23, v14, v23
	v_div_scale_f32 v14, vcc, v15, v34, v15
	v_mul_f32_e32 v16, v14, v23
	v_fma_f32 v25, -v21, v16, v14
	v_fmac_f32_e32 v16, v25, v23
	v_add_f32_e64 v18, v18, 1.0
	v_add_f32_e64 v19, v19, 1.0
	v_fma_f32 v14, -v21, v16, v14
	v_div_scale_f32 v21, s[6:7], v19, v19, v216
	v_rcp_f32_e32 v25, v21
	v_div_fmas_f32 v14, v14, v23, v16
	v_div_fixup_f32 v16, v14, v34, v15
	v_fma_f32 v12, v28, v16, v12
	v_fma_f32 v13, v28, v17, v13
	v_fma_f32 v14, -v21, v25, 1.0
	v_fmac_f32_e32 v25, v14, v25
	v_div_scale_f32 v14, vcc, v216, v19, v216
	v_mul_f32_e32 v15, v14, v25
	v_fma_f32 v16, -v21, v15, v14
	v_fmac_f32_e32 v15, v16, v25
	v_fma_f32 v14, -v21, v15, v14
	v_div_scale_f32 v21, s[6:7], v18, v18, v8
	v_rcp_f32_e32 v23, v21
	v_div_fmas_f32 v14, v14, v25, v15
	v_mul_f32_e32 v16, 0xbfb8aa3b, v9
	v_mul_f32_e32 v17, 0xbfb8aa3b, v217
	v_div_fixup_f32 v15, v14, v19, v216
	v_fma_f32 v14, -v21, v23, 1.0
	v_exp_f32_e32 v16, v16
	v_exp_f32_e32 v17, v17
	v_fmac_f32_e32 v23, v14, v23
	v_div_scale_f32 v14, vcc, v8, v18, v8
	v_mul_f32_e32 v19, v14, v23
	v_fma_f32 v25, -v21, v19, v14
	v_fmac_f32_e32 v19, v25, v23
	v_add_f32_e64 v16, v16, 1.0
	v_add_f32_e64 v17, v17, 1.0
	v_fma_f32 v14, -v21, v19, v14
	v_div_scale_f32 v21, s[6:7], v17, v17, v217
	v_rcp_f32_e32 v25, v21
	v_div_fmas_f32 v14, v14, v23, v19
	v_div_fixup_f32 v14, v14, v18, v8
	v_fma_f32 v12, v26, v14, v12
	v_fma_f32 v13, v26, v15, v13
	v_fma_f32 v8, -v21, v25, 1.0
	v_fmac_f32_e32 v25, v8, v25
	v_div_scale_f32 v8, vcc, v217, v17, v217
	v_mul_f32_e32 v14, v8, v25
	v_fma_f32 v15, -v21, v14, v8
	v_fmac_f32_e32 v14, v15, v25
	v_fma_f32 v8, -v21, v14, v8
	v_div_scale_f32 v21, s[6:7], v16, v16, v9
	v_rcp_f32_e32 v23, v21
	v_div_fmas_f32 v8, v8, v25, v14
	v_div_fixup_f32 v15, v8, v17, v217
	v_mul_f32_e32 v17, 0xbfb8aa3b, v10
	v_exp_f32_e32 v18, v17
	v_mul_f32_e32 v17, 0xbfb8aa3b, v218
	v_exp_f32_e32 v19, v17
	v_fma_f32 v8, -v21, v23, 1.0
; DI void ada_item(const Params& p, float* red, int item) {
;     ...
;   for (int kq = 0; kq < 2; ++kq) {
;     float wv[32];
; #pragma unroll
;     for (int j = 0; j < 32; ++j) wv[j] = p.w_ada[(size_t)(ks * 64 + kq * 32 + j) * 3072 + n];
; #pragma unroll
;     for (int j = 0; j < 32; ++j) {
;       const int k = ks * 64 + kq * 32 + j;
;       const float c0 = p.c[k], c1 = p.c[1024 + k];
;       a0 += (c0 / (1.f + __expf(-c0))) * wv[j];
;       a1 += (c1 / (1.f + __expf(-c1))) * wv[j];
;     }
	v_fmac_f32_e32 v23, v8, v23
	v_div_scale_f32 v8, vcc, v9, v16, v9
	v_mul_f32_e32 v14, v8, v23
	v_fma_f32 v17, -v21, v14, v8
	v_add_f32_e64 v18, v18, 1.0
	v_add_f32_e64 v19, v19, 1.0
	v_fmac_f32_e32 v14, v17, v23
	v_div_scale_f32 v17, s[6:7], v19, v19, v218
	v_fma_f32 v8, -v21, v14, v8
	v_rcp_f32_e32 v21, v17
	v_div_fmas_f32 v8, v8, v23, v14
	v_div_fixup_f32 v14, v8, v16, v9
	v_fma_f32 v8, v24, v14, v12
	v_fma_f32 v9, v24, v15, v13
	v_fma_f32 v12, -v17, v21, 1.0
	v_fmac_f32_e32 v21, v12, v21
	v_div_scale_f32 v12, vcc, v218, v19, v218
	v_mul_f32_e32 v13, v12, v21
	v_fma_f32 v14, -v17, v13, v12
	v_fmac_f32_e32 v13, v14, v21
	v_div_scale_f32 v16, s[6:7], v18, v18, v10
	v_fma_f32 v12, -v17, v13, v12
	v_rcp_f32_e32 v17, v16
	v_div_fmas_f32 v12, v12, v21, v13
	v_mul_f32_e32 v14, 0xbfb8aa3b, v11
	v_mul_f32_e32 v15, 0xbfb8aa3b, v219
	v_div_fixup_f32 v13, v12, v19, v218
	v_fma_f32 v12, -v16, v17, 1.0
	v_exp_f32_e32 v14, v14
	v_exp_f32_e32 v15, v15
	v_fmac_f32_e32 v17, v12, v17
	v_div_scale_f32 v12, vcc, v10, v18, v10
	v_mul_f32_e32 v19, v12, v17
	v_fma_f32 v21, -v16, v19, v12
	v_fmac_f32_e32 v19, v21, v17
	v_add_f32_e64 v14, v14, 1.0
	v_add_f32_e64 v15, v15, 1.0
	v_fma_f32 v12, -v16, v19, v12
	v_div_scale_f32 v16, s[6:7], v15, v15, v219
	v_rcp_f32_e32 v21, v16
	v_div_fmas_f32 v12, v12, v17, v19
	v_div_fixup_f32 v12, v12, v18, v10
	v_fma_f32 v8, v22, v12, v8
	v_fma_f32 v9, v22, v13, v9
	v_fma_f32 v10, -v16, v21, 1.0
	v_fmac_f32_e32 v21, v10, v21
	v_div_scale_f32 v10, vcc, v219, v15, v219
	v_mul_f32_e32 v12, v10, v21
	v_fma_f32 v13, -v16, v12, v10
	v_fmac_f32_e32 v12, v13, v21
	v_fma_f32 v10, -v16, v12, v10
	v_div_scale_f32 v16, s[6:7], v14, v14, v11
	v_rcp_f32_e32 v18, v16
	global_load_dwordx4 v[24:27], v[132:133], off offset:76
	global_load_dwordx4 v[28:31], v[136:137], off offset:16
	v_div_fmas_f32 v10, v10, v21, v12
	v_div_fixup_f32 v13, v10, v15, v219
	v_fma_f32 v10, -v16, v18, 1.0
	v_fmac_f32_e32 v18, v10, v18
	v_div_scale_f32 v10, vcc, v11, v14, v11
	v_mul_f32_e32 v12, v10, v18
	v_fma_f32 v15, -v16, v12, v10
	v_fmac_f32_e32 v12, v15, v18
	v_fma_f32 v10, -v16, v12, v10
	v_add_f32_e64 v16, v220, 1.0
	v_add_f32_e64 v17, v221, 1.0
	v_div_fmas_f32 v10, v10, v18, v12
	v_div_scale_f32 v15, s[6:7], v17, v17, v4
	v_rcp_f32_e32 v19, v15
	v_div_fixup_f32 v12, v10, v14, v11
	v_fma_f32 v8, v20, v12, v8
	v_fma_f32 v9, v20, v13, v9
	v_div_scale_f32 v14, s[6:7], v16, v16, v0
	v_fma_f32 v10, -v15, v19, 1.0
	v_fmac_f32_e32 v19, v10, v19
	v_div_scale_f32 v10, vcc, v4, v17, v4
	v_mul_f32_e32 v11, v10, v19
	v_fma_f32 v12, -v15, v11, v10
	v_fmac_f32_e32 v11, v12, v19
	v_fma_f32 v10, -v15, v11, v10
	v_rcp_f32_e32 v15, v14
	v_div_fmas_f32 v10, v10, v19, v11
	v_mul_f32_e32 v12, 0xbfb8aa3b, v1
	v_mul_f32_e32 v13, 0xbfb8aa3b, v5
	v_div_fixup_f32 v11, v10, v17, v4
	v_fma_f32 v4, -v14, v15, 1.0
	v_exp_f32_e32 v12, v12
	v_exp_f32_e32 v13, v13
	v_fmac_f32_e32 v15, v4, v15
	v_div_scale_f32 v4, vcc, v0, v16, v0
	v_mul_f32_e32 v10, v4, v15
	v_fma_f32 v17, -v14, v10, v4
	v_fmac_f32_e32 v10, v17, v15
	v_add_f32_e64 v12, v12, 1.0
	v_add_f32_e64 v13, v13, 1.0
	v_fma_f32 v4, -v14, v10, v4
	v_div_scale_f32 v14, s[6:7], v13, v13, v5
	v_rcp_f32_e32 v17, v14
	v_div_fmas_f32 v4, v4, v15, v10
	v_div_fixup_f32 v10, v4, v16, v0
	v_fma_f32 v216, v32, v10, v8
	v_fma_f32 v217, v32, v11, v9
	v_fma_f32 v0, -v14, v17, 1.0
	v_fmac_f32_e32 v17, v0, v17
	v_div_scale_f32 v0, vcc, v5, v13, v5
	v_mul_f32_e32 v4, v0, v17
	v_div_scale_f32 v10, s[6:7], v12, v12, v1
	v_fma_f32 v8, -v14, v4, v0
	v_rcp_f32_e32 v11, v10
	v_fmac_f32_e32 v4, v8, v17
	v_fma_f32 v0, -v14, v4, v0
	v_div_fmas_f32 v0, v0, v17, v4
	v_mul_f32_e32 v8, 0xbfb8aa3b, v2
	v_mul_f32_e32 v9, 0xbfb8aa3b, v6
	v_div_fixup_f32 v5, v0, v13, v5
	v_fma_f32 v0, -v10, v11, 1.0
	v_exp_f32_e32 v8, v8
	v_exp_f32_e32 v9, v9
	v_fmac_f32_e32 v11, v0, v11
	v_div_scale_f32 v0, vcc, v1, v12, v1
	v_mul_f32_e32 v4, v0, v11
	v_fma_f32 v13, -v10, v4, v0
	v_fmac_f32_e32 v4, v13, v11
	v_add_f32_e64 v8, v8, 1.0
	v_add_f32_e64 v9, v9, 1.0
	v_fma_f32 v0, -v10, v4, v0
	v_div_scale_f32 v10, s[6:7], v9, v9, v6
	v_rcp_f32_e32 v13, v10
	v_div_fmas_f32 v0, v0, v11, v4
	v_div_fixup_f32 v4, v0, v12, v1
	v_fma_f32 v4, v208, v4, v216
	v_fma_f32 v5, v208, v5, v217
	v_fma_f32 v0, -v10, v13, 1.0
	v_fmac_f32_e32 v13, v0, v13
	v_div_scale_f32 v0, vcc, v6, v9, v6
	v_mul_f32_e32 v1, v0, v13
	v_fma_f32 v11, -v10, v1, v0
	v_fmac_f32_e32 v1, v11, v13
	v_fma_f32 v0, -v10, v1, v0
	v_div_scale_f32 v10, s[6:7], v8, v8, v2
	v_rcp_f32_e32 v11, v10
	v_div_fmas_f32 v0, v0, v13, v1
	v_div_fixup_f32 v1, v0, v9, v6
	v_lshl_add_u64 v[222:223], v[114:115], 2, v[160:161]
	v_fma_f32 v0, -v10, v11, 1.0
	v_fmac_f32_e32 v11, v0, v11
	v_div_scale_f32 v0, vcc, v2, v8, v2
	v_mul_f32_e32 v6, v0, v11
	v_fma_f32 v9, -v10, v6, v0
	v_fmac_f32_e32 v6, v9, v11
	v_fma_f32 v0, -v10, v6, v0
	v_div_fmas_f32 v0, v0, v11, v6
	v_div_fixup_f32 v0, v0, v8, v2
	global_load_dwordx4 v[32:35], v[132:133], off offset:60
	global_load_dwordx4 v[8:11], v[132:133], off offset:108
	global_load_dwordx4 v[16:19], v[132:133], off offset:92
	global_load_dwordx4 v[12:15], v[136:137], off offset:48
	global_load_dwordx4 v[212:215], v[136:137], off
	global_load_dwordx4 v[20:23], v[136:137], off offset:32
	v_mul_f32_e32 v2, 0xbfb8aa3b, v3
	v_exp_f32_e32 v218, v2
	v_mul_f32_e32 v2, 0xbfb8aa3b, v7
	v_exp_f32_e32 v219, v2
	s_waitcnt vmcnt(7)
	v_mul_f32_e32 v2, 0xbfb8aa3b, v24
	v_exp_f32_e32 v220, v2
	s_waitcnt vmcnt(6)
; DI void ada_item(const Params& p, float* red, int item) {
;     ...
;   for (int kq = 0; kq < 2; ++kq) {
;     float wv[32];
; #pragma unroll
;     for (int j = 0; j < 32; ++j) wv[j] = p.w_ada[(size_t)(ks * 64 + kq * 32 + j) * 3072 + n];
; #pragma unroll
;     for (int j = 0; j < 32; ++j) {
;       const int k = ks * 64 + kq * 32 + j;
;       const float c0 = p.c[k], c1 = p.c[1024 + k];
;       a0 += (c0 / (1.f + __expf(-c0))) * wv[j];
;       a1 += (c1 / (1.f + __expf(-c1))) * wv[j];
;     }
	v_mul_f32_e32 v2, 0xbfb8aa3b, v28
	v_add_f32_e64 v218, v218, 1.0
	v_add_f32_e64 v219, v219, 1.0
	v_exp_f32_e32 v221, v2
	v_div_scale_f32 v6, s[6:7], v219, v219, v7
	v_rcp_f32_e32 v145, v6
	v_fma_f32 v0, v210, v0, v4
	v_fma_f32 v1, v210, v1, v5
	v_div_scale_f32 v187, s[6:7], v218, v218, v3
	v_fma_f32 v2, -v6, v145, 1.0
	v_fmac_f32_e32 v145, v2, v145
	v_div_scale_f32 v2, vcc, v7, v219, v7
	v_mul_f32_e32 v4, v2, v145
	v_fma_f32 v5, -v6, v4, v2
	v_fmac_f32_e32 v4, v5, v145
	v_fma_f32 v2, -v6, v4, v2
	v_rcp_f32_e32 v189, v187
	v_div_fmas_f32 v2, v2, v145, v4
	v_div_fixup_f32 v5, v2, v219, v7
	v_mul_f32_e32 v6, 0xbfb8aa3b, v36
	v_mul_f32_e32 v7, 0xbfb8aa3b, v44
	v_exp_f32_e32 v6, v6
	v_exp_f32_e32 v7, v7
	v_fma_f32 v2, -v187, v189, 1.0
	v_fmac_f32_e32 v189, v2, v189
	v_div_scale_f32 v2, vcc, v3, v218, v3
	v_mul_f32_e32 v4, v2, v189
	v_fma_f32 v145, -v187, v4, v2
	v_add_f32_e64 v6, v6, 1.0
	v_add_f32_e64 v7, v7, 1.0
	v_fmac_f32_e32 v4, v145, v189
	v_div_scale_f32 v145, s[6:7], v7, v7, v44
	v_fma_f32 v2, -v187, v4, v2
	v_rcp_f32_e32 v187, v145
	v_div_fmas_f32 v2, v2, v189, v4
	v_div_fixup_f32 v4, v2, v218, v3
	v_fma_f32 v0, v206, v4, v0
	v_fma_f32 v1, v206, v5, v1
	v_fma_f32 v2, -v145, v187, 1.0
	v_fmac_f32_e32 v187, v2, v187
	v_div_scale_f32 v2, vcc, v44, v7, v44
	v_mul_f32_e32 v3, v2, v187
	v_fma_f32 v4, -v145, v3, v2
	v_fmac_f32_e32 v3, v4, v187
	v_fma_f32 v2, -v145, v3, v2
	v_div_scale_f32 v145, s[6:7], v6, v6, v36
	v_rcp_f32_e32 v189, v145
	v_mul_f32_e32 v4, 0xbfb8aa3b, v37
	v_mul_f32_e32 v5, 0xbfb8aa3b, v45
	v_div_fmas_f32 v2, v2, v187, v3
	v_exp_f32_e32 v4, v4
	v_exp_f32_e32 v5, v5
	v_div_fixup_f32 v3, v2, v7, v44
	v_fma_f32 v2, -v145, v189, 1.0
	v_fmac_f32_e32 v189, v2, v189
	v_div_scale_f32 v2, vcc, v36, v6, v36
	v_mul_f32_e32 v7, v2, v189
	v_fma_f32 v44, -v145, v7, v2
	v_add_f32_e64 v4, v4, 1.0
	v_add_f32_e64 v5, v5, 1.0
	v_fmac_f32_e32 v7, v44, v189
	v_div_scale_f32 v44, s[6:7], v5, v5, v45
	v_fma_f32 v2, -v145, v7, v2
	v_rcp_f32_e32 v145, v44
	v_div_fmas_f32 v2, v2, v189, v7
	v_div_fixup_f32 v2, v2, v6, v36
	v_fma_f32 v0, v204, v2, v0
	v_fma_f32 v1, v204, v3, v1
	v_fma_f32 v2, -v44, v145, 1.0
	v_fmac_f32_e32 v145, v2, v145
	v_div_scale_f32 v2, vcc, v45, v5, v45
	v_mul_f32_e32 v3, v2, v145
	v_fma_f32 v6, -v44, v3, v2
	v_fmac_f32_e32 v3, v6, v145
	v_div_scale_f32 v36, s[6:7], v4, v4, v37
	v_fma_f32 v2, -v44, v3, v2
	v_rcp_f32_e32 v44, v36
	v_div_fmas_f32 v2, v2, v145, v3
	v_mul_f32_e32 v6, 0xbfb8aa3b, v38
	v_mul_f32_e32 v7, 0xbfb8aa3b, v46
	v_div_fixup_f32 v3, v2, v5, v45
	v_fma_f32 v2, -v36, v44, 1.0
	v_exp_f32_e32 v6, v6
	v_exp_f32_e32 v7, v7
	v_fmac_f32_e32 v44, v2, v44
	v_div_scale_f32 v2, vcc, v37, v4, v37
	v_mul_f32_e32 v5, v2, v44
	v_fma_f32 v45, -v36, v5, v2
	v_fmac_f32_e32 v5, v45, v44
	v_add_f32_e64 v6, v6, 1.0
	v_add_f32_e64 v7, v7, 1.0
	v_fma_f32 v2, -v36, v5, v2
	v_div_scale_f32 v36, s[6:7], v7, v7, v46
	v_rcp_f32_e32 v45, v36
	v_div_fmas_f32 v2, v2, v44, v5
	v_div_fixup_f32 v2, v2, v4, v37
	v_fma_f32 v0, v202, v2, v0
	v_fma_f32 v1, v202, v3, v1
	v_fma_f32 v2, -v36, v45, 1.0
	v_fmac_f32_e32 v45, v2, v45
	v_div_scale_f32 v2, vcc, v46, v7, v46
	v_mul_f32_e32 v3, v2, v45
	v_fma_f32 v4, -v36, v3, v2
	v_fmac_f32_e32 v3, v4, v45
	v_fma_f32 v2, -v36, v3, v2
	v_div_scale_f32 v36, s[6:7], v6, v6, v38
	v_rcp_f32_e32 v37, v36
	v_div_fmas_f32 v2, v2, v45, v3
	s_waitcnt vmcnt(5)
	v_mul_f32_e32 v4, 0xbfb8aa3b, v32
	s_waitcnt vmcnt(1)
	v_mul_f32_e32 v5, 0xbfb8aa3b, v212
	v_div_fixup_f32 v3, v2, v7, v46
	v_fma_f32 v2, -v36, v37, 1.0
	v_exp_f32_e32 v4, v4
	v_exp_f32_e32 v5, v5
	v_fmac_f32_e32 v37, v2, v37
	v_div_scale_f32 v2, vcc, v38, v6, v38
	v_mul_f32_e32 v7, v2, v37
	v_fma_f32 v44, -v36, v7, v2
	v_fmac_f32_e32 v7, v44, v37
	v_add_f32_e64 v4, v4, 1.0
	v_add_f32_e64 v5, v5, 1.0
	v_fma_f32 v2, -v36, v7, v2
	v_div_scale_f32 v36, s[6:7], v5, v5, v212
	v_rcp_f32_e32 v44, v36
	v_div_fmas_f32 v2, v2, v37, v7
	v_div_fixup_f32 v2, v2, v6, v38
	v_fma_f32 v0, v200, v2, v0
	v_fma_f32 v1, v200, v3, v1
	v_fma_f32 v2, -v36, v44, 1.0
	v_fmac_f32_e32 v44, v2, v44
	v_div_scale_f32 v2, vcc, v212, v5, v212
	v_mul_f32_e32 v3, v2, v44
	v_fma_f32 v6, -v36, v3, v2
	v_fmac_f32_e32 v3, v6, v44
	v_fma_f32 v2, -v36, v3, v2
	v_div_scale_f32 v36, s[6:7], v4, v4, v32
	v_rcp_f32_e32 v37, v36
	v_div_fmas_f32 v2, v2, v44, v3
	v_mul_f32_e32 v6, 0xbfb8aa3b, v33
	v_mul_f32_e32 v7, 0xbfb8aa3b, v213
	v_div_fixup_f32 v3, v2, v5, v212
	v_fma_f32 v2, -v36, v37, 1.0
	v_exp_f32_e32 v6, v6
	v_exp_f32_e32 v7, v7
	v_fmac_f32_e32 v37, v2, v37
	v_div_scale_f32 v2, vcc, v32, v4, v32
	v_mul_f32_e32 v5, v2, v37
	v_fma_f32 v38, -v36, v5, v2
	v_fmac_f32_e32 v5, v38, v37
	v_add_f32_e64 v6, v6, 1.0
	v_add_f32_e64 v7, v7, 1.0
	v_fma_f32 v2, -v36, v5, v2
	v_div_scale_f32 v36, s[6:7], v7, v7, v213
	v_rcp_f32_e32 v38, v36
	v_div_fmas_f32 v2, v2, v37, v5
	v_div_fixup_f32 v2, v2, v4, v32
	v_fma_f32 v0, v198, v2, v0
	v_fma_f32 v1, v198, v3, v1
	v_fma_f32 v2, -v36, v38, 1.0
	v_fmac_f32_e32 v38, v2, v38
	v_div_scale_f32 v2, vcc, v213, v7, v213
	v_mul_f32_e32 v3, v2, v38
	v_fma_f32 v4, -v36, v3, v2
	v_fmac_f32_e32 v3, v4, v38
	v_div_scale_f32 v32, s[6:7], v6, v6, v33
	v_fma_f32 v2, -v36, v3, v2
	v_rcp_f32_e32 v36, v32
	v_div_fmas_f32 v2, v2, v38, v3
	v_mul_f32_e32 v4, 0xbfb8aa3b, v34
	v_mul_f32_e32 v5, 0xbfb8aa3b, v214
	v_div_fixup_f32 v3, v2, v7, v213
	v_fma_f32 v2, -v32, v36, 1.0
	v_exp_f32_e32 v4, v4
	v_exp_f32_e32 v5, v5
	v_fmac_f32_e32 v36, v2, v36
	v_div_scale_f32 v2, vcc, v33, v6, v33
	v_mul_f32_e32 v7, v2, v36
	v_fma_f32 v37, -v32, v7, v2
	v_fmac_f32_e32 v7, v37, v36
	v_add_f32_e64 v4, v4, 1.0
	v_add_f32_e64 v5, v5, 1.0
	v_fma_f32 v2, -v32, v7, v2
	v_div_scale_f32 v32, s[6:7], v5, v5, v214
; DI void ada_item(const Params& p, float* red, int item) {
;     ...
;   for (int kq = 0; kq < 2; ++kq) {
;     float wv[32];
; #pragma unroll
;     for (int j = 0; j < 32; ++j) wv[j] = p.w_ada[(size_t)(ks * 64 + kq * 32 + j) * 3072 + n];
; #pragma unroll
;     for (int j = 0; j < 32; ++j) {
;       const int k = ks * 64 + kq * 32 + j;
;       const float c0 = p.c[k], c1 = p.c[1024 + k];
;       a0 += (c0 / (1.f + __expf(-c0))) * wv[j];
;       a1 += (c1 / (1.f + __expf(-c1))) * wv[j];
;     }
	v_rcp_f32_e32 v37, v32
	v_div_fmas_f32 v2, v2, v36, v7
	v_div_fixup_f32 v2, v2, v6, v33
	v_fma_f32 v0, v196, v2, v0
	v_fma_f32 v1, v196, v3, v1
	v_fma_f32 v2, -v32, v37, 1.0
	v_fmac_f32_e32 v37, v2, v37
	v_div_scale_f32 v2, vcc, v214, v5, v214
	v_mul_f32_e32 v3, v2, v37
	v_fma_f32 v6, -v32, v3, v2
	v_fmac_f32_e32 v3, v6, v37
	v_fma_f32 v2, -v32, v3, v2
	v_div_scale_f32 v32, s[6:7], v4, v4, v34
	v_rcp_f32_e32 v33, v32
	v_div_fmas_f32 v2, v2, v37, v3
	v_mul_f32_e32 v6, 0xbfb8aa3b, v35
	v_mul_f32_e32 v7, 0xbfb8aa3b, v215
	v_div_fixup_f32 v3, v2, v5, v214
	v_fma_f32 v2, -v32, v33, 1.0
	v_exp_f32_e32 v6, v6
	v_exp_f32_e32 v7, v7
	v_fmac_f32_e32 v33, v2, v33
	v_div_scale_f32 v2, vcc, v34, v4, v34
	v_mul_f32_e32 v5, v2, v33
	v_fma_f32 v36, -v32, v5, v2
	v_fmac_f32_e32 v5, v36, v33
	v_add_f32_e64 v6, v6, 1.0
	v_add_f32_e64 v7, v7, 1.0
	v_fma_f32 v2, -v32, v5, v2
	v_div_scale_f32 v32, s[6:7], v7, v7, v215
	v_rcp_f32_e32 v36, v32
	v_div_fmas_f32 v2, v2, v33, v5
	v_div_fixup_f32 v2, v2, v4, v34
	v_fma_f32 v0, v194, v2, v0
	v_fma_f32 v1, v194, v3, v1
	v_fma_f32 v2, -v32, v36, 1.0
	v_fmac_f32_e32 v36, v2, v36
	v_div_scale_f32 v2, vcc, v215, v7, v215
	v_mul_f32_e32 v3, v2, v36
	v_fma_f32 v4, -v32, v3, v2
	v_fmac_f32_e32 v3, v4, v36
	v_div_scale_f32 v4, s[6:7], v6, v6, v35
	v_fma_f32 v2, -v32, v3, v2
	v_rcp_f32_e32 v32, v4
	v_div_fmas_f32 v2, v2, v36, v3
	v_div_fixup_f32 v3, v2, v7, v215
	v_lshl_add_u64 v[44:45], v[88:89], 2, v[160:161]
	v_fma_f32 v2, -v4, v32, 1.0
	v_fmac_f32_e32 v32, v2, v32
	v_div_scale_f32 v2, vcc, v35, v6, v35
	v_mul_f32_e32 v7, v2, v32
	v_fma_f32 v5, -v4, v7, v2
	v_fmac_f32_e32 v7, v5, v32
	v_fma_f32 v2, -v4, v7, v2
	v_add_f32_e64 v4, v220, 1.0
	v_add_f32_e64 v5, v221, 1.0
	v_div_fmas_f32 v2, v2, v32, v7
	v_div_scale_f32 v33, s[6:7], v5, v5, v28
	v_rcp_f32_e32 v34, v33
	v_div_fixup_f32 v2, v2, v6, v35
	v_fma_f32 v0, v192, v2, v0
	v_fma_f32 v1, v192, v3, v1
	v_div_scale_f32 v32, s[6:7], v4, v4, v24
	v_fma_f32 v2, -v33, v34, 1.0
	v_fmac_f32_e32 v34, v2, v34
	v_div_scale_f32 v2, vcc, v28, v5, v28
	v_mul_f32_e32 v3, v2, v34
	v_fma_f32 v6, -v33, v3, v2
	v_fmac_f32_e32 v3, v6, v34
	v_fma_f32 v2, -v33, v3, v2
	v_rcp_f32_e32 v33, v32
	v_mul_f32_e32 v6, 0xbfb8aa3b, v25
	v_mul_f32_e32 v7, 0xbfb8aa3b, v29
	v_div_fmas_f32 v2, v2, v34, v3
	v_exp_f32_e32 v6, v6
	v_exp_f32_e32 v7, v7
	v_div_fixup_f32 v3, v2, v5, v28
	v_fma_f32 v2, -v32, v33, 1.0
	v_fmac_f32_e32 v33, v2, v33
	v_div_scale_f32 v2, vcc, v24, v4, v24
	v_mul_f32_e32 v5, v2, v33
	v_fma_f32 v28, -v32, v5, v2
	v_add_f32_e64 v6, v6, 1.0
	v_add_f32_e64 v7, v7, 1.0
	v_fmac_f32_e32 v5, v28, v33
	v_div_scale_f32 v28, s[6:7], v7, v7, v29
	v_fma_f32 v2, -v32, v5, v2
	v_rcp_f32_e32 v32, v28
	v_div_fmas_f32 v2, v2, v33, v5
	v_div_fixup_f32 v2, v2, v4, v24
	v_fma_f32 v4, v190, v2, v0
	v_fma_f32 v5, v190, v3, v1
	v_fma_f32 v0, -v28, v32, 1.0
	v_fmac_f32_e32 v32, v0, v32
	v_div_scale_f32 v0, vcc, v29, v7, v29
	v_mul_f32_e32 v1, v0, v32
	v_fma_f32 v2, -v28, v1, v0
	v_fmac_f32_e32 v1, v2, v32
	v_div_scale_f32 v2, s[6:7], v6, v6, v25
	v_rcp_f32_e32 v3, v2
	v_fma_f32 v0, -v28, v1, v0
	v_div_fmas_f32 v0, v0, v32, v1
	v_div_fixup_f32 v7, v0, v7, v29
	v_fma_f32 v0, -v2, v3, 1.0
	v_fmac_f32_e32 v3, v0, v3
	v_mul_f32_e32 v0, 0xbfb8aa3b, v26
	v_mul_f32_e32 v1, 0xbfb8aa3b, v30
	v_exp_f32_e32 v0, v0
	v_exp_f32_e32 v1, v1
	v_div_scale_f32 v24, vcc, v25, v6, v25
	v_mul_f32_e32 v28, v24, v3
	v_fma_f32 v29, -v2, v28, v24
	v_fmac_f32_e32 v28, v29, v3
	v_add_f32_e64 v0, v0, 1.0
	v_add_f32_e64 v1, v1, 1.0
	v_fma_f32 v2, -v2, v28, v24
	v_div_scale_f32 v24, s[6:7], v1, v1, v30
	v_rcp_f32_e32 v29, v24
	v_div_fmas_f32 v2, v2, v3, v28
	v_div_fixup_f32 v6, v2, v6, v25
	v_fma_f32 v4, v186, v6, v4
	v_fma_f32 v5, v186, v7, v5
	v_fma_f32 v2, -v24, v29, 1.0
	v_fmac_f32_e32 v29, v2, v29
	v_div_scale_f32 v2, vcc, v30, v1, v30
	v_mul_f32_e32 v3, v2, v29
	v_fma_f32 v25, -v24, v3, v2
	v_fmac_f32_e32 v3, v25, v29
	v_fma_f32 v2, -v24, v3, v2
	v_div_scale_f32 v24, s[6:7], v0, v0, v26
	v_rcp_f32_e32 v28, v24
	v_div_fmas_f32 v2, v2, v29, v3
	v_div_fixup_f32 v25, v2, v1, v30
	v_lshl_add_u64 v[192:193], v[92:93], 2, v[160:161]
	v_fma_f32 v1, -v24, v28, 1.0
	v_fmac_f32_e32 v28, v1, v28
	v_div_scale_f32 v1, vcc, v26, v0, v26
	v_mul_f32_e32 v2, v1, v28
	v_fma_f32 v3, -v24, v2, v1
	v_fmac_f32_e32 v2, v3, v28
	v_fma_f32 v1, -v24, v2, v1
	v_div_fmas_f32 v1, v1, v28, v2
	v_div_fixup_f32 v24, v1, v0, v26
	v_mul_f32_e32 v1, 0xbfb8aa3b, v27
	v_exp_f32_e32 v28, v1
	v_mul_f32_e32 v1, 0xbfb8aa3b, v31
	v_exp_f32_e32 v29, v1
	v_mul_f32_e32 v26, 0xbfb8aa3b, v15
	v_fma_f32 v4, v188, v24, v4
	v_fma_f32 v5, v188, v25, v5
	v_exp_f32_e32 v33, v26
	v_add_f32_e64 v28, v28, 1.0
	v_add_f32_e64 v29, v29, 1.0
	s_waitcnt vmcnt(0)
; DI void ada_item(const Params& p, float* red, int item) {
;     ...
;   for (int kq = 0; kq < 2; ++kq) {
;     float wv[32];
; #pragma unroll
;     for (int j = 0; j < 32; ++j) wv[j] = p.w_ada[(size_t)(ks * 64 + kq * 32 + j) * 3072 + n];
; #pragma unroll
;     for (int j = 0; j < 32; ++j) {
;       const int k = ks * 64 + kq * 32 + j;
;       const float c0 = p.c[k], c1 = p.c[1024 + k];
;       a0 += (c0 / (1.f + __expf(-c0))) * wv[j];
;       a1 += (c1 / (1.f + __expf(-c1))) * wv[j];
;     }
	v_mul_f32_e32 v25, 0xbfb8aa3b, v20
	v_div_scale_f32 v30, s[6:7], v29, v29, v31
	v_rcp_f32_e32 v34, v30
	v_div_scale_f32 v26, s[6:7], v28, v28, v27
	v_exp_f32_e32 v25, v25
	v_fma_f32 v6, -v30, v34, 1.0
	v_fmac_f32_e32 v34, v6, v34
	v_div_scale_f32 v6, vcc, v31, v29, v31
	v_mul_f32_e32 v7, v6, v34
	v_fma_f32 v24, -v30, v7, v6
	v_fmac_f32_e32 v7, v24, v34
	v_fma_f32 v6, -v30, v7, v6
	v_rcp_f32_e32 v30, v26
	v_div_fmas_f32 v6, v6, v34, v7
	v_mul_f32_e32 v24, 0xbfb8aa3b, v16
	v_div_fixup_f32 v7, v6, v29, v31
	v_fma_f32 v6, -v26, v30, 1.0
	v_exp_f32_e32 v24, v24
	v_fmac_f32_e32 v30, v6, v30
	v_div_scale_f32 v6, vcc, v27, v28, v27
	v_mul_f32_e32 v29, v6, v30
	v_fma_f32 v31, -v26, v29, v6
	v_fmac_f32_e32 v29, v31, v30
	v_add_f32_e64 v24, v24, 1.0
	v_add_f32_e64 v25, v25, 1.0
	v_fma_f32 v6, -v26, v29, v6
	v_div_scale_f32 v26, s[6:7], v25, v25, v20
	v_rcp_f32_e32 v31, v26
	v_div_fmas_f32 v6, v6, v30, v29
	v_div_fixup_f32 v6, v6, v28, v27
	v_fma_f32 v4, v184, v6, v4
	v_fma_f32 v5, v184, v7, v5
	v_fma_f32 v6, -v26, v31, 1.0
	v_fmac_f32_e32 v31, v6, v31
	v_div_scale_f32 v6, vcc, v20, v25, v20
	v_mul_f32_e32 v7, v6, v31
	v_fma_f32 v27, -v26, v7, v6
	v_fmac_f32_e32 v7, v27, v31
	v_fma_f32 v6, -v26, v7, v6
	v_div_scale_f32 v28, s[6:7], v24, v24, v16
	v_rcp_f32_e32 v29, v28
	v_div_fmas_f32 v6, v6, v31, v7
	v_div_fixup_f32 v7, v6, v25, v20
	v_mul_f32_e32 v25, 0xbfb8aa3b, v17
	v_exp_f32_e32 v26, v25
	v_mul_f32_e32 v25, 0xbfb8aa3b, v21
	v_exp_f32_e32 v27, v25
	v_fma_f32 v6, -v28, v29, 1.0
	v_fmac_f32_e32 v29, v6, v29
	v_div_scale_f32 v6, vcc, v16, v24, v16
	v_mul_f32_e32 v20, v6, v29
	v_fma_f32 v25, -v28, v20, v6
	v_add_f32_e64 v26, v26, 1.0
	v_add_f32_e64 v27, v27, 1.0
	v_fmac_f32_e32 v20, v25, v29
	v_div_scale_f32 v25, s[6:7], v27, v27, v21
	v_fma_f32 v6, -v28, v20, v6
	v_rcp_f32_e32 v28, v25
	v_div_fmas_f32 v6, v6, v29, v20
	v_div_fixup_f32 v6, v6, v24, v16
	v_fma_f32 v4, v182, v6, v4
	v_fma_f32 v5, v182, v7, v5
	v_fma_f32 v6, -v25, v28, 1.0
	v_fmac_f32_e32 v28, v6, v28
	v_div_scale_f32 v6, vcc, v21, v27, v21
	v_mul_f32_e32 v7, v6, v28
	v_fma_f32 v16, -v25, v7, v6
	v_fmac_f32_e32 v7, v16, v28
	v_div_scale_f32 v16, s[6:7], v26, v26, v17
	v_rcp_f32_e32 v24, v16
	v_fma_f32 v6, -v25, v7, v6
	v_div_fmas_f32 v6, v6, v28, v7
	v_div_fixup_f32 v7, v6, v27, v21
	v_mul_f32_e32 v20, 0xbfb8aa3b, v18
	v_mul_f32_e32 v21, 0xbfb8aa3b, v22
	v_fma_f32 v6, -v16, v24, 1.0
	v_exp_f32_e32 v20, v20
	v_exp_f32_e32 v21, v21
	v_fmac_f32_e32 v24, v6, v24
	v_div_scale_f32 v6, vcc, v17, v26, v17
	v_mul_f32_e32 v25, v6, v24
	v_fma_f32 v27, -v16, v25, v6
	v_fmac_f32_e32 v25, v27, v24
	v_add_f32_e64 v20, v20, 1.0
	v_add_f32_e64 v21, v21, 1.0
	v_fma_f32 v6, -v16, v25, v6
	v_div_scale_f32 v16, s[6:7], v21, v21, v22
	v_rcp_f32_e32 v27, v16
	v_div_fmas_f32 v6, v6, v24, v25
	v_div_fixup_f32 v6, v6, v26, v17
	v_fma_f32 v4, v180, v6, v4
	v_fma_f32 v5, v180, v7, v5
	v_fma_f32 v6, -v16, v27, 1.0
	v_fmac_f32_e32 v27, v6, v27
	v_div_scale_f32 v6, vcc, v22, v21, v22
	v_mul_f32_e32 v7, v6, v27
	v_div_scale_f32 v24, s[6:7], v20, v20, v18
	v_fma_f32 v17, -v16, v7, v6
	v_rcp_f32_e32 v25, v24
	v_fmac_f32_e32 v7, v17, v27
	v_fma_f32 v6, -v16, v7, v6
	v_mul_f32_e32 v16, 0xbfb8aa3b, v19
	v_mul_f32_e32 v17, 0xbfb8aa3b, v23
	v_div_fmas_f32 v6, v6, v27, v7
	v_exp_f32_e32 v16, v16
	v_exp_f32_e32 v17, v17
	v_div_fixup_f32 v7, v6, v21, v22
	v_fma_f32 v6, -v24, v25, 1.0
	v_fmac_f32_e32 v25, v6, v25
	v_div_scale_f32 v6, vcc, v18, v20, v18
	v_mul_f32_e32 v21, v6, v25
	v_fma_f32 v22, -v24, v21, v6
	v_add_f32_e64 v16, v16, 1.0
	v_add_f32_e64 v17, v17, 1.0
	v_fmac_f32_e32 v21, v22, v25
	v_div_scale_f32 v22, s[6:7], v17, v17, v23
	v_fma_f32 v6, -v24, v21, v6
	v_rcp_f32_e32 v24, v22
	v_div_fmas_f32 v6, v6, v25, v21
	v_div_fixup_f32 v6, v6, v20, v18
	v_fma_f32 v4, v178, v6, v4
	v_fma_f32 v5, v178, v7, v5
	v_fma_f32 v6, -v22, v24, 1.0
	v_fmac_f32_e32 v24, v6, v24
	v_div_scale_f32 v6, vcc, v23, v17, v23
	v_mul_f32_e32 v7, v6, v24
	v_fma_f32 v18, -v22, v7, v6
	v_fmac_f32_e32 v7, v18, v24
	v_div_scale_f32 v18, s[6:7], v16, v16, v19
	v_fma_f32 v6, -v22, v7, v6
	v_rcp_f32_e32 v22, v18
	v_div_fmas_f32 v6, v6, v24, v7
	v_mul_f32_e32 v20, 0xbfb8aa3b, v8
	v_mul_f32_e32 v21, 0xbfb8aa3b, v12
	v_div_fixup_f32 v7, v6, v17, v23
	v_fma_f32 v6, -v18, v22, 1.0
	v_exp_f32_e32 v20, v20
	v_exp_f32_e32 v21, v21
	v_fmac_f32_e32 v22, v6, v22
	v_div_scale_f32 v6, vcc, v19, v16, v19
	v_mul_f32_e32 v17, v6, v22
	v_fma_f32 v23, -v18, v17, v6
	v_fmac_f32_e32 v17, v23, v22
	v_add_f32_e64 v20, v20, 1.0
	v_add_f32_e64 v21, v21, 1.0
	v_fma_f32 v6, -v18, v17, v6
	v_div_scale_f32 v18, s[6:7], v21, v21, v12
	v_rcp_f32_e32 v23, v18
	v_div_fmas_f32 v6, v6, v22, v17
	v_div_fixup_f32 v6, v6, v16, v19
	v_fma_f32 v4, v174, v6, v4
	v_fma_f32 v5, v174, v7, v5
	v_fma_f32 v6, -v18, v23, 1.0
	v_fmac_f32_e32 v23, v6, v23
	v_div_scale_f32 v6, vcc, v12, v21, v12
	v_mul_f32_e32 v7, v6, v23
	v_fma_f32 v16, -v18, v7, v6
	v_fmac_f32_e32 v7, v16, v23
	v_fma_f32 v6, -v18, v7, v6
	v_div_scale_f32 v18, s[6:7], v20, v20, v8
	v_rcp_f32_e32 v19, v18
	v_mul_f32_e32 v16, 0xbfb8aa3b, v9
	v_mul_f32_e32 v17, 0xbfb8aa3b, v13
	v_exp_f32_e32 v16, v16
	v_exp_f32_e32 v17, v17
	v_div_fmas_f32 v6, v6, v23, v7
	v_div_fixup_f32 v7, v6, v21, v12
	v_fma_f32 v6, -v18, v19, 1.0
	v_fmac_f32_e32 v19, v6, v19
	v_div_scale_f32 v6, vcc, v8, v20, v8
	v_mul_f32_e32 v12, v6, v19
	v_add_f32_e64 v24, v16, 1.0
	v_add_f32_e64 v25, v17, 1.0
	v_fma_f32 v21, -v18, v12, v6
	v_div_scale_f32 v16, s[6:7], v25, v25, v13
	v_fmac_f32_e32 v12, v21, v19
	v_rcp_f32_e32 v26, v16
	v_fma_f32 v6, -v18, v12, v6
	v_div_fmas_f32 v6, v6, v19, v12
	v_div_fixup_f32 v6, v6, v20, v8
	v_fma_f32 v4, v172, v6, v4
	v_fma_f32 v5, v172, v7, v5
; DI void ada_item(const Params& p, float* red, int item) {
;     ...
;   for (int kq = 0; kq < 2; ++kq) {
;     float wv[32];
; #pragma unroll
;     for (int j = 0; j < 32; ++j) wv[j] = p.w_ada[(size_t)(ks * 64 + kq * 32 + j) * 3072 + n];
; #pragma unroll
;     for (int j = 0; j < 32; ++j) {
;       const int k = ks * 64 + kq * 32 + j;
;       const float c0 = p.c[k], c1 = p.c[1024 + k];
;       a0 += (c0 / (1.f + __expf(-c0))) * wv[j];
;       a1 += (c1 / (1.f + __expf(-c1))) * wv[j];
;     }
	v_fma_f32 v6, -v16, v26, 1.0
	v_fmac_f32_e32 v26, v6, v26
	v_div_scale_f32 v6, vcc, v13, v25, v13
	v_mul_f32_e32 v7, v6, v26
	v_fma_f32 v8, -v16, v7, v6
	v_mul_f32_e32 v0, 0xbfb8aa3b, v11
	v_fmac_f32_e32 v7, v8, v26
	v_exp_f32_e32 v32, v0
	global_load_dwordx4 v[0:3], v[138:139], off
	v_fma_f32 v6, -v16, v7, v6
	global_load_dwordx4 v[16:19], v[132:133], off offset:140
	global_load_dwordx4 v[20:23], v[132:133], off offset:124
	v_div_scale_f32 v8, s[6:7], v24, v24, v9
	v_rcp_f32_e32 v27, v8
	v_div_fmas_f32 v6, v6, v26, v7
	v_div_fixup_f32 v7, v6, v25, v13
	v_mul_f32_e32 v12, 0xbfb8aa3b, v10
	v_mul_f32_e32 v13, 0xbfb8aa3b, v14
	v_fma_f32 v6, -v8, v27, 1.0
	v_exp_f32_e32 v12, v12
	v_exp_f32_e32 v13, v13
	v_fmac_f32_e32 v27, v6, v27
	v_div_scale_f32 v6, vcc, v9, v24, v9
	v_mul_f32_e32 v25, v6, v27
	v_fma_f32 v26, -v8, v25, v6
	v_fmac_f32_e32 v25, v26, v27
	v_add_f32_e64 v12, v12, 1.0
	v_add_f32_e64 v13, v13, 1.0
	v_fma_f32 v6, -v8, v25, v6
	v_div_scale_f32 v8, s[6:7], v13, v13, v14
	v_rcp_f32_e32 v26, v8
	v_div_fmas_f32 v6, v6, v27, v25
	v_div_fixup_f32 v6, v6, v24, v9
	v_fma_f32 v4, v170, v6, v4
	v_fma_f32 v5, v170, v7, v5
	v_fma_f32 v6, -v8, v26, 1.0
	v_fmac_f32_e32 v26, v6, v26
	v_div_scale_f32 v6, vcc, v14, v13, v14
	v_mul_f32_e32 v7, v6, v26
	v_fma_f32 v9, -v8, v7, v6
	v_fmac_f32_e32 v7, v9, v26
	v_fma_f32 v6, -v8, v7, v6
	v_div_scale_f32 v8, s[6:7], v12, v12, v10
	v_rcp_f32_e32 v24, v8
	v_div_fmas_f32 v6, v6, v26, v7
	v_div_fixup_f32 v7, v6, v13, v14
	v_lshl_add_u64 v[188:189], v[90:91], 2, v[160:161]
	v_fma_f32 v6, -v8, v24, 1.0
	v_fmac_f32_e32 v24, v6, v24
	v_div_scale_f32 v6, vcc, v10, v12, v10
	v_mul_f32_e32 v13, v6, v24
	v_fma_f32 v9, -v8, v13, v6
	v_fmac_f32_e32 v13, v9, v24
	v_fma_f32 v6, -v8, v13, v6
	v_add_f32_e64 v8, v32, 1.0
	v_add_f32_e64 v9, v33, 1.0
	v_div_fmas_f32 v6, v6, v24, v13
	v_div_scale_f32 v14, s[6:7], v9, v9, v15
	v_rcp_f32_e32 v25, v14
	v_div_fixup_f32 v6, v6, v12, v10
	v_fma_f32 v4, v168, v6, v4
	v_fma_f32 v5, v168, v7, v5
	v_lshl_add_u64 v[218:219], v[102:103], 2, v[160:161]
	v_fma_f32 v6, -v14, v25, 1.0
	v_fmac_f32_e32 v25, v6, v25
	v_div_scale_f32 v6, vcc, v15, v9, v15
	v_mul_f32_e32 v7, v6, v25
	v_fma_f32 v10, -v14, v7, v6
	v_fmac_f32_e32 v7, v10, v25
	v_div_scale_f32 v10, s[6:7], v8, v8, v11
	v_rcp_f32_e32 v12, v10
	v_fma_f32 v6, -v14, v7, v6
	v_div_fmas_f32 v6, v6, v25, v7
	v_div_fixup_f32 v7, v6, v9, v15
	v_fma_f32 v6, -v10, v12, 1.0
	v_fmac_f32_e32 v12, v6, v12
	v_div_scale_f32 v6, vcc, v11, v8, v11
	v_mul_f32_e32 v9, v6, v12
	v_fma_f32 v13, -v10, v9, v6
	v_fmac_f32_e32 v9, v13, v12
	v_fma_f32 v6, -v10, v9, v6
	v_div_fmas_f32 v6, v6, v12, v9
	v_div_fixup_f32 v6, v6, v8, v11
	s_waitcnt vmcnt(2)
	v_mul_f32_e32 v9, 0xbfb8aa3b, v0
	v_exp_f32_e32 v9, v9
	s_waitcnt vmcnt(0)
	v_mul_f32_e32 v8, 0xbfb8aa3b, v20
	v_exp_f32_e32 v8, v8
	v_fma_f32 v200, v166, v6, v4
	v_fma_f32 v201, v166, v7, v5
	global_load_dwordx3 v[24:26], v[132:133], off offset:172
	global_load_dwordx4 v[4:7], v[132:133], off offset:156
	v_add_f32_e64 v32, v8, 1.0
	v_add_f32_e64 v33, v9, 1.0
	s_nop 0
	v_div_scale_f32 v27, s[6:7], v33, v33, v0
	v_rcp_f32_e32 v31, v27
	global_load_dwordx3 v[28:30], v[138:139], off offset:48
	global_load_dwordx4 v[8:11], v[138:139], off offset:32
	global_load_dwordx4 v[12:15], v[138:139], off offset:16
	v_fma_f32 v34, -v27, v31, 1.0
	v_fmac_f32_e32 v31, v34, v31
	v_div_scale_f32 v34, vcc, v0, v33, v0
	v_mul_f32_e32 v35, v34, v31
	v_fma_f32 v36, -v27, v35, v34
	v_fmac_f32_e32 v35, v36, v31
	v_fma_f32 v27, -v27, v35, v34
	v_div_scale_f32 v34, s[6:7], v32, v32, v20
	v_rcp_f32_e32 v36, v34
	v_div_fmas_f32 v27, v27, v31, v35
	v_div_fixup_f32 v203, v27, v33, v0
	v_fma_f32 v0, -v34, v36, 1.0
	v_fmac_f32_e32 v36, v0, v36
	v_div_scale_f32 v0, vcc, v20, v32, v20
	v_mul_f32_e32 v27, v0, v36
	v_fma_f32 v31, -v34, v27, v0
	v_fmac_f32_e32 v27, v31, v36
	v_fma_f32 v0, -v34, v27, v0
	v_div_fmas_f32 v0, v0, v36, v27
	v_add_co_u32_e32 v36, vcc, s85, v162
	v_div_fixup_f32 v202, v0, v32, v20
	s_nop 0
	v_addc_co_u32_e32 v37, vcc, 0, v163, vcc
	v_add_co_u32_e32 v186, vcc, s86, v162
	v_lshl_add_u64 v[32:33], v[84:85], 2, v[160:161]
	s_nop 0
	v_addc_co_u32_e32 v187, vcc, 0, v163, vcc
	v_add_co_u32_e32 v190, vcc, s87, v162
	v_lshl_add_u64 v[34:35], v[86:87], 2, v[160:161]
	s_nop 0
	v_addc_co_u32_e32 v191, vcc, 0, v163, vcc
	global_load_dword v204, v[32:33], off
	global_load_dword v206, v[34:35], off
	global_load_dword v208, v[36:37], off
	global_load_dword v210, v[44:45], off
	global_load_dword v212, v[186:187], off
	global_load_dword v214, v[188:189], off
	global_load_dword v198, v[190:191], off
	global_load_dword v196, v[192:193], off
	v_add_co_u32_e32 v32, vcc, s88, v162
	v_lshl_add_u64 v[34:35], v[94:95], 2, v[160:161]
	s_nop 0
	v_addc_co_u32_e32 v33, vcc, 0, v163, vcc
	v_add_co_u32_e32 v216, vcc, s89, v162
	v_lshl_add_u64 v[186:187], v[100:101], 2, v[160:161]
	s_nop 0
	v_addc_co_u32_e32 v217, vcc, 0, v163, vcc
	v_add_co_u32_e32 v220, vcc, s90, v162
	v_lshl_add_u64 v[36:37], v[96:97], 2, v[160:161]
	s_nop 0
	v_addc_co_u32_e32 v221, vcc, 0, v163, vcc
	v_lshl_add_u64 v[44:45], v[98:99], 2, v[160:161]
	global_load_dword v0, v[32:33], off
	global_load_dword v194, v[34:35], off
	global_load_dword v190, v[36:37], off
	global_load_dword v192, v[44:45], off
	global_load_dword v188, v[186:187], off
	s_nop 0
	global_load_dword v186, v[216:217], off
	global_load_dword v184, v[218:219], off
	global_load_dword v182, v[220:221], off
	v_add_co_u32_e32 v34, vcc, s91, v162
	v_lshl_add_u64 v[32:33], v[104:105], 2, v[160:161]
	s_nop 0
	v_addc_co_u32_e32 v35, vcc, 0, v163, vcc
	v_add_co_u32_e32 v44, vcc, s92, v162
	v_lshl_add_u64 v[220:221], v[112:113], 2, v[160:161]
; DI void ada_item(const Params& p, float* red, int item) {
;     ...
;   for (int kq = 0; kq < 2; ++kq) {
;     float wv[32];
; #pragma unroll
;     for (int j = 0; j < 32; ++j) wv[j] = p.w_ada[(size_t)(ks * 64 + kq * 32 + j) * 3072 + n];
; #pragma unroll
;     for (int j = 0; j < 32; ++j) {
;       const int k = ks * 64 + kq * 32 + j;
;       const float c0 = p.c[k], c1 = p.c[1024 + k];
;       a0 += (c0 / (1.f + __expf(-c0))) * wv[j];
;       a1 += (c1 / (1.f + __expf(-c1))) * wv[j];
;     }
	v_mul_f32_e32 v27, 0xbfb8aa3b, v21
	v_lshl_add_u64 v[36:37], v[106:107], 2, v[160:161]
	v_addc_co_u32_e32 v45, vcc, 0, v163, vcc
	v_lshl_add_u64 v[216:217], v[108:109], 2, v[160:161]
	v_lshl_add_u64 v[218:219], v[110:111], 2, v[160:161]
	global_load_dword v180, v[32:33], off
	global_load_dword v178, v[34:35], off
	global_load_dword v174, v[36:37], off
	global_load_dword v20, v[44:45], off
	global_load_dword v172, v[216:217], off
	global_load_dword v168, v[218:219], off
	global_load_dword v170, v[220:221], off
	global_load_dword v166, v[222:223], off
	v_exp_f32_e32 v220, v27
	v_mul_f32_e32 v27, 0xbfb8aa3b, v1
	v_exp_f32_e32 v221, v27
	v_add_co_u32_e32 v32, vcc, s93, v162
	v_lshl_add_u64 v[34:35], v[116:117], 2, v[160:161]
	s_nop 0
	v_addc_co_u32_e32 v33, vcc, 0, v163, vcc
	v_add_f32_e64 v220, v220, 1.0
	v_add_f32_e64 v221, v221, 1.0
	v_add_co_u32_e32 v36, vcc, s94, v162
	v_div_scale_f32 v27, s[6:7], v221, v221, v1
	s_nop 0
	v_addc_co_u32_e32 v37, vcc, 0, v163, vcc
	v_rcp_f32_e32 v31, v27
	v_add_co_u32_e32 v216, vcc, s95, v162
	v_lshl_add_u64 v[44:45], v[118:119], 2, v[160:161]
	s_nop 0
	v_addc_co_u32_e32 v217, vcc, 0, v163, vcc
	v_add_co_u32_e32 v222, vcc, s96, v162
	v_lshl_add_u64 v[218:219], v[120:121], 2, v[160:161]
	s_nop 0
	v_addc_co_u32_e32 v223, vcc, 0, v163, vcc
	global_load_dword v162, v[32:33], off
	global_load_dword v160, v[34:35], off
	global_load_dword v46, v[36:37], off
	s_nop 0
	global_load_dword v44, v[44:45], off
	s_nop 0
	global_load_dword v38, v[216:217], off
	global_load_dword v36, v[218:219], off
	global_load_dword v34, v[222:223], off
	global_load_dword v32, v[224:225], off
	v_fma_f32 v33, -v27, v31, 1.0
	v_fmac_f32_e32 v31, v33, v31
	v_div_scale_f32 v33, vcc, v1, v221, v1
	v_mul_f32_e32 v35, v33, v31
	v_fma_f32 v37, -v27, v35, v33
	v_fmac_f32_e32 v35, v37, v31
	v_fma_f32 v27, -v27, v35, v33
	v_div_scale_f32 v33, s[6:7], v220, v220, v21
	v_rcp_f32_e32 v37, v33
	v_div_fmas_f32 v27, v27, v31, v35
	v_div_fixup_f32 v217, v27, v221, v1
	v_fma_f32 v200, v164, v202, v200
	v_fma_f32 v201, v164, v203, v201
	v_fma_f32 v1, -v33, v37, 1.0
	v_fmac_f32_e32 v37, v1, v37
	v_div_scale_f32 v1, vcc, v21, v220, v21
	v_mul_f32_e32 v27, v1, v37
	v_fma_f32 v31, -v33, v27, v1
	v_fmac_f32_e32 v27, v31, v37
	v_fma_f32 v1, -v33, v27, v1
	v_div_fmas_f32 v1, v1, v37, v27
	v_div_fixup_f32 v216, v1, v220, v21
	v_mul_f32_e32 v1, 0xbfb8aa3b, v22
	v_exp_f32_e32 v218, v1
	v_mul_f32_e32 v1, 0xbfb8aa3b, v2
	v_exp_f32_e32 v219, v1
	s_waitcnt vmcnt(35)
	v_mul_f32_e32 v1, 0xbfb8aa3b, v6
	v_exp_f32_e32 v220, v1
	s_waitcnt vmcnt(33)
	v_mul_f32_e32 v1, 0xbfb8aa3b, v10
	v_add_f32_e64 v218, v218, 1.0
	v_add_f32_e64 v219, v219, 1.0
	v_exp_f32_e32 v221, v1
	v_div_scale_f32 v21, s[6:7], v219, v219, v2
	v_rcp_f32_e32 v27, v21
	s_waitcnt vmcnt(31)
	v_fma_f32 v200, v204, v216, v200
	v_fma_f32 v201, v204, v217, v201
	v_fma_f32 v1, -v21, v27, 1.0
	v_fmac_f32_e32 v27, v1, v27
	v_div_scale_f32 v1, vcc, v2, v219, v2
	v_mul_f32_e32 v31, v1, v27
	v_fma_f32 v33, -v21, v31, v1
	v_fmac_f32_e32 v31, v33, v27
	v_fma_f32 v1, -v21, v31, v1
	v_div_scale_f32 v21, s[6:7], v218, v218, v22
	v_rcp_f32_e32 v33, v21
	v_div_fmas_f32 v1, v1, v27, v31
	v_mul_f32_e32 v27, 0xbfb8aa3b, v23
	v_exp_f32_e32 v204, v27
	v_mul_f32_e32 v27, 0xbfb8aa3b, v3
	v_div_fixup_f32 v203, v1, v219, v2
	v_fma_f32 v1, -v21, v33, 1.0
	v_exp_f32_e32 v205, v27
	v_fmac_f32_e32 v33, v1, v33
	v_div_scale_f32 v1, vcc, v22, v218, v22
	v_mul_f32_e32 v2, v1, v33
	v_fma_f32 v27, -v21, v2, v1
	v_fmac_f32_e32 v2, v27, v33
	v_add_f32_e64 v204, v204, 1.0
	v_add_f32_e64 v205, v205, 1.0
	v_fma_f32 v1, -v21, v2, v1
	v_div_scale_f32 v21, s[6:7], v205, v205, v3
	v_rcp_f32_e32 v27, v21
	v_div_fmas_f32 v1, v1, v33, v2
	v_div_fixup_f32 v202, v1, v218, v22
	s_waitcnt vmcnt(30)
	v_fma_f32 v200, v206, v202, v200
	v_fma_f32 v201, v206, v203, v201
	v_fma_f32 v1, -v21, v27, 1.0
	v_fmac_f32_e32 v27, v1, v27
	v_div_scale_f32 v1, vcc, v3, v205, v3
	v_mul_f32_e32 v2, v1, v27
	v_fma_f32 v22, -v21, v2, v1
	v_fmac_f32_e32 v2, v22, v27
	v_fma_f32 v1, -v21, v2, v1
	v_div_scale_f32 v21, s[6:7], v204, v204, v23
	v_rcp_f32_e32 v22, v21
	v_div_fmas_f32 v1, v1, v27, v2
	v_mul_f32_e32 v27, 0xbfb8aa3b, v16
	v_exp_f32_e32 v202, v27
	v_mul_f32_e32 v27, 0xbfb8aa3b, v12
	v_div_fixup_f32 v3, v1, v205, v3
	v_fma_f32 v1, -v21, v22, 1.0
	v_exp_f32_e32 v203, v27
	v_fmac_f32_e32 v22, v1, v22
	v_div_scale_f32 v1, vcc, v23, v204, v23
	v_mul_f32_e32 v2, v1, v22
	v_fma_f32 v27, -v21, v2, v1
	v_fmac_f32_e32 v2, v27, v22
	v_add_f32_e64 v202, v202, 1.0
	v_add_f32_e64 v203, v203, 1.0
	v_fma_f32 v1, -v21, v2, v1
	v_div_scale_f32 v21, s[6:7], v203, v203, v12
	v_rcp_f32_e32 v27, v21
	v_div_fmas_f32 v1, v1, v22, v2
	v_div_fixup_f32 v2, v1, v204, v23
	s_waitcnt vmcnt(29)
	v_fma_f32 v2, v208, v2, v200
	v_fma_f32 v3, v208, v3, v201
	v_fma_f32 v1, -v21, v27, 1.0
	v_fmac_f32_e32 v27, v1, v27
	v_div_scale_f32 v1, vcc, v12, v203, v12
	v_mul_f32_e32 v22, v1, v27
	v_fma_f32 v23, -v21, v22, v1
	v_fmac_f32_e32 v22, v23, v27
	v_fma_f32 v1, -v21, v22, v1
	v_div_scale_f32 v21, s[6:7], v202, v202, v16
	v_rcp_f32_e32 v31, v21
	v_div_fmas_f32 v1, v1, v27, v22
	v_mul_f32_e32 v22, 0xbfb8aa3b, v17
	v_exp_f32_e32 v200, v22
	v_mul_f32_e32 v22, 0xbfb8aa3b, v13
	v_div_fixup_f32 v23, v1, v203, v12
	v_fma_f32 v1, -v21, v31, 1.0
	v_exp_f32_e32 v201, v22
	v_fmac_f32_e32 v31, v1, v31
	v_div_scale_f32 v1, vcc, v16, v202, v16
	v_mul_f32_e32 v12, v1, v31
	v_fma_f32 v22, -v21, v12, v1
	v_fmac_f32_e32 v12, v22, v31
	v_add_f32_e64 v200, v200, 1.0
	v_add_f32_e64 v201, v201, 1.0
	v_fma_f32 v1, -v21, v12, v1
	v_div_scale_f32 v21, s[6:7], v201, v201, v13
	v_rcp_f32_e32 v27, v21
	v_div_fmas_f32 v1, v1, v31, v12
	v_div_fixup_f32 v22, v1, v202, v16
	s_waitcnt vmcnt(28)
; DI void ada_item(const Params& p, float* red, int item) {
;     ...
;   for (int kq = 0; kq < 2; ++kq) {
;     float wv[32];
; #pragma unroll
;     for (int j = 0; j < 32; ++j) wv[j] = p.w_ada[(size_t)(ks * 64 + kq * 32 + j) * 3072 + n];
; #pragma unroll
;     for (int j = 0; j < 32; ++j) {
;       const int k = ks * 64 + kq * 32 + j;
;       const float c0 = p.c[k], c1 = p.c[1024 + k];
;       a0 += (c0 / (1.f + __expf(-c0))) * wv[j];
;       a1 += (c1 / (1.f + __expf(-c1))) * wv[j];
;     }
	v_fma_f32 v2, v210, v22, v2
	v_fma_f32 v3, v210, v23, v3
	v_fma_f32 v1, -v21, v27, 1.0
	v_fmac_f32_e32 v27, v1, v27
	v_div_scale_f32 v1, vcc, v13, v201, v13
	v_mul_f32_e32 v12, v1, v27
	v_fma_f32 v16, -v21, v12, v1
	v_fmac_f32_e32 v12, v16, v27
	v_div_scale_f32 v16, s[6:7], v200, v200, v17
	v_fma_f32 v1, -v21, v12, v1
	v_rcp_f32_e32 v21, v16
	v_div_fmas_f32 v1, v1, v27, v12
	v_mul_f32_e32 v22, 0xbfb8aa3b, v18
	v_mul_f32_e32 v23, 0xbfb8aa3b, v14
	v_div_fixup_f32 v13, v1, v201, v13
	v_fma_f32 v1, -v16, v21, 1.0
	v_exp_f32_e32 v22, v22
	v_exp_f32_e32 v23, v23
	v_fmac_f32_e32 v21, v1, v21
	v_div_scale_f32 v1, vcc, v17, v200, v17
	v_mul_f32_e32 v12, v1, v21
	v_fma_f32 v27, -v16, v12, v1
	v_fmac_f32_e32 v12, v27, v21
	v_add_f32_e64 v22, v22, 1.0
	v_add_f32_e64 v23, v23, 1.0
	v_fma_f32 v1, -v16, v12, v1
	v_div_scale_f32 v16, s[6:7], v23, v23, v14
	v_rcp_f32_e32 v27, v16
	v_div_fmas_f32 v1, v1, v21, v12
	v_div_fixup_f32 v12, v1, v200, v17
	s_waitcnt vmcnt(27)
	v_fma_f32 v2, v212, v12, v2
	v_fma_f32 v3, v212, v13, v3
	v_fma_f32 v1, -v16, v27, 1.0
	v_fmac_f32_e32 v27, v1, v27
	v_div_scale_f32 v1, vcc, v14, v23, v14
	v_mul_f32_e32 v12, v1, v27
	v_fma_f32 v13, -v16, v12, v1
	v_fmac_f32_e32 v12, v13, v27
	v_fma_f32 v1, -v16, v12, v1
	v_div_scale_f32 v21, s[6:7], v22, v22, v18
	v_rcp_f32_e32 v31, v21
	v_div_fmas_f32 v1, v1, v27, v12
	v_div_fixup_f32 v13, v1, v23, v14
	v_mul_f32_e32 v14, 0xbfb8aa3b, v19
	v_exp_f32_e32 v16, v14
	v_mul_f32_e32 v14, 0xbfb8aa3b, v15
	v_exp_f32_e32 v17, v14
	v_fma_f32 v1, -v21, v31, 1.0
	v_fmac_f32_e32 v31, v1, v31
	v_div_scale_f32 v1, vcc, v18, v22, v18
	v_mul_f32_e32 v12, v1, v31
	v_fma_f32 v14, -v21, v12, v1
	v_add_f32_e64 v16, v16, 1.0
	v_add_f32_e64 v17, v17, 1.0
	v_fmac_f32_e32 v12, v14, v31
	v_div_scale_f32 v14, s[6:7], v17, v17, v15
	v_fma_f32 v1, -v21, v12, v1
	v_rcp_f32_e32 v21, v14
	v_div_fmas_f32 v1, v1, v31, v12
	v_div_fixup_f32 v12, v1, v22, v18
	s_waitcnt vmcnt(26)
	v_fma_f32 v2, v214, v12, v2
	v_fma_f32 v3, v214, v13, v3
	v_fma_f32 v1, -v14, v21, 1.0
	v_fmac_f32_e32 v21, v1, v21
	v_div_scale_f32 v1, vcc, v15, v17, v15
	v_mul_f32_e32 v12, v1, v21
	v_fma_f32 v13, -v14, v12, v1
	v_fmac_f32_e32 v12, v13, v21
	v_div_scale_f32 v18, s[6:7], v16, v16, v19
	v_fma_f32 v1, -v14, v12, v1
	v_rcp_f32_e32 v22, v18
	v_div_fmas_f32 v1, v1, v21, v12
	v_div_fixup_f32 v13, v1, v17, v15
	v_mul_f32_e32 v14, 0xbfb8aa3b, v4
	v_mul_f32_e32 v15, 0xbfb8aa3b, v8
	v_exp_f32_e32 v14, v14
	v_exp_f32_e32 v15, v15
	v_fma_f32 v1, -v18, v22, 1.0
	v_fmac_f32_e32 v22, v1, v22
	v_div_scale_f32 v1, vcc, v19, v16, v19
	v_mul_f32_e32 v12, v1, v22
	v_fma_f32 v17, -v18, v12, v1
	v_add_f32_e64 v14, v14, 1.0
	v_add_f32_e64 v15, v15, 1.0
	v_fmac_f32_e32 v12, v17, v22
	v_div_scale_f32 v17, s[6:7], v15, v15, v8
	v_fma_f32 v1, -v18, v12, v1
	v_rcp_f32_e32 v18, v17
	v_div_fmas_f32 v1, v1, v22, v12
	v_div_fixup_f32 v12, v1, v16, v19
	s_waitcnt vmcnt(25)
	v_fma_f32 v2, v198, v12, v2
	v_fma_f32 v3, v198, v13, v3
	v_fma_f32 v1, -v17, v18, 1.0
	v_fmac_f32_e32 v18, v1, v18
	v_div_scale_f32 v1, vcc, v8, v15, v8
	v_mul_f32_e32 v12, v1, v18
	v_fma_f32 v13, -v17, v12, v1
	v_fmac_f32_e32 v12, v13, v18
	v_fma_f32 v1, -v17, v12, v1
	v_div_scale_f32 v19, s[6:7], v14, v14, v4
	v_div_fmas_f32 v1, v1, v18, v12
	v_mul_f32_e32 v12, 0xbfb8aa3b, v5
	v_rcp_f32_e32 v21, v19
	v_exp_f32_e32 v16, v12
	v_mul_f32_e32 v12, 0xbfb8aa3b, v9
	v_exp_f32_e32 v17, v12
	v_div_fixup_f32 v13, v1, v15, v8
	v_fma_f32 v1, -v19, v21, 1.0
	v_fmac_f32_e32 v21, v1, v21
	v_div_scale_f32 v1, vcc, v4, v14, v4
	v_add_f32_e64 v16, v16, 1.0
	v_add_f32_e64 v17, v17, 1.0
	v_mul_f32_e32 v8, v1, v21
	v_div_scale_f32 v15, s[6:7], v17, v17, v9
	v_fma_f32 v12, -v19, v8, v1
	v_rcp_f32_e32 v18, v15
	v_fmac_f32_e32 v8, v12, v21
	v_fma_f32 v1, -v19, v8, v1
	v_div_fmas_f32 v1, v1, v21, v8
	v_div_fixup_f32 v12, v1, v14, v4
	v_fma_f32 v1, -v15, v18, 1.0
	v_fmac_f32_e32 v18, v1, v18
	v_div_scale_f32 v1, vcc, v9, v17, v9
	v_mul_f32_e32 v4, v1, v18
	v_fma_f32 v8, -v15, v4, v1
	v_fmac_f32_e32 v4, v8, v18
	v_div_scale_f32 v8, s[6:7], v16, v16, v5
	s_waitcnt vmcnt(24)
	v_fma_f32 v2, v196, v12, v2
	v_fma_f32 v3, v196, v13, v3
	v_rcp_f32_e32 v12, v8
	v_fma_f32 v1, -v15, v4, v1
	v_div_fmas_f32 v1, v1, v18, v4
	v_div_fixup_f32 v9, v1, v17, v9
	v_fma_f32 v1, -v8, v12, 1.0
	v_fmac_f32_e32 v12, v1, v12
	v_div_scale_f32 v1, vcc, v5, v16, v5
	v_mul_f32_e32 v4, v1, v12
	v_fma_f32 v13, -v8, v4, v1
	v_add_f32_e64 v22, v220, 1.0
	v_add_f32_e64 v23, v221, 1.0
	v_fmac_f32_e32 v4, v13, v12
	v_div_scale_f32 v13, s[6:7], v23, v23, v10
	v_rcp_f32_e32 v14, v13
	v_fma_f32 v1, -v8, v4, v1
	v_div_fmas_f32 v1, v1, v12, v4
	v_div_fixup_f32 v8, v1, v16, v5
	s_waitcnt vmcnt(23)
	v_fma_f32 v4, v0, v8, v2
	v_fma_f32 v5, v0, v9, v3
	v_fma_f32 v0, -v13, v14, 1.0
	v_fmac_f32_e32 v14, v0, v14
	v_div_scale_f32 v0, vcc, v10, v23, v10
	v_mul_f32_e32 v1, v0, v14
	v_div_scale_f32 v8, s[6:7], v22, v22, v6
	v_fma_f32 v2, -v13, v1, v0
	v_rcp_f32_e32 v21, v8
	v_fmac_f32_e32 v1, v2, v14
	v_fma_f32 v0, -v13, v1, v0
	v_div_fmas_f32 v0, v0, v14, v1
	v_div_fixup_f32 v9, v0, v23, v10
	v_fma_f32 v0, -v8, v21, 1.0
	v_fmac_f32_e32 v21, v0, v21
	v_mul_f32_e32 v0, 0xbfb8aa3b, v7
	v_exp_f32_e32 v196, v0
	v_mul_f32_e32 v0, 0xbfb8aa3b, v11
	v_exp_f32_e32 v197, v0
	global_load_dwordx4 v[12:15], v[132:133], off offset:200
	global_load_dwordx4 v[0:3], v[140:141], off offset:32
	global_load_dwordx4 v[16:19], v[140:141], off offset:16
	v_div_scale_f32 v10, vcc, v6, v22, v6
	v_mul_f32_e32 v23, v10, v21
	v_fma_f32 v27, -v8, v23, v10
	v_fmac_f32_e32 v23, v27, v21
	v_add_f32_e64 v198, v196, 1.0
	v_add_f32_e64 v199, v197, 1.0
	v_fma_f32 v8, -v8, v23, v10
	v_div_scale_f32 v10, s[6:7], v199, v199, v11
	v_rcp_f32_e32 v27, v10
	v_div_fmas_f32 v8, v8, v21, v23
	v_div_fixup_f32 v8, v8, v22, v6
	s_waitcnt vmcnt(25)
; DI void ada_item(const Params& p, float* red, int item) {
;     ...
;   for (int kq = 0; kq < 2; ++kq) {
;     float wv[32];
; #pragma unroll
;     for (int j = 0; j < 32; ++j) wv[j] = p.w_ada[(size_t)(ks * 64 + kq * 32 + j) * 3072 + n];
; #pragma unroll
;     for (int j = 0; j < 32; ++j) {
;       const int k = ks * 64 + kq * 32 + j;
;       const float c0 = p.c[k], c1 = p.c[1024 + k];
;       a0 += (c0 / (1.f + __expf(-c0))) * wv[j];
;       a1 += (c1 / (1.f + __expf(-c1))) * wv[j];
;     }
	v_fma_f32 v22, v194, v8, v4
	v_fma_f32 v23, v194, v9, v5
	v_fma_f32 v4, -v10, v27, 1.0
	v_fmac_f32_e32 v27, v4, v27
	v_div_scale_f32 v4, vcc, v11, v199, v11
	v_mul_f32_e32 v5, v4, v27
	v_fma_f32 v6, -v10, v5, v4
	v_fmac_f32_e32 v5, v6, v27
	v_div_scale_f32 v6, s[6:7], v198, v198, v7
	v_rcp_f32_e32 v8, v6
	v_fma_f32 v4, -v10, v5, v4
	v_div_fmas_f32 v4, v4, v27, v5
	v_div_fixup_f32 v203, v4, v199, v11
	v_fma_f32 v4, -v6, v8, 1.0
	v_fmac_f32_e32 v8, v4, v8
	v_div_scale_f32 v9, vcc, v7, v198, v7
	v_mul_f32_e32 v10, v9, v8
	v_fma_f32 v11, -v6, v10, v9
	v_fmac_f32_e32 v10, v11, v8
	v_fma_f32 v6, -v6, v10, v9
	v_div_fmas_f32 v6, v6, v8, v10
	global_load_dwordx4 v[194:197], v[140:141], off
	v_div_fixup_f32 v202, v6, v198, v7
	global_load_dwordx4 v[198:201], v[132:133], off offset:184
	v_mul_f32_e32 v4, 0xbfb8aa3b, v24
	v_mul_f32_e32 v5, 0xbfb8aa3b, v28
	v_exp_f32_e32 v4, v4
	v_exp_f32_e32 v5, v5
	s_waitcnt vmcnt(26)
	v_fma_f32 v22, v190, v202, v22
	v_fma_f32 v23, v190, v203, v23
	v_add_f32_e64 v4, v4, 1.0
	v_add_f32_e64 v5, v5, 1.0
	s_nop 0
	v_div_scale_f32 v9, s[6:7], v5, v5, v28
	v_rcp_f32_e32 v11, v9
	s_nop 0
	v_fma_f32 v6, -v9, v11, 1.0
	v_fmac_f32_e32 v11, v6, v11
	v_div_scale_f32 v6, vcc, v28, v5, v28
	v_mul_f32_e32 v7, v6, v11
	v_fma_f32 v8, -v9, v7, v6
	v_fmac_f32_e32 v7, v8, v11
	v_div_scale_f32 v8, s[6:7], v4, v4, v24
	v_fma_f32 v6, -v9, v7, v6
	v_rcp_f32_e32 v9, v8
	v_div_fmas_f32 v6, v6, v11, v7
	v_mul_f32_e32 v11, 0xbfb8aa3b, v25
	v_div_fixup_f32 v205, v6, v5, v28
	v_fma_f32 v5, -v8, v9, 1.0
	v_exp_f32_e32 v206, v11
	v_mul_f32_e32 v11, 0xbfb8aa3b, v29
	v_fmac_f32_e32 v9, v5, v9
	v_div_scale_f32 v5, vcc, v24, v4, v24
	v_exp_f32_e32 v207, v11
	v_mul_f32_e32 v6, v5, v9
	v_fma_f32 v7, -v8, v6, v5
	v_fmac_f32_e32 v6, v7, v9
	v_fma_f32 v5, -v8, v6, v5
	v_add_f32_e64 v206, v206, 1.0
	v_add_f32_e64 v207, v207, 1.0
	v_div_fmas_f32 v5, v5, v9, v6
	v_div_scale_f32 v21, s[6:7], v207, v207, v29
	v_div_fixup_f32 v204, v5, v4, v24
	v_rcp_f32_e32 v24, v21
	s_waitcnt vmcnt(4)
	v_mul_f32_e32 v11, 0xbfb8aa3b, v14
	v_exp_f32_e32 v208, v11
	s_waitcnt vmcnt(2)
	v_mul_f32_e32 v11, 0xbfb8aa3b, v18
	v_exp_f32_e32 v209, v11
	v_fma_f32 v11, -v21, v24, 1.0
	v_fmac_f32_e32 v24, v11, v24
	v_div_scale_f32 v11, vcc, v29, v207, v29
	v_mul_f32_e32 v27, v11, v24
	v_fma_f32 v28, -v21, v27, v11
	v_fmac_f32_e32 v27, v28, v24
	v_fma_f32 v11, -v21, v27, v11
	v_div_scale_f32 v21, s[6:7], v206, v206, v25
	v_rcp_f32_e32 v28, v21
	v_div_fmas_f32 v11, v11, v24, v27
	v_mul_f32_e32 v27, 0xbfb8aa3b, v26
	v_exp_f32_e32 v190, v27
	v_mul_f32_e32 v27, 0xbfb8aa3b, v30
	v_div_fixup_f32 v29, v11, v207, v29
	v_fma_f32 v11, -v21, v28, 1.0
	v_exp_f32_e32 v191, v27
	v_fmac_f32_e32 v28, v11, v28
	v_div_scale_f32 v11, vcc, v25, v206, v25
	v_mul_f32_e32 v24, v11, v28
	v_fma_f32 v27, -v21, v24, v11
	v_fmac_f32_e32 v24, v27, v28
	v_add_f32_e64 v190, v190, 1.0
	v_add_f32_e64 v191, v191, 1.0
	v_fma_f32 v11, -v21, v24, v11
	v_div_scale_f32 v21, s[6:7], v191, v191, v30
	v_rcp_f32_e32 v27, v21
	v_div_fmas_f32 v11, v11, v28, v24
	v_div_fixup_f32 v28, v11, v206, v25
	v_fma_f32 v22, v192, v204, v22
	v_fma_f32 v23, v192, v205, v23
	v_fma_f32 v11, -v21, v27, 1.0
	v_fmac_f32_e32 v27, v11, v27
	v_div_scale_f32 v11, vcc, v30, v191, v30
	v_mul_f32_e32 v24, v11, v27
	v_fma_f32 v25, -v21, v24, v11
	v_fmac_f32_e32 v24, v25, v27
	v_fma_f32 v11, -v21, v24, v11
	v_div_scale_f32 v21, s[6:7], v190, v190, v26
	v_rcp_f32_e32 v31, v21
	v_div_fmas_f32 v11, v11, v27, v24
	s_waitcnt vmcnt(0)
	v_mul_f32_e32 v27, 0xbfb8aa3b, v198
	v_fma_f32 v22, v188, v28, v22
	v_fma_f32 v23, v188, v29, v23
	v_exp_f32_e32 v28, v27
	v_mul_f32_e32 v27, 0xbfb8aa3b, v194
	v_div_fixup_f32 v25, v11, v191, v30
	v_fma_f32 v11, -v21, v31, 1.0
	v_exp_f32_e32 v29, v27
	v_fmac_f32_e32 v31, v11, v31
	v_div_scale_f32 v11, vcc, v26, v190, v26
	v_mul_f32_e32 v24, v11, v31
	v_fma_f32 v27, -v21, v24, v11
	v_fmac_f32_e32 v24, v27, v31
	v_add_f32_e64 v28, v28, 1.0
	v_add_f32_e64 v29, v29, 1.0
	v_fma_f32 v11, -v21, v24, v11
	v_div_scale_f32 v21, s[6:7], v29, v29, v194
	v_rcp_f32_e32 v27, v21
	v_div_fmas_f32 v11, v11, v31, v24
	v_div_fixup_f32 v24, v11, v190, v26
	v_fma_f32 v22, v186, v24, v22
	v_fma_f32 v23, v186, v25, v23
	v_fma_f32 v11, -v21, v27, 1.0
	v_fmac_f32_e32 v27, v11, v27
	v_div_scale_f32 v11, vcc, v194, v29, v194
	v_mul_f32_e32 v24, v11, v27
	v_fma_f32 v25, -v21, v24, v11
	v_fmac_f32_e32 v24, v25, v27
	v_fma_f32 v11, -v21, v24, v11
	v_div_scale_f32 v21, s[6:7], v28, v28, v198
	v_rcp_f32_e32 v30, v21
	v_div_fmas_f32 v11, v11, v27, v24
	v_mul_f32_e32 v26, 0xbfb8aa3b, v199
	v_mul_f32_e32 v27, 0xbfb8aa3b, v195
	v_div_fixup_f32 v25, v11, v29, v194
	v_fma_f32 v11, -v21, v30, 1.0
	v_exp_f32_e32 v26, v26
	v_exp_f32_e32 v27, v27
	v_fmac_f32_e32 v30, v11, v30
	v_div_scale_f32 v11, vcc, v198, v28, v198
	v_mul_f32_e32 v24, v11, v30
	v_fma_f32 v29, -v21, v24, v11
	v_fmac_f32_e32 v24, v29, v30
	v_add_f32_e64 v26, v26, 1.0
	v_add_f32_e64 v27, v27, 1.0
	v_fma_f32 v11, -v21, v24, v11
	v_div_scale_f32 v21, s[6:7], v27, v27, v195
	v_rcp_f32_e32 v29, v21
	v_div_fmas_f32 v11, v11, v30, v24
	v_div_fixup_f32 v24, v11, v28, v198
	v_fma_f32 v22, v184, v24, v22
	v_fma_f32 v23, v184, v25, v23
	v_fma_f32 v11, -v21, v29, 1.0
	v_fmac_f32_e32 v29, v11, v29
	v_div_scale_f32 v11, vcc, v195, v27, v195
	v_mul_f32_e32 v24, v11, v29
	v_fma_f32 v25, -v21, v24, v11
	v_fmac_f32_e32 v24, v25, v29
	v_fma_f32 v11, -v21, v24, v11
	v_div_scale_f32 v21, s[6:7], v26, v26, v199
	v_rcp_f32_e32 v30, v21
	v_div_fmas_f32 v11, v11, v29, v24
	v_div_fixup_f32 v25, v11, v27, v195
	v_mul_f32_e32 v27, 0xbfb8aa3b, v200
	v_exp_f32_e32 v28, v27
	v_mul_f32_e32 v27, 0xbfb8aa3b, v196
	v_fma_f32 v11, -v21, v30, 1.0
; DI void ada_item(const Params& p, float* red, int item) {
;     ...
;   for (int kq = 0; kq < 2; ++kq) {
;     float wv[32];
; #pragma unroll
;     for (int j = 0; j < 32; ++j) wv[j] = p.w_ada[(size_t)(ks * 64 + kq * 32 + j) * 3072 + n];
; #pragma unroll
;     for (int j = 0; j < 32; ++j) {
;       const int k = ks * 64 + kq * 32 + j;
;       const float c0 = p.c[k], c1 = p.c[1024 + k];
;       a0 += (c0 / (1.f + __expf(-c0))) * wv[j];
;       a1 += (c1 / (1.f + __expf(-c1))) * wv[j];
;     }
	v_exp_f32_e32 v29, v27
	v_fmac_f32_e32 v30, v11, v30
	v_div_scale_f32 v11, vcc, v199, v26, v199
	v_mul_f32_e32 v24, v11, v30
	v_fma_f32 v27, -v21, v24, v11
	v_fmac_f32_e32 v24, v27, v30
	v_add_f32_e64 v28, v28, 1.0
	v_add_f32_e64 v29, v29, 1.0
	v_fma_f32 v11, -v21, v24, v11
	v_div_scale_f32 v21, s[6:7], v29, v29, v196
	v_rcp_f32_e32 v27, v21
	v_div_fmas_f32 v11, v11, v30, v24
	v_div_fixup_f32 v24, v11, v26, v199
	v_fma_f32 v22, v182, v24, v22
	v_fma_f32 v23, v182, v25, v23
	v_fma_f32 v11, -v21, v27, 1.0
	v_fmac_f32_e32 v27, v11, v27
	v_div_scale_f32 v11, vcc, v196, v29, v196
	v_mul_f32_e32 v24, v11, v27
	v_fma_f32 v25, -v21, v24, v11
	v_fmac_f32_e32 v24, v25, v27
	v_fma_f32 v11, -v21, v24, v11
	v_div_scale_f32 v21, s[6:7], v28, v28, v200
	v_rcp_f32_e32 v30, v21
	v_div_fmas_f32 v11, v11, v27, v24
	v_mul_f32_e32 v26, 0xbfb8aa3b, v201
	v_mul_f32_e32 v27, 0xbfb8aa3b, v197
	v_div_fixup_f32 v25, v11, v29, v196
	v_fma_f32 v11, -v21, v30, 1.0
	v_exp_f32_e32 v26, v26
	v_exp_f32_e32 v27, v27
	v_fmac_f32_e32 v30, v11, v30
	v_div_scale_f32 v11, vcc, v200, v28, v200
	v_mul_f32_e32 v24, v11, v30
	v_fma_f32 v29, -v21, v24, v11
	v_fmac_f32_e32 v24, v29, v30
	v_add_f32_e64 v26, v26, 1.0
	v_add_f32_e64 v27, v27, 1.0
	v_fma_f32 v11, -v21, v24, v11
	v_div_scale_f32 v21, s[6:7], v27, v27, v197
	v_rcp_f32_e32 v29, v21
	v_div_fmas_f32 v11, v11, v30, v24
	v_div_fixup_f32 v24, v11, v28, v200
	v_fma_f32 v22, v180, v24, v22
	v_fma_f32 v23, v180, v25, v23
	v_fma_f32 v11, -v21, v29, 1.0
	v_fmac_f32_e32 v29, v11, v29
	v_div_scale_f32 v11, vcc, v197, v27, v197
	v_mul_f32_e32 v24, v11, v29
	v_fma_f32 v25, -v21, v24, v11
	v_fmac_f32_e32 v24, v25, v29
	v_fma_f32 v11, -v21, v24, v11
	v_div_scale_f32 v21, s[6:7], v26, v26, v201
	v_rcp_f32_e32 v30, v21
	v_div_fmas_f32 v11, v11, v29, v24
	v_div_fixup_f32 v25, v11, v27, v197
	v_mul_f32_e32 v27, 0xbfb8aa3b, v12
	v_exp_f32_e32 v28, v27
	v_mul_f32_e32 v27, 0xbfb8aa3b, v16
	v_fma_f32 v11, -v21, v30, 1.0
	v_exp_f32_e32 v29, v27
	v_fmac_f32_e32 v30, v11, v30
	v_div_scale_f32 v11, vcc, v201, v26, v201
	v_mul_f32_e32 v24, v11, v30
	v_fma_f32 v27, -v21, v24, v11
	v_fmac_f32_e32 v24, v27, v30
	v_add_f32_e64 v28, v28, 1.0
	v_add_f32_e64 v29, v29, 1.0
	v_fma_f32 v11, -v21, v24, v11
	v_div_scale_f32 v21, s[6:7], v29, v29, v16
	v_rcp_f32_e32 v27, v21
	v_div_fmas_f32 v11, v11, v30, v24
	v_div_fixup_f32 v24, v11, v26, v201
	v_fma_f32 v22, v178, v24, v22
	v_fma_f32 v23, v178, v25, v23
	v_fma_f32 v11, -v21, v27, 1.0
	v_fmac_f32_e32 v27, v11, v27
	v_div_scale_f32 v11, vcc, v16, v29, v16
	v_mul_f32_e32 v24, v11, v27
	v_fma_f32 v25, -v21, v24, v11
	v_fmac_f32_e32 v24, v25, v27
	v_fma_f32 v11, -v21, v24, v11
	v_div_scale_f32 v21, s[6:7], v28, v28, v12
	v_rcp_f32_e32 v30, v21
	global_load_dwordx4 v[4:7], v[132:133], off offset:216
	global_load_dwordx3 v[8:10], v[132:133], off offset:232
	v_div_fmas_f32 v11, v11, v27, v24
	v_mul_f32_e32 v24, 0xbfb8aa3b, v13
	v_exp_f32_e32 v26, v24
	v_mul_f32_e32 v24, 0xbfb8aa3b, v17
	v_div_fixup_f32 v25, v11, v29, v16
	v_fma_f32 v11, -v21, v30, 1.0
	v_exp_f32_e32 v27, v24
	v_fmac_f32_e32 v30, v11, v30
	v_div_scale_f32 v11, vcc, v12, v28, v12
	v_mul_f32_e32 v16, v11, v30
	v_fma_f32 v24, -v21, v16, v11
	v_fmac_f32_e32 v16, v24, v30
	v_add_f32_e64 v26, v26, 1.0
	v_add_f32_e64 v27, v27, 1.0
	v_fma_f32 v11, -v21, v16, v11
	v_div_scale_f32 v21, s[6:7], v27, v27, v17
	v_rcp_f32_e32 v29, v21
	v_div_fmas_f32 v11, v11, v30, v16
	v_div_fixup_f32 v24, v11, v28, v12
	v_fma_f32 v22, v174, v24, v22
	v_fma_f32 v23, v174, v25, v23
	v_fma_f32 v11, -v21, v29, 1.0
	v_fmac_f32_e32 v29, v11, v29
	v_div_scale_f32 v11, vcc, v17, v27, v17
	v_mul_f32_e32 v12, v11, v29
	v_fma_f32 v16, -v21, v12, v11
	v_fmac_f32_e32 v12, v16, v29
	v_div_scale_f32 v16, s[6:7], v26, v26, v13
	v_fma_f32 v11, -v21, v12, v11
	v_rcp_f32_e32 v21, v16
	v_div_fmas_f32 v11, v11, v29, v12
	v_div_fixup_f32 v17, v11, v27, v17
	v_fma_f32 v11, -v16, v21, 1.0
	v_fmac_f32_e32 v21, v11, v21
	v_div_scale_f32 v11, vcc, v13, v26, v13
	v_mul_f32_e32 v12, v11, v21
	v_fma_f32 v24, -v16, v12, v11
	v_fmac_f32_e32 v12, v24, v21
	v_add_f32_e64 v24, v208, 1.0
	v_add_f32_e64 v25, v209, 1.0
	v_fma_f32 v11, -v16, v12, v11
	v_div_scale_f32 v27, s[6:7], v25, v25, v18
	v_rcp_f32_e32 v28, v27
	v_div_fmas_f32 v11, v11, v21, v12
	v_div_fixup_f32 v16, v11, v26, v13
	v_fma_f32 v12, v20, v16, v22
	v_fma_f32 v13, v20, v17, v23
	v_fma_f32 v11, -v27, v28, 1.0
	v_fmac_f32_e32 v28, v11, v28
	v_div_scale_f32 v11, vcc, v18, v25, v18
	v_mul_f32_e32 v16, v11, v28
	v_fma_f32 v17, -v27, v16, v11
	v_fmac_f32_e32 v16, v17, v28
	v_fma_f32 v11, -v27, v16, v11
	v_div_fmas_f32 v11, v11, v28, v16
	v_div_fixup_f32 v25, v11, v25, v18
	global_load_dwordx3 v[20:22], v[140:141], off offset:48
	global_load_dwordx3 v[16:18], v[142:143], off
	v_div_scale_f32 v23, s[6:7], v24, v24, v14
	v_rcp_f32_e32 v29, v23
	v_mul_f32_e32 v26, 0xbfb8aa3b, v15
	v_mul_f32_e32 v27, 0xbfb8aa3b, v19
	v_exp_f32_e32 v26, v26
	v_fma_f32 v11, -v23, v29, 1.0
	v_exp_f32_e32 v27, v27
	v_fmac_f32_e32 v29, v11, v29
	v_div_scale_f32 v11, vcc, v14, v24, v14
	v_mul_f32_e32 v28, v11, v29
	v_fma_f32 v30, -v23, v28, v11
	v_fmac_f32_e32 v28, v30, v29
	v_add_f32_e64 v26, v26, 1.0
	v_add_f32_e64 v27, v27, 1.0
	v_fma_f32 v11, -v23, v28, v11
	v_div_scale_f32 v23, s[6:7], v27, v27, v19
	v_rcp_f32_e32 v30, v23
	v_div_fmas_f32 v11, v11, v29, v28
	v_div_fixup_f32 v24, v11, v24, v14
	v_fma_f32 v24, v172, v24, v12
	v_fma_f32 v25, v172, v25, v13
	v_fma_f32 v11, -v23, v30, 1.0
	v_fmac_f32_e32 v30, v11, v30
	v_div_scale_f32 v11, vcc, v19, v27, v19
	v_mul_f32_e32 v12, v11, v30
	v_fma_f32 v13, -v23, v12, v11
	v_fmac_f32_e32 v12, v13, v30
	v_div_scale_f32 v14, s[6:7], v26, v26, v15
	v_fma_f32 v11, -v23, v12, v11
	v_rcp_f32_e32 v23, v14
	v_div_fmas_f32 v11, v11, v30, v12
	s_waitcnt vmcnt(3)
; DI void ada_item(const Params& p, float* red, int item) {
;     ...
;   for (int kq = 0; kq < 2; ++kq) {
;     float wv[32];
; #pragma unroll
;     for (int j = 0; j < 32; ++j) wv[j] = p.w_ada[(size_t)(ks * 64 + kq * 32 + j) * 3072 + n];
; #pragma unroll
;     for (int j = 0; j < 32; ++j) {
;       const int k = ks * 64 + kq * 32 + j;
;       const float c0 = p.c[k], c1 = p.c[1024 + k];
;       a0 += (c0 / (1.f + __expf(-c0))) * wv[j];
;       a1 += (c1 / (1.f + __expf(-c1))) * wv[j];
;     }
	v_mul_f32_e32 v12, 0xbfb8aa3b, v4
	v_mul_f32_e32 v13, 0xbfb8aa3b, v0
	v_div_fixup_f32 v27, v11, v27, v19
	v_fma_f32 v11, -v14, v23, 1.0
	v_exp_f32_e32 v12, v12
	v_exp_f32_e32 v13, v13
	v_fmac_f32_e32 v23, v11, v23
	v_div_scale_f32 v11, vcc, v15, v26, v15
	v_mul_f32_e32 v19, v11, v23
	v_fma_f32 v28, -v14, v19, v11
	v_fmac_f32_e32 v19, v28, v23
	v_add_f32_e64 v12, v12, 1.0
	v_add_f32_e64 v13, v13, 1.0
	v_fma_f32 v11, -v14, v19, v11
	v_div_scale_f32 v14, s[6:7], v13, v13, v0
	v_rcp_f32_e32 v28, v14
	v_div_fmas_f32 v11, v11, v23, v19
	v_div_fixup_f32 v26, v11, v26, v15
	v_fma_f32 v24, v168, v26, v24
	v_fma_f32 v25, v168, v27, v25
	v_fma_f32 v11, -v14, v28, 1.0
	v_fmac_f32_e32 v28, v11, v28
	v_div_scale_f32 v11, vcc, v0, v13, v0
	v_mul_f32_e32 v15, v11, v28
	v_fma_f32 v19, -v14, v15, v11
	v_fmac_f32_e32 v15, v19, v28
	v_fma_f32 v11, -v14, v15, v11
	v_div_scale_f32 v14, s[6:7], v12, v12, v4
	v_rcp_f32_e32 v19, v14
	v_div_fmas_f32 v11, v11, v28, v15
	v_div_fixup_f32 v15, v11, v13, v0
	v_fma_f32 v0, -v14, v19, 1.0
	v_fmac_f32_e32 v19, v0, v19
	v_div_scale_f32 v0, vcc, v4, v12, v4
	v_mul_f32_e32 v11, v0, v19
	v_fma_f32 v13, -v14, v11, v0
	v_fmac_f32_e32 v11, v13, v19
	v_fma_f32 v0, -v14, v11, v0
	v_div_fmas_f32 v0, v0, v19, v11
	v_div_fixup_f32 v14, v0, v12, v4
	v_mul_f32_e32 v0, 0xbfb8aa3b, v5
	v_exp_f32_e32 v28, v0
	v_mul_f32_e32 v0, 0xbfb8aa3b, v1
	v_exp_f32_e32 v29, v0
	v_mul_f32_e32 v0, 0xbfb8aa3b, v42
	v_exp_f32_e32 v12, v0
	s_waitcnt vmcnt(0)
	v_mul_f32_e32 v0, 0xbfb8aa3b, v18
	v_add_f32_e64 v28, v28, 1.0
	v_add_f32_e64 v29, v29, 1.0
	v_exp_f32_e32 v13, v0
	v_div_scale_f32 v4, s[6:7], v29, v29, v1
	v_rcp_f32_e32 v11, v4
	v_fma_f32 v14, v170, v14, v24
	v_fma_f32 v15, v170, v15, v25
	v_fma_f32 v0, -v4, v11, 1.0
	v_fmac_f32_e32 v11, v0, v11
	v_div_scale_f32 v0, vcc, v1, v29, v1
	v_mul_f32_e32 v19, v0, v11
	v_fma_f32 v23, -v4, v19, v0
	v_fmac_f32_e32 v19, v23, v11
	v_fma_f32 v0, -v4, v19, v0
	v_div_scale_f32 v4, s[6:7], v28, v28, v5
	v_rcp_f32_e32 v23, v4
	v_div_fmas_f32 v0, v0, v11, v19
	v_mul_f32_e32 v19, 0xbfb8aa3b, v6
	v_exp_f32_e32 v24, v19
	v_mul_f32_e32 v19, 0xbfb8aa3b, v2
	v_div_fixup_f32 v1, v0, v29, v1
	v_fma_f32 v0, -v4, v23, 1.0
	v_exp_f32_e32 v25, v19
	v_fmac_f32_e32 v23, v0, v23
	v_div_scale_f32 v0, vcc, v5, v28, v5
	v_mul_f32_e32 v11, v0, v23
	v_fma_f32 v19, -v4, v11, v0
	v_fmac_f32_e32 v11, v19, v23
	v_add_f32_e64 v24, v24, 1.0
	v_add_f32_e64 v25, v25, 1.0
	v_fma_f32 v0, -v4, v11, v0
	v_div_scale_f32 v4, s[6:7], v25, v25, v2
	v_rcp_f32_e32 v19, v4
	v_div_fmas_f32 v0, v0, v23, v11
	v_div_fixup_f32 v0, v0, v28, v5
	v_fma_f32 v0, v166, v0, v14
	v_fma_f32 v1, v166, v1, v15
	v_fma_f32 v5, -v4, v19, 1.0
	v_fmac_f32_e32 v19, v5, v19
	v_div_scale_f32 v5, vcc, v2, v25, v2
	v_mul_f32_e32 v11, v5, v19
	v_fma_f32 v14, -v4, v11, v5
	v_fmac_f32_e32 v11, v14, v19
	v_div_scale_f32 v23, s[6:7], v24, v24, v6
	v_fma_f32 v4, -v4, v11, v5
	v_rcp_f32_e32 v26, v23
	v_div_fmas_f32 v4, v4, v19, v11
	v_mul_f32_e32 v11, 0xbfb8aa3b, v7
	v_exp_f32_e32 v14, v11
	v_mul_f32_e32 v11, 0xbfb8aa3b, v3
	v_exp_f32_e32 v15, v11
	v_div_fixup_f32 v5, v4, v25, v2
	v_fma_f32 v2, -v23, v26, 1.0
	v_fmac_f32_e32 v26, v2, v26
	v_div_scale_f32 v2, vcc, v6, v24, v6
	v_mul_f32_e32 v4, v2, v26
	v_fma_f32 v11, -v23, v4, v2
	v_add_f32_e64 v14, v14, 1.0
	v_add_f32_e64 v15, v15, 1.0
	v_fmac_f32_e32 v4, v11, v26
	v_div_scale_f32 v11, s[6:7], v15, v15, v3
	v_rcp_f32_e32 v19, v11
	v_fma_f32 v2, -v23, v4, v2
	v_div_fmas_f32 v2, v2, v26, v4
	v_div_fixup_f32 v4, v2, v24, v6
	v_fma_f32 v2, -v11, v19, 1.0
	v_fmac_f32_e32 v19, v2, v19
	v_div_scale_f32 v2, vcc, v3, v15, v3
	v_fma_f32 v0, v162, v4, v0
	v_fma_f32 v1, v162, v5, v1
	v_mul_f32_e32 v4, v2, v19
	v_fma_f32 v5, -v11, v4, v2
	v_fmac_f32_e32 v4, v5, v19
	v_div_scale_f32 v6, s[6:7], v14, v14, v7
	v_fma_f32 v2, -v11, v4, v2
	v_rcp_f32_e32 v11, v6
	v_div_fmas_f32 v2, v2, v19, v4
	v_mul_f32_e32 v4, 0xbfb8aa3b, v8
	v_mul_f32_e32 v5, 0xbfb8aa3b, v20
	v_div_fixup_f32 v3, v2, v15, v3
	v_fma_f32 v2, -v6, v11, 1.0
	v_exp_f32_e32 v4, v4
	v_exp_f32_e32 v5, v5
	v_fmac_f32_e32 v11, v2, v11
	v_div_scale_f32 v2, vcc, v7, v14, v7
	v_mul_f32_e32 v15, v2, v11
	v_fma_f32 v19, -v6, v15, v2
	v_fmac_f32_e32 v15, v19, v11
	v_add_f32_e64 v4, v4, 1.0
	v_add_f32_e64 v5, v5, 1.0
	v_fma_f32 v2, -v6, v15, v2
	v_div_scale_f32 v6, s[6:7], v5, v5, v20
	v_rcp_f32_e32 v19, v6
	v_div_fmas_f32 v2, v2, v11, v15
	v_div_fixup_f32 v2, v2, v14, v7
	v_fma_f32 v0, v160, v2, v0
	v_fma_f32 v1, v160, v3, v1
	v_fma_f32 v2, -v6, v19, 1.0
	v_fmac_f32_e32 v19, v2, v19
	v_div_scale_f32 v2, vcc, v20, v5, v20
	v_mul_f32_e32 v3, v2, v19
	v_div_scale_f32 v11, s[6:7], v4, v4, v8
	v_fma_f32 v7, -v6, v3, v2
	v_rcp_f32_e32 v14, v11
	v_fmac_f32_e32 v3, v7, v19
	v_fma_f32 v2, -v6, v3, v2
	v_div_fmas_f32 v2, v2, v19, v3
	v_mul_f32_e32 v6, 0xbfb8aa3b, v9
	v_mul_f32_e32 v7, 0xbfb8aa3b, v21
	v_div_fixup_f32 v3, v2, v5, v20
	v_fma_f32 v2, -v11, v14, 1.0
	v_exp_f32_e32 v6, v6
	v_exp_f32_e32 v7, v7
	v_fmac_f32_e32 v14, v2, v14
	v_div_scale_f32 v2, vcc, v8, v4, v8
	v_mul_f32_e32 v5, v2, v14
	v_fma_f32 v15, -v11, v5, v2
	v_fmac_f32_e32 v5, v15, v14
	v_add_f32_e64 v6, v6, 1.0
	v_add_f32_e64 v7, v7, 1.0
	v_fma_f32 v2, -v11, v5, v2
	v_div_scale_f32 v11, s[6:7], v7, v7, v21
	v_rcp_f32_e32 v15, v11
	v_div_fmas_f32 v2, v2, v14, v5
	v_div_fixup_f32 v2, v2, v4, v8
	v_fma_f32 v0, v46, v2, v0
	v_fma_f32 v1, v46, v3, v1
	v_fma_f32 v2, -v11, v15, 1.0
	v_fmac_f32_e32 v15, v2, v15
	v_div_scale_f32 v2, vcc, v21, v7, v21
; DI void ada_item(const Params& p, float* red, int item) {
;     ...
;     for (int j = 0; j < 32; ++j) {
;       const int k = ks * 64 + kq * 32 + j;
;       const float c0 = p.c[k], c1 = p.c[1024 + k];
;       a0 += (c0 / (1.f + __expf(-c0))) * wv[j];
;       a1 += (c1 / (1.f + __expf(-c1))) * wv[j];
;     }
;   }
;   red[(ks * 16 + col) * 2 + 0] = a0;
;   red[(ks * 16 + col) * 2 + 1] = a1;
;   __syncthreads();
;   if (tid < 32) {
;     const int cc = tid & 15, b = tid >> 4;
;     float s = 0.f;
;     for (int q = 0; q < 16; ++q) s += red[(q * 16 + cc) * 2 + b];
;     p.ada[b * 3072 + item * 16 + cc] = s + p.b_ada[item * 16 + cc];
;   }
	v_mul_f32_e32 v3, v2, v15
	v_fma_f32 v4, -v11, v3, v2
	v_fmac_f32_e32 v3, v4, v15
	v_div_scale_f32 v8, s[6:7], v6, v6, v9
	v_fma_f32 v2, -v11, v3, v2
	v_rcp_f32_e32 v11, v8
	v_div_fmas_f32 v2, v2, v15, v3
	v_mul_f32_e32 v4, 0xbfb8aa3b, v10
	v_mul_f32_e32 v5, 0xbfb8aa3b, v22
	v_div_fixup_f32 v3, v2, v7, v21
	v_fma_f32 v2, -v8, v11, 1.0
	v_exp_f32_e32 v4, v4
	v_exp_f32_e32 v5, v5
	v_fmac_f32_e32 v11, v2, v11
	v_div_scale_f32 v2, vcc, v9, v6, v9
	v_mul_f32_e32 v7, v2, v11
	v_fma_f32 v14, -v8, v7, v2
	v_fmac_f32_e32 v7, v14, v11
	v_add_f32_e64 v4, v4, 1.0
	v_add_f32_e64 v5, v5, 1.0
	v_fma_f32 v2, -v8, v7, v2
	v_div_scale_f32 v8, s[6:7], v5, v5, v22
	v_rcp_f32_e32 v14, v8
	v_div_fmas_f32 v2, v2, v11, v7
	v_div_fixup_f32 v2, v2, v6, v9
	v_fma_f32 v0, v44, v2, v0
	v_fma_f32 v1, v44, v3, v1
	v_fma_f32 v2, -v8, v14, 1.0
	v_fmac_f32_e32 v14, v2, v14
	v_div_scale_f32 v2, vcc, v22, v5, v22
	v_mul_f32_e32 v3, v2, v14
	v_fma_f32 v6, -v8, v3, v2
	v_fmac_f32_e32 v3, v6, v14
	v_fma_f32 v2, -v8, v3, v2
	v_div_scale_f32 v8, s[6:7], v4, v4, v10
	v_rcp_f32_e32 v9, v8
	v_div_fmas_f32 v2, v2, v14, v3
	v_mul_f32_e32 v6, 0xbfb8aa3b, v40
	v_mul_f32_e32 v7, 0xbfb8aa3b, v16
	v_div_fixup_f32 v3, v2, v5, v22
	v_fma_f32 v2, -v8, v9, 1.0
	v_exp_f32_e32 v6, v6
	v_exp_f32_e32 v7, v7
	v_fmac_f32_e32 v9, v2, v9
	v_div_scale_f32 v2, vcc, v10, v4, v10
	v_mul_f32_e32 v5, v2, v9
	v_fma_f32 v11, -v8, v5, v2
	v_fmac_f32_e32 v5, v11, v9
	v_add_f32_e64 v6, v6, 1.0
	v_add_f32_e64 v7, v7, 1.0
	v_fma_f32 v2, -v8, v5, v2
	v_div_scale_f32 v8, s[6:7], v7, v7, v16
	v_rcp_f32_e32 v11, v8
	v_div_fmas_f32 v2, v2, v9, v5
	v_div_fixup_f32 v2, v2, v4, v10
	v_fma_f32 v0, v38, v2, v0
	v_fma_f32 v1, v38, v3, v1
	v_fma_f32 v2, -v8, v11, 1.0
	v_fmac_f32_e32 v11, v2, v11
	v_div_scale_f32 v2, vcc, v16, v7, v16
	v_mul_f32_e32 v3, v2, v11
	v_fma_f32 v4, -v8, v3, v2
	v_fmac_f32_e32 v3, v4, v11
	v_fma_f32 v2, -v8, v3, v2
	v_div_scale_f32 v8, s[6:7], v6, v6, v40
	v_rcp_f32_e32 v9, v8
	v_div_fmas_f32 v2, v2, v11, v3
	v_mul_f32_e32 v4, 0xbfb8aa3b, v41
	v_mul_f32_e32 v5, 0xbfb8aa3b, v17
	v_div_fixup_f32 v3, v2, v7, v16
	v_fma_f32 v2, -v8, v9, 1.0
	v_exp_f32_e32 v4, v4
	v_exp_f32_e32 v5, v5
	v_fmac_f32_e32 v9, v2, v9
	v_div_scale_f32 v2, vcc, v40, v6, v40
	v_mul_f32_e32 v7, v2, v9
	v_fma_f32 v10, -v8, v7, v2
	v_fmac_f32_e32 v7, v10, v9
	v_add_f32_e64 v4, v4, 1.0
	v_add_f32_e64 v5, v5, 1.0
	v_fma_f32 v2, -v8, v7, v2
	v_div_scale_f32 v8, s[6:7], v5, v5, v17
	v_rcp_f32_e32 v10, v8
	v_div_fmas_f32 v2, v2, v9, v7
	v_div_fixup_f32 v2, v2, v6, v40
	v_fma_f32 v0, v36, v2, v0
	v_fma_f32 v1, v36, v3, v1
	v_fma_f32 v2, -v8, v10, 1.0
	v_fmac_f32_e32 v10, v2, v10
	v_div_scale_f32 v2, vcc, v17, v5, v17
	v_mul_f32_e32 v3, v2, v10
	v_fma_f32 v6, -v8, v3, v2
	v_fmac_f32_e32 v3, v6, v10
	v_div_scale_f32 v6, s[6:7], v4, v4, v41
	v_fma_f32 v2, -v8, v3, v2
	v_rcp_f32_e32 v8, v6
	v_div_fmas_f32 v2, v2, v10, v3
	v_div_fixup_f32 v3, v2, v5, v17
	v_fma_f32 v2, -v6, v8, 1.0
	v_fmac_f32_e32 v8, v2, v8
	v_div_scale_f32 v2, vcc, v41, v4, v41
	v_mul_f32_e32 v5, v2, v8
	v_fma_f32 v7, -v6, v5, v2
	v_fmac_f32_e32 v5, v7, v8
	v_fma_f32 v2, -v6, v5, v2
	v_add_f32_e64 v6, v12, 1.0
	v_add_f32_e64 v7, v13, 1.0
	v_div_fmas_f32 v2, v2, v8, v5
	v_div_scale_f32 v9, s[6:7], v7, v7, v18
	v_rcp_f32_e32 v10, v9
	v_div_fixup_f32 v2, v2, v4, v41
	v_fma_f32 v0, v34, v2, v0
	v_fma_f32 v1, v34, v3, v1
	v_fma_f32 v2, -v9, v10, 1.0
	v_fmac_f32_e32 v10, v2, v10
	v_div_scale_f32 v2, vcc, v18, v7, v18
	v_mul_f32_e32 v3, v2, v10
	v_fma_f32 v4, -v9, v3, v2
	v_fmac_f32_e32 v3, v4, v10
	v_div_scale_f32 v4, s[6:7], v6, v6, v42
	v_rcp_f32_e32 v5, v4
	v_fma_f32 v2, -v9, v3, v2
	v_div_fmas_f32 v2, v2, v10, v3
	v_div_fixup_f32 v3, v2, v7, v18
	v_fma_f32 v2, -v4, v5, 1.0
	v_fmac_f32_e32 v5, v2, v5
	v_div_scale_f32 v2, vcc, v42, v6, v42
	v_mul_f32_e32 v7, v2, v5
	v_fma_f32 v8, -v4, v7, v2
	v_fmac_f32_e32 v7, v8, v5
	v_fma_f32 v2, -v4, v7, v2
	v_div_fmas_f32 v2, v2, v5, v7
	v_div_fixup_f32 v2, v2, v6, v42
	v_fma_f32 v0, v32, v2, v0
	v_fma_f32 v1, v32, v3, v1
	ds_write_b64 v176, v[0:1]
	s_waitcnt lgkmcnt(0)
	s_barrier
	s_and_saveexec_b64 s[6:7], s[4:5]
	s_cbranch_execz .LBB0_22
	v_lshl_add_u64 v[0:1], v[146:147], 2, s[14:15]
	global_load_dword v18, v[0:1], off
	ds_read2_b32 v[0:1], v171 offset1:32
	ds_read2_b32 v[2:3], v171 offset0:64 offset1:96
	ds_read2_b32 v[4:5], v171 offset0:128 offset1:160
	ds_read2_b32 v[6:7], v171 offset0:192 offset1:224
	v_add_u32_e32 v9, 0x400, v171
	s_waitcnt lgkmcnt(3)
	v_add_f32_e32 v0, 0, v0
	v_add_f32_e32 v0, v0, v1
	s_waitcnt lgkmcnt(2)
	v_add_f32_e32 v0, v0, v2
	v_add_f32_e32 v0, v0, v3
	s_waitcnt lgkmcnt(1)
	v_add_f32_e32 v0, v0, v4
	v_add_f32_e32 v0, v0, v5
	ds_read2_b32 v[10:11], v9 offset1:32
	ds_read2_b32 v[12:13], v9 offset0:64 offset1:96
	ds_read2_b32 v[14:15], v9 offset0:128 offset1:160
	ds_read2_b32 v[16:17], v9 offset0:192 offset1:224
	s_waitcnt lgkmcnt(4)
	v_add_f32_e32 v0, v0, v6
	v_add_f32_e32 v0, v0, v7
	s_waitcnt lgkmcnt(3)
	v_add_f32_e32 v0, v0, v10
	v_add_f32_e32 v0, v0, v11
	s_waitcnt lgkmcnt(2)
	v_add_f32_e32 v0, v0, v12
	v_add_f32_e32 v0, v0, v13
	s_waitcnt lgkmcnt(1)
	v_add_f32_e32 v0, v0, v14
	v_add_f32_e32 v0, v0, v15
	v_add_u32_e32 v8, v173, v146
	s_waitcnt lgkmcnt(0)
	v_add_f32_e32 v0, v0, v16
	v_ashrrev_i32_e32 v9, 31, v8
	v_add_f32_e32 v0, v0, v17
	s_waitcnt vmcnt(0)
	v_add_f32_e32 v2, v0, v18
	v_lshl_add_u64 v[0:1], v[8:9], 2, s[34:35]
	global_store_dword v[0:1], v2, off sc1
	s_branch .LBB0_22

; DI void phase1(const Params& p, const Sched sc) {
;     ...
;     for (int q = 0; q < 4; ++q) {
;       const f32x4* xr = (const f32x4*)(p.x + (size_t)(rowa + q) * DM);
; #pragma unroll
;       for (int i = 0; i < 2; ++i) { v4[q][2 * i] = xr[2 * lane + 128 * i]; v4[q][2 * i + 1] = xr[2 * lane + 128 * i + 1]; }
;     }
;     const float* ad = p.ada + b * 3072;
;     f32x4 nw[4], sh[4];
; #pragma unroll
;     for (int j = 0; j < 4; ++j) {
;       const int k = (2 * lane + 128 * (j >> 1) + (j & 1)) * 4;
;       nw[j] = *(const f32x4*)(p.norm_w + k); sh[j] = *(const f32x4*)(ad + k);
;       const f32x4 sc4 = *(const f32x4*)(ad + 1024 + k);
; #pragma unroll
;       for (int e = 0; e < 4; ++e) nw[j][e] *= 1.f + sc4[e];
;     }
; #pragma unroll
;     for (int q = 0; q < 4; ++q) {
;       float ss = 0.f;
; #pragma unroll
;       for (int j = 0; j < 4; ++j) ss += v4[q][j][0] * v4[q][j][0] + v4[q][j][1] * v4[q][j][1] + v4[q][j][2] * v4[q][j][2] + v4[q][j][3] * v4[q][j][3];
; #pragma unroll
;       for (int o = 1; o < 64; o <<= 1) ss += __shfl_xor(ss, o);
.LBB0_161:
	v_ashrrev_i32_e32 v93, 31, v92
	v_lshlrev_b64 v[0:1], 12, v[92:93]
	v_add_u32_e32 v98, 1, v92
	v_lshl_add_u64 v[0:1], v[88:89], 0, v[0:1]
	v_ashrrev_i32_e32 v99, 31, v98
	global_load_dwordx4 v[76:79], v[0:1], off
	global_load_dwordx4 v[72:75], v[0:1], off offset:16
	global_load_dwordx4 v[68:71], v[0:1], off offset:2048
	global_load_dwordx4 v[64:67], v[0:1], off offset:2064
	v_lshlrev_b64 v[0:1], 12, v[98:99]
	v_lshl_add_u64 v[0:1], v[88:89], 0, v[0:1]
	global_load_dwordx4 v[36:39], v[0:1], off
	global_load_dwordx4 v[32:35], v[0:1], off offset:16
	global_load_dwordx4 v[20:23], v[0:1], off offset:2048
	global_load_dwordx4 v[16:19], v[0:1], off offset:2064
	v_ashrrev_i32_e32 v0, 13, v92
	v_add_u32_e32 v94, 2, v92
	v_mul_i32_i24_e32 v0, 0xc00, v0
	v_ashrrev_i32_e32 v95, 31, v94
	v_ashrrev_i32_e32 v1, 31, v0
	v_mov_b32_e32 v91, v81
	v_lshlrev_b64 v[2:3], 12, v[94:95]
	v_lshl_add_u64 v[0:1], v[0:1], 2, s[2:3]
	v_lshl_add_u64 v[40:41], v[88:89], 0, v[2:3]
	v_lshl_add_u64 v[42:43], v[0:1], 0, s[6:7]
	v_lshl_add_u64 v[2:3], v[0:1], 0, v[80:81]
	v_lshl_add_u64 v[44:45], v[0:1], 0, v[90:91]
	global_load_dwordx4 v[106:109], v[82:83], off offset:16
	global_load_dwordx4 v[100:103], v[82:83], off
	global_load_dwordx4 v[112:115], v[84:85], off offset:16
	global_load_dwordx4 v[132:135], v[84:85], off
	global_load_dwordx4 v[28:31], v[40:41], off
	global_load_dwordx4 v[24:27], v[40:41], off offset:16
	global_load_dwordx4 v[8:11], v[2:3], off offset:16
	global_load_dwordx4 v[12:15], v[2:3], off
	v_lshl_add_u64 v[46:47], v[42:43], 0, v[80:81]
	global_load_dwordx4 v[0:3], v[44:45], off offset:16
	global_load_dwordx4 v[4:7], v[44:45], off
	global_load_dwordx4 v[136:139], v[46:47], off offset:16
	global_load_dwordx4 v[140:143], v[46:47], off
	v_lshl_add_u64 v[42:43], v[42:43], 0, v[90:91]
	global_load_dwordx4 v[144:147], v[42:43], off offset:16
	global_load_dwordx4 v[148:151], v[42:43], off
	s_add_i32 s14, s14, s33
	s_cmpk_gt_i32 s14, 0x7f
	s_waitcnt vmcnt(21)
	v_mov_b32_e32 v44, v77
	s_waitcnt vmcnt(20)
	v_mov_b32_e32 v45, v73
	s_waitcnt vmcnt(19)
	v_mov_b32_e32 v52, v69
	s_waitcnt vmcnt(18)
	v_mov_b32_e32 v53, v65
	v_mov_b32_e32 v42, v76
	v_mov_b32_e32 v43, v72
	v_mov_b32_e32 v50, v68
	v_mov_b32_e32 v51, v64
	v_mul_f32_e64 v44, v44, v44
	v_mul_f32_e64 v45, v45, v45
	v_mul_f32_e64 v52, v52, v52
	v_mul_f32_e64 v53, v53, v53
	s_waitcnt vmcnt(17)
	v_mov_b32_e32 v60, v37
	s_waitcnt vmcnt(16)
	v_mov_b32_e32 v61, v33
	v_mov_b32_e32 v46, v78
	v_mov_b32_e32 v47, v74
	v_mov_b32_e32 v58, v36
	v_mov_b32_e32 v59, v32
	s_waitcnt vmcnt(15)
	v_mov_b32_e32 v110, v21
	s_waitcnt vmcnt(14)
	v_mov_b32_e32 v111, v17
	v_fma_f32 v42, v42, v42, v44
	v_fma_f32 v43, v43, v43, v45
	v_fma_f32 v44, v50, v50, v52
	v_fma_f32 v45, v51, v51, v53
	v_mul_f32_e64 v50, v60, v60
	v_mul_f32_e64 v51, v61, v61
	v_mov_b32_e32 v62, v38
	v_mov_b32_e32 v63, v34
	v_mov_b32_e32 v104, v20
	v_mov_b32_e32 v105, v16
	v_mul_f32_e64 v52, v110, v110
	v_mul_f32_e64 v53, v111, v111
	v_fma_f32 v42, v46, v46, v42
	v_fma_f32 v43, v47, v47, v43
	v_fma_f32 v46, v58, v58, v50
	v_fma_f32 v47, v59, v59, v51
	v_mov_b32_e32 v48, v79
	v_mov_b32_e32 v49, v75
	v_mov_b32_e32 v54, v70
	v_mov_b32_e32 v55, v66
	v_mov_b32_e32 v96, v39
	v_mov_b32_e32 v97, v35
	v_mov_b32_e32 v152, v22
	v_mov_b32_e32 v153, v18
	v_fma_f32 v50, v104, v104, v52
	v_fma_f32 v51, v105, v105, v53
	v_fma_f32 v46, v62, v62, v46
	v_fma_f32 v47, v63, v63, v47
	v_mov_b32_e32 v56, v71
	v_mov_b32_e32 v57, v67
	v_mov_b32_e32 v154, v23
	v_fma_f32 v44, v54, v54, v44
	v_fma_f32 v45, v55, v55, v45
	v_fma_f32 v42, v48, v48, v42
	v_fma_f32 v43, v49, v49, v43
	v_fma_f32 v48, v152, v152, v50
	v_fma_f32 v49, v153, v153, v51
	v_fma_f32 v46, v96, v96, v46
	v_fma_f32 v47, v97, v97, v47
	v_mov_b32_e32 v155, v19
	v_fma_f32 v44, v56, v56, v44
	v_fma_f32 v45, v57, v57, v45
	v_fma_f32 v48, v154, v154, v48
	v_fma_f32 v49, v155, v155, v49
	v_mov_b32_e32 v50, v46
	v_mov_b32_e32 v51, v42
	v_mov_b32_e32 v42, v47
	v_add_f32_e64 v42, v50, v42
	v_add_f32_e64 v43, v51, v43
	v_mov_b32_e32 v46, v48
	v_mov_b32_e32 v47, v44
	v_add_f32_e64 v42, v42, v46
	v_add_f32_e64 v43, v43, v47
	v_mov_b32_e32 v44, v49
	v_add_f32_e64 v42, v42, v44
	v_add_f32_e64 v43, v43, v45
	ds_bpermute_b32 v45, v125, v43
	ds_bpermute_b32 v44, v125, v42
	v_add_u32_e32 v96, 3, v92
	global_load_dwordx4 v[60:63], v[40:41], off offset:2048
	global_load_dwordx4 v[56:59], v[40:41], off offset:2064
	v_ashrrev_i32_e32 v97, 31, v96
	v_lshlrev_b64 v[154:155], 11, v[92:93]
	s_waitcnt lgkmcnt(0)
	v_add_f32_e64 v40, v42, v44
	v_add_f32_e64 v41, v43, v45
	ds_bpermute_b32 v43, v126, v41
	ds_bpermute_b32 v42, v126, v40
	v_lshlrev_b64 v[44:45], 12, v[96:97]
	v_lshl_add_u64 v[104:105], v[88:89], 0, v[44:45]
	global_load_dwordx4 v[52:55], v[104:105], off
	global_load_dwordx4 v[48:51], v[104:105], off offset:16
	v_add_u32_e32 v92, s11, v92
	s_waitcnt lgkmcnt(0)
	v_add_f32_e64 v110, v40, v42
	v_add_f32_e64 v111, v41, v43
	global_load_dwordx4 v[44:47], v[104:105], off offset:2048
	global_load_dwordx4 v[40:43], v[104:105], off offset:2064
	ds_bpermute_b32 v153, v127, v111
	ds_bpermute_b32 v152, v127, v110
	s_waitcnt vmcnt(8)
	v_add_f32_e64 v104, v140, 1.0
	v_add_f32_e64 v105, v141, 1.0
	s_waitcnt lgkmcnt(0)
	v_add_f32_e64 v110, v110, v152
	v_add_f32_e64 v111, v111, v153
	ds_bpermute_b32 v141, v128, v111
	ds_bpermute_b32 v140, v128, v110
	v_mul_f32_e64 v100, v100, v104
	v_mul_f32_e64 v101, v101, v105
	v_add_f32_e64 v104, v142, 1.0
	v_add_f32_e64 v105, v143, 1.0
	s_nop 0
	v_mul_f32_e64 v104, v102, v104
	v_mul_f32_e64 v105, v103, v105
	v_add_f32_e64 v102, v136, 1.0
	v_add_f32_e64 v103, v137, 1.0
	s_nop 0
	v_mul_f32_e64 v102, v106, v102
	v_mul_f32_e64 v103, v107, v103
	s_waitcnt lgkmcnt(0)
; DI unsigned pk_bf16(float lo, float hi) { f32x2 v = {lo, hi}; bf2_t b = __builtin_convertvector(v, bf2_t); return __builtin_bit_cast(unsigned, b); }
; DI void phase1(const Params& p, const Sched sc) {
;     ...
;     for (int j = 0; j < 4; ++j) {
;       const int k = (2 * lane + 128 * (j >> 1) + (j & 1)) * 4;
;       nw[j] = *(const f32x4*)(p.norm_w + k); sh[j] = *(const f32x4*)(ad + k);
;       const f32x4 sc4 = *(const f32x4*)(ad + 1024 + k);
; #pragma unroll
;       for (int e = 0; e < 4; ++e) nw[j][e] *= 1.f + sc4[e];
;     }
; #pragma unroll
;     for (int q = 0; q < 4; ++q) {
;       float ss = 0.f;
; #pragma unroll
;       for (int j = 0; j < 4; ++j) ss += v4[q][j][0] * v4[q][j][0] + v4[q][j][1] * v4[q][j][1] + v4[q][j][2] * v4[q][j][2] + v4[q][j][3] * v4[q][j][3];
; #pragma unroll
;       for (int o = 1; o < 64; o <<= 1) ss += __shfl_xor(ss, o);
;       const float rstd = rsqrtf(ss * (1.f / DM) + 1e-6f);
; #pragma unroll
;       for (int i = 0; i < 2; ++i) {
;         u32x4 w;
; #pragma unroll
;         for (int jj = 0; jj < 2; ++jj) {
;           const int j = 2 * i + jj;
;           float o[4];
; #pragma unroll
;           for (int e = 0; e < 4; ++e) o[e] = (v4[q][j][e] * rstd) * nw[j][e] + sh[j][e];
;           w[2 * jj] = pk_bf16(o[0], o[1]); w[2 * jj + 1] = pk_bf16(o[2], o[3]);
;         }
;         *(u32x4*)(p.H + (size_t)(rowa + q) * DM + (2 * lane + 128 * i) * 4) = w;
;       }
	v_add_f32_e64 v106, v110, v140
	v_add_f32_e64 v107, v111, v141
	ds_bpermute_b32 v137, v129, v107
	ds_bpermute_b32 v136, v129, v106
	v_add_f32_e64 v110, v138, 1.0
	v_add_f32_e64 v111, v139, 1.0
	v_lshl_add_u64 v[138:139], v[86:87], 0, v[154:155]
	v_mul_f32_e64 v110, v108, v110
	v_mul_f32_e64 v111, v109, v111
	s_waitcnt vmcnt(6)
	v_add_f32_e64 v108, v148, 1.0
	v_add_f32_e64 v109, v149, 1.0
	s_waitcnt lgkmcnt(0)
	v_add_f32_e64 v136, v106, v136
	v_add_f32_e64 v137, v107, v137
	ds_bpermute_b32 v141, v130, v137
	ds_bpermute_b32 v140, v130, v136
	v_mul_f32_e64 v106, v132, v108
	v_mul_f32_e64 v107, v133, v109
	v_add_f32_e64 v108, v150, 1.0
	v_add_f32_e64 v109, v151, 1.0
	v_add_f32_e64 v132, v144, 1.0
	v_add_f32_e64 v133, v145, 1.0
	v_mul_f32_e64 v108, v134, v108
	v_mul_f32_e64 v109, v135, v109
	s_waitcnt lgkmcnt(0)
	v_add_f32_e64 v134, v136, v140
	v_add_f32_e64 v135, v137, v141
	v_mov_b64_e32 v[136:137], s[10:11]
	v_fma_f32 v134, v134, s8, v136
	v_fma_f32 v135, v135, s8, v136
	v_mul_f32_e64 v112, v112, v132
	v_mul_f32_e64 v113, v113, v133
	v_mul_f32_e32 v91, 0x4b800000, v135
	v_cmp_gt_f32_e32 vcc, s12, v135
	v_add_f32_e64 v132, v146, 1.0
	v_add_f32_e64 v133, v147, 1.0
	s_nop 0
	v_cndmask_b32_e32 v91, v135, v91, vcc
	v_rsq_f32_e32 v91, v91
	v_mul_f32_e64 v114, v114, v132
	v_mul_f32_e64 v115, v115, v133
	v_mul_f32_e32 v93, 0x45800000, v91
	v_cndmask_b32_e32 v132, v91, v93, vcc
	v_mul_f32_e64 v68, v68, v132
	v_mul_f32_e64 v69, v69, v132
	v_mul_f32_e64 v70, v70, v132
	v_mul_f32_e64 v71, v71, v132
	v_fma_f32 v68, v106, v68, v4
	v_fma_f32 v69, v107, v69, v5
	v_fma_f32 v70, v108, v70, v6
	v_fma_f32 v71, v109, v71, v7
	v_mul_f32_e64 v76, v76, v132
	v_mul_f32_e64 v77, v77, v132
	v_mul_f32_e64 v78, v78, v132
	v_mul_f32_e64 v79, v79, v132
	v_mul_f32_e64 v72, v72, v132
	v_mul_f32_e64 v73, v73, v132
	v_cvt_pk_bf16_f32 v68, v68, v69
	v_cvt_pk_bf16_f32 v69, v70, v71
	v_mul_f32_e32 v70, 0x4b800000, v134
	v_cmp_gt_f32_e32 vcc, s12, v134
	v_fma_f32 v76, v100, v76, v12
	v_fma_f32 v77, v101, v77, v13
	v_fma_f32 v78, v104, v78, v14
	v_fma_f32 v79, v105, v79, v15
	v_fma_f32 v72, v102, v72, v8
	v_fma_f32 v73, v103, v73, v9
	v_mul_f32_e64 v64, v64, v132
	v_mul_f32_e64 v65, v65, v132
	v_mul_f32_e64 v66, v66, v132
	v_mul_f32_e64 v67, v67, v132
	v_cndmask_b32_e32 v70, v134, v70, vcc
	v_cvt_pk_bf16_f32 v76, v76, v77
	v_cvt_pk_bf16_f32 v77, v78, v79
	v_cvt_pk_bf16_f32 v78, v72, v73
	v_fma_f32 v64, v112, v64, v0
	v_fma_f32 v65, v113, v65, v1
	v_fma_f32 v66, v114, v66, v2
	v_fma_f32 v67, v115, v67, v3
	v_rsq_f32_e32 v72, v70
	v_cvt_pk_bf16_f32 v70, v64, v65
	v_cvt_pk_bf16_f32 v71, v66, v67
	global_store_dwordx4 v[138:139], v[68:71], off offset:1024
	v_mul_f32_e32 v64, 0x45800000, v72
	v_cndmask_b32_e32 v64, v72, v64, vcc
	v_mov_b32_e32 v70, v29
	v_mov_b32_e32 v71, v25
	v_mov_b32_e32 v68, v28
	v_mov_b32_e32 v69, v24
	v_mul_f32_e64 v70, v70, v70
	v_mul_f32_e64 v71, v71, v71
	s_waitcnt vmcnt(6)
	v_mov_b32_e32 v72, v61
	v_fma_f32 v68, v68, v68, v70
	v_fma_f32 v69, v69, v69, v71
	v_mov_b32_e32 v70, v30
	v_mov_b32_e32 v71, v26
	v_fma_f32 v68, v70, v70, v68
	v_fma_f32 v69, v71, v71, v69
	v_mov_b32_e32 v70, v31
	v_mov_b32_e32 v71, v27
	s_waitcnt vmcnt(5)
	v_mov_b32_e32 v73, v57
	v_mul_f32_e64 v74, v74, v132
	v_mul_f32_e64 v75, v75, v132
	v_fma_f32 v68, v70, v70, v68
	v_fma_f32 v69, v71, v71, v69
	v_mov_b32_e32 v70, v60
	v_mov_b32_e32 v71, v56
	v_mul_f32_e64 v72, v72, v72
	v_mul_f32_e64 v73, v73, v73
	v_fma_f32 v74, v110, v74, v10
	v_fma_f32 v75, v111, v75, v11
	v_fma_f32 v70, v70, v70, v72
	v_fma_f32 v71, v71, v71, v73
	v_mov_b32_e32 v72, v62
	v_mov_b32_e32 v73, v58
	v_cvt_pk_bf16_f32 v79, v74, v75
	v_fma_f32 v70, v72, v72, v70
	v_fma_f32 v71, v73, v73, v71
	v_mov_b32_e32 v72, v63
	v_mov_b32_e32 v73, v59
	s_waitcnt vmcnt(4)
	v_mov_b32_e32 v74, v53
	s_waitcnt vmcnt(3)
	v_mov_b32_e32 v75, v49
	v_fma_f32 v70, v72, v72, v70
	v_fma_f32 v71, v73, v73, v71
	v_mov_b32_e32 v72, v52
	v_mov_b32_e32 v73, v48
	v_mul_f32_e64 v74, v74, v74
	v_mul_f32_e64 v75, v75, v75
	global_store_dwordx4 v[138:139], v[76:79], off
	v_fma_f32 v72, v72, v72, v74
	v_fma_f32 v73, v73, v73, v75
	v_mov_b32_e32 v74, v54
	v_mov_b32_e32 v75, v50
	v_fma_f32 v72, v74, v74, v72
	v_fma_f32 v73, v75, v75, v73
	v_mov_b32_e32 v74, v55
	v_mov_b32_e32 v75, v51
	s_waitcnt vmcnt(3)
	v_mov_b32_e32 v76, v45
	s_waitcnt vmcnt(2)
	v_mov_b32_e32 v77, v41
	v_fma_f32 v72, v74, v74, v72
	v_fma_f32 v73, v75, v75, v73
	v_mov_b32_e32 v74, v44
	v_mov_b32_e32 v75, v40
	v_mul_f32_e64 v76, v76, v76
	v_mul_f32_e64 v77, v77, v77
	v_mul_f32_e64 v36, v36, v64
	v_mul_f32_e64 v37, v37, v64
	v_fma_f32 v74, v74, v74, v76
	v_fma_f32 v75, v75, v75, v77
	v_mov_b32_e32 v76, v46
	v_mov_b32_e32 v77, v42
	v_fma_f32 v74, v76, v76, v74
	v_fma_f32 v75, v77, v77, v75
	v_mov_b32_e32 v76, v47
	v_mov_b32_e32 v77, v43
	v_fma_f32 v74, v76, v76, v74
	v_fma_f32 v75, v77, v77, v75
	v_mov_b32_e32 v76, v72
	v_mov_b32_e32 v77, v68
	v_mov_b32_e32 v68, v73
	v_add_f32_e64 v68, v76, v68
	v_add_f32_e64 v69, v77, v69
	v_mov_b32_e32 v72, v74
	v_mov_b32_e32 v73, v70
	v_add_f32_e64 v68, v68, v72
	v_add_f32_e64 v69, v69, v73
	v_mov_b32_e32 v70, v75
	v_add_f32_e64 v68, v68, v70
	v_add_f32_e64 v69, v69, v71
	ds_bpermute_b32 v71, v125, v69
	ds_bpermute_b32 v70, v125, v68
	v_mul_f32_e64 v38, v38, v64
	v_mul_f32_e64 v39, v39, v64
	v_fma_f32 v36, v100, v36, v12
	v_fma_f32 v37, v101, v37, v13
	v_fma_f32 v38, v104, v38, v14
	v_fma_f32 v39, v105, v39, v15
	v_cvt_pk_bf16_f32 v36, v36, v37
	v_cvt_pk_bf16_f32 v37, v38, v39
	s_waitcnt lgkmcnt(0)
; DI unsigned pk_bf16(float lo, float hi) { f32x2 v = {lo, hi}; bf2_t b = __builtin_convertvector(v, bf2_t); return __builtin_bit_cast(unsigned, b); }
; DI void phase1(const Params& p, const Sched sc) {
;     ...
; #pragma unroll
;     for (int q = 0; q < 4; ++q) {
;       float ss = 0.f;
; #pragma unroll
;       for (int j = 0; j < 4; ++j) ss += v4[q][j][0] * v4[q][j][0] + v4[q][j][1] * v4[q][j][1] + v4[q][j][2] * v4[q][j][2] + v4[q][j][3] * v4[q][j][3];
; #pragma unroll
;       for (int o = 1; o < 64; o <<= 1) ss += __shfl_xor(ss, o);
;       const float rstd = rsqrtf(ss * (1.f / DM) + 1e-6f);
; #pragma unroll
;       for (int i = 0; i < 2; ++i) {
;         u32x4 w;
; #pragma unroll
;         for (int jj = 0; jj < 2; ++jj) {
;           const int j = 2 * i + jj;
;           float o[4];
; #pragma unroll
;           for (int e = 0; e < 4; ++e) o[e] = (v4[q][j][e] * rstd) * nw[j][e] + sh[j][e];
;           w[2 * jj] = pk_bf16(o[0], o[1]); w[2 * jj + 1] = pk_bf16(o[2], o[3]);
;         }
;         *(u32x4*)(p.H + (size_t)(rowa + q) * DM + (2 * lane + 128 * i) * 4) = w;
;       }
	v_add_f32_e64 v38, v68, v70
	v_add_f32_e64 v39, v69, v71
	ds_bpermute_b32 v69, v126, v39
	ds_bpermute_b32 v68, v126, v38
	v_mul_f32_e64 v32, v32, v64
	v_mul_f32_e64 v33, v33, v64
	v_mul_f32_e64 v34, v34, v64
	v_mul_f32_e64 v35, v35, v64
	v_lshlrev_b64 v[66:67], 11, v[98:99]
	v_fma_f32 v32, v102, v32, v8
	v_fma_f32 v33, v103, v33, v9
	s_waitcnt lgkmcnt(0)
	v_add_f32_e64 v68, v38, v68
	v_add_f32_e64 v69, v39, v69
	ds_bpermute_b32 v71, v127, v69
	ds_bpermute_b32 v70, v127, v68
	v_fma_f32 v34, v110, v34, v10
	v_fma_f32 v35, v111, v35, v11
	v_cvt_pk_bf16_f32 v38, v32, v33
	v_cvt_pk_bf16_f32 v39, v34, v35
	v_lshl_add_u64 v[32:33], v[86:87], 0, v[66:67]
	s_waitcnt lgkmcnt(0)
	v_add_f32_e64 v34, v68, v70
	v_add_f32_e64 v35, v69, v71
	global_store_dwordx4 v[32:33], v[36:39], off
	ds_bpermute_b32 v37, v128, v35
	ds_bpermute_b32 v36, v128, v34
	v_mul_f32_e64 v20, v20, v64
	v_mul_f32_e64 v21, v21, v64
	v_mul_f32_e64 v22, v22, v64
	v_mul_f32_e64 v23, v23, v64
	v_mul_f32_e64 v16, v16, v64
	v_mul_f32_e64 v17, v17, v64
	v_fma_f32 v20, v106, v20, v4
	v_fma_f32 v21, v107, v21, v5
	s_waitcnt lgkmcnt(0)
	v_add_f32_e64 v34, v34, v36
	v_add_f32_e64 v35, v35, v37
	ds_bpermute_b32 v37, v129, v35
	ds_bpermute_b32 v36, v129, v34
	v_fma_f32 v22, v108, v22, v6
	v_fma_f32 v23, v109, v23, v7
	v_fma_f32 v16, v112, v16, v0
	v_fma_f32 v17, v113, v17, v1
	v_cvt_pk_bf16_f32 v20, v20, v21
	v_cvt_pk_bf16_f32 v21, v22, v23
	s_waitcnt lgkmcnt(0)
	v_add_f32_e64 v34, v34, v36
	v_add_f32_e64 v35, v35, v37
	ds_bpermute_b32 v37, v130, v35
	ds_bpermute_b32 v36, v130, v34
	v_cvt_pk_bf16_f32 v22, v16, v17
	v_mul_f32_e64 v18, v18, v64
	v_mul_f32_e64 v19, v19, v64
	s_waitcnt lgkmcnt(0)
	v_add_f32_e64 v16, v34, v36
	v_add_f32_e64 v17, v35, v37
	s_nop 0
	v_fma_f32 v34, v16, s8, v136
	v_fma_f32 v35, v17, s8, v136
	v_fma_f32 v18, v114, v18, v2
	v_fma_f32 v19, v115, v19, v3
	v_mul_f32_e32 v16, 0x4b800000, v35
	v_cmp_gt_f32_e32 vcc, s12, v35
	v_cvt_pk_bf16_f32 v23, v18, v19
	global_store_dwordx4 v[32:33], v[20:23], off offset:1024
	v_cndmask_b32_e32 v16, v35, v16, vcc
	v_rsq_f32_e32 v18, v16
	v_lshlrev_b64 v[16:17], 11, v[94:95]
	v_lshl_add_u64 v[20:21], v[86:87], 0, v[16:17]
	v_mul_f32_e32 v16, 0x45800000, v18
	v_cndmask_b32_e32 v22, v18, v16, vcc
	v_mul_f32_e64 v16, v28, v22
	v_mul_f32_e64 v17, v29, v22
	v_mul_f32_e64 v18, v30, v22
	v_mul_f32_e64 v19, v31, v22
	v_fma_f32 v16, v100, v16, v12
	v_fma_f32 v17, v101, v17, v13
	v_fma_f32 v18, v104, v18, v14
	v_fma_f32 v19, v105, v19, v15
	v_cvt_pk_bf16_f32 v16, v16, v17
	v_cvt_pk_bf16_f32 v17, v18, v19
	v_mul_f32_e64 v18, v24, v22
	v_mul_f32_e64 v19, v25, v22
	v_mul_f32_e64 v24, v26, v22
	v_mul_f32_e64 v25, v27, v22
	v_fma_f32 v18, v102, v18, v8
	v_fma_f32 v19, v103, v19, v9
	v_fma_f32 v24, v110, v24, v10
	v_fma_f32 v25, v111, v25, v11
	v_cvt_pk_bf16_f32 v18, v18, v19
	v_cvt_pk_bf16_f32 v19, v24, v25
	v_mul_f32_e32 v24, 0x4b800000, v34
	v_cmp_gt_f32_e32 vcc, s12, v34
	global_store_dwordx4 v[20:21], v[16:19], off
	s_nop 0
	v_cndmask_b32_e32 v24, v34, v24, vcc
	v_mul_f32_e64 v16, v60, v22
	v_mul_f32_e64 v17, v61, v22
	v_mul_f32_e64 v18, v62, v22
	v_mul_f32_e64 v19, v63, v22
	v_fma_f32 v16, v106, v16, v4
	v_fma_f32 v17, v107, v17, v5
	v_fma_f32 v18, v108, v18, v6
	v_fma_f32 v19, v109, v19, v7
	v_rsq_f32_e32 v24, v24
	v_cvt_pk_bf16_f32 v16, v16, v17
	v_cvt_pk_bf16_f32 v17, v18, v19
	v_mul_f32_e64 v18, v56, v22
	v_mul_f32_e64 v19, v57, v22
	v_mul_f32_e64 v23, v59, v22
	v_mul_f32_e64 v22, v58, v22
	v_fma_f32 v18, v112, v18, v0
	v_fma_f32 v19, v113, v19, v1
	v_fma_f32 v22, v114, v22, v2
	v_fma_f32 v23, v115, v23, v3
	v_cvt_pk_bf16_f32 v18, v18, v19
	v_cvt_pk_bf16_f32 v19, v22, v23
	global_store_dwordx4 v[20:21], v[16:19], off offset:1024
	s_nop 1
	v_mul_f32_e32 v16, 0x45800000, v24
	v_cndmask_b32_e32 v16, v24, v16, vcc
	v_mul_f32_e64 v20, v52, v16
	v_mul_f32_e64 v21, v53, v16
	v_lshlrev_b64 v[18:19], 11, v[96:97]
	v_fma_f32 v12, v100, v20, v12
	v_fma_f32 v13, v101, v21, v13
	v_mul_f32_e64 v20, v54, v16
	v_mul_f32_e64 v21, v55, v16
	v_cvt_pk_bf16_f32 v12, v12, v13
	v_fma_f32 v14, v104, v20, v14
	v_fma_f32 v15, v105, v21, v15
	s_nop 0
	v_cvt_pk_bf16_f32 v13, v14, v15
	v_mul_f32_e64 v14, v48, v16
	v_mul_f32_e64 v15, v49, v16
	s_nop 0
	v_fma_f32 v8, v102, v14, v8
	v_fma_f32 v9, v103, v15, v9
	v_mul_f32_e64 v14, v50, v16
	v_mul_f32_e64 v15, v51, v16
	s_nop 0
	v_fma_f32 v10, v110, v14, v10
	v_fma_f32 v11, v111, v15, v11
	v_cvt_pk_bf16_f32 v14, v8, v9
	v_cvt_pk_bf16_f32 v15, v10, v11
	v_mul_f32_e64 v10, v44, v16
	v_mul_f32_e64 v11, v45, v16
	v_lshl_add_u64 v[8:9], v[86:87], 0, v[18:19]
	v_fma_f32 v4, v106, v10, v4
	v_fma_f32 v5, v107, v11, v5
	v_mul_f32_e64 v10, v46, v16
	v_mul_f32_e64 v11, v47, v16
	v_cvt_pk_bf16_f32 v4, v4, v5
	v_fma_f32 v6, v108, v10, v6
	v_fma_f32 v7, v109, v11, v7
	global_store_dwordx4 v[8:9], v[12:15], off
	v_cvt_pk_bf16_f32 v5, v6, v7
	v_mul_f32_e64 v6, v40, v16
	v_mul_f32_e64 v7, v41, v16
	s_nop 0
	v_fma_f32 v0, v112, v6, v0
	v_fma_f32 v1, v113, v7, v1
	v_mul_f32_e64 v6, v42, v16
	v_mul_f32_e64 v7, v43, v16
	s_nop 0
	v_fma_f32 v2, v114, v6, v2
	v_fma_f32 v3, v115, v7, v3
	v_cvt_pk_bf16_f32 v6, v0, v1
	v_cvt_pk_bf16_f32 v7, v2, v3
	global_store_dwordx4 v[8:9], v[4:7], off offset:1024
	s_cbranch_scc0 .LBB0_161
	s_branch .LBB0_158

; DI unsigned pk_bf16(float lo, float hi) { f32x2 v = {lo, hi}; bf2_t b = __builtin_convertvector(v, bf2_t); return __builtin_bit_cast(unsigned, b); }
; DI float silu_f(float v) { return v * __builtin_amdgcn_rcpf(1.f + fast_exp2(-v * LOG2E)); }
; template <int NI>
; DI void p2_store_group(const Params& p, const f32x16 (&a)[NI], int colg, int tok0, int b, int h) {
;     ...
;       bf16_t* d = base + (size_t)idx * stride + 8 * h;
; #pragma unroll
;       for (int q = 0; q < 2; ++q) {
;         u32x2 w[2];
; #pragma unroll
;         for (int gg = 0; gg < 2; ++gg) {
;           const int g = 2 * q + gg;
;           float v0 = a[ni][4 * g] * scale, v1 = a[ni][4 * g + 1] * scale, v2 = a[ni][4 * g + 2] * scale, v3 = a[ni][4 * g + 3] * scale;
;           if (mode == 1) { v0 = silu_f(v0); v1 = silu_f(v1); v2 = silu_f(v2); v3 = silu_f(v3); }
;           w[gg].x = pk_bf16(v0, v1); w[gg].y = pk_bf16(v2, v3);
;         }
;         *(u32x4*)(d + 16 * q) = widen_pair(w[0], w[1]);
;         __builtin_amdgcn_sched_barrier(0);
;       }
.LBB0_232:
	s_or_b64 exec, exec, s[36:37]
	v_mul_f32_e64 v16, v16, v32
	v_mul_f32_e64 v17, v17, v32
	v_mul_f32_e64 v18, v18, v32
	v_mul_f32_e64 v19, v19, v32
	s_and_saveexec_b64 s[36:37], s[2:3]
	s_cbranch_execz .LBB0_234
	v_mul_f32_e32 v33, 0xbfb8aa3b, v16
	v_exp_f32_e32 v33, v33
	v_mul_f32_e32 v38, 0xbfb8aa3b, v17
	v_exp_f32_e32 v38, v38
	v_mul_f32_e32 v40, 0xbfb8aa3b, v19
	v_add_f32_e32 v33, 1.0, v33
	v_exp_f32_e32 v41, v40
	v_add_f32_e32 v39, 1.0, v38
	v_rcp_f32_e32 v38, v33
	v_mul_f32_e32 v33, 0xbfb8aa3b, v18
	v_exp_f32_e32 v33, v33
	v_rcp_f32_e32 v39, v39
	v_add_f32_e32 v33, 1.0, v33
	v_rcp_f32_e32 v40, v33
	v_add_f32_e32 v33, 1.0, v41
	v_rcp_f32_e32 v41, v33
	v_mul_f32_e64 v16, v16, v38
	v_mul_f32_e64 v17, v17, v39
	v_mul_f32_e64 v18, v18, v40
	v_mul_f32_e64 v19, v19, v41
.LBB0_234:
	s_or_b64 exec, exec, s[36:37]
	v_mov_b32_e32 v33, v32
	v_mul_f32_e64 v20, v20, v32
	v_mul_f32_e64 v21, v21, v33
	v_mul_f32_e64 v22, v22, v32
	v_mul_f32_e64 v23, v23, v33
	s_and_saveexec_b64 s[36:37], s[2:3]
	s_cbranch_execz .LBB0_236
	v_mul_f32_e32 v38, 0xbfb8aa3b, v20
	v_mul_f32_e32 v39, 0xbfb8aa3b, v21
	v_mul_f32_e32 v40, 0xbfb8aa3b, v22
	v_mul_f32_e32 v41, 0xbfb8aa3b, v23
	v_exp_f32_e32 v38, v38
	v_exp_f32_e32 v39, v39
	v_exp_f32_e32 v40, v40
	v_exp_f32_e32 v41, v41
	v_add_f32_e32 v38, 1.0, v38
	v_add_f32_e32 v39, 1.0, v39
	v_add_f32_e32 v40, 1.0, v40
	v_add_f32_e32 v41, 1.0, v41
	v_rcp_f32_e32 v38, v38
	v_rcp_f32_e32 v39, v39
	v_rcp_f32_e32 v40, v40
	v_rcp_f32_e32 v41, v41
	v_mul_f32_e64 v20, v20, v38
	v_mul_f32_e64 v21, v21, v39
	v_mul_f32_e64 v22, v22, v40
	v_mul_f32_e64 v23, v23, v41
.LBB0_236:
	s_or_b64 exec, exec, s[36:37]
	v_lshlrev_b32_e32 v144, 1, v180
	v_cvt_pk_bf16_f32 v38, v16, v17
	v_cvt_pk_bf16_f32 v39, v18, v19
	v_lshl_add_u64 v[16:17], v[36:37], 0, v[144:145]
	v_mul_lo_u32 v36, v35, v132
	v_mul_lo_u32 v37, v34, v133
	v_mad_u64_u32 v[18:19], s[36:37], v34, v132, 0
	v_add3_u32 v19, v19, v37, v36
	v_cvt_pk_bf16_f32 v40, v20, v21
	v_cvt_pk_bf16_f32 v41, v22, v23
	v_lshl_add_u64 v[18:19], v[18:19], 1, v[16:17]
	v_permlane32_swap_b32_e32 v38, v40
	v_permlane32_swap_b32_e32 v39, v41
	global_store_dwordx4 v[18:19], v[38:41], off
	v_mul_f32_e64 v20, v24, v32
	v_mul_f32_e64 v21, v25, v33
	v_mul_f32_e64 v22, v26, v32
	v_mul_f32_e64 v23, v27, v33
	s_and_saveexec_b64 s[36:37], s[2:3]
	s_cbranch_execz .LBB0_238
	v_mul_f32_e32 v24, 0xbfb8aa3b, v20
	v_mul_f32_e32 v25, 0xbfb8aa3b, v21
	v_mul_f32_e32 v26, 0xbfb8aa3b, v22
	v_mul_f32_e32 v27, 0xbfb8aa3b, v23
	v_exp_f32_e32 v24, v24
	v_exp_f32_e32 v25, v25
	v_exp_f32_e32 v26, v26
	v_exp_f32_e32 v27, v27
	v_add_f32_e32 v24, 1.0, v24
	v_add_f32_e32 v25, 1.0, v25
	v_add_f32_e32 v26, 1.0, v26
	v_add_f32_e32 v27, 1.0, v27
	v_rcp_f32_e32 v24, v24
	v_rcp_f32_e32 v25, v25
	v_rcp_f32_e32 v26, v26
	v_rcp_f32_e32 v27, v27
	v_mul_f32_e64 v20, v20, v24
	v_mul_f32_e64 v21, v21, v25
	v_mul_f32_e64 v22, v22, v26
	v_mul_f32_e64 v23, v23, v27
.LBB0_238:
	s_or_b64 exec, exec, s[36:37]
	v_mul_f32_e64 v24, v28, v32
	v_mul_f32_e64 v25, v29, v33
	v_mul_f32_e64 v26, v30, v32
	v_mul_f32_e64 v27, v31, v33
	s_and_saveexec_b64 s[36:37], s[2:3]
	s_cbranch_execz .LBB0_240
	v_mul_f32_e32 v28, 0xbfb8aa3b, v24
	v_mul_f32_e32 v29, 0xbfb8aa3b, v25
	v_mul_f32_e32 v30, 0xbfb8aa3b, v26
	v_mul_f32_e32 v31, 0xbfb8aa3b, v27
	v_exp_f32_e32 v28, v28
	v_exp_f32_e32 v29, v29
	v_exp_f32_e32 v30, v30
	v_exp_f32_e32 v31, v31
	v_add_f32_e32 v28, 1.0, v28
	v_add_f32_e32 v29, 1.0, v29
	v_add_f32_e32 v30, 1.0, v30
	v_add_f32_e32 v31, 1.0, v31
	v_rcp_f32_e32 v28, v28
	v_rcp_f32_e32 v29, v29
	v_rcp_f32_e32 v30, v30
	v_rcp_f32_e32 v31, v31
	v_mul_f32_e64 v24, v24, v28
	v_mul_f32_e64 v25, v25, v29
	v_mul_f32_e64 v26, v26, v30
	v_mul_f32_e64 v27, v27, v31
.LBB0_240:
	s_or_b64 exec, exec, s[36:37]
	v_cvt_pk_bf16_f32 v20, v20, v21
	v_cvt_pk_bf16_f32 v21, v22, v23
	v_cvt_pk_bf16_f32 v22, v24, v25
	v_cvt_pk_bf16_f32 v23, v26, v27
	s_nop 0
	v_permlane32_swap_b32_e32 v20, v22
	v_permlane32_swap_b32_e32 v21, v23
	global_store_dwordx4 v[18:19], v[20:23], off offset:32
	v_mul_f32_e64 v0, v0, v32
	v_mul_f32_e64 v1, v1, v33
	v_mul_f32_e64 v2, v2, v32
	v_mul_f32_e64 v3, v3, v33
	s_and_saveexec_b64 s[36:37], s[2:3]
	s_cbranch_execz .LBB0_242
	v_mul_f32_e32 v18, 0xbfb8aa3b, v0
	v_mul_f32_e32 v19, 0xbfb8aa3b, v1
	v_mul_f32_e32 v20, 0xbfb8aa3b, v2
	v_mul_f32_e32 v21, 0xbfb8aa3b, v3
	v_exp_f32_e32 v18, v18
	v_exp_f32_e32 v19, v19
	v_exp_f32_e32 v20, v20
	v_exp_f32_e32 v21, v21
	v_add_f32_e32 v18, 1.0, v18
	v_add_f32_e32 v19, 1.0, v19
	v_add_f32_e32 v20, 1.0, v20
	v_add_f32_e32 v21, 1.0, v21
	v_rcp_f32_e32 v18, v18
	v_rcp_f32_e32 v19, v19
	v_rcp_f32_e32 v20, v20
	v_rcp_f32_e32 v21, v21
	v_mul_f32_e64 v0, v0, v18
	v_mul_f32_e64 v1, v1, v19
	v_mul_f32_e64 v2, v2, v20
	v_mul_f32_e64 v3, v3, v21
.LBB0_242:
	s_or_b64 exec, exec, s[36:37]
	v_mul_f32_e64 v4, v4, v32
	v_mul_f32_e64 v5, v5, v33
	v_mul_f32_e64 v6, v6, v32
	v_mul_f32_e64 v7, v7, v33
	s_and_saveexec_b64 s[36:37], s[2:3]
	s_cbranch_execz .LBB0_244
	v_mul_f32_e32 v18, 0xbfb8aa3b, v4
	v_mul_f32_e32 v19, 0xbfb8aa3b, v5
	v_mul_f32_e32 v20, 0xbfb8aa3b, v6
	v_mul_f32_e32 v21, 0xbfb8aa3b, v7
	v_exp_f32_e32 v18, v18
	v_exp_f32_e32 v19, v19
	v_exp_f32_e32 v20, v20
	v_exp_f32_e32 v21, v21
	v_add_f32_e32 v18, 1.0, v18
	v_add_f32_e32 v19, 1.0, v19
	v_add_f32_e32 v20, 1.0, v20
	v_add_f32_e32 v21, 1.0, v21
	v_rcp_f32_e32 v18, v18
	v_rcp_f32_e32 v19, v19
	v_rcp_f32_e32 v20, v20
	v_rcp_f32_e32 v21, v21
	v_mul_f32_e64 v4, v4, v18
	v_mul_f32_e64 v5, v5, v19
	v_mul_f32_e64 v6, v6, v20
	v_mul_f32_e64 v7, v7, v21
; DI unsigned pk_bf16(float lo, float hi) { f32x2 v = {lo, hi}; bf2_t b = __builtin_convertvector(v, bf2_t); return __builtin_bit_cast(unsigned, b); }
; DI float silu_f(float v) { return v * __builtin_amdgcn_rcpf(1.f + fast_exp2(-v * LOG2E)); }
; template <int NI>
; DI void p2_store_group(const Params& p, const f32x16 (&a)[NI], int colg, int tok0, int b, int h) {
;     ...
;       bf16_t* d = base + (size_t)idx * stride + 8 * h;
; #pragma unroll
;       for (int q = 0; q < 2; ++q) {
;         u32x2 w[2];
; #pragma unroll
;         for (int gg = 0; gg < 2; ++gg) {
;           const int g = 2 * q + gg;
;           float v0 = a[ni][4 * g] * scale, v1 = a[ni][4 * g + 1] * scale, v2 = a[ni][4 * g + 2] * scale, v3 = a[ni][4 * g + 3] * scale;
;           if (mode == 1) { v0 = silu_f(v0); v1 = silu_f(v1); v2 = silu_f(v2); v3 = silu_f(v3); }
;           w[gg].x = pk_bf16(v0, v1); w[gg].y = pk_bf16(v2, v3);
;         }
;         *(u32x4*)(d + 16 * q) = widen_pair(w[0], w[1]);
;         __builtin_amdgcn_sched_barrier(0);
;       }
.LBB0_244:
	s_or_b64 exec, exec, s[36:37]
	v_cvt_pk_bf16_f32 v18, v0, v1
	v_cndmask_b32_e32 v0, v152, v128, vcc
	v_ashrrev_i32_e32 v1, 31, v0
	v_cvt_pk_bf16_f32 v19, v2, v3
	v_mul_lo_u32 v2, v34, v1
	v_mul_lo_u32 v3, v35, v0
	v_mad_u64_u32 v[0:1], s[36:37], v34, v0, 0
	v_add3_u32 v1, v1, v2, v3
	v_cvt_pk_bf16_f32 v20, v4, v5
	v_cvt_pk_bf16_f32 v21, v6, v7
	v_lshl_add_u64 v[0:1], v[0:1], 1, v[16:17]
	v_permlane32_swap_b32_e32 v18, v20
	v_permlane32_swap_b32_e32 v19, v21
	global_store_dwordx4 v[0:1], v[18:21], off
	v_mul_f32_e64 v2, v8, v32
	v_mul_f32_e64 v3, v9, v33
	v_mul_f32_e64 v4, v10, v32
	v_mul_f32_e64 v5, v11, v33
	s_and_saveexec_b64 s[36:37], s[2:3]
	s_cbranch_execz .LBB0_246
	v_mul_f32_e32 v6, 0xbfb8aa3b, v2
	v_mul_f32_e32 v7, 0xbfb8aa3b, v3
	v_mul_f32_e32 v8, 0xbfb8aa3b, v4
	v_mul_f32_e32 v9, 0xbfb8aa3b, v5
	v_exp_f32_e32 v6, v6
	v_exp_f32_e32 v7, v7
	v_exp_f32_e32 v8, v8
	v_exp_f32_e32 v9, v9
	v_add_f32_e32 v6, 1.0, v6
	v_add_f32_e32 v7, 1.0, v7
	v_add_f32_e32 v8, 1.0, v8
	v_add_f32_e32 v9, 1.0, v9
	v_rcp_f32_e32 v6, v6
	v_rcp_f32_e32 v7, v7
	v_rcp_f32_e32 v8, v8
	v_rcp_f32_e32 v9, v9
	v_mul_f32_e64 v2, v2, v6
	v_mul_f32_e64 v3, v3, v7
	v_mul_f32_e64 v4, v4, v8
	v_mul_f32_e64 v5, v5, v9
.LBB0_246:
	s_or_b64 exec, exec, s[36:37]
	v_mul_f32_e64 v6, v12, v32
	v_mul_f32_e64 v7, v13, v33
	v_mul_f32_e64 v8, v14, v32
	v_mul_f32_e64 v9, v15, v33
	s_and_saveexec_b64 s[36:37], s[2:3]
	s_cbranch_execz .LBB0_185
	v_mul_f32_e32 v10, 0xbfb8aa3b, v6
	v_mul_f32_e32 v11, 0xbfb8aa3b, v7
	v_mul_f32_e32 v12, 0xbfb8aa3b, v8
	v_mul_f32_e32 v13, 0xbfb8aa3b, v9
	v_exp_f32_e32 v10, v10
	v_exp_f32_e32 v11, v11
	v_exp_f32_e32 v12, v12
	v_exp_f32_e32 v13, v13
	v_add_f32_e32 v10, 1.0, v10
	v_add_f32_e32 v11, 1.0, v11
	v_add_f32_e32 v12, 1.0, v12
	v_add_f32_e32 v13, 1.0, v13
	v_rcp_f32_e32 v10, v10
	v_rcp_f32_e32 v11, v11
	v_rcp_f32_e32 v12, v12
	v_rcp_f32_e32 v13, v13
	v_mul_f32_e64 v6, v6, v10
	v_mul_f32_e64 v7, v7, v11
	v_mul_f32_e64 v8, v8, v12
	v_mul_f32_e64 v9, v9, v13
	s_branch .LBB0_185
.LBB0_248:
	v_mul_f32_e64 v48, v48, v140
	v_mul_f32_e64 v49, v49, v140
	v_mul_f32_e64 v50, v50, v140
	v_mul_f32_e64 v51, v51, v140
	s_and_saveexec_b64 s[40:41], s[2:3]
	s_cbranch_execz .LBB0_250
	v_mul_f32_e32 v129, 0xbfb8aa3b, v48
	v_exp_f32_e32 v129, v129
	v_mul_f32_e32 v135, 0xbfb8aa3b, v49
	v_mul_f32_e32 v141, 0xbfb8aa3b, v51
	v_exp_f32_e32 v135, v135
	v_add_f32_e32 v129, 1.0, v129
	v_rcp_f32_e32 v154, v129
	v_mul_f32_e32 v129, 0xbfb8aa3b, v50
	v_exp_f32_e32 v129, v129
	v_exp_f32_e32 v141, v141
	v_add_f32_e32 v135, 1.0, v135
	v_rcp_f32_e32 v155, v135
	v_add_f32_e32 v129, 1.0, v129
	v_rcp_f32_e32 v172, v129
	v_add_f32_e32 v129, 1.0, v141
	v_rcp_f32_e32 v173, v129
	v_mul_f32_e64 v48, v48, v154
	v_mul_f32_e64 v49, v49, v155
	v_mul_f32_e64 v50, v50, v172
	v_mul_f32_e64 v51, v51, v173
.LBB0_250:
	s_or_b64 exec, exec, s[40:41]
	v_mov_b32_e32 v141, v140
	v_mul_f32_e64 v52, v52, v140
	v_mul_f32_e64 v53, v53, v141
	v_mul_f32_e64 v54, v54, v140
	v_mul_f32_e64 v55, v55, v141
	s_and_saveexec_b64 s[40:41], s[2:3]
	s_cbranch_execz .LBB0_252
	v_mul_f32_e32 v129, 0xbfb8aa3b, v52
	v_exp_f32_e32 v129, v129
	v_mul_f32_e32 v135, 0xbfb8aa3b, v53
	v_mul_f32_e32 v144, 0xbfb8aa3b, v55
	v_exp_f32_e32 v135, v135
	v_add_f32_e32 v129, 1.0, v129
	v_rcp_f32_e32 v154, v129
	v_mul_f32_e32 v129, 0xbfb8aa3b, v54
	v_exp_f32_e32 v129, v129
	v_exp_f32_e32 v144, v144
	v_add_f32_e32 v135, 1.0, v135
	v_rcp_f32_e32 v155, v135
	v_add_f32_e32 v129, 1.0, v129
	v_rcp_f32_e32 v172, v129
	v_add_f32_e32 v129, 1.0, v144
	v_rcp_f32_e32 v173, v129
	v_mul_f32_e64 v52, v52, v154
	v_mul_f32_e64 v53, v53, v155
	v_mul_f32_e64 v54, v54, v172
	v_mul_f32_e64 v55, v55, v173
.LBB0_252:
	s_or_b64 exec, exec, s[40:41]
	v_cvt_pk_bf16_f32 v172, v48, v49
	v_cndmask_b32_e32 v48, v132, v130, vcc
	v_ashrrev_i32_e32 v49, 31, v48
	v_cvt_pk_bf16_f32 v173, v50, v51
	v_mul_lo_u32 v50, v138, v49
	v_mul_lo_u32 v51, v139, v48
	v_mad_u64_u32 v[48:49], s[40:41], v138, v48, 0
	v_add3_u32 v49, v49, v50, v51
	v_cvt_pk_bf16_f32 v174, v52, v53
	v_cvt_pk_bf16_f32 v175, v54, v55
	v_lshl_add_u64 v[48:49], v[48:49], 1, v[142:143]
	v_permlane32_swap_b32_e32 v172, v174
	v_permlane32_swap_b32_e32 v173, v175
	global_store_dwordx4 v[48:49], v[172:175], off
	v_mul_f32_e64 v50, v56, v140
	v_mul_f32_e64 v51, v57, v141
	v_mul_f32_e64 v52, v58, v140
	v_mul_f32_e64 v53, v59, v141
	s_and_saveexec_b64 s[40:41], s[2:3]
	s_cbranch_execz .LBB0_254
	v_mul_f32_e32 v54, 0xbfb8aa3b, v50
	v_mul_f32_e32 v55, 0xbfb8aa3b, v51
	v_mul_f32_e32 v56, 0xbfb8aa3b, v52
	v_mul_f32_e32 v57, 0xbfb8aa3b, v53
	v_exp_f32_e32 v54, v54
	v_exp_f32_e32 v55, v55
	v_exp_f32_e32 v56, v56
	v_exp_f32_e32 v57, v57
	v_add_f32_e32 v54, 1.0, v54
	v_add_f32_e32 v55, 1.0, v55
	v_add_f32_e32 v56, 1.0, v56
	v_add_f32_e32 v57, 1.0, v57
	v_rcp_f32_e32 v54, v54
	v_rcp_f32_e32 v55, v55
	v_rcp_f32_e32 v56, v56
	v_rcp_f32_e32 v57, v57
	v_mul_f32_e64 v50, v50, v54
	v_mul_f32_e64 v51, v51, v55
	v_mul_f32_e64 v52, v52, v56
	v_mul_f32_e64 v53, v53, v57
.LBB0_254:
	s_or_b64 exec, exec, s[40:41]
	v_mul_f32_e64 v54, v60, v140
	v_mul_f32_e64 v55, v61, v141
	v_mul_f32_e64 v56, v62, v140
	v_mul_f32_e64 v57, v63, v141
	s_and_saveexec_b64 s[40:41], s[2:3]
	s_cbranch_execz .LBB0_256
	v_mul_f32_e32 v58, 0xbfb8aa3b, v54
	v_mul_f32_e32 v59, 0xbfb8aa3b, v55
	v_mul_f32_e32 v60, 0xbfb8aa3b, v56
	v_mul_f32_e32 v61, 0xbfb8aa3b, v57
	v_exp_f32_e32 v58, v58
	v_exp_f32_e32 v59, v59
	v_exp_f32_e32 v60, v60
	v_exp_f32_e32 v61, v61
	v_add_f32_e32 v58, 1.0, v58
	v_add_f32_e32 v59, 1.0, v59
	v_add_f32_e32 v60, 1.0, v60
	v_add_f32_e32 v61, 1.0, v61
	v_rcp_f32_e32 v58, v58
	v_rcp_f32_e32 v59, v59
	v_rcp_f32_e32 v60, v60
	v_rcp_f32_e32 v61, v61
	v_mul_f32_e64 v54, v54, v58
	v_mul_f32_e64 v55, v55, v59
	v_mul_f32_e64 v56, v56, v60
	v_mul_f32_e64 v57, v57, v61

; DI unsigned pk_bf16(float lo, float hi) { f32x2 v = {lo, hi}; bf2_t b = __builtin_convertvector(v, bf2_t); return __builtin_bit_cast(unsigned, b); }
; DI float silu_f(float v) { return v * __builtin_amdgcn_rcpf(1.f + fast_exp2(-v * LOG2E)); }
; template <int NI>
; DI void p2_store_group(const Params& p, const f32x16 (&a)[NI], int colg, int tok0, int b, int h) {
;     ...
;       bf16_t* d = base + (size_t)idx * stride + 8 * h;
; #pragma unroll
;       for (int q = 0; q < 2; ++q) {
;         u32x2 w[2];
; #pragma unroll
;         for (int gg = 0; gg < 2; ++gg) {
;           const int g = 2 * q + gg;
;           float v0 = a[ni][4 * g] * scale, v1 = a[ni][4 * g + 1] * scale, v2 = a[ni][4 * g + 2] * scale, v3 = a[ni][4 * g + 3] * scale;
;           if (mode == 1) { v0 = silu_f(v0); v1 = silu_f(v1); v2 = silu_f(v2); v3 = silu_f(v3); }
;           w[gg].x = pk_bf16(v0, v1); w[gg].y = pk_bf16(v2, v3);
;         }
;         *(u32x4*)(d + 16 * q) = widen_pair(w[0], w[1]);
;         __builtin_amdgcn_sched_barrier(0);
;       }
.LBB0_258:
	v_mul_f32_e64 v32, v32, v140
	v_mul_f32_e64 v33, v33, v140
	v_mul_f32_e64 v34, v34, v140
	v_mul_f32_e64 v35, v35, v140
	s_and_saveexec_b64 s[38:39], s[2:3]
	s_cbranch_execz .LBB0_260
	v_mul_f32_e32 v48, 0xbfb8aa3b, v32
	v_mul_f32_e32 v49, 0xbfb8aa3b, v33
	v_mul_f32_e32 v50, 0xbfb8aa3b, v34
	v_mul_f32_e32 v51, 0xbfb8aa3b, v35
	v_exp_f32_e32 v48, v48
	v_exp_f32_e32 v49, v49
	v_exp_f32_e32 v50, v50
	v_exp_f32_e32 v51, v51
	v_add_f32_e32 v48, 1.0, v48
	v_add_f32_e32 v49, 1.0, v49
	v_add_f32_e32 v50, 1.0, v50
	v_add_f32_e32 v51, 1.0, v51
	v_rcp_f32_e32 v48, v48
	v_rcp_f32_e32 v49, v49
	v_rcp_f32_e32 v50, v50
	v_rcp_f32_e32 v51, v51
	v_mul_f32_e64 v32, v32, v48
	v_mul_f32_e64 v33, v33, v49
	v_mul_f32_e64 v34, v34, v50
	v_mul_f32_e64 v35, v35, v51
.LBB0_260:
	s_or_b64 exec, exec, s[38:39]
	v_mov_b32_e32 v141, v140
	v_mul_f32_e64 v36, v36, v140
	v_mul_f32_e64 v37, v37, v141
	v_mul_f32_e64 v38, v38, v140
	v_mul_f32_e64 v39, v39, v141
	s_and_saveexec_b64 s[38:39], s[2:3]
	s_cbranch_execz .LBB0_262
	v_mul_f32_e32 v48, 0xbfb8aa3b, v36
	v_mul_f32_e32 v49, 0xbfb8aa3b, v37
	v_mul_f32_e32 v50, 0xbfb8aa3b, v38
	v_mul_f32_e32 v51, 0xbfb8aa3b, v39
	v_exp_f32_e32 v48, v48
	v_exp_f32_e32 v49, v49
	v_exp_f32_e32 v50, v50
	v_exp_f32_e32 v51, v51
	v_add_f32_e32 v48, 1.0, v48
	v_add_f32_e32 v49, 1.0, v49
	v_add_f32_e32 v50, 1.0, v50
	v_add_f32_e32 v51, 1.0, v51
	v_rcp_f32_e32 v48, v48
	v_rcp_f32_e32 v49, v49
	v_rcp_f32_e32 v50, v50
	v_rcp_f32_e32 v51, v51
	v_mul_f32_e64 v36, v36, v48
	v_mul_f32_e64 v37, v37, v49
	v_mul_f32_e64 v38, v38, v50
	v_mul_f32_e64 v39, v39, v51
.LBB0_262:
	s_or_b64 exec, exec, s[38:39]
	v_cvt_pk_bf16_f32 v48, v32, v33
	v_cndmask_b32_e32 v32, v152, v128, vcc
	v_ashrrev_i32_e32 v33, 31, v32
	v_cvt_pk_bf16_f32 v49, v34, v35
	v_mul_lo_u32 v34, v138, v33
	v_mul_lo_u32 v35, v139, v32
	v_mad_u64_u32 v[32:33], s[38:39], v138, v32, 0
	v_add3_u32 v33, v33, v34, v35
	v_cvt_pk_bf16_f32 v50, v36, v37
	v_cvt_pk_bf16_f32 v51, v38, v39
	v_lshl_add_u64 v[32:33], v[32:33], 1, v[142:143]
	v_permlane32_swap_b32_e32 v48, v50
	v_permlane32_swap_b32_e32 v49, v51
	global_store_dwordx4 v[32:33], v[48:51], off
	v_mul_f32_e64 v34, v40, v140
	v_mul_f32_e64 v35, v41, v141
	v_mul_f32_e64 v36, v42, v140
	v_mul_f32_e64 v37, v43, v141
	s_and_saveexec_b64 s[38:39], s[2:3]
	s_cbranch_execz .LBB0_264
	v_mul_f32_e32 v38, 0xbfb8aa3b, v34
	v_mul_f32_e32 v39, 0xbfb8aa3b, v35
	v_mul_f32_e32 v40, 0xbfb8aa3b, v36
	v_mul_f32_e32 v41, 0xbfb8aa3b, v37
	v_exp_f32_e32 v38, v38
	v_exp_f32_e32 v39, v39
	v_exp_f32_e32 v40, v40
	v_exp_f32_e32 v41, v41
	v_add_f32_e32 v38, 1.0, v38
	v_add_f32_e32 v39, 1.0, v39
	v_add_f32_e32 v40, 1.0, v40
	v_add_f32_e32 v41, 1.0, v41
	v_rcp_f32_e32 v38, v38
	v_rcp_f32_e32 v39, v39
	v_rcp_f32_e32 v40, v40
	v_rcp_f32_e32 v41, v41
	v_mul_f32_e64 v34, v34, v38
	v_mul_f32_e64 v35, v35, v39
	v_mul_f32_e64 v36, v36, v40
	v_mul_f32_e64 v37, v37, v41
.LBB0_264:
	s_or_b64 exec, exec, s[38:39]
	v_mul_f32_e64 v38, v44, v140
	v_mul_f32_e64 v39, v45, v141
	v_mul_f32_e64 v40, v46, v140
	v_mul_f32_e64 v41, v47, v141
	s_and_saveexec_b64 s[38:39], s[2:3]
	s_cbranch_execz .LBB0_266
	v_mul_f32_e32 v42, 0xbfb8aa3b, v38
	v_mul_f32_e32 v43, 0xbfb8aa3b, v39
	v_mul_f32_e32 v44, 0xbfb8aa3b, v40
	v_mul_f32_e32 v45, 0xbfb8aa3b, v41
	v_exp_f32_e32 v42, v42
	v_exp_f32_e32 v43, v43
	v_exp_f32_e32 v44, v44
	v_exp_f32_e32 v45, v45
	v_add_f32_e32 v42, 1.0, v42
	v_add_f32_e32 v43, 1.0, v43
	v_add_f32_e32 v44, 1.0, v44
	v_add_f32_e32 v45, 1.0, v45
	v_rcp_f32_e32 v42, v42
	v_rcp_f32_e32 v43, v43
	v_rcp_f32_e32 v44, v44
	v_rcp_f32_e32 v45, v45
	v_mul_f32_e64 v38, v38, v42
	v_mul_f32_e64 v39, v39, v43
	v_mul_f32_e64 v40, v40, v44
	v_mul_f32_e64 v41, v41, v45

; DI unsigned pk_bf16(float lo, float hi) { f32x2 v = {lo, hi}; bf2_t b = __builtin_convertvector(v, bf2_t); return __builtin_bit_cast(unsigned, b); }
; DI float silu_f(float v) { return v * __builtin_amdgcn_rcpf(1.f + fast_exp2(-v * LOG2E)); }
; template <int NI>
; DI void p2_store_group(const Params& p, const f32x16 (&a)[NI], int colg, int tok0, int b, int h) {
;     ...
;       bf16_t* d = base + (size_t)idx * stride + 8 * h;
; #pragma unroll
;       for (int q = 0; q < 2; ++q) {
;         u32x2 w[2];
; #pragma unroll
;         for (int gg = 0; gg < 2; ++gg) {
;           const int g = 2 * q + gg;
;           float v0 = a[ni][4 * g] * scale, v1 = a[ni][4 * g + 1] * scale, v2 = a[ni][4 * g + 2] * scale, v3 = a[ni][4 * g + 3] * scale;
;           if (mode == 1) { v0 = silu_f(v0); v1 = silu_f(v1); v2 = silu_f(v2); v3 = silu_f(v3); }
;           w[gg].x = pk_bf16(v0, v1); w[gg].y = pk_bf16(v2, v3);
;         }
;         *(u32x4*)(d + 16 * q) = widen_pair(w[0], w[1]);
;         __builtin_amdgcn_sched_barrier(0);
;       }
.LBB0_297:
	v_mul_f32_e64 v16, v16, v38
	v_mul_f32_e64 v17, v17, v38
	v_mul_f32_e64 v18, v18, v38
	v_mul_f32_e64 v19, v19, v38
	s_and_b64 vcc, exec, s[38:39]
	s_cbranch_vccz .LBB0_299
	v_mul_f32_e32 v35, 0xbfb8aa3b, v16
	v_exp_f32_e32 v35, v35
	v_mul_f32_e32 v39, 0xbfb8aa3b, v17
	v_mul_f32_e32 v43, 0xbfb8aa3b, v19
	v_exp_f32_e32 v39, v39
	v_add_f32_e32 v35, 1.0, v35
	v_rcp_f32_e32 v42, v35
	v_mul_f32_e32 v35, 0xbfb8aa3b, v18
	v_exp_f32_e32 v35, v35
	v_exp_f32_e32 v45, v43
	v_add_f32_e32 v39, 1.0, v39
	v_rcp_f32_e32 v43, v39
	v_add_f32_e32 v35, 1.0, v35
	v_rcp_f32_e32 v44, v35
	v_add_f32_e32 v35, 1.0, v45
	v_rcp_f32_e32 v45, v35
	v_mul_f32_e64 v16, v16, v42
	v_mul_f32_e64 v17, v17, v43
	v_mul_f32_e64 v18, v18, v44
	v_mul_f32_e64 v19, v19, v45
.LBB0_299:
	v_mov_b32_e32 v39, v38
	v_cndmask_b32_e64 v35, 0, 1, s[38:39]
	v_mul_f32_e64 v20, v20, v38
	v_mul_f32_e64 v21, v21, v39
	v_cmp_ne_u32_e64 s[8:9], 1, v35
	s_andn2_b64 vcc, exec, s[38:39]
	v_mul_f32_e64 v22, v22, v38
	v_mul_f32_e64 v23, v23, v39
	s_cbranch_vccnz .LBB0_301
	v_mul_f32_e32 v35, 0xbfb8aa3b, v20
	v_exp_f32_e32 v35, v35
	v_mul_f32_e32 v42, 0xbfb8aa3b, v21
	v_exp_f32_e32 v42, v42
	v_mul_f32_e32 v44, 0xbfb8aa3b, v23
	v_add_f32_e32 v35, 1.0, v35
	v_exp_f32_e32 v45, v44
	v_add_f32_e32 v43, 1.0, v42
	v_rcp_f32_e32 v42, v35
	v_mul_f32_e32 v35, 0xbfb8aa3b, v22
	v_exp_f32_e32 v35, v35
	v_rcp_f32_e32 v43, v43
	v_add_f32_e32 v35, 1.0, v35
	v_rcp_f32_e32 v44, v35
	v_add_f32_e32 v35, 1.0, v45
	v_rcp_f32_e32 v45, v35
	v_mul_f32_e64 v20, v20, v42
	v_mul_f32_e64 v21, v21, v43
	v_mul_f32_e64 v22, v22, v44
	v_mul_f32_e64 v23, v23, v45
.LBB0_301:
	v_cvt_pk_bf16_f32 v42, v16, v17
	v_cvt_pk_bf16_f32 v43, v18, v19
	v_mul_lo_u32 v18, s41, v40
	v_mul_lo_u32 v19, s40, v41
	v_mad_u64_u32 v[16:17], s[38:39], s40, v40, 0
	v_add3_u32 v17, v17, v19, v18
	v_lshl_add_u64 v[16:17], v[16:17], 1, s[36:37]
	v_lshlrev_b32_e32 v144, 1, v180
	v_cvt_pk_bf16_f32 v44, v20, v21
	v_cvt_pk_bf16_f32 v45, v22, v23
	v_lshl_add_u64 v[16:17], v[16:17], 0, v[144:145]
	v_permlane32_swap_b32_e32 v42, v44
	v_permlane32_swap_b32_e32 v43, v45
	global_store_dwordx4 v[16:17], v[42:45], off
	v_mul_f32_e64 v18, v24, v38
	v_mul_f32_e64 v19, v25, v39
	s_and_b64 vcc, exec, s[8:9]
	v_mul_f32_e64 v20, v26, v38
	v_mul_f32_e64 v21, v27, v39
	s_cbranch_vccnz .LBB0_303
	v_mul_f32_e32 v22, 0xbfb8aa3b, v18
	v_mul_f32_e32 v23, 0xbfb8aa3b, v19
	v_mul_f32_e32 v24, 0xbfb8aa3b, v20
	v_mul_f32_e32 v25, 0xbfb8aa3b, v21
	v_exp_f32_e32 v22, v22
	v_exp_f32_e32 v23, v23
	v_exp_f32_e32 v24, v24
	v_exp_f32_e32 v25, v25
	v_add_f32_e32 v22, 1.0, v22
	v_add_f32_e32 v23, 1.0, v23
	v_add_f32_e32 v24, 1.0, v24
	v_add_f32_e32 v25, 1.0, v25
	v_rcp_f32_e32 v22, v22
	v_rcp_f32_e32 v23, v23
	v_rcp_f32_e32 v24, v24
	v_rcp_f32_e32 v25, v25
	v_mul_f32_e64 v18, v18, v22
	v_mul_f32_e64 v19, v19, v23
	v_mul_f32_e64 v20, v20, v24
	v_mul_f32_e64 v21, v21, v25
.LBB0_303:
	v_mul_f32_e64 v22, v28, v38
	v_mul_f32_e64 v23, v29, v39
	s_and_b64 vcc, exec, s[8:9]
	v_mul_f32_e64 v24, v30, v38
	v_mul_f32_e64 v25, v31, v39
	s_cbranch_vccnz .LBB0_305
	v_mul_f32_e32 v26, 0xbfb8aa3b, v22
	v_mul_f32_e32 v27, 0xbfb8aa3b, v23
	v_mul_f32_e32 v28, 0xbfb8aa3b, v24
	v_mul_f32_e32 v29, 0xbfb8aa3b, v25
	v_exp_f32_e32 v26, v26
	v_exp_f32_e32 v27, v27
	v_exp_f32_e32 v28, v28
	v_exp_f32_e32 v29, v29
	v_add_f32_e32 v26, 1.0, v26
	v_add_f32_e32 v27, 1.0, v27
	v_add_f32_e32 v28, 1.0, v28
	v_add_f32_e32 v29, 1.0, v29
	v_rcp_f32_e32 v26, v26
	v_rcp_f32_e32 v27, v27
	v_rcp_f32_e32 v28, v28
	v_rcp_f32_e32 v29, v29
	v_mul_f32_e64 v22, v22, v26
	v_mul_f32_e64 v23, v23, v27
	v_mul_f32_e64 v24, v24, v28
	v_mul_f32_e64 v25, v25, v29

; DI unsigned pk_bf16(float lo, float hi) { f32x2 v = {lo, hi}; bf2_t b = __builtin_convertvector(v, bf2_t); return __builtin_bit_cast(unsigned, b); }
; DI float silu_f(float v) { return v * __builtin_amdgcn_rcpf(1.f + fast_exp2(-v * LOG2E)); }
; template <int NI>
; DI void p2_store_group(const Params& p, const f32x16 (&a)[NI], int colg, int tok0, int b, int h) {
;     ...
;       bf16_t* d = base + (size_t)idx * stride + 8 * h;
; #pragma unroll
;       for (int q = 0; q < 2; ++q) {
;         u32x2 w[2];
; #pragma unroll
;         for (int gg = 0; gg < 2; ++gg) {
;           const int g = 2 * q + gg;
;           float v0 = a[ni][4 * g] * scale, v1 = a[ni][4 * g + 1] * scale, v2 = a[ni][4 * g + 2] * scale, v3 = a[ni][4 * g + 3] * scale;
;           if (mode == 1) { v0 = silu_f(v0); v1 = silu_f(v1); v2 = silu_f(v2); v3 = silu_f(v3); }
;           w[gg].x = pk_bf16(v0, v1); w[gg].y = pk_bf16(v2, v3);
;         }
;         *(u32x4*)(d + 16 * q) = widen_pair(w[0], w[1]);
;         __builtin_amdgcn_sched_barrier(0);
;       }
.LBB0_327:
	v_mul_f32_e64 v0, v0, v16
	v_mul_f32_e64 v1, v1, v16
	v_cndmask_b32_e64 v17, 0, 1, s[36:37]
	v_cmp_ne_u32_e64 s[8:9], 1, v17
	s_andn2_b64 vcc, exec, s[36:37]
	v_mul_f32_e64 v2, v2, v16
	v_mul_f32_e64 v3, v3, v16
	s_cbranch_vccnz .LBB0_329
	v_mul_f32_e32 v17, 0xbfb8aa3b, v0
	v_exp_f32_e32 v17, v17
	v_mul_f32_e32 v18, 0xbfb8aa3b, v1
	v_exp_f32_e32 v18, v18
	v_mul_f32_e32 v20, 0xbfb8aa3b, v3
	v_add_f32_e32 v17, 1.0, v17
	v_exp_f32_e32 v21, v20
	v_add_f32_e32 v19, 1.0, v18
	v_rcp_f32_e32 v18, v17
	v_mul_f32_e32 v17, 0xbfb8aa3b, v2
	v_exp_f32_e32 v17, v17
	v_rcp_f32_e32 v19, v19
	v_add_f32_e32 v17, 1.0, v17
	v_rcp_f32_e32 v20, v17
	v_add_f32_e32 v17, 1.0, v21
	v_rcp_f32_e32 v21, v17
	v_mul_f32_e64 v0, v0, v18
	v_mul_f32_e64 v1, v1, v19
	v_mul_f32_e64 v2, v2, v20
	v_mul_f32_e64 v3, v3, v21
.LBB0_329:
	v_mov_b32_e32 v17, v16
	v_mul_f32_e64 v4, v4, v16
	v_mul_f32_e64 v5, v5, v17
	s_and_b64 vcc, exec, s[8:9]
	v_mul_f32_e64 v6, v6, v16
	v_mul_f32_e64 v7, v7, v17
	s_cbranch_vccnz .LBB0_331
	v_mul_f32_e32 v18, 0xbfb8aa3b, v4
	v_mul_f32_e32 v19, 0xbfb8aa3b, v5
	v_mul_f32_e32 v20, 0xbfb8aa3b, v6
	v_mul_f32_e32 v21, 0xbfb8aa3b, v7
	v_exp_f32_e32 v18, v18
	v_exp_f32_e32 v19, v19
	v_exp_f32_e32 v20, v20
	v_exp_f32_e32 v21, v21
	v_add_f32_e32 v18, 1.0, v18
	v_add_f32_e32 v19, 1.0, v19
	v_add_f32_e32 v20, 1.0, v20
	v_add_f32_e32 v21, 1.0, v21
	v_rcp_f32_e32 v18, v18
	v_rcp_f32_e32 v19, v19
	v_rcp_f32_e32 v20, v20
	v_rcp_f32_e32 v21, v21
	v_mul_f32_e64 v4, v4, v18
	v_mul_f32_e64 v5, v5, v19
	v_mul_f32_e64 v6, v6, v20
	v_mul_f32_e64 v7, v7, v21
.LBB0_331:
	v_cvt_pk_bf16_f32 v18, v0, v1
	v_cvt_pk_bf16_f32 v19, v2, v3
	v_mul_lo_u32 v2, s39, v32
	v_mul_lo_u32 v3, s38, v33
	v_mad_u64_u32 v[0:1], s[2:3], s38, v32, 0
	v_add3_u32 v1, v1, v3, v2
	v_lshl_add_u64 v[0:1], v[0:1], 1, s[34:35]
	v_lshlrev_b32_e32 v144, 1, v180
	v_cvt_pk_bf16_f32 v20, v4, v5
	v_cvt_pk_bf16_f32 v21, v6, v7
	v_lshl_add_u64 v[0:1], v[0:1], 0, v[144:145]
	v_permlane32_swap_b32_e32 v18, v20
	v_permlane32_swap_b32_e32 v19, v21
	global_store_dwordx4 v[0:1], v[18:21], off
	v_mul_f32_e64 v2, v8, v16
	v_mul_f32_e64 v3, v9, v17
	s_and_b64 vcc, exec, s[8:9]
	v_mul_f32_e64 v4, v10, v16
	v_mul_f32_e64 v5, v11, v17
	s_cbranch_vccnz .LBB0_333
	v_mul_f32_e32 v6, 0xbfb8aa3b, v2
	v_mul_f32_e32 v7, 0xbfb8aa3b, v3
	v_mul_f32_e32 v8, 0xbfb8aa3b, v4
	v_mul_f32_e32 v9, 0xbfb8aa3b, v5
	v_exp_f32_e32 v6, v6
	v_exp_f32_e32 v7, v7
	v_exp_f32_e32 v8, v8
	v_exp_f32_e32 v9, v9
	v_add_f32_e32 v6, 1.0, v6
	v_add_f32_e32 v7, 1.0, v7
	v_add_f32_e32 v8, 1.0, v8
	v_add_f32_e32 v9, 1.0, v9
	v_rcp_f32_e32 v6, v6
	v_rcp_f32_e32 v7, v7
	v_rcp_f32_e32 v8, v8
	v_rcp_f32_e32 v9, v9
	v_mul_f32_e64 v2, v2, v6
	v_mul_f32_e64 v3, v3, v7
	v_mul_f32_e64 v4, v4, v8
	v_mul_f32_e64 v5, v5, v9
.LBB0_333:
	v_mul_f32_e64 v6, v12, v16
	v_mul_f32_e64 v7, v13, v17
	s_and_b64 vcc, exec, s[8:9]
	v_mul_f32_e64 v8, v14, v16
	v_mul_f32_e64 v9, v15, v17
	s_cbranch_vccnz .LBB0_269
	v_mul_f32_e32 v10, 0xbfb8aa3b, v6
	v_mul_f32_e32 v11, 0xbfb8aa3b, v7
	v_mul_f32_e32 v12, 0xbfb8aa3b, v8
	v_mul_f32_e32 v13, 0xbfb8aa3b, v9
	v_exp_f32_e32 v10, v10
	v_exp_f32_e32 v11, v11
	v_exp_f32_e32 v12, v12
	v_exp_f32_e32 v13, v13
	v_add_f32_e32 v10, 1.0, v10
	v_add_f32_e32 v11, 1.0, v11
	v_add_f32_e32 v12, 1.0, v12
	v_add_f32_e32 v13, 1.0, v13
	v_rcp_f32_e32 v10, v10
	v_rcp_f32_e32 v11, v11
	v_rcp_f32_e32 v12, v12
	v_rcp_f32_e32 v13, v13
	v_mul_f32_e64 v6, v6, v10
	v_mul_f32_e64 v7, v7, v11
	v_mul_f32_e64 v8, v8, v12
	v_mul_f32_e64 v9, v9, v13
	s_branch .LBB0_269

; DI void phase3(const Params& p, char* smem, const Sched sc) {
;     ...
;       gemm_tile<96, 128, 1, 4, true, true>(p.WuqT + (size_t)head * 96 * 384, 384, p.CQ + (size_t)m0 * 384, 384, 384, smem, acc, sumsq);
;       const float rstd = rsqrtf(sumsq[tl] * (1.f / 384) + 1e-6f);
;       float ssq = 0.f;
; #pragma unroll
;       for (int rb = 0; rb < 3; ++rb)
; #pragma unroll
;         for (int i = 0; i < 16; ++i) { const float v = acc[rb][0][i] * rstd; acc[rb][0][i] = v; ssq += v * v; }
;       ssq += other_half(ssq);
;       const float r2 = rsqrtf(ssq * (1.f / 96) + 1e-6f);
; #pragma unroll
;       for (int rb = 0; rb < 3; ++rb)
; #pragma unroll
;         for (int g = 0; g < 4; ++g) {
;           const f32x4 w4 = *(const f32x4*)(p.qhn + rb * 32 + 8 * g + 4 * h);
; #pragma unroll
;           for (int e = 0; e < 4; ++e) acc[rb][0][4 * g + e] *= r2 * w4[e];
;         }
; #pragma unroll
;       for (int g = 0; g < 2; ++g) {
;         const f32x4 c4 = *(const f32x4*)(p.cosT + (size_t)token * 16 + 8 * g + 4 * h), s4 = *(const f32x4*)(p.sinT + (size_t)token * 16 + 8 * g + 4 * h);
.LBB0_358:
	s_or_b64 exec, exec, s[4:5]
	s_waitcnt lgkmcnt(0)
	s_barrier
	ds_read_b32 v48, v231
	global_load_dwordx4 v[64:67], v[202:203], off
	global_load_dwordx4 v[68:71], v[202:203], off offset:32
	global_load_dwordx4 v[72:75], v[202:203], off offset:64
	global_load_dwordx4 v[76:79], v[202:203], off offset:96
	global_load_dwordx4 v[80:83], v[202:203], off offset:128
	global_load_dwordx4 v[84:87], v[202:203], off offset:160
	global_load_dwordx4 v[88:91], v[202:203], off offset:192
	global_load_dwordx4 v[92:95], v[202:203], off offset:224
	global_load_dwordx4 v[96:99], v[202:203], off offset:256
	global_load_dwordx4 v[100:103], v[202:203], off offset:288
	global_load_dwordx4 v[104:107], v[202:203], off offset:320
	global_load_dwordx4 v[108:111], v[202:203], off offset:352
	v_ashrrev_i32_e32 v209, 31, v208
	v_lshl_or_b32 v120, v240, 3, s25
	v_ashrrev_i32_e32 v121, 31, v120
	s_waitcnt lgkmcnt(0)
	v_fmamk_f32 v48, v48, 0x3b2aaaab, v233
	v_mul_f32_e32 v49, 0x4b800000, v48
	v_cmp_gt_f32_e32 vcc, s19, v48
	v_lshlrev_b64 v[120:121], 13, v[120:121]
	v_or_b32_e32 v120, v120, v239
	v_cndmask_b32_e32 v48, v48, v49, vcc
	v_rsq_f32_e32 v48, v48
	s_nop 0
	v_mul_f32_e32 v49, 0x45800000, v48
	v_cndmask_b32_e32 v112, v48, v49, vcc
	v_mul_f32_e64 v32, v32, v112
	v_mul_f32_e64 v33, v33, v112
	v_mul_f32_e64 v34, v34, v112
	v_mul_f32_e64 v35, v35, v112
	v_mul_f32_e64 v136, v32, v32
	v_mul_f32_e64 v137, v33, v33
	v_mul_f32_e64 v134, v34, v34
	v_mul_f32_e64 v135, v35, v35
	v_add_f32_e32 v136, v136, v137
	v_mul_f32_e64 v36, v36, v112
	v_mul_f32_e64 v37, v37, v112
	v_add_f32_e32 v134, v134, v136
	v_mul_f32_e64 v132, v36, v36
	v_mul_f32_e64 v133, v37, v37
	v_add_f32_e32 v134, v135, v134
	v_mul_f32_e64 v60, v10, v112
	v_mul_f32_e64 v61, v11, v112
	v_lshlrev_b64 v[10:11], 6, v[208:209]
	v_mul_f32_e64 v38, v38, v112
	v_mul_f32_e64 v39, v39, v112
	v_add_f32_e32 v132, v132, v134
	v_mul_f32_e64 v62, v12, v112
	v_mul_f32_e64 v63, v13, v112
	v_lshl_add_u64 v[12:13], v[192:193], 0, v[10:11]
	v_lshl_add_u64 v[48:49], v[194:195], 0, v[10:11]
	v_mul_f32_e64 v130, v38, v38
	v_mul_f32_e64 v131, v39, v39
	v_add_f32_e32 v132, v133, v132
	global_load_dwordx4 v[52:55], v[12:13], off
	s_nop 0
	global_load_dwordx4 v[10:13], v[12:13], off offset:32
	s_nop 0
	global_load_dwordx4 v[56:59], v[48:49], off
	s_nop 0
	global_load_dwordx4 v[48:51], v[48:49], off offset:32
	v_mul_f32_e64 v40, v40, v112
	v_mul_f32_e64 v41, v41, v112
	v_add_f32_e32 v130, v130, v132
	v_mul_f32_e64 v128, v40, v40
	v_mul_f32_e64 v129, v41, v41
	v_add_f32_e32 v130, v131, v130
	v_mul_f32_e64 v42, v42, v112
	v_mul_f32_e64 v43, v43, v112
	v_add_f32_e32 v128, v128, v130
	v_mul_f32_e64 v126, v42, v42
	v_mul_f32_e64 v127, v43, v43
	v_add_f32_e32 v128, v129, v128
	v_mul_f32_e64 v44, v44, v112
	v_mul_f32_e64 v45, v45, v112
	v_add_f32_e32 v126, v126, v128
	v_mul_f32_e64 v124, v44, v44
	v_mul_f32_e64 v125, v45, v45
	v_add_f32_e32 v126, v127, v126
	v_mul_f32_e64 v46, v46, v112
	v_mul_f32_e64 v47, v47, v112
	v_add_f32_e32 v124, v124, v126
	v_mul_f32_e64 v122, v46, v46
	v_mul_f32_e64 v123, v47, v47
	v_add_f32_e32 v124, v125, v124
	v_mul_f32_e64 v16, v16, v112
	v_mul_f32_e64 v17, v17, v112
	v_add_f32_e32 v122, v122, v124
	v_mul_f32_e64 v152, v16, v16
	v_mul_f32_e64 v153, v17, v17
	v_add_f32_e32 v122, v123, v122
	v_mul_f32_e64 v18, v18, v112
	v_mul_f32_e64 v19, v19, v112
	v_add_f32_e32 v122, v152, v122
	v_mul_f32_e64 v150, v18, v18
	v_mul_f32_e64 v151, v19, v19
	v_add_f32_e32 v122, v153, v122
	v_mul_f32_e64 v20, v20, v112
	v_mul_f32_e64 v21, v21, v112
	v_add_f32_e32 v122, v150, v122
	v_mul_f32_e64 v148, v20, v20
	v_mul_f32_e64 v149, v21, v21
	v_add_f32_e32 v122, v151, v122
	v_mul_f32_e64 v22, v22, v112
	v_mul_f32_e64 v23, v23, v112
	v_add_f32_e32 v122, v148, v122
	v_mul_f32_e64 v146, v22, v22
	v_mul_f32_e64 v147, v23, v23
	v_add_f32_e32 v122, v149, v122
	v_mul_f32_e64 v24, v24, v112
	v_mul_f32_e64 v25, v25, v112
	v_add_f32_e32 v122, v146, v122
	v_mul_f32_e64 v144, v24, v24
	v_mul_f32_e64 v145, v25, v25
	v_add_f32_e32 v122, v147, v122
	v_mul_f32_e64 v26, v26, v112
	v_mul_f32_e64 v27, v27, v112
	v_add_f32_e32 v122, v144, v122
	v_mul_f32_e64 v142, v26, v26
	v_mul_f32_e64 v143, v27, v27
	v_add_f32_e32 v122, v145, v122
	v_mul_f32_e64 v28, v28, v112
	v_mul_f32_e64 v29, v29, v112
	v_add_f32_e32 v122, v142, v122
	v_mul_f32_e64 v140, v28, v28
	v_mul_f32_e64 v141, v29, v29
	v_add_f32_e32 v122, v143, v122
	v_mul_f32_e64 v30, v30, v112
	v_mul_f32_e64 v31, v31, v112
	v_add_f32_e32 v122, v140, v122
	v_mul_f32_e64 v138, v30, v30
	v_mul_f32_e64 v139, v31, v31
	v_add_f32_e32 v122, v141, v122
	v_mul_f32_e64 v0, v0, v112
	v_mul_f32_e64 v1, v1, v112
	v_add_f32_e32 v122, v138, v122
	v_mul_f32_e64 v160, v0, v0
	v_mul_f32_e64 v161, v1, v1
	v_add_f32_e32 v122, v139, v122
	v_mul_f32_e64 v2, v2, v112
	v_mul_f32_e64 v3, v3, v112
	v_add_f32_e32 v122, v160, v122
	v_mul_f32_e64 v158, v2, v2
	v_mul_f32_e64 v159, v3, v3
	v_add_f32_e32 v122, v161, v122
	v_mul_f32_e64 v4, v4, v112
	v_mul_f32_e64 v5, v5, v112
	v_add_f32_e32 v122, v158, v122
	v_mul_f32_e64 v156, v4, v4
	v_mul_f32_e64 v157, v5, v5
	v_add_f32_e32 v122, v159, v122
	v_mul_f32_e64 v6, v6, v112
	v_mul_f32_e64 v7, v7, v112
	v_add_f32_e32 v122, v156, v122
	v_mul_f32_e64 v154, v6, v6
	v_mul_f32_e64 v155, v7, v7
	v_add_f32_e32 v122, v157, v122
	v_mul_f32_e64 v8, v8, v112
	v_mul_f32_e64 v9, v9, v112
	v_add_f32_e32 v122, v154, v122
	v_mul_f32_e64 v14, v14, v112
	v_mul_f32_e64 v15, v15, v112
	v_mul_f32_e64 v112, v8, v8
	v_mul_f32_e64 v113, v9, v9
	v_add_f32_e32 v122, v155, v122
	v_add_f32_e32 v112, v112, v122
	v_mul_f32_e64 v114, v60, v60
	v_mul_f32_e64 v115, v61, v61
	v_add_f32_e32 v112, v113, v112
	v_add_f32_e32 v112, v114, v112
	v_mul_f32_e64 v116, v62, v62
	v_mul_f32_e64 v117, v63, v63
	v_add_f32_e32 v112, v115, v112
	v_add_f32_e32 v112, v116, v112
	v_mul_f32_e64 v118, v14, v14
	v_mul_f32_e64 v119, v15, v15
	v_add_f32_e32 v112, v117, v112
	v_add_f32_e32 v112, v118, v112
	v_add_f32_e32 v112, v119, v112
	v_mov_b32_e32 v113, v112
	v_mov_b32_e32 v114, v112
	s_nop 1
	v_permlane32_swap_b32_e32 v113, v114
	v_cndmask_b32_e64 v113, v113, v114, s[8:9]
	v_add_f32_e32 v112, v112, v113
	v_fmamk_f32 v112, v112, 0x3c2aaaab, v233
	v_mul_f32_e32 v113, 0x4b800000, v112
	v_cmp_gt_f32_e32 vcc, s19, v112
	s_nop 1
	v_cndmask_b32_e32 v112, v112, v113, vcc
	v_rsq_f32_e32 v114, v112
	v_mad_u64_u32 v[112:113], s[4:5], v120, s20, v[204:205]
	v_mad_i32_i24 v113, v121, s20, v113
	v_mul_f32_e32 v115, 0x45800000, v114
	v_cndmask_b32_e32 v114, v114, v115, vcc
	s_waitcnt vmcnt(15)
; DI unsigned pk_bf16(float lo, float hi) { f32x2 v = {lo, hi}; bf2_t b = __builtin_convertvector(v, bf2_t); return __builtin_bit_cast(unsigned, b); }
; DI void phase3(const Params& p, char* smem, const Sched sc) {
;     ...
; #pragma unroll
;       for (int rb = 0; rb < 3; ++rb)
; #pragma unroll
;         for (int g = 0; g < 4; ++g) {
;           const f32x4 w4 = *(const f32x4*)(p.qhn + rb * 32 + 8 * g + 4 * h);
; #pragma unroll
;           for (int e = 0; e < 4; ++e) acc[rb][0][4 * g + e] *= r2 * w4[e];
;         }
; #pragma unroll
;       for (int g = 0; g < 2; ++g) {
;         const f32x4 c4 = *(const f32x4*)(p.cosT + (size_t)token * 16 + 8 * g + 4 * h), s4 = *(const f32x4*)(p.sinT + (size_t)token * 16 + 8 * g + 4 * h);
; #pragma unroll
;         for (int e = 0; e < 4; ++e) {
;           const float x1 = acc[2][0][4 * g + e], x2 = acc[2][0][4 * (g + 2) + e];
;           acc[2][0][4 * g + e] = x1 * c4[e] - x2 * s4[e];
;           acc[2][0][4 * (g + 2) + e] = x2 * c4[e] + x1 * s4[e];
;         }
;       }
;       const float qs = LOG2E * 0.10206207261596577f;
;       bf16_t* dst = p.Qm + ((size_t)(b * 8 + head) * S_ + s) * 96;
; #pragma unroll
;       for (int rb = 0; rb < 3; ++rb) {
;         u32x2 w[4];
; #pragma unroll
;         for (int g = 0; g < 4; ++g) { w[g].x = pk_bf16(acc[rb][0][4 * g] * qs, acc[rb][0][4 * g + 1] * qs); w[g].y = pk_bf16(acc[rb][0][4 * g + 2] * qs, acc[rb][0][4 * g + 3] * qs); }
; #pragma unroll
;         for (int q = 0; q < 2; ++q) *(u32x4*)(dst + rb * 32 + 16 * q + 8 * h) = widen_pair(w[2 * q], w[2 * q + 1]);
;       }
	v_mul_f32_e64 v64, v64, v114
	v_mul_f32_e64 v65, v65, v114
	s_nop 0
	v_mul_f32_e64 v32, v32, v64
	v_mul_f32_e64 v33, v33, v65
	v_mul_f32_e64 v64, v66, v114
	v_mul_f32_e64 v65, v67, v114
	s_nop 0
	v_mul_f32_e64 v34, v34, v64
	v_mul_f32_e64 v35, v35, v65
	s_waitcnt vmcnt(14)
	v_mul_f32_e64 v64, v68, v114
	v_mul_f32_e64 v65, v69, v114
	s_nop 0
	v_mul_f32_e64 v36, v36, v64
	v_mul_f32_e64 v37, v37, v65
	v_mul_f32_e64 v64, v70, v114
	v_mul_f32_e64 v65, v71, v114
	s_nop 0
	v_mul_f32_e64 v38, v38, v64
	v_mul_f32_e64 v39, v39, v65
	s_waitcnt vmcnt(13)
	v_mul_f32_e64 v64, v72, v114
	v_mul_f32_e64 v65, v73, v114
	s_nop 0
	v_mul_f32_e64 v40, v40, v64
	v_mul_f32_e64 v41, v41, v65
	v_mul_f32_e64 v64, v74, v114
	v_mul_f32_e64 v65, v75, v114
	s_nop 0
	v_mul_f32_e64 v42, v42, v64
	v_mul_f32_e64 v43, v43, v65
	s_waitcnt vmcnt(12)
	v_mul_f32_e64 v64, v76, v114
	v_mul_f32_e64 v65, v77, v114
	s_nop 0
	v_mul_f32_e64 v44, v44, v64
	v_mul_f32_e64 v45, v45, v65
	v_mul_f32_e64 v64, v78, v114
	v_mul_f32_e64 v65, v79, v114
	s_nop 0
	v_mul_f32_e64 v46, v46, v64
	v_mul_f32_e64 v47, v47, v65
	s_waitcnt vmcnt(11)
	v_mul_f32_e64 v64, v80, v114
	v_mul_f32_e64 v65, v81, v114
	s_nop 0
	v_mul_f32_e64 v16, v16, v64
	v_mul_f32_e64 v17, v17, v65
	v_mul_f32_e64 v64, v82, v114
	v_mul_f32_e64 v65, v83, v114
	s_nop 0
	v_mul_f32_e64 v18, v18, v64
	v_mul_f32_e64 v19, v19, v65
	s_waitcnt vmcnt(10)
	v_mul_f32_e64 v64, v84, v114
	v_mul_f32_e64 v65, v85, v114
	s_nop 0
	v_mul_f32_e64 v20, v20, v64
	v_mul_f32_e64 v21, v21, v65
	v_mul_f32_e64 v64, v86, v114
	v_mul_f32_e64 v65, v87, v114
	s_nop 0
	v_mul_f32_e64 v22, v22, v64
	v_mul_f32_e64 v23, v23, v65
	s_waitcnt vmcnt(9)
	v_mul_f32_e64 v64, v88, v114
	v_mul_f32_e64 v65, v89, v114
	s_nop 0
	v_mul_f32_e64 v24, v24, v64
	v_mul_f32_e64 v25, v25, v65
	v_mul_f32_e64 v64, v90, v114
	v_mul_f32_e64 v65, v91, v114
	s_nop 0
	v_mul_f32_e64 v26, v26, v64
	v_mul_f32_e64 v27, v27, v65
	s_waitcnt vmcnt(8)
	v_mul_f32_e64 v64, v92, v114
	v_mul_f32_e64 v65, v93, v114
	s_nop 0
	v_mul_f32_e64 v28, v28, v64
	v_mul_f32_e64 v29, v29, v65
	v_mul_f32_e64 v64, v94, v114
	v_mul_f32_e64 v65, v95, v114
	s_nop 0
	v_mul_f32_e64 v30, v30, v64
	v_mul_f32_e64 v31, v31, v65
	s_waitcnt vmcnt(7)
	v_mul_f32_e64 v64, v96, v114
	v_mul_f32_e64 v65, v97, v114
	s_nop 0
	v_mul_f32_e64 v64, v0, v64
	v_mul_f32_e64 v65, v1, v65
	v_mul_f32_e64 v0, v98, v114
	v_mul_f32_e64 v1, v99, v114
	s_nop 0
	v_mul_f32_e64 v66, v2, v0
	v_mul_f32_e64 v67, v3, v1
	s_waitcnt vmcnt(6)
	v_mul_f32_e64 v0, v100, v114
	v_mul_f32_e64 v1, v101, v114
	v_mul_f32_e64 v2, v34, s2
	v_mul_f32_e64 v3, v35, s2
	v_mul_f32_e64 v68, v4, v0
	v_mul_f32_e64 v69, v5, v1
	v_mul_f32_e64 v0, v102, v114
	v_mul_f32_e64 v1, v103, v114
	v_mul_f32_e64 v4, v38, s2
	v_mul_f32_e64 v5, v39, s2
	v_mul_f32_e64 v70, v6, v0
	v_mul_f32_e64 v71, v7, v1
	s_waitcnt vmcnt(5)
	v_mul_f32_e64 v0, v104, v114
	v_mul_f32_e64 v1, v105, v114
	v_mul_f32_e64 v6, v42, s2
	v_mul_f32_e64 v7, v43, s2
	v_mul_f32_e64 v8, v8, v0
	v_mul_f32_e64 v9, v9, v1
	v_mul_f32_e64 v0, v106, v114
	v_mul_f32_e64 v1, v107, v114
	s_nop 0
	v_mul_f32_e64 v60, v60, v0
	v_mul_f32_e64 v61, v61, v1
	s_waitcnt vmcnt(4)
	v_mul_f32_e64 v0, v108, v114
	v_mul_f32_e64 v1, v109, v114
	s_nop 0
	v_mul_f32_e64 v62, v62, v0
	v_mul_f32_e64 v63, v63, v1
	v_mul_f32_e64 v0, v110, v114
	v_mul_f32_e64 v1, v111, v114
	s_nop 0
	v_mul_f32_e64 v14, v14, v0
	v_mul_f32_e64 v15, v15, v1
	s_waitcnt vmcnt(1)
	v_mul_f32_e64 v0, v56, v64
	v_mul_f32_e64 v1, v57, v65
	s_nop 0
	v_fma_f32 v72, v52, v8, v0
	v_fma_f32 v73, v53, v9, v1
	v_mul_f32_e64 v0, v58, v66
	v_mul_f32_e64 v1, v59, v67
	s_nop 0
	v_fma_f32 v74, v54, v60, v0
	v_fma_f32 v75, v55, v61, v1
	s_waitcnt vmcnt(0)
	v_mul_f32_e64 v0, v48, v68
	v_mul_f32_e64 v1, v49, v69
	s_nop 0
	v_fma_f32 v76, v10, v62, v0
	v_fma_f32 v77, v11, v63, v1
	v_mul_f32_e64 v0, v50, v70
	v_mul_f32_e64 v1, v51, v71
	s_nop 0
	v_fma_f32 v78, v12, v14, v0
	v_fma_f32 v79, v13, v15, v1
	v_mul_f32_e64 v0, v32, s2
	v_mul_f32_e64 v1, v33, s2
	v_mul_f32_e64 v32, v46, s2
	v_mul_f32_e64 v33, v47, s2
	v_cvt_pk_bf16_f32 v0, v0, v1
	v_cvt_pk_bf16_f32 v1, v2, v3
	v_mul_f32_e64 v2, v36, s2
	v_mul_f32_e64 v3, v37, s2
	s_nop 0
	v_cvt_pk_bf16_f32 v2, v2, v3
	v_cvt_pk_bf16_f32 v3, v4, v5
	v_mul_f32_e64 v4, v40, s2
	v_mul_f32_e64 v5, v41, s2
	v_permlane32_swap_b32_e32 v0, v2
	v_cvt_pk_bf16_f32 v4, v4, v5
	v_cvt_pk_bf16_f32 v5, v6, v7
	v_mul_f32_e64 v6, v44, s2
	v_mul_f32_e64 v7, v45, s2
	v_permlane32_swap_b32_e32 v1, v3
	v_cvt_pk_bf16_f32 v6, v6, v7
	v_cvt_pk_bf16_f32 v7, v32, v33
	global_store_dwordx4 v[112:113], v[0:3], off
	v_permlane32_swap_b32_e32 v4, v6
	v_permlane32_swap_b32_e32 v5, v7
	v_mul_f32_e64 v0, v16, s2
	v_mul_f32_e64 v1, v17, s2
	v_mul_f32_e64 v2, v18, s2
	v_mul_f32_e64 v3, v19, s2
	global_store_dwordx4 v[112:113], v[4:7], off offset:32
	v_cvt_pk_bf16_f32 v0, v0, v1
	v_cvt_pk_bf16_f32 v1, v2, v3
	v_mul_f32_e64 v2, v20, s2
	v_mul_f32_e64 v3, v21, s2
	v_mul_f32_e64 v4, v22, s2
	v_mul_f32_e64 v5, v23, s2
	v_cvt_pk_bf16_f32 v2, v2, v3
	v_cvt_pk_bf16_f32 v3, v4, v5
	v_mul_f32_e64 v4, v24, s2
	v_mul_f32_e64 v5, v25, s2
	v_mul_f32_e64 v6, v26, s2
	v_mul_f32_e64 v7, v27, s2
	v_permlane32_swap_b32_e32 v0, v2
	v_permlane32_swap_b32_e32 v1, v3
	v_cvt_pk_bf16_f32 v4, v4, v5
	v_cvt_pk_bf16_f32 v5, v6, v7
	v_mul_f32_e64 v6, v28, s2
	v_mul_f32_e64 v7, v29, s2
	v_mul_f32_e64 v16, v30, s2
	v_mul_f32_e64 v17, v31, s2
	global_store_dwordx4 v[112:113], v[0:3], off offset:64
	v_cvt_pk_bf16_f32 v6, v6, v7
	v_cvt_pk_bf16_f32 v7, v16, v17
	v_mul_f32_e64 v0, v56, v8
	v_mul_f32_e64 v1, v57, v9
	v_mul_f32_e64 v2, v58, v60
	v_mul_f32_e64 v3, v59, v61
	v_fma_f32 v0, v52, v64, -v0
	v_fma_f32 v1, v53, v65, -v1
	v_fma_f32 v2, v54, v66, -v2
	v_fma_f32 v3, v55, v67, -v3
	v_permlane32_swap_b32_e32 v4, v6
	v_permlane32_swap_b32_e32 v5, v7
	v_mul_f32_e64 v0, v0, s2
	v_mul_f32_e64 v1, v1, s2
	v_mul_f32_e64 v2, v2, s2
	v_mul_f32_e64 v3, v3, s2
	global_store_dwordx4 v[112:113], v[4:7], off offset:96
	v_cvt_pk_bf16_f32 v0, v0, v1
	v_cvt_pk_bf16_f32 v1, v2, v3
	v_mul_f32_e64 v2, v48, v62
	v_mul_f32_e64 v3, v49, v63
	v_mul_f32_e64 v4, v50, v14
	v_mul_f32_e64 v5, v51, v15
	v_fma_f32 v2, v10, v68, -v2
	v_fma_f32 v3, v11, v69, -v3
	v_fma_f32 v4, v12, v70, -v4
	v_fma_f32 v5, v13, v71, -v5
	v_mul_f32_e64 v2, v2, s2
	v_mul_f32_e64 v3, v3, s2
	v_mul_f32_e64 v4, v4, s2
	v_mul_f32_e64 v5, v5, s2
	v_cvt_pk_bf16_f32 v2, v2, v3
	v_cvt_pk_bf16_f32 v3, v4, v5
	v_mul_f32_e64 v4, v72, s2
	v_mul_f32_e64 v5, v73, s2
	v_mul_f32_e64 v6, v74, s2
	v_mul_f32_e64 v7, v75, s2
	v_cvt_pk_bf16_f32 v4, v4, v5
	v_cvt_pk_bf16_f32 v5, v6, v7
	v_mul_f32_e64 v6, v76, s2
	v_mul_f32_e64 v7, v77, s2
	v_mul_f32_e64 v8, v78, s2
	v_mul_f32_e64 v9, v79, s2
	v_cvt_pk_bf16_f32 v6, v6, v7
	v_cvt_pk_bf16_f32 v7, v8, v9
	v_permlane32_swap_b32_e32 v0, v2
	v_permlane32_swap_b32_e32 v1, v3
	v_permlane32_swap_b32_e32 v4, v6
	v_permlane32_swap_b32_e32 v5, v7
	global_store_dwordx4 v[112:113], v[0:3], off offset:128
	global_store_dwordx4 v[112:113], v[4:7], off offset:160

; DI void phase3(const Params& p, char* smem, const Sched sc) {
;     ...
;       gemm_tile<128, 128, 1, 4, true, true>(p.WukvT + (size_t)head * 128 * 256, 256, p.CKV + (size_t)m0 * 256, 256, 256, smem, acc, sumsq);
;       const float rstd = rsqrtf(sumsq[tl] * (1.f / 256) + 1e-6f);
;       float kr[16];
; #pragma unroll
;       for (int g = 0; g < 4; ++g) {
;         const f32x4 k4 = *(const f32x4*)(p.KR + (size_t)token * 32 + 8 * g + 4 * h);
; #pragma unroll
;         for (int e = 0; e < 4; ++e) kr[4 * g + e] = k4[e];
;       }
;       float ssq = 0.f;
; #pragma unroll
;       for (int rb = 0; rb < 2; ++rb)
; #pragma unroll
;         for (int i = 0; i < 16; ++i) { const float v = acc[rb][0][i] * rstd; acc[rb][0][i] = v; ssq += v * v; }
; #pragma unroll
;       for (int i = 0; i < 16; ++i) ssq += kr[i] * kr[i];
.LBB0_370:
	s_or_b64 exec, exec, s[12:13]
	v_ashrrev_i32_e32 v209, 31, v208
	s_waitcnt lgkmcnt(0)
	v_lshlrev_b64 v[64:65], 7, v[208:209]
	v_lshl_add_u64 v[92:93], v[188:189], 0, v[64:65]
	s_barrier
	global_load_dwordx4 v[68:71], v[92:93], off offset:32
	global_load_dwordx4 v[72:75], v[92:93], off offset:64
	global_load_dwordx4 v[64:67], v[92:93], off offset:96
	ds_read_b32 v94, v231
	global_load_dwordx4 v[88:91], v[190:191], off
	global_load_dwordx4 v[84:87], v[190:191], off offset:32
	global_load_dwordx4 v[80:83], v[190:191], off offset:64
	global_load_dwordx4 v[76:79], v[190:191], off offset:96
	global_load_dwordx4 v[104:107], v[190:191], off offset:128
	global_load_dwordx4 v[96:99], v[190:191], off offset:160
	s_waitcnt lgkmcnt(0)
	v_fmamk_f32 v94, v94, 0x3b800000, v233
	v_mul_f32_e32 v95, 0x4b800000, v94
	v_cmp_gt_f32_e32 vcc, s19, v94
	s_waitcnt vmcnt(8)
	v_mul_f32_e64 v146, v70, v70
	v_mul_f32_e64 v147, v71, v71
	v_cndmask_b32_e32 v94, v94, v95, vcc
	v_rsq_f32_e32 v112, v94
	global_load_dwordx4 v[92:95], v[92:93], off
	s_nop 0
	global_load_dwordx4 v[108:111], v[190:191], off offset:192
	global_load_dwordx4 v[100:103], v[190:191], off offset:224
	s_waitcnt vmcnt(10)
	v_mul_f32_e64 v150, v72, v72
	v_mul_f32_e64 v151, v73, v73
	v_mul_f32_e64 v148, v74, v74
	v_mul_f32_e64 v149, v75, v75
	v_mul_f32_e32 v113, 0x45800000, v112
	v_cndmask_b32_e32 v112, v112, v113, vcc
	v_mul_f32_e64 v132, v48, v112
	v_mul_f32_e64 v133, v49, v112
	v_mul_f32_e64 v130, v50, v112
	v_mul_f32_e64 v131, v51, v112
	v_mul_f32_e64 v50, v132, v132
	v_mul_f32_e64 v51, v133, v133
	v_mul_f32_e64 v48, v130, v130
	v_mul_f32_e64 v49, v131, v131
	v_add_f32_e32 v50, v50, v51
	v_mul_f32_e64 v128, v52, v112
	v_mul_f32_e64 v129, v53, v112
	v_add_f32_e32 v48, v48, v50
	v_mul_f32_e64 v134, v42, v112
	v_mul_f32_e64 v135, v43, v112
	v_mul_f32_e64 v42, v128, v128
	v_mul_f32_e64 v43, v129, v129
	v_add_f32_e32 v48, v49, v48
	v_mul_f32_e64 v126, v54, v112
	v_mul_f32_e64 v127, v55, v112
	v_add_f32_e32 v42, v42, v48
	v_mul_f32_e64 v136, v40, v112
	v_mul_f32_e64 v137, v41, v112
	v_mul_f32_e64 v40, v126, v126
	v_mul_f32_e64 v41, v127, v127
	v_add_f32_e32 v42, v43, v42
	v_mul_f32_e64 v124, v56, v112
	v_mul_f32_e64 v125, v57, v112
	v_add_f32_e32 v40, v40, v42
	v_mul_f32_e64 v138, v38, v112
	v_mul_f32_e64 v139, v39, v112
	v_mul_f32_e64 v38, v124, v124
	v_mul_f32_e64 v39, v125, v125
	v_add_f32_e32 v40, v41, v40
	v_mul_f32_e64 v122, v58, v112
	v_mul_f32_e64 v123, v59, v112
	v_add_f32_e32 v38, v38, v40
	v_mul_f32_e64 v140, v36, v112
	v_mul_f32_e64 v141, v37, v112
	v_mul_f32_e64 v36, v122, v122
	v_mul_f32_e64 v37, v123, v123
	v_add_f32_e32 v38, v39, v38
	v_mul_f32_e64 v120, v60, v112
	v_mul_f32_e64 v121, v61, v112
	v_add_f32_e32 v36, v36, v38
	v_mul_f32_e64 v142, v34, v112
	v_mul_f32_e64 v143, v35, v112
	v_mul_f32_e64 v34, v120, v120
	v_mul_f32_e64 v35, v121, v121
	v_add_f32_e32 v36, v37, v36
	v_mul_f32_e64 v118, v62, v112
	v_mul_f32_e64 v119, v63, v112
	v_add_f32_e32 v34, v34, v36
	v_mul_f32_e64 v144, v32, v112
	v_mul_f32_e64 v145, v33, v112
	v_mul_f32_e64 v32, v118, v118
	v_mul_f32_e64 v33, v119, v119
	v_add_f32_e32 v34, v35, v34
	v_add_f32_e32 v32, v32, v34
	v_mul_f32_e64 v116, v144, v144
	v_mul_f32_e64 v117, v145, v145
	v_add_f32_e32 v32, v33, v32
	v_add_f32_e32 v32, v116, v32
	v_mul_f32_e64 v114, v142, v142
	v_mul_f32_e64 v115, v143, v143
	v_add_f32_e32 v32, v117, v32
	v_add_f32_e32 v32, v114, v32
	v_mul_f32_e64 v62, v140, v140
	v_mul_f32_e64 v63, v141, v141
	v_add_f32_e32 v32, v115, v32
	v_add_f32_e32 v32, v62, v32
	v_mul_f32_e64 v60, v138, v138
	v_mul_f32_e64 v61, v139, v139
	v_add_f32_e32 v32, v63, v32
	v_add_f32_e32 v32, v60, v32
	v_mul_f32_e64 v58, v136, v136
	v_mul_f32_e64 v59, v137, v137
	v_add_f32_e32 v32, v61, v32
	v_add_f32_e32 v32, v58, v32
	v_mul_f32_e64 v56, v134, v134
	v_mul_f32_e64 v57, v135, v135
	v_add_f32_e32 v58, v59, v32
	global_load_dwordx4 v[32:35], v[190:191], off offset:256
	global_load_dwordx4 v[36:39], v[190:191], off offset:320
	v_lshlrev_b64 v[40:41], 6, v[208:209]
	v_mul_f32_e64 v44, v44, v112
	v_mul_f32_e64 v45, v45, v112
	v_lshl_add_u64 v[60:61], v[194:195], 0, v[40:41]
	v_add_f32_e32 v56, v56, v58
	v_mul_f32_e64 v54, v44, v44
	v_mul_f32_e64 v55, v45, v45
	v_lshl_add_u64 v[114:115], v[192:193], 0, v[40:41]
	global_load_dwordx4 v[40:43], v[60:61], off
	global_load_dwordx4 v[48:51], v[114:115], off
	v_add_f32_e32 v56, v57, v56
	v_mul_f32_e64 v46, v46, v112
	v_mul_f32_e64 v47, v47, v112
	v_add_f32_e32 v54, v54, v56
	v_mul_f32_e64 v52, v46, v46
	v_mul_f32_e64 v53, v47, v47
	v_add_f32_e32 v54, v55, v54
	v_add_f32_e32 v52, v52, v54
	v_add_f32_e32 v113, v53, v52
	global_load_dwordx4 v[52:55], v[190:191], off offset:288
	global_load_dwordx4 v[56:59], v[190:191], off offset:352
	s_nop 0
	global_load_dwordx4 v[60:63], v[60:61], off offset:32
	s_nop 0
	global_load_dwordx4 v[114:117], v[114:115], off offset:32
	s_waitcnt vmcnt(17)
	v_mul_f32_e64 v154, v64, v64
	v_mul_f32_e64 v155, v65, v65
	v_mul_f32_e64 v152, v66, v66
	v_mul_f32_e64 v153, v67, v67
	s_waitcnt vmcnt(10)
; DI void phase3(const Params& p, char* smem, const Sched sc) {
;     ...
;       float ssq = 0.f;
; #pragma unroll
;       for (int rb = 0; rb < 2; ++rb)
; #pragma unroll
;         for (int i = 0; i < 16; ++i) { const float v = acc[rb][0][i] * rstd; acc[rb][0][i] = v; ssq += v * v; }
; #pragma unroll
;       for (int i = 0; i < 16; ++i) ssq += kr[i] * kr[i];
;       ssq += other_half(ssq);
;       const float r2 = rsqrtf(ssq * (1.f / 96) + 1e-6f);
; #pragma unroll
;       for (int rb = 0; rb < 2; ++rb)
; #pragma unroll
;         for (int g = 0; g < 4; ++g) {
;           const f32x4 w4 = *(const f32x4*)(p.khn + rb * 32 + 8 * g + 4 * h);
; #pragma unroll
;           for (int e = 0; e < 4; ++e) acc[rb][0][4 * g + e] *= r2 * w4[e];
;         }
; #pragma unroll
;       for (int g = 0; g < 4; ++g) {
;         const f32x4 w4 = *(const f32x4*)(p.khn + 64 + 8 * g + 4 * h);
; #pragma unroll
;         for (int e = 0; e < 4; ++e) kr[4 * g + e] *= r2 * w4[e];
;       }
; #pragma unroll
;       for (int g = 0; g < 2; ++g) {
;         const f32x4 c4 = *(const f32x4*)(p.cosT + (size_t)token * 16 + 8 * g + 4 * h), s4 = *(const f32x4*)(p.sinT + (size_t)token * 16 + 8 * g + 4 * h);
; #pragma unroll
;         for (int e = 0; e < 4; ++e) {
;           const float x1 = kr[4 * g + e], x2 = kr[4 * (g + 2) + e];
;           kr[4 * g + e] = x1 * c4[e] - x2 * s4[e];
;           kr[4 * (g + 2) + e] = x2 * c4[e] + x1 * s4[e];
;         }
;       }
	v_fmac_f32_e32 v113, v92, v92
	v_fmac_f32_e32 v113, v93, v93
	v_fmac_f32_e32 v113, v94, v94
	v_fmac_f32_e32 v113, v95, v95
	v_fmac_f32_e32 v113, v68, v68
	v_fmac_f32_e32 v113, v69, v69
	v_add_f32_e32 v113, v146, v113
	v_add_f32_e32 v113, v147, v113
	v_add_f32_e32 v113, v150, v113
	v_add_f32_e32 v113, v151, v113
	v_add_f32_e32 v113, v148, v113
	v_add_f32_e32 v113, v149, v113
	v_add_f32_e32 v113, v154, v113
	v_add_f32_e32 v113, v155, v113
	v_add_f32_e32 v113, v152, v113
	v_add_f32_e32 v113, v153, v113
	v_mov_b32_e32 v146, v113
	v_mov_b32_e32 v147, v113
	s_nop 1
	v_permlane32_swap_b32_e32 v146, v147
	v_cndmask_b32_e64 v146, v146, v147, s[8:9]
	v_add_f32_e32 v113, v113, v146
	v_fmamk_f32 v113, v113, 0x3c2aaaab, v233
	v_mul_f32_e32 v146, 0x4b800000, v113
	v_cmp_gt_f32_e32 vcc, s19, v113
	s_nop 1
	v_cndmask_b32_e32 v113, v113, v146, vcc
	v_rsq_f32_e32 v113, v113
	s_nop 0
	v_mul_f32_e32 v146, 0x45800000, v113
	v_cndmask_b32_e32 v146, v113, v146, vcc
	v_mul_f32_e64 v88, v88, v146
	v_mul_f32_e64 v89, v89, v146
	v_mul_f32_e64 v90, v90, v146
	v_mul_f32_e64 v91, v91, v146
	v_mul_f32_e64 v84, v84, v146
	v_mul_f32_e64 v85, v85, v146
	v_mul_f32_e64 v86, v86, v146
	v_mul_f32_e64 v87, v87, v146
	v_mul_f32_e64 v16, v16, v112
	v_mul_f32_e64 v17, v17, v112
	v_mul_f32_e64 v18, v18, v112
	v_mul_f32_e64 v19, v19, v112
	v_mul_f32_e64 v88, v132, v88
	v_mul_f32_e64 v89, v133, v89
	v_mul_f32_e64 v90, v130, v90
	v_mul_f32_e64 v91, v131, v91
	v_mul_f32_e64 v84, v128, v84
	v_mul_f32_e64 v85, v129, v85
	v_mul_f32_e64 v86, v126, v86
	v_mul_f32_e64 v87, v127, v87
	s_waitcnt vmcnt(8)
	v_mul_f32_e64 v100, v100, v146
	v_mul_f32_e64 v101, v101, v146
	v_cvt_pk_bf16_f32 v16, v16, v17
	v_cvt_pk_bf16_f32 v17, v18, v19
	v_mul_f32_e64 v18, v20, v112
	v_mul_f32_e64 v19, v21, v112
	v_mul_f32_e64 v20, v22, v112
	v_mul_f32_e64 v21, v23, v112
	v_mul_f32_e64 v0, v0, v112
	v_mul_f32_e64 v1, v1, v112
	v_mul_f32_e64 v2, v2, v112
	v_mul_f32_e64 v3, v3, v112
	v_mul_f32_e64 v80, v80, v146
	v_mul_f32_e64 v81, v81, v146
	v_mul_f32_e64 v82, v82, v146
	v_mul_f32_e64 v83, v83, v146
	v_mul_f32_e64 v76, v76, v146
	v_mul_f32_e64 v77, v77, v146
	v_mul_f32_e64 v78, v78, v146
	v_mul_f32_e64 v79, v79, v146
	v_mul_f32_e64 v104, v104, v146
	v_mul_f32_e64 v105, v105, v146
	v_mul_f32_e64 v106, v106, v146
	v_mul_f32_e64 v107, v107, v146
	v_mul_f32_e64 v96, v96, v146
	v_mul_f32_e64 v97, v97, v146
	v_mul_f32_e64 v98, v98, v146
	v_mul_f32_e64 v99, v99, v146
	s_waitcnt vmcnt(7)
	v_mul_f32_e64 v32, v32, v146
	v_mul_f32_e64 v33, v33, v146
	s_waitcnt vmcnt(6)
	v_mul_f32_e64 v36, v36, v146
	v_mul_f32_e64 v37, v37, v146
	v_mul_f32_e64 v32, v92, v32
	v_mul_f32_e64 v33, v93, v33
	v_mul_f32_e64 v36, v72, v36
	v_mul_f32_e64 v37, v73, v37
	v_mul_f32_e64 v108, v108, v146
	v_mul_f32_e64 v109, v109, v146
	v_mul_f32_e64 v110, v110, v146
	v_mul_f32_e64 v111, v111, v146
	v_mul_f32_e64 v44, v44, v100
	v_mul_f32_e64 v45, v45, v101
	s_waitcnt vmcnt(5)
	v_mul_f32_e64 v72, v40, v36
	v_mul_f32_e64 v73, v41, v37
	s_waitcnt vmcnt(4)
	v_mul_f32_e64 v36, v48, v36
	v_mul_f32_e64 v37, v49, v37
	v_fma_f32 v72, v48, v32, -v72
	v_fma_f32 v73, v49, v33, -v73
	v_fma_f32 v36, v40, v32, v36
	v_fma_f32 v37, v41, v33, v37
	v_mul_f32_e64 v32, v34, v146
	v_mul_f32_e64 v33, v35, v146
	v_mul_f32_e64 v34, v38, v146
	v_mul_f32_e64 v35, v39, v146
	v_mul_f32_e64 v32, v94, v32
	v_mul_f32_e64 v33, v95, v33
	v_mul_f32_e64 v34, v74, v34
	v_mul_f32_e64 v35, v75, v35
	v_mul_f32_e64 v100, v102, v146
	v_mul_f32_e64 v101, v103, v146
	v_mul_f32_e64 v38, v42, v34
	v_mul_f32_e64 v39, v43, v35
	v_mul_f32_e64 v34, v50, v34
	v_mul_f32_e64 v35, v51, v35
	v_fma_f32 v38, v50, v32, -v38
	v_fma_f32 v39, v51, v33, -v39
	v_fma_f32 v40, v42, v32, v34
	v_fma_f32 v41, v43, v33, v35
	s_waitcnt vmcnt(2)
	v_mul_f32_e64 v34, v56, v146
	v_mul_f32_e64 v35, v57, v146
	v_mul_f32_e64 v32, v52, v146
	v_mul_f32_e64 v33, v53, v146
	v_mul_f32_e64 v34, v64, v34
	v_mul_f32_e64 v35, v65, v35
	v_mul_f32_e64 v32, v68, v32
	v_mul_f32_e64 v33, v69, v33
	s_waitcnt vmcnt(1)
	v_mul_f32_e64 v42, v60, v34
	v_mul_f32_e64 v43, v61, v35
	s_waitcnt vmcnt(0)
; DI unsigned pk_bf16(float lo, float hi) { f32x2 v = {lo, hi}; bf2_t b = __builtin_convertvector(v, bf2_t); return __builtin_bit_cast(unsigned, b); }
; DI void phase3(const Params& p, char* smem, const Sched sc) {
;     ...
;       for (int g = 0; g < 2; ++g) {
;         const f32x4 c4 = *(const f32x4*)(p.cosT + (size_t)token * 16 + 8 * g + 4 * h), s4 = *(const f32x4*)(p.sinT + (size_t)token * 16 + 8 * g + 4 * h);
; #pragma unroll
;         for (int e = 0; e < 4; ++e) {
;           const float x1 = kr[4 * g + e], x2 = kr[4 * (g + 2) + e];
;           kr[4 * g + e] = x1 * c4[e] - x2 * s4[e];
;           kr[4 * (g + 2) + e] = x2 * c4[e] + x1 * s4[e];
;         }
;       }
;       bf16_t* dk = p.Km + ((size_t)(b * 8 + head) * S_ + s) * 96;
;       bf16_t* dv = p.Vm + ((size_t)(b * 8 + head) * S_ + s) * 64;
; #pragma unroll
;       for (int rb = 0; rb < 2; ++rb) {
;         u32x2 w[4], u[4];
; #pragma unroll
;         for (int g = 0; g < 4; ++g) {
;           w[g].x = pk_bf16(acc[rb][0][4 * g], acc[rb][0][4 * g + 1]); w[g].y = pk_bf16(acc[rb][0][4 * g + 2], acc[rb][0][4 * g + 3]);
;           u[g].x = pk_bf16(acc[rb + 2][0][4 * g] * rstd, acc[rb + 2][0][4 * g + 1] * rstd); u[g].y = pk_bf16(acc[rb + 2][0][4 * g + 2] * rstd, acc[rb + 2][0][4 * g + 3] * rstd);
;         }
; #pragma unroll
;         for (int q = 0; q < 2; ++q) {
;           *(u32x4*)(dk + rb * 32 + 16 * q + 8 * h) = widen_pair(w[2 * q], w[2 * q + 1]);
;           *(u32x4*)(dv + rb * 32 + 16 * q + 8 * h) = widen_pair(u[2 * q], u[2 * q + 1]);
;         }
;       }
;       {
;         u32x2 w[4];
; #pragma unroll
;         for (int g = 0; g < 4; ++g) { w[g].x = pk_bf16(kr[4 * g], kr[4 * g + 1]); w[g].y = pk_bf16(kr[4 * g + 2], kr[4 * g + 3]); }
; #pragma unroll
;         for (int q = 0; q < 2; ++q) *(u32x4*)(dk + 64 + 16 * q + 8 * h) = widen_pair(w[2 * q], w[2 * q + 1]);
;       }
	v_mul_f32_e64 v34, v114, v34
	v_mul_f32_e64 v35, v115, v35
	v_fma_f32 v42, v114, v32, -v42
	v_fma_f32 v43, v115, v33, -v43
	v_fma_f32 v48, v60, v32, v34
	v_fma_f32 v49, v61, v33, v35
	v_mul_f32_e64 v34, v58, v146
	v_mul_f32_e64 v35, v59, v146
	v_mul_f32_e64 v32, v54, v146
	v_mul_f32_e64 v33, v55, v146
	v_mul_f32_e64 v34, v66, v34
	v_mul_f32_e64 v35, v67, v35
	v_mul_f32_e64 v32, v70, v32
	v_mul_f32_e64 v33, v71, v33
	v_mul_f32_e64 v50, v62, v34
	v_mul_f32_e64 v51, v63, v35
	v_mul_f32_e64 v34, v116, v34
	v_mul_f32_e64 v35, v117, v35
	v_fma_f32 v50, v116, v32, -v50
	v_fma_f32 v51, v117, v33, -v51
	v_fma_f32 v52, v62, v32, v34
	v_fma_f32 v53, v63, v33, v35
	v_lshl_or_b32 v32, v240, 3, s25
	v_ashrrev_i32_e32 v33, 31, v32
	v_lshlrev_b64 v[32:33], 13, v[32:33]
	v_or_b32_e32 v32, v32, v239
	v_lshlrev_b64 v[34:35], 7, v[32:33]
	v_mad_u64_u32 v[54:55], s[12:13], v32, s20, v[206:207]
	v_mad_i32_i24 v55, v33, s20, v55
	v_lshl_add_u64 v[56:57], v[196:197], 0, v[34:35]
	v_cvt_pk_bf16_f32 v32, v88, v89
	v_cvt_pk_bf16_f32 v33, v90, v91
	v_cvt_pk_bf16_f32 v34, v84, v85
	v_cvt_pk_bf16_f32 v35, v86, v87
	v_cvt_pk_bf16_f32 v18, v18, v19
	v_cvt_pk_bf16_f32 v19, v20, v21
	v_mul_f32_e64 v22, v24, v112
	v_mul_f32_e64 v23, v25, v112
	v_cvt_pk_bf16_f32 v0, v0, v1
	v_cvt_pk_bf16_f32 v1, v2, v3
	v_mul_f32_e64 v2, v4, v112
	v_mul_f32_e64 v3, v5, v112
	v_mul_f32_e64 v4, v6, v112
	v_mul_f32_e64 v5, v7, v112
	v_mul_f32_e64 v6, v8, v112
	v_mul_f32_e64 v7, v9, v112
	v_mul_f32_e64 v80, v124, v80
	v_mul_f32_e64 v81, v125, v81
	v_mul_f32_e64 v82, v122, v82
	v_mul_f32_e64 v83, v123, v83
	v_mul_f32_e64 v76, v120, v76
	v_mul_f32_e64 v77, v121, v77
	v_mul_f32_e64 v78, v118, v78
	v_mul_f32_e64 v79, v119, v79
	v_mul_f32_e64 v104, v144, v104
	v_mul_f32_e64 v105, v145, v105
	v_mul_f32_e64 v106, v142, v106
	v_mul_f32_e64 v107, v143, v107
	v_mul_f32_e64 v96, v140, v96
	v_mul_f32_e64 v97, v141, v97
	v_mul_f32_e64 v98, v138, v98
	v_mul_f32_e64 v99, v139, v99
	v_mul_f32_e64 v108, v136, v108
	v_mul_f32_e64 v109, v137, v109
	v_mul_f32_e64 v110, v134, v110
	v_mul_f32_e64 v111, v135, v111
	v_mul_f32_e64 v46, v46, v100
	v_mul_f32_e64 v47, v47, v101
	v_cvt_pk_bf16_f32 v24, v22, v23
	v_mul_f32_e64 v22, v26, v112
	v_mul_f32_e64 v23, v27, v112
	v_mul_f32_e64 v26, v28, v112
	v_mul_f32_e64 v27, v29, v112
	v_mul_f32_e64 v28, v30, v112
	v_mul_f32_e64 v29, v31, v112
	v_permlane32_swap_b32_e32 v32, v34
	v_permlane32_swap_b32_e32 v33, v35
	v_permlane32_swap_b32_e32 v16, v18
	v_permlane32_swap_b32_e32 v17, v19
	v_cvt_pk_bf16_f32 v8, v6, v7
	v_mul_f32_e64 v6, v10, v112
	v_mul_f32_e64 v7, v11, v112
	v_cvt_pk_bf16_f32 v20, v80, v81
	v_cvt_pk_bf16_f32 v21, v82, v83
	v_cvt_pk_bf16_f32 v25, v22, v23
	v_cvt_pk_bf16_f32 v22, v76, v77
	v_cvt_pk_bf16_f32 v23, v78, v79
	v_cvt_pk_bf16_f32 v26, v26, v27
	v_cvt_pk_bf16_f32 v27, v28, v29
	global_store_dwordx4 v[54:55], v[32:35], off
	global_store_dwordx4 v[56:57], v[16:19], off
	v_cvt_pk_bf16_f32 v2, v2, v3
	v_cvt_pk_bf16_f32 v3, v4, v5
	v_cvt_pk_bf16_f32 v16, v104, v105
	v_cvt_pk_bf16_f32 v17, v106, v107
	v_cvt_pk_bf16_f32 v18, v96, v97
	v_cvt_pk_bf16_f32 v19, v98, v99
	v_cvt_pk_bf16_f32 v4, v108, v109
	v_cvt_pk_bf16_f32 v5, v110, v111
	v_cvt_pk_bf16_f32 v9, v6, v7
	v_cvt_pk_bf16_f32 v6, v44, v45
	v_cvt_pk_bf16_f32 v7, v46, v47
	v_permlane32_swap_b32_e32 v20, v22
	v_permlane32_swap_b32_e32 v21, v23
	v_permlane32_swap_b32_e32 v24, v26
	v_permlane32_swap_b32_e32 v25, v27
	v_mul_f32_e64 v10, v12, v112
	v_mul_f32_e64 v11, v13, v112
	v_mul_f32_e64 v12, v14, v112
	v_mul_f32_e64 v13, v15, v112
	v_permlane32_swap_b32_e32 v16, v18
	v_permlane32_swap_b32_e32 v17, v19
	v_permlane32_swap_b32_e32 v0, v2
	v_permlane32_swap_b32_e32 v1, v3
	v_permlane32_swap_b32_e32 v4, v6
	v_permlane32_swap_b32_e32 v5, v7
	global_store_dwordx4 v[54:55], v[20:23], off offset:32
	global_store_dwordx4 v[56:57], v[24:27], off offset:32
	v_cvt_pk_bf16_f32 v10, v10, v11
	v_cvt_pk_bf16_f32 v11, v12, v13
	global_store_dwordx4 v[54:55], v[16:19], off offset:64
	global_store_dwordx4 v[56:57], v[0:3], off offset:64
	global_store_dwordx4 v[54:55], v[4:7], off offset:96
	v_permlane32_swap_b32_e32 v8, v10
	v_cvt_pk_bf16_f32 v0, v72, v73
	v_cvt_pk_bf16_f32 v1, v38, v39
	v_cvt_pk_bf16_f32 v2, v42, v43
	v_cvt_pk_bf16_f32 v3, v50, v51
	v_cvt_pk_bf16_f32 v4, v36, v37
	v_cvt_pk_bf16_f32 v5, v40, v41
	v_cvt_pk_bf16_f32 v6, v48, v49
	v_cvt_pk_bf16_f32 v7, v52, v53
	v_permlane32_swap_b32_e32 v9, v11
	v_permlane32_swap_b32_e32 v0, v2
	v_permlane32_swap_b32_e32 v1, v3
	v_permlane32_swap_b32_e32 v4, v6
	v_permlane32_swap_b32_e32 v5, v7
	global_store_dwordx4 v[56:57], v[8:11], off offset:96
	global_store_dwordx4 v[54:55], v[0:3], off offset:128
	global_store_dwordx4 v[54:55], v[4:7], off offset:160
	s_branch .LBB0_359

; DI unsigned pk_bf16(float lo, float hi) { f32x2 v = {lo, hi}; bf2_t b = __builtin_convertvector(v, bf2_t); return __builtin_bit_cast(unsigned, b); }
; DI float bf_lo(unsigned u) { return __uint_as_float(u << 16); }
; DI float bf_hi(unsigned u) { return __uint_as_float(u & 0xffff0000u); }
; template <int DQK, bool SB, bool SMAX>
; DI void attn_item(const Params& p, char* smem, int bh, int qb, float Mb) {
;     ...
;   float inv = 1.f;
;   if (!SB) { const float lt = lsum + other_half(lsum); inv = 1.f / lt; }
;   const size_t token = (size_t)(bh >> 3) * S_ + query;
;   const int colbase = (SB ? 0 : 512) + (bh & 7) * 64;
; #pragma unroll
;   for (int db = 0; db < 2; ++db) {
;     u32x2 w[4];
; #pragma unroll
;     for (int g = 0; g < 4; ++g) {
;       const int col = colbase + db * 32 + 8 * g + 4 * h;
;       const u32x2 gt = *(const u32x2*)(p.Gate + token * 1024 + col);
;       w[g].x = pk_bf16(O[db][4 * g] * inv * bf_lo(gt.x), O[db][4 * g + 1] * inv * bf_hi(gt.x));
;       w[g].y = pk_bf16(O[db][4 * g + 2] * inv * bf_lo(gt.y), O[db][4 * g + 3] * inv * bf_hi(gt.y));
;     }
; #pragma unroll
;     for (int q = 0; q < 2; ++q) *(u32x4*)(p.Mixed + token * 1024 + colbase + db * 32 + 16 * q + 8 * h) = widen_pair(w[2 * q], w[2 * q + 1]);
;   }
.LBB0_424:
	s_setprio 0
	s_lshl_b32 s0, s0, 6
	v_readlane_b32 s2, v255, 15
	s_and_b32 s0, s0, 0x1c0
	v_lshlrev_b64 v[48:49], 11, v[176:177]
	v_readlane_b32 s3, v255, 16
	v_or_b32_e32 v52, s0, v197
	v_lshlrev_b32_e32 v176, 1, v52
	v_lshl_add_u64 v[48:49], v[48:49], 0, s[2:3]
	v_lshl_add_u64 v[50:51], s[94:95], 0, v[48:49]
	v_lshl_add_u64 v[50:51], v[50:51], 0, v[176:177]
	global_load_dwordx2 v[52:53], v[50:51], off offset:1024
	global_load_dwordx2 v[54:55], v[50:51], off offset:1040
	global_load_dwordx2 v[56:57], v[50:51], off offset:1056
	global_load_dwordx2 v[58:59], v[50:51], off offset:1072
	v_mov_b32_e32 v60, v152
	v_mov_b32_e32 v61, v152
	s_nop 1
	v_permlane32_swap_b32_e32 v60, v61
	v_cndmask_b32_e64 v60, v60, v61, s[8:9]
	v_add_f32_e32 v60, v152, v60
	s_lshl_b32 s4, s0, 1
	v_div_scale_f32 v61, s[0:1], v60, v60, 1.0
	v_rcp_f32_e32 v62, v61
	v_div_scale_f32 v63, vcc, 1.0, v60, 1.0
	v_lshl_add_u64 v[48:49], s[86:87], 0, v[48:49]
	v_fma_f32 v64, -v61, v62, 1.0
	v_fmac_f32_e32 v62, v64, v62
	v_mul_f32_e32 v64, v63, v62
	v_fma_f32 v65, -v61, v64, v63
	v_fmac_f32_e32 v64, v65, v62
	v_fma_f32 v61, -v61, v64, v63
	v_div_fmas_f32 v61, v61, v62, v64
	v_div_fixup_f32 v60, v61, v60, 1.0
	v_mul_f32_e64 v32, v32, v60
	v_mul_f32_e64 v33, v33, v60
	v_mul_f32_e64 v34, v34, v60
	v_mul_f32_e64 v35, v35, v60
	v_mul_f32_e64 v36, v36, v60
	v_mul_f32_e64 v37, v37, v60
	v_mul_f32_e64 v38, v38, v60
	v_mul_f32_e64 v39, v39, v60
	v_mul_f32_e64 v40, v40, v60
	v_mul_f32_e64 v41, v41, v60
	v_mul_f32_e64 v42, v42, v60
	v_mul_f32_e64 v43, v43, v60
	v_mul_f32_e64 v44, v44, v60
	v_mul_f32_e64 v45, v45, v60
	v_mul_f32_e64 v46, v46, v60
	v_mul_f32_e64 v47, v47, v60
	v_mov_b32_e32 v181, v177
	v_lshl_add_u64 v[48:49], v[48:49], 0, s[4:5]
	v_lshl_add_u64 v[48:49], v[48:49], 0, v[180:181]
	v_mul_f32_e64 v16, v16, v60
	v_mul_f32_e64 v17, v17, v60
	v_mul_f32_e64 v18, v18, v60
	v_mul_f32_e64 v19, v19, v60
	v_mul_f32_e64 v20, v20, v60
	v_mul_f32_e64 v21, v21, v60
	v_mul_f32_e64 v22, v22, v60
	v_mul_f32_e64 v23, v23, v60
	v_mul_f32_e64 v24, v24, v60
	v_mul_f32_e64 v25, v25, v60
	v_mul_f32_e64 v26, v26, v60
	v_mul_f32_e64 v27, v27, v60
	v_mul_f32_e64 v28, v28, v60
	v_mul_f32_e64 v29, v29, v60
	v_mul_f32_e64 v30, v30, v60
	v_mul_f32_e64 v31, v31, v60
	s_waitcnt vmcnt(3)
	v_lshlrev_b32_e32 v62, 16, v52
	v_and_b32_e32 v63, 0xffff0000, v52
	v_lshlrev_b32_e32 v52, 16, v53
	v_and_b32_e32 v53, 0xffff0000, v53
	s_waitcnt vmcnt(2)
	v_lshlrev_b32_e32 v64, 16, v54
	v_and_b32_e32 v65, 0xffff0000, v54
	v_lshlrev_b32_e32 v54, 16, v55
	v_and_b32_e32 v55, 0xffff0000, v55
	s_waitcnt vmcnt(1)
	v_lshlrev_b32_e32 v66, 16, v56
	v_and_b32_e32 v67, 0xffff0000, v56
	v_lshlrev_b32_e32 v56, 16, v57
	v_and_b32_e32 v57, 0xffff0000, v57
	s_waitcnt vmcnt(0)
	v_lshlrev_b32_e32 v68, 16, v58
	v_and_b32_e32 v69, 0xffff0000, v58
	v_lshlrev_b32_e32 v58, 16, v59
	v_and_b32_e32 v59, 0xffff0000, v59
	v_mul_f32_e64 v32, v32, v62
	v_mul_f32_e64 v33, v33, v63
	v_mul_f32_e64 v34, v34, v52
	v_mul_f32_e64 v35, v35, v53
	v_mul_f32_e64 v36, v36, v64
	v_mul_f32_e64 v37, v37, v65
	v_mul_f32_e64 v38, v38, v54
	v_mul_f32_e64 v39, v39, v55
	v_mul_f32_e64 v40, v40, v66
	v_mul_f32_e64 v41, v41, v67
	v_mul_f32_e64 v42, v42, v56
	v_mul_f32_e64 v43, v43, v57
	v_mul_f32_e64 v44, v44, v68
	v_mul_f32_e64 v45, v45, v69
	v_mul_f32_e64 v46, v46, v58
	v_mul_f32_e64 v47, v47, v59
	v_cvt_pk_bf16_f32 v32, v32, v33
	v_cvt_pk_bf16_f32 v33, v34, v35
	v_cvt_pk_bf16_f32 v34, v36, v37
	v_cvt_pk_bf16_f32 v35, v38, v39
	v_cvt_pk_bf16_f32 v36, v40, v41
	v_cvt_pk_bf16_f32 v37, v42, v43
	v_cvt_pk_bf16_f32 v38, v44, v45
	v_cvt_pk_bf16_f32 v39, v46, v47
	v_permlane32_swap_b32_e32 v32, v34
	v_permlane32_swap_b32_e32 v33, v35
	v_permlane32_swap_b32_e32 v36, v38
	v_permlane32_swap_b32_e32 v37, v39
	global_store_dwordx4 v[48:49], v[32:35], off offset:1024
	global_store_dwordx4 v[48:49], v[36:39], off offset:1056
	global_load_dwordx2 v[32:33], v[50:51], off offset:1088
	s_nop 0
	global_load_dwordx2 v[34:35], v[50:51], off offset:1104
	global_load_dwordx2 v[36:37], v[50:51], off offset:1120
	global_load_dwordx2 v[38:39], v[50:51], off offset:1136
	s_waitcnt vmcnt(3)
	v_lshlrev_b32_e32 v40, 16, v32
	v_and_b32_e32 v41, 0xffff0000, v32
	v_lshlrev_b32_e32 v32, 16, v33
	v_and_b32_e32 v33, 0xffff0000, v33
	s_waitcnt vmcnt(2)
	v_lshlrev_b32_e32 v42, 16, v34
	v_and_b32_e32 v43, 0xffff0000, v34
	v_lshlrev_b32_e32 v34, 16, v35
	v_and_b32_e32 v35, 0xffff0000, v35
	s_waitcnt vmcnt(1)
	v_lshlrev_b32_e32 v44, 16, v36
	v_and_b32_e32 v45, 0xffff0000, v36
	v_lshlrev_b32_e32 v36, 16, v37
	v_and_b32_e32 v37, 0xffff0000, v37
	s_waitcnt vmcnt(0)
	v_lshlrev_b32_e32 v46, 16, v38
	v_and_b32_e32 v47, 0xffff0000, v38
	v_lshlrev_b32_e32 v38, 16, v39
	v_and_b32_e32 v39, 0xffff0000, v39
	v_mul_f32_e64 v16, v16, v40
	v_mul_f32_e64 v17, v17, v41
	v_mul_f32_e64 v18, v18, v32
	v_mul_f32_e64 v19, v19, v33
	v_mul_f32_e64 v20, v20, v42
	v_mul_f32_e64 v21, v21, v43
	v_mul_f32_e64 v22, v22, v34
	v_mul_f32_e64 v23, v23, v35
	v_mul_f32_e64 v24, v24, v44
	v_mul_f32_e64 v25, v25, v45
	v_mul_f32_e64 v26, v26, v36
	v_mul_f32_e64 v27, v27, v37
	v_mul_f32_e64 v28, v28, v46
	v_mul_f32_e64 v29, v29, v47
	v_mul_f32_e64 v30, v30, v38
	v_mul_f32_e64 v31, v31, v39
	v_cvt_pk_bf16_f32 v16, v16, v17
	v_cvt_pk_bf16_f32 v17, v18, v19
	v_cvt_pk_bf16_f32 v18, v20, v21
	v_cvt_pk_bf16_f32 v19, v22, v23
	v_cvt_pk_bf16_f32 v20, v24, v25
	v_cvt_pk_bf16_f32 v21, v26, v27
	v_cvt_pk_bf16_f32 v22, v28, v29
	v_cvt_pk_bf16_f32 v23, v30, v31
	v_permlane32_swap_b32_e32 v16, v18
	v_permlane32_swap_b32_e32 v17, v19
	v_permlane32_swap_b32_e32 v20, v22
	v_permlane32_swap_b32_e32 v21, v23
	global_store_dwordx4 v[48:49], v[16:19], off offset:1088
	global_store_dwordx4 v[48:49], v[20:23], off offset:1120
	s_barrier

; DI unsigned pk_bf16(float lo, float hi) { f32x2 v = {lo, hi}; bf2_t b = __builtin_convertvector(v, bf2_t); return __builtin_bit_cast(unsigned, b); }
; DI float bf_lo(unsigned u) { return __uint_as_float(u << 16); }
; DI float bf_hi(unsigned u) { return __uint_as_float(u & 0xffff0000u); }
; DI int crow(int i, int h) { return (i & 3) + 8 * (i >> 2) + 4 * h; }
; DI float fast_exp2(float x) { return __builtin_amdgcn_exp2f(x); }
; DI float fast_log2(float x) { return __builtin_amdgcn_logf(x); }
; #define AT_LOAD(SET, IT) { const int kl_ = AT_KB(IT); \
;     _Pragma("unroll") for (int i = 0; i < KPT; ++i) kreg[SET][i] = *(const u32x4*)(Kg + (size_t)kl_ * DQK + (tid + 256 * i) * 8); \
;     _Pragma("unroll") for (int i = 0; i < 2; ++i) vreg[SET][i] = *(const u32x4*)(Vg + (size_t)kl_ * 64 + (tid + 256 * i) * 8); \
;     __builtin_amdgcn_sched_barrier(0); }
; template <int DQK, bool SB, bool SMAX>
; DI void attn_item(const Params& p, char* smem, int bh, int qb, float Mb) {
;     ...
;     AT_WRITE(0, st2 ^ 1)
;     AT_LOAD(0, (it + 2 < nt) ? it + 2 : nt - 1)
;     ...
; #pragma unroll
;         for (int kb = 0; kb < 2; ++kb)
; #pragma unroll
;           for (int i2 = 0; i2 < 8; ++i2) {
;             float lk[2];
; #pragma unroll
;             for (int e = 0; e < 2; ++e) {
;               const int i = 2 * i2 + e;
;               const float z = fminf(st[kb][i], 100.f);
;               const int key = kb0 + kb * 32 + crow(i, h);
;               const bool valid = !diag || (key < query);
;               float l = -fast_log2(1.f + fast_exp2(z));
;               l = valid ? l : 0.f;
;               lk[e] = l;
;               tsum += l;
;               ca[kb][i] = z + carry;
;             }
;             const unsigned hp = pk_bf16(lk[0], lk[1]);
;             const unsigned lp = pk_bf16(lk[0] - bf_lo(hp), lk[1] - bf_hi(hp));
;             const int kk = kb * 2 + (i2 >> 2), w = i2 & 3;
;             hi[kk][2 * w] = (short)(hp & 0xffffu); hi[kk][2 * w + 1] = (short)(hp >> 16);
;             lo[kk][2 * w] = (short)(lp & 0xffffu); lo[kk][2 * w + 1] = (short)(lp >> 16);
;           }
.LBB0_435:
	s_or_b64 exec, exec, s[2:3]
	s_cmp_lt_u32 s4, s1
	s_cselect_b32 s2, s78, 0
	s_ashr_i32 s3, s2, 31
	s_lshl_b64 s[2:3], s[2:3], 7
	v_lshl_add_u64 v[80:81], v[148:149], 0, s[2:3]
	s_waitcnt vmcnt(3)
	ds_write_b128 v203, v[120:123] offset:9216
	s_waitcnt vmcnt(2)
	ds_write_b128 v204, v[124:127] offset:9216
	s_waitcnt vmcnt(1)
	ds_write_b128 v203, v[128:131] offset:27648
	s_waitcnt vmcnt(0)
	ds_write_b128 v204, v[132:135] offset:27648
	v_add_co_u32_e32 v82, vcc, 0x1000, v80
	s_nop 1
	v_addc_co_u32_e32 v83, vcc, 0, v81, vcc
	global_load_dwordx4 v[120:123], v[80:81], off
	global_load_dwordx4 v[124:127], v[82:83], off
	v_lshl_add_u64 v[80:81], v[150:151], 0, s[2:3]
	v_add_co_u32_e32 v82, vcc, 0x1000, v80
	s_nop 1
	v_addc_co_u32_e32 v83, vcc, 0, v81, vcc
	global_load_dwordx4 v[128:131], v[80:81], off
	global_load_dwordx4 v[132:135], v[82:83], off
	s_and_saveexec_b64 s[80:81], s[12:13]
	s_cbranch_execz .LBB0_437
	v_cmp_le_i32_e64 s[44:45], s14, v181
	s_nop 0
	s_cmp_eq_u64 s[44:45], exec
	s_cbranch_scc1 .Lsbf_1
	s_nop 0
	v_add_u32_e32 v143, s78, v197
	v_min_f32_e32 v84, 0x42c80000, v64
	s_nop 0
	v_exp_f32_e32 v64, v84
	v_min_f32_e32 v85, 0x42c80000, v65
	v_add_u32_e32 v65, 0x81, v143
	v_cmp_lt_i32_e64 s[2:3], v65, v176
	v_exp_f32_e32 v65, v85
	v_add_f32_e32 v64, 1.0, v64
	v_log_f32_e32 v64, v64
	v_add_u32_e32 v80, 0x80, v143
	v_add_f32_e32 v65, 1.0, v65
	v_log_f32_e32 v65, v65
	v_cmp_le_i32_e64 s[44:45], s14, v181
	v_cmp_lt_i32_e32 vcc, v80, v176
	s_or_b64 vcc, s[44:45], vcc
	s_or_b64 s[12:13], s[44:45], s[2:3]
	v_cndmask_b32_e64 v64, 0, -v64, vcc
	v_add_f32_e32 v80, 0, v64
	v_cndmask_b32_e64 v65, 0, -v65, s[12:13]
	v_add_f32_e32 v81, v65, v80
	v_cvt_pk_bf16_f32 v80, v64, v65
	v_lshlrev_b32_e32 v82, 16, v80
	v_sub_f32_e32 v64, v64, v82
	v_and_b32_e32 v82, 0xffff0000, v80
	v_sub_f32_e32 v65, v65, v82
	v_cvt_pk_bf16_f32 v64, v64, v65
	s_nop 0
	v_min_f32_e32 v86, 0x42c80000, v66
	v_add_u32_e32 v65, 0x82, v143
	s_nop 0
	v_cmp_lt_i32_e64 s[2:3], v65, v176
	v_min_f32_e32 v87, 0x42c80000, v67
	v_add_u32_e32 v67, 0x83, v143
	s_or_b64 s[14:15], s[44:45], s[2:3]
	v_exp_f32_e32 v65, v86
	v_cmp_lt_i32_e64 s[2:3], v67, v176
	v_exp_f32_e32 v67, v87
	s_or_b64 s[16:17], s[44:45], s[2:3]
	v_add_f32_e32 v65, 1.0, v65
	v_log_f32_e32 v65, v65
	v_add_f32_e32 v67, 1.0, v67
	v_log_f32_e32 v67, v67
	s_nop 0
	v_cndmask_b32_e64 v65, 0, -v65, s[14:15]
	v_add_f32_e32 v66, v65, v81
	v_cndmask_b32_e64 v67, 0, -v67, s[16:17]
	v_cvt_pk_bf16_f32 v81, v65, v67
	v_lshlrev_b32_e32 v82, 16, v81
	v_sub_f32_e32 v65, v65, v82
	v_and_b32_e32 v82, 0xffff0000, v81
	v_add_f32_e32 v66, v67, v66
	v_sub_f32_e32 v67, v67, v82
	v_cvt_pk_bf16_f32 v65, v65, v67
	s_nop 0
	v_min_f32_e32 v88, 0x42c80000, v68
	v_add_u32_e32 v67, 0x88, v143
	s_nop 0
	v_cmp_lt_i32_e64 s[2:3], v67, v176
	v_min_f32_e32 v89, 0x42c80000, v69
	v_add_u32_e32 v68, 0x89, v143
	s_or_b64 s[18:19], s[44:45], s[2:3]
	v_exp_f32_e32 v67, v88
	v_cmp_lt_i32_e64 s[2:3], v68, v176
	v_exp_f32_e32 v68, v89
	s_or_b64 s[20:21], s[44:45], s[2:3]
	v_add_f32_e32 v67, 1.0, v67
	v_log_f32_e32 v67, v67
	v_add_f32_e32 v68, 1.0, v68
	v_log_f32_e32 v68, v68
	s_nop 0
	v_cndmask_b32_e64 v67, 0, -v67, s[18:19]
	v_add_f32_e32 v66, v67, v66
	v_cndmask_b32_e64 v68, 0, -v68, s[20:21]
	v_cvt_pk_bf16_f32 v82, v67, v68
	v_add_f32_e32 v69, v68, v66
	v_lshlrev_b32_e32 v66, 16, v82
	v_sub_f32_e32 v66, v67, v66
	v_and_b32_e32 v67, 0xffff0000, v82
	v_sub_f32_e32 v67, v68, v67
	v_cvt_pk_bf16_f32 v66, v66, v67
	s_nop 0
	v_min_f32_e32 v90, 0x42c80000, v70
	v_add_u32_e32 v67, 0x8a, v143
	v_cmp_lt_i32_e64 s[2:3], v67, v176
	v_exp_f32_e32 v67, v90
	s_or_b64 s[22:23], s[44:45], s[2:3]
	v_min_f32_e32 v156, 0x42c80000, v48
	v_min_f32_e32 v157, 0x42c80000, v49
	v_add_f32_e32 v67, 1.0, v67
	v_log_f32_e32 v67, v67
	v_add_u32_e32 v49, 0xa1, v143
	v_exp_f32_e32 v48, v156
	s_mov_b32 s97, s96
	v_cndmask_b32_e64 v67, 0, -v67, s[22:23]
	v_add_f32_e32 v68, v67, v69
	s_nop 0
	v_min_f32_e32 v91, 0x42c80000, v71
	v_add_u32_e32 v69, 0x8b, v143
	v_cmp_lt_i32_e64 s[2:3], v69, v176
	v_exp_f32_e32 v69, v91
	s_or_b64 s[24:25], s[44:45], s[2:3]
	v_add_f32_e32 v48, 1.0, v48
	v_log_f32_e32 v48, v48
	v_add_f32_e32 v69, 1.0, v69
	v_log_f32_e32 v69, v69
	s_mov_b32 s98, s96
	s_mov_b32 s99, s96
	v_cndmask_b32_e64 v69, 0, -v69, s[24:25]
	v_cvt_pk_bf16_f32 v83, v67, v69
	v_lshlrev_b32_e32 v70, 16, v83
	v_sub_f32_e32 v67, v67, v70
	v_and_b32_e32 v70, 0xffff0000, v83
	v_add_f32_e32 v68, v69, v68
	v_sub_f32_e32 v69, v69, v70
	v_cvt_pk_bf16_f32 v67, v67, v69
	s_nop 0
	v_min_f32_e32 v92, 0x42c80000, v72
	v_add_u32_e32 v69, 0x90, v143
	s_nop 0
	v_cmp_lt_i32_e64 s[2:3], v69, v176
	v_min_f32_e32 v93, 0x42c80000, v73
	v_add_u32_e32 v70, 0x91, v143
	s_or_b64 s[26:27], s[44:45], s[2:3]
	v_exp_f32_e32 v69, v92
	v_cmp_lt_i32_e64 s[2:3], v70, v176
	v_exp_f32_e32 v70, v93
	s_or_b64 s[28:29], s[44:45], s[2:3]
	v_add_f32_e32 v69, 1.0, v69
	v_log_f32_e32 v69, v69
	v_add_f32_e32 v70, 1.0, v70
	v_log_f32_e32 v70, v70
	v_cndmask_b32_e64 v69, 0, -v69, s[26:27]
	v_add_f32_e32 v68, v69, v68
	v_cndmask_b32_e64 v70, 0, -v70, s[28:29]
	v_cvt_pk_bf16_f32 v72, v69, v70
	v_add_f32_e32 v71, v70, v68
	v_lshlrev_b32_e32 v68, 16, v72
	v_sub_f32_e32 v68, v69, v68
	v_and_b32_e32 v69, 0xffff0000, v72
	v_sub_f32_e32 v69, v70, v69
	v_cvt_pk_bf16_f32 v68, v68, v69
	s_nop 0
	v_min_f32_e32 v94, 0x42c80000, v74
	v_add_u32_e32 v69, 0x92, v143
	v_cmp_lt_i32_e64 s[2:3], v69, v176
	v_exp_f32_e32 v69, v94
	s_or_b64 s[30:31], s[44:45], s[2:3]
	v_add_f32_e32 v69, 1.0, v69
	v_log_f32_e32 v69, v69
	s_nop 0
	v_cndmask_b32_e64 v69, 0, -v69, s[30:31]
	v_add_f32_e32 v70, v69, v71
	s_nop 0
	v_min_f32_e32 v95, 0x42c80000, v75
	v_add_u32_e32 v71, 0x93, v143
; DI unsigned pk_bf16(float lo, float hi) { f32x2 v = {lo, hi}; bf2_t b = __builtin_convertvector(v, bf2_t); return __builtin_bit_cast(unsigned, b); }
; DI float bf_lo(unsigned u) { return __uint_as_float(u << 16); }
; DI float bf_hi(unsigned u) { return __uint_as_float(u & 0xffff0000u); }
; DI int crow(int i, int h) { return (i & 3) + 8 * (i >> 2) + 4 * h; }
; DI float fast_exp2(float x) { return __builtin_amdgcn_exp2f(x); }
; DI float fast_log2(float x) { return __builtin_amdgcn_logf(x); }
; template <int DQK, bool SB, bool SMAX>
; DI void attn_item(const Params& p, char* smem, int bh, int qb, float Mb) {
;     ...
; #pragma unroll
;         for (int kb = 0; kb < 2; ++kb)
; #pragma unroll
;           for (int i2 = 0; i2 < 8; ++i2) {
;             float lk[2];
; #pragma unroll
;             for (int e = 0; e < 2; ++e) {
;               const int i = 2 * i2 + e;
;               const float z = fminf(st[kb][i], 100.f);
;               const int key = kb0 + kb * 32 + crow(i, h);
;               const bool valid = !diag || (key < query);
;               float l = -fast_log2(1.f + fast_exp2(z));
;               l = valid ? l : 0.f;
;               lk[e] = l;
;               tsum += l;
;               ca[kb][i] = z + carry;
;             }
;             const unsigned hp = pk_bf16(lk[0], lk[1]);
;             const unsigned lp = pk_bf16(lk[0] - bf_lo(hp), lk[1] - bf_hi(hp));
;             const int kk = kb * 2 + (i2 >> 2), w = i2 & 3;
;             hi[kk][2 * w] = (short)(hp & 0xffffu); hi[kk][2 * w + 1] = (short)(hp >> 16);
;             lo[kk][2 * w] = (short)(lp & 0xffffu); lo[kk][2 * w + 1] = (short)(lp >> 16);
;           }
	v_cmp_lt_i32_e64 s[2:3], v71, v176
	v_exp_f32_e32 v71, v95
	s_or_b64 s[34:35], s[44:45], s[2:3]
	v_add_f32_e32 v71, 1.0, v71
	v_log_f32_e32 v71, v71
	s_nop 0
	v_cndmask_b32_e64 v71, 0, -v71, s[34:35]
	v_cvt_pk_bf16_f32 v73, v69, v71
	v_lshlrev_b32_e32 v74, 16, v73
	v_sub_f32_e32 v69, v69, v74
	v_and_b32_e32 v74, 0xffff0000, v73
	v_add_f32_e32 v70, v71, v70
	v_sub_f32_e32 v71, v71, v74
	v_cvt_pk_bf16_f32 v69, v69, v71
	s_nop 0
	v_min_f32_e32 v154, 0x42c80000, v76
	v_add_u32_e32 v71, 0x98, v143
	s_nop 0
	v_cmp_lt_i32_e64 s[2:3], v71, v176
	v_min_f32_e32 v155, 0x42c80000, v77
	v_add_u32_e32 v74, 0x99, v143
	s_or_b64 s[36:37], s[44:45], s[2:3]
	v_exp_f32_e32 v71, v154
	v_cmp_lt_i32_e64 s[2:3], v74, v176
	v_exp_f32_e32 v74, v155
	s_or_b64 s[38:39], s[44:45], s[2:3]
	v_add_f32_e32 v71, 1.0, v71
	v_log_f32_e32 v71, v71
	v_add_f32_e32 v74, 1.0, v74
	v_log_f32_e32 v74, v74
	v_cndmask_b32_e64 v71, 0, -v71, s[36:37]
	v_add_f32_e32 v70, v71, v70
	v_cndmask_b32_e64 v75, 0, -v74, s[38:39]
	v_cvt_pk_bf16_f32 v74, v71, v75
	v_add_f32_e32 v76, v75, v70
	v_lshlrev_b32_e32 v70, 16, v74
	v_sub_f32_e32 v70, v71, v70
	v_and_b32_e32 v71, 0xffff0000, v74
	v_sub_f32_e32 v71, v75, v71
	v_cvt_pk_bf16_f32 v70, v70, v71
	s_nop 0
	v_min_f32_e32 v158, 0x42c80000, v78
	v_add_u32_e32 v71, 0x9a, v143
	v_cmp_lt_i32_e64 s[2:3], v71, v176
	v_exp_f32_e32 v71, v158
	s_or_b64 s[40:41], s[44:45], s[2:3]
	v_add_f32_e32 v71, 1.0, v71
	v_log_f32_e32 v71, v71
	s_nop 0
	v_cndmask_b32_e64 v71, 0, -v71, s[40:41]
	v_add_f32_e32 v75, v71, v76
	s_nop 0
	v_min_f32_e32 v159, 0x42c80000, v79
	v_add_u32_e32 v76, 0x9b, v143
	v_cmp_lt_i32_e64 s[2:3], v76, v176
	v_exp_f32_e32 v76, v159
	s_or_b64 s[42:43], s[44:45], s[2:3]
	v_add_f32_e32 v76, 1.0, v76
	v_log_f32_e32 v76, v76
	s_nop 0
	v_cndmask_b32_e64 v76, 0, -v76, s[42:43]
	v_add_f32_e32 v77, v76, v75
	v_cvt_pk_bf16_f32 v75, v71, v76
	v_lshlrev_b32_e32 v78, 16, v75
	v_sub_f32_e32 v71, v71, v78
	v_and_b32_e32 v78, 0xffff0000, v75
	v_sub_f32_e32 v76, v76, v78
	v_cvt_pk_bf16_f32 v71, v71, v76
	v_add_u32_e32 v76, 0xa0, v143
	v_cmp_lt_i32_e64 s[2:3], v76, v176
	s_or_b64 s[46:47], s[44:45], s[2:3]
	v_cmp_lt_i32_e64 s[2:3], v49, v176
	v_exp_f32_e32 v49, v157
	s_or_b64 s[48:49], s[44:45], s[2:3]
	v_cndmask_b32_e64 v48, 0, -v48, s[46:47]
	v_add_f32_e32 v76, v48, v77
	v_add_f32_e32 v49, 1.0, v49
	v_log_f32_e32 v49, v49
	s_nop 0
	v_cndmask_b32_e64 v49, 0, -v49, s[48:49]
	v_cvt_pk_bf16_f32 v136, v48, v49
	v_add_f32_e32 v77, v49, v76
	v_lshlrev_b32_e32 v76, 16, v136
	v_sub_f32_e32 v48, v48, v76
	v_and_b32_e32 v76, 0xffff0000, v136
	v_sub_f32_e32 v49, v49, v76
	v_cvt_pk_bf16_f32 v76, v48, v49
	s_nop 0
	v_min_f32_e32 v160, 0x42c80000, v50
	v_add_u32_e32 v48, 0xa2, v143
	s_nop 0
	v_cmp_lt_i32_e64 s[2:3], v48, v176
	v_min_f32_e32 v161, 0x42c80000, v51
	v_add_u32_e32 v50, 0xa3, v143
	s_or_b64 s[50:51], s[44:45], s[2:3]
	v_exp_f32_e32 v48, v160
	v_cmp_lt_i32_e64 s[2:3], v50, v176
	v_exp_f32_e32 v50, v161
	s_or_b64 s[52:53], s[44:45], s[2:3]
	v_add_f32_e32 v48, 1.0, v48
	v_log_f32_e32 v48, v48
	v_add_f32_e32 v50, 1.0, v50
	v_log_f32_e32 v50, v50
	v_cndmask_b32_e64 v48, 0, -v48, s[50:51]
	v_add_f32_e32 v49, v48, v77
	v_cndmask_b32_e64 v50, 0, -v50, s[52:53]
	v_cvt_pk_bf16_f32 v137, v48, v50
	v_lshlrev_b32_e32 v51, 16, v137
	v_sub_f32_e32 v48, v48, v51
	v_and_b32_e32 v51, 0xffff0000, v137
	v_add_f32_e32 v49, v50, v49
	v_sub_f32_e32 v50, v50, v51
	v_cvt_pk_bf16_f32 v77, v48, v50
	s_nop 0
	v_min_f32_e32 v162, 0x42c80000, v52
	v_add_u32_e32 v48, 0xa8, v143
	s_nop 0
	v_cmp_lt_i32_e64 s[2:3], v48, v176
	v_min_f32_e32 v163, 0x42c80000, v53
	v_add_u32_e32 v50, 0xa9, v143
	s_or_b64 s[54:55], s[44:45], s[2:3]
	v_exp_f32_e32 v48, v162
	v_cmp_lt_i32_e64 s[2:3], v50, v176
	v_exp_f32_e32 v50, v163
	s_or_b64 s[56:57], s[44:45], s[2:3]
	v_add_f32_e32 v48, 1.0, v48
	v_log_f32_e32 v48, v48
	v_add_f32_e32 v50, 1.0, v50
	v_log_f32_e32 v50, v50
	v_add_f32_e64 v52, v152, v88
	v_add_f32_e64 v53, v152, v89
	v_cndmask_b32_e64 v48, 0, -v48, s[54:55]
	v_add_f32_e32 v49, v48, v49
	v_cndmask_b32_e64 v50, 0, -v50, s[56:57]
	v_cvt_pk_bf16_f32 v138, v48, v50
	v_lshlrev_b32_e32 v51, 16, v138
	v_sub_f32_e32 v48, v48, v51
	v_and_b32_e32 v51, 0xffff0000, v138
	v_add_f32_e32 v49, v50, v49
	v_sub_f32_e32 v50, v50, v51
	v_cvt_pk_bf16_f32 v78, v48, v50
	s_nop 0
	v_min_f32_e32 v164, 0x42c80000, v54
	v_add_u32_e32 v48, 0xaa, v143
	s_nop 0
	v_cmp_lt_i32_e64 s[2:3], v48, v176
	v_min_f32_e32 v165, 0x42c80000, v55
	v_add_u32_e32 v50, 0xab, v143
	s_or_b64 s[58:59], s[44:45], s[2:3]
	v_exp_f32_e32 v48, v164
	v_cmp_lt_i32_e64 s[2:3], v50, v176
	v_exp_f32_e32 v50, v165
	s_or_b64 s[60:61], s[44:45], s[2:3]
	v_add_f32_e32 v48, 1.0, v48
	v_log_f32_e32 v48, v48
	v_add_f32_e32 v50, 1.0, v50
	v_log_f32_e32 v50, v50
	v_add_f32_e64 v54, v152, v90
	v_add_f32_e64 v55, v152, v91
	v_cndmask_b32_e64 v48, 0, -v48, s[58:59]
	v_add_f32_e32 v49, v48, v49
	v_cndmask_b32_e64 v50, 0, -v50, s[60:61]
	v_cvt_pk_bf16_f32 v139, v48, v50
	v_lshlrev_b32_e32 v51, 16, v139
	v_sub_f32_e32 v48, v48, v51
	v_and_b32_e32 v51, 0xffff0000, v139
	v_add_f32_e32 v49, v50, v49
	v_sub_f32_e32 v50, v50, v51
	v_cvt_pk_bf16_f32 v79, v48, v50
	s_nop 0
	v_min_f32_e32 v166, 0x42c80000, v56
	v_add_u32_e32 v48, 0xb0, v143
	s_nop 0
	v_cmp_lt_i32_e64 s[2:3], v48, v176
	v_min_f32_e32 v167, 0x42c80000, v57
	v_add_u32_e32 v50, 0xb1, v143
	s_or_b64 s[62:63], s[44:45], s[2:3]
	v_exp_f32_e32 v48, v166
	v_cmp_lt_i32_e64 s[2:3], v50, v176
	v_exp_f32_e32 v50, v167
	s_or_b64 s[64:65], s[44:45], s[2:3]
	v_add_f32_e32 v48, 1.0, v48
	v_log_f32_e32 v48, v48
	v_add_f32_e32 v50, 1.0, v50
	v_log_f32_e32 v50, v50
	v_add_f32_e64 v56, v152, v92
	v_add_f32_e64 v57, v152, v93
; template <int DQK, bool SB, bool SMAX>
; DI void attn_item(const Params& p, char* smem, int bh, int qb, float Mb) {
;     ...
; #pragma unroll
;         for (int kb = 0; kb < 2; ++kb)
; #pragma unroll
;           for (int i2 = 0; i2 < 8; ++i2) {
;             float lk[2];
; #pragma unroll
;             for (int e = 0; e < 2; ++e) {
;               const int i = 2 * i2 + e;
;               const float z = fminf(st[kb][i], 100.f);
;               const int key = kb0 + kb * 32 + crow(i, h);
;               const bool valid = !diag || (key < query);
;               float l = -fast_log2(1.f + fast_exp2(z));
;               l = valid ? l : 0.f;
;               lk[e] = l;
;               tsum += l;
;               ca[kb][i] = z + carry;
;             }
;             const unsigned hp = pk_bf16(lk[0], lk[1]);
;             const unsigned lp = pk_bf16(lk[0] - bf_lo(hp), lk[1] - bf_hi(hp));
;             const int kk = kb * 2 + (i2 >> 2), w = i2 & 3;
;             hi[kk][2 * w] = (short)(hp & 0xffffu); hi[kk][2 * w + 1] = (short)(hp >> 16);
;             lo[kk][2 * w] = (short)(lp & 0xffffu); lo[kk][2 * w + 1] = (short)(lp >> 16);
;           }
;         tsum += other_half(tsum);
; #pragma unroll
;         for (int s = 0; s < 2; ++s) {
;           ca[0] = MFMA32(tri[s], hi[s], ca[0]);
;           ca[0] = MFMA32(tri[s], lo[s], ca[0]);
;           ca[0] = MFMA32(ones, hi[2 + s], ca[0]);
;           ca[0] = MFMA32(ones, lo[2 + s], ca[0]);
;           ca[1] = MFMA32(tri[s], hi[2 + s], ca[1]);
;           ca[1] = MFMA32(tri[s], lo[2 + s], ca[1]);
;         }
; #pragma unroll
;         for (int kb = 0; kb < 2; ++kb)
; #pragma unroll
;           for (int i = 0; i < 16; ++i) {
;             const int key = kb0 + kb * 32 + crow(i, h);
;             const bool valid = !diag || (key < query);
;             st[kb][i] = valid ? fast_exp2(ca[kb][i]) : 0.f;
;           }
;         carry += tsum;
;       }
; #pragma unroll
;       for (int kb = 0; kb < 2; ++kb)
; #pragma unroll
;         for (int s = 0; s < 2; ++s) {
;           u32x4 w;
; #pragma unroll
;           for (int e = 0; e < 4; ++e) w[e] = pk_bf16(st[kb][8 * s + 2 * e], st[kb][8 * s + 2 * e + 1]);
;           pk[kb * 2 + s] = __builtin_bit_cast(bf16x8, w);
;         }
; #pragma unroll
;       for (int kk = 0; kk < 4; ++kk)
; #pragma unroll
;         for (int db = 0; db < 2; ++db) {
	v_cndmask_b32_e64 v48, 0, -v48, s[62:63]
	v_add_f32_e32 v49, v48, v49
	v_cndmask_b32_e64 v50, 0, -v50, s[64:65]
	v_cvt_pk_bf16_f32 v140, v48, v50
	v_lshlrev_b32_e32 v51, 16, v140
	v_sub_f32_e32 v48, v48, v51
	v_and_b32_e32 v51, 0xffff0000, v140
	v_add_f32_e32 v49, v50, v49
	v_sub_f32_e32 v50, v50, v51
	v_cvt_pk_bf16_f32 v144, v48, v50
	s_nop 0
	v_min_f32_e32 v168, 0x42c80000, v58
	v_add_u32_e32 v48, 0xb2, v143
	s_nop 0
	v_cmp_lt_i32_e64 s[2:3], v48, v176
	v_min_f32_e32 v169, 0x42c80000, v59
	v_add_u32_e32 v50, 0xb3, v143
	s_or_b64 s[66:67], s[44:45], s[2:3]
	v_exp_f32_e32 v48, v168
	v_cmp_lt_i32_e64 s[2:3], v50, v176
	v_exp_f32_e32 v50, v169
	s_or_b64 s[68:69], s[44:45], s[2:3]
	v_add_f32_e32 v48, 1.0, v48
	v_log_f32_e32 v48, v48
	v_add_f32_e32 v50, 1.0, v50
	v_log_f32_e32 v50, v50
	v_add_f32_e64 v58, v152, v94
	v_add_f32_e64 v59, v152, v95
	v_cndmask_b32_e64 v48, 0, -v48, s[66:67]
	v_add_f32_e32 v49, v48, v49
	v_cndmask_b32_e64 v50, 0, -v50, s[68:69]
	v_cvt_pk_bf16_f32 v141, v48, v50
	v_lshlrev_b32_e32 v51, 16, v141
	v_sub_f32_e32 v48, v48, v51
	v_and_b32_e32 v51, 0xffff0000, v141
	v_add_f32_e32 v49, v50, v49
	v_sub_f32_e32 v50, v50, v51
	v_cvt_pk_bf16_f32 v145, v48, v50
	s_nop 0
	v_min_f32_e32 v170, 0x42c80000, v60
	v_add_u32_e32 v48, 0xb8, v143
	s_nop 0
	v_cmp_lt_i32_e64 s[2:3], v48, v176
	v_min_f32_e32 v171, 0x42c80000, v61
	v_add_u32_e32 v50, 0xb9, v143
	s_or_b64 s[70:71], s[44:45], s[2:3]
	v_exp_f32_e32 v48, v170
	v_cmp_lt_i32_e64 s[2:3], v50, v176
	v_exp_f32_e32 v50, v171
	s_or_b64 s[72:73], s[44:45], s[2:3]
	v_add_f32_e32 v48, 1.0, v48
	v_log_f32_e32 v48, v48
	v_add_f32_e32 v50, 1.0, v50
	v_log_f32_e32 v50, v50
	v_add_f32_e64 v60, v152, v154
	v_add_f32_e64 v61, v152, v155
	v_cndmask_b32_e64 v48, 0, -v48, s[70:71]
	v_add_f32_e32 v49, v48, v49
	v_cndmask_b32_e64 v50, 0, -v50, s[72:73]
	v_cvt_pk_bf16_f32 v142, v48, v50
	v_lshlrev_b32_e32 v51, 16, v142
	v_sub_f32_e32 v48, v48, v51
	v_and_b32_e32 v51, 0xffff0000, v142
	v_add_f32_e32 v49, v50, v49
	v_sub_f32_e32 v50, v50, v51
	v_cvt_pk_bf16_f32 v146, v48, v50
	s_nop 0
	v_min_f32_e32 v182, 0x42c80000, v62
	v_add_u32_e32 v48, 0xba, v143
	s_nop 0
	v_cmp_lt_i32_e64 s[2:3], v48, v176
	v_min_f32_e32 v183, 0x42c80000, v63
	v_add_u32_e32 v50, 0xbb, v143
	s_or_b64 s[74:75], s[44:45], s[2:3]
	v_exp_f32_e32 v48, v182
	v_cmp_lt_i32_e64 s[2:3], v50, v176
	v_exp_f32_e32 v50, v183
	s_or_b64 s[44:45], s[44:45], s[2:3]
	v_add_f32_e32 v48, 1.0, v48
	v_log_f32_e32 v48, v48
	v_add_f32_e32 v50, 1.0, v50
	v_log_f32_e32 v50, v50
	v_add_f32_e64 v62, v152, v158
	v_add_f32_e64 v63, v152, v159
	v_cndmask_b32_e64 v48, 0, -v48, s[74:75]
	v_add_f32_e32 v49, v48, v49
	v_cndmask_b32_e64 v50, 0, -v50, s[44:45]
	v_cvt_pk_bf16_f32 v143, v48, v50
	v_add_f32_e32 v184, v50, v49
	v_lshlrev_b32_e32 v49, 16, v143
	v_sub_f32_e32 v48, v48, v49
	v_and_b32_e32 v49, 0xffff0000, v143
	v_sub_f32_e32 v49, v50, v49
	v_cvt_pk_bf16_f32 v147, v48, v49
	v_mov_b32_e32 v48, v184
	v_mov_b32_e32 v49, v184
	s_nop 1
	v_permlane32_swap_b32_e32 v48, v49
	v_cndmask_b32_e64 v185, v48, v49, s[8:9]
	v_add_f32_e64 v50, v152, v86
	v_add_f32_e64 v51, v152, v87
	v_add_f32_e64 v48, v152, v84
	v_add_f32_e64 v49, v152, v85
	v_add_f32_e64 v94, v152, v182
	v_add_f32_e64 v95, v152, v183
	v_add_f32_e64 v92, v152, v170
	v_add_f32_e64 v93, v152, v171
	v_mfma_f32_32x32x16_bf16 v[48:63], v[96:99], v[80:83], v[48:63]
	v_add_f32_e64 v90, v152, v168
	v_add_f32_e64 v91, v152, v169
	v_add_f32_e64 v88, v152, v166
	v_add_f32_e64 v89, v152, v167
	v_add_f32_e64 v86, v152, v164
	v_add_f32_e64 v87, v152, v165
	v_add_f32_e64 v84, v152, v162
	v_add_f32_e64 v85, v152, v163
	v_add_f32_e64 v82, v152, v160
	v_add_f32_e64 v83, v152, v161
	v_add_f32_e64 v80, v152, v156
	v_add_f32_e64 v81, v152, v157
	v_mfma_f32_32x32x16_bf16 v[48:63], v[96:99], v[64:67], v[48:63]
	v_mov_b64_e32 v[64:65], s[96:97]
	v_mov_b64_e32 v[66:67], s[98:99]
	s_nop 1
	v_mfma_f32_32x32x16_bf16 v[48:63], v[64:67], v[136:139], v[48:63]
	v_mfma_f32_32x32x16_bf16 v[48:63], v[64:67], v[76:79], v[48:63]
	v_mfma_f32_32x32x16_bf16 v[48:63], v[100:103], v[72:75], v[48:63]
	v_mfma_f32_32x32x16_bf16 v[48:63], v[100:103], v[68:71], v[48:63]
	v_mfma_f32_32x32x16_bf16 v[48:63], v[64:67], v[140:143], v[48:63]
	v_mfma_f32_32x32x16_bf16 v[48:63], v[64:67], v[144:147], v[48:63]
	v_mfma_f32_32x32x16_bf16 v[80:95], v[96:99], v[136:139], v[80:95]
	s_nop 10
	v_exp_f32_e32 v48, v48
	s_nop 0
	v_cndmask_b32_e32 v64, 0, v48, vcc
	v_exp_f32_e32 v48, v49
	v_mfma_f32_32x32x16_bf16 v[80:95], v[96:99], v[76:79], v[80:95]
	v_cndmask_b32_e64 v65, 0, v48, s[12:13]
	v_exp_f32_e32 v48, v50
	s_nop 0
	v_cndmask_b32_e64 v66, 0, v48, s[14:15]
	v_exp_f32_e32 v48, v51
	v_mfma_f32_32x32x16_bf16 v[80:95], v[100:103], v[140:143], v[80:95]
	v_add_u32_e32 v141, v198, v200
	ds_read_b64_tr_b16 v[136:137], v141 offset:18432
	ds_read_b64_tr_b16 v[138:139], v141 offset:19584
	v_cndmask_b32_e64 v67, 0, v48, s[16:17]
	v_exp_f32_e32 v48, v52
	v_add_f32_e32 v140, v184, v185
	v_add_f32_e32 v152, v152, v140
	v_cndmask_b32_e64 v68, 0, v48, s[18:19]
	v_exp_f32_e32 v48, v53
	v_mfma_f32_32x32x16_bf16 v[80:95], v[100:103], v[144:147], v[80:95]
	v_cndmask_b32_e64 v69, 0, v48, s[20:21]
	v_exp_f32_e32 v48, v54
	s_nop 0
	v_cndmask_b32_e64 v70, 0, v48, s[22:23]
	v_exp_f32_e32 v48, v55
	s_nop 6
	v_exp_f32_e32 v49, v81
	v_exp_f32_e32 v50, v82
	v_exp_f32_e32 v51, v83
	v_cndmask_b32_e64 v71, 0, v48, s[24:25]
	v_exp_f32_e32 v48, v56
	v_exp_f32_e32 v56, v88
	v_exp_f32_e32 v52, v84
	v_exp_f32_e32 v53, v85
	v_cndmask_b32_e64 v72, 0, v48, s[26:27]
	v_exp_f32_e32 v48, v57
	v_exp_f32_e32 v57, v89
	v_exp_f32_e32 v54, v86
	v_exp_f32_e32 v55, v87
	v_cndmask_b32_e64 v73, 0, v48, s[28:29]
	v_exp_f32_e32 v48, v58
	v_exp_f32_e32 v58, v90
	v_cvt_pk_bf16_f32 v88, v72, v73
	v_cndmask_b32_e64 v49, 0, v49, s[48:49]
	v_cndmask_b32_e64 v74, 0, v48, s[30:31]
	v_exp_f32_e32 v48, v59
	v_exp_f32_e32 v59, v91
	v_cndmask_b32_e64 v50, 0, v50, s[50:51]
	v_cndmask_b32_e64 v51, 0, v51, s[52:53]
	v_cndmask_b32_e64 v75, 0, v48, s[34:35]
	v_exp_f32_e32 v48, v60
	v_exp_f32_e32 v60, v92
	v_cvt_pk_bf16_f32 v92, v64, v65
	v_cvt_pk_bf16_f32 v89, v74, v75
	v_cndmask_b32_e64 v76, 0, v48, s[36:37]
	v_exp_f32_e32 v48, v61
	v_exp_f32_e32 v61, v93
	v_cvt_pk_bf16_f32 v93, v66, v67
	v_cndmask_b32_e64 v52, 0, v52, s[54:55]
	v_cndmask_b32_e64 v77, 0, v48, s[38:39]
	v_exp_f32_e32 v48, v62
	v_exp_f32_e32 v62, v94
	v_cvt_pk_bf16_f32 v94, v68, v69
	v_cvt_pk_bf16_f32 v90, v76, v77
	v_cndmask_b32_e64 v78, 0, v48, s[40:41]
	v_exp_f32_e32 v48, v63
	v_exp_f32_e32 v63, v95
	v_cvt_pk_bf16_f32 v95, v70, v71
	v_cndmask_b32_e64 v53, 0, v53, s[56:57]
	v_cndmask_b32_e64 v79, 0, v48, s[42:43]
	s_waitcnt lgkmcnt(0)
; #define MFMA32(a, b, c) __builtin_amdgcn_mfma_f32_32x32x16_bf16((a), (b), (c), 0, 0, 0)
; DI unsigned pk_bf16(float lo, float hi) { f32x2 v = {lo, hi}; bf2_t b = __builtin_convertvector(v, bf2_t); return __builtin_bit_cast(unsigned, b); }
; DI float bf_lo(unsigned u) { return __uint_as_float(u << 16); }
; DI float bf_hi(unsigned u) { return __uint_as_float(u & 0xffff0000u); }
; DI int crow(int i, int h) { return (i & 3) + 8 * (i >> 2) + 4 * h; }
; DI float fast_exp2(float x) { return __builtin_amdgcn_exp2f(x); }
; DI float fast_log2(float x) { return __builtin_amdgcn_logf(x); }
; template <int DQK, bool SB, bool SMAX>
; DI void attn_item(const Params& p, char* smem, int bh, int qb, float Mb) {
;     ...
; #pragma unroll
;         for (int kb = 0; kb < 2; ++kb)
; #pragma unroll
;           for (int i2 = 0; i2 < 8; ++i2) {
;             float lk[2];
; #pragma unroll
;             for (int e = 0; e < 2; ++e) {
;               const int i = 2 * i2 + e;
;               const float z = fminf(st[kb][i], 100.f);
;               const int key = kb0 + kb * 32 + crow(i, h);
;               const bool valid = !diag || (key < query);
;               float l = -fast_log2(1.f + fast_exp2(z));
;               l = valid ? l : 0.f;
;               lk[e] = l;
;               tsum += l;
;               ca[kb][i] = z + carry;
;             }
;             const unsigned hp = pk_bf16(lk[0], lk[1]);
;             const unsigned lp = pk_bf16(lk[0] - bf_lo(hp), lk[1] - bf_hi(hp));
;             const int kk = kb * 2 + (i2 >> 2), w = i2 & 3;
;             hi[kk][2 * w] = (short)(hp & 0xffffu); hi[kk][2 * w + 1] = (short)(hp >> 16);
;             lo[kk][2 * w] = (short)(lp & 0xffffu); lo[kk][2 * w + 1] = (short)(lp >> 16);
;           }
;     ...
; #pragma unroll
;       for (int kk = 0; kk < 4; ++kk)
; #pragma unroll
;         for (int db = 0; db < 2; ++db) {
;           const s16x4 v0 = __builtin_amdgcn_ds_read_tr16_b64_v4i16((lds_s16x4*)(vc + voff + (16 * kk) * VSTR + 32 * db));
;           const s16x4 v1 = __builtin_amdgcn_ds_read_tr16_b64_v4i16((lds_s16x4*)(vc + voff + (16 * kk + 8) * VSTR + 32 * db));
;           const bf16x8 vf = __builtin_shufflevector(v0, v1, 0, 1, 2, 3, 4, 5, 6, 7);
;           O[db] = MFMA32(vf, pk[kk], O[db]);
;         }
	v_mfma_f32_32x32x16_bf16 v[32:47], v[136:139], v[92:95], v[32:47]
	ds_read_b64_tr_b16 v[136:137], v141 offset:18496
	ds_read_b64_tr_b16 v[138:139], v141 offset:19648
	v_cvt_pk_bf16_f32 v91, v78, v79
	v_exp_f32_e32 v48, v80
	v_cndmask_b32_e64 v54, 0, v54, s[58:59]
	v_cndmask_b32_e64 v55, 0, v55, s[60:61]
	v_cvt_pk_bf16_f32 v85, v50, v51
	v_cndmask_b32_e64 v48, 0, v48, s[46:47]
	s_waitcnt lgkmcnt(0)
	v_mfma_f32_32x32x16_bf16 v[16:31], v[136:139], v[92:95], v[16:31]
	ds_read_b64_tr_b16 v[92:93], v141 offset:20736
	ds_read_b64_tr_b16 v[94:95], v141 offset:21888
	v_cvt_pk_bf16_f32 v84, v48, v49
	v_cvt_pk_bf16_f32 v86, v52, v53
	v_cvt_pk_bf16_f32 v87, v54, v55
	v_cndmask_b32_e64 v56, 0, v56, s[62:63]
	v_cndmask_b32_e64 v57, 0, v57, s[64:65]
	v_cndmask_b32_e64 v58, 0, v58, s[66:67]
	s_waitcnt lgkmcnt(0)
	v_mfma_f32_32x32x16_bf16 v[32:47], v[92:95], v[88:91], v[32:47]
	ds_read_b64_tr_b16 v[92:93], v141 offset:20800
	ds_read_b64_tr_b16 v[94:95], v141 offset:21952
	v_cndmask_b32_e64 v59, 0, v59, s[68:69]
	v_cndmask_b32_e64 v60, 0, v60, s[70:71]
	v_cndmask_b32_e64 v61, 0, v61, s[72:73]
	v_cndmask_b32_e64 v62, 0, v62, s[74:75]
	v_cndmask_b32_e64 v63, 0, v63, s[44:45]
	v_cvt_pk_bf16_f32 v80, v56, v57
	s_waitcnt lgkmcnt(0)
	v_mfma_f32_32x32x16_bf16 v[16:31], v[92:95], v[88:91], v[16:31]
	ds_read_b64_tr_b16 v[88:89], v141 offset:23040
	ds_read_b64_tr_b16 v[90:91], v141 offset:24192
	v_cvt_pk_bf16_f32 v81, v58, v59
	v_cvt_pk_bf16_f32 v82, v60, v61
	v_cvt_pk_bf16_f32 v83, v62, v63
	s_waitcnt lgkmcnt(0)
	v_mfma_f32_32x32x16_bf16 v[32:47], v[88:91], v[84:87], v[32:47]
	ds_read_b64_tr_b16 v[88:89], v141 offset:23104
	ds_read_b64_tr_b16 v[90:91], v141 offset:24256
	s_waitcnt lgkmcnt(0)
	v_mfma_f32_32x32x16_bf16 v[16:31], v[88:91], v[84:87], v[16:31]
	ds_read_b64_tr_b16 v[84:85], v141 offset:25344
	ds_read_b64_tr_b16 v[86:87], v141 offset:26496
	s_waitcnt lgkmcnt(0)
	v_mfma_f32_32x32x16_bf16 v[32:47], v[84:87], v[80:83], v[32:47]
	ds_read_b64_tr_b16 v[84:85], v141 offset:25408
	ds_read_b64_tr_b16 v[86:87], v141 offset:26560
	s_waitcnt lgkmcnt(0)
	v_mfma_f32_32x32x16_bf16 v[16:31], v[84:87], v[80:83], v[16:31]
	s_branch .LBB0_437
.Lsbf_1:
	s_nop 0
	v_add_u32_e32 v143, s78, v197
	v_min_f32_e32 v84, 0x42c80000, v64
	s_nop 0
	v_exp_f32_e32 v64, v84
	v_min_f32_e32 v85, 0x42c80000, v65
	s_nop 0
	s_nop 0
	v_exp_f32_e32 v65, v85
	v_add_f32_e32 v64, 1.0, v64
	v_log_f32_e32 v64, v64
	s_nop 0
	v_add_f32_e32 v65, 1.0, v65
	v_log_f32_e32 v65, v65
	s_nop 0
	s_nop 0
	s_nop 0
	s_nop 0
	v_xor_b32_e32 v64, 0x80000000, v64
	v_add_f32_e32 v80, 0, v64
	v_xor_b32_e32 v65, 0x80000000, v65
	v_add_f32_e32 v81, v65, v80
	v_cvt_pk_bf16_f32 v80, v64, v65
	v_lshlrev_b32_e32 v82, 16, v80
	v_sub_f32_e32 v64, v64, v82
	v_and_b32_e32 v82, 0xffff0000, v80
	v_sub_f32_e32 v65, v65, v82
	v_cvt_pk_bf16_f32 v64, v64, v65
	s_nop 0
	v_min_f32_e32 v86, 0x42c80000, v66
	s_nop 0
	s_nop 0
	s_nop 0
	v_min_f32_e32 v87, 0x42c80000, v67
	s_nop 0
	s_nop 0
	v_exp_f32_e32 v65, v86
	s_nop 0
	v_exp_f32_e32 v67, v87
	s_nop 0
	v_add_f32_e32 v65, 1.0, v65
	v_log_f32_e32 v65, v65
	v_add_f32_e32 v67, 1.0, v67
	v_log_f32_e32 v67, v67
	s_nop 0
	v_xor_b32_e32 v65, 0x80000000, v65
	v_add_f32_e32 v66, v65, v81
	v_xor_b32_e32 v67, 0x80000000, v67
	v_cvt_pk_bf16_f32 v81, v65, v67
	v_lshlrev_b32_e32 v82, 16, v81
	v_sub_f32_e32 v65, v65, v82
	v_and_b32_e32 v82, 0xffff0000, v81
	v_add_f32_e32 v66, v67, v66
	v_sub_f32_e32 v67, v67, v82
	v_cvt_pk_bf16_f32 v65, v65, v67
	s_nop 0
	v_min_f32_e32 v88, 0x42c80000, v68
	s_nop 0
	s_nop 0
	s_nop 0
	v_min_f32_e32 v89, 0x42c80000, v69
	s_nop 0
	s_nop 0
	v_exp_f32_e32 v67, v88
	s_nop 0
	v_exp_f32_e32 v68, v89
	s_nop 0
	v_add_f32_e32 v67, 1.0, v67
	v_log_f32_e32 v67, v67
	v_add_f32_e32 v68, 1.0, v68
	v_log_f32_e32 v68, v68
	s_nop 0
	v_xor_b32_e32 v67, 0x80000000, v67
	v_add_f32_e32 v66, v67, v66
	v_xor_b32_e32 v68, 0x80000000, v68
	v_cvt_pk_bf16_f32 v82, v67, v68
	v_add_f32_e32 v69, v68, v66
	v_lshlrev_b32_e32 v66, 16, v82
	v_sub_f32_e32 v66, v67, v66
	v_and_b32_e32 v67, 0xffff0000, v82
	v_sub_f32_e32 v67, v68, v67
	v_cvt_pk_bf16_f32 v66, v66, v67
	s_nop 0
	v_min_f32_e32 v90, 0x42c80000, v70
	s_nop 0
	s_nop 0
	v_exp_f32_e32 v67, v90
	s_nop 0
	v_min_f32_e32 v156, 0x42c80000, v48
	v_min_f32_e32 v157, 0x42c80000, v49
	v_add_f32_e32 v67, 1.0, v67
	v_log_f32_e32 v67, v67
	s_nop 0
	v_exp_f32_e32 v48, v156
	s_mov_b32 s97, s96
	v_xor_b32_e32 v67, 0x80000000, v67
	v_add_f32_e32 v68, v67, v69
	s_nop 0
	v_min_f32_e32 v91, 0x42c80000, v71
	s_nop 0
	s_nop 0
	v_exp_f32_e32 v69, v91
	s_nop 0
	v_add_f32_e32 v48, 1.0, v48
	v_log_f32_e32 v48, v48
	v_add_f32_e32 v69, 1.0, v69
	v_log_f32_e32 v69, v69
	s_mov_b32 s98, s96
	s_mov_b32 s99, s96
	v_xor_b32_e32 v69, 0x80000000, v69
	v_cvt_pk_bf16_f32 v83, v67, v69
	v_lshlrev_b32_e32 v70, 16, v83
	v_sub_f32_e32 v67, v67, v70
	v_and_b32_e32 v70, 0xffff0000, v83
	v_add_f32_e32 v68, v69, v68
	v_sub_f32_e32 v69, v69, v70
	v_cvt_pk_bf16_f32 v67, v67, v69
	s_nop 0
	v_min_f32_e32 v92, 0x42c80000, v72
	s_nop 0
	s_nop 0
	s_nop 0
	v_min_f32_e32 v93, 0x42c80000, v73
	s_nop 0
	s_nop 0
	v_exp_f32_e32 v69, v92
	s_nop 0
	v_exp_f32_e32 v70, v93
	s_nop 0
	v_add_f32_e32 v69, 1.0, v69
	v_log_f32_e32 v69, v69
	v_add_f32_e32 v70, 1.0, v70
	v_log_f32_e32 v70, v70
	v_xor_b32_e32 v69, 0x80000000, v69
	v_add_f32_e32 v68, v69, v68
	v_xor_b32_e32 v70, 0x80000000, v70
	v_cvt_pk_bf16_f32 v72, v69, v70
	v_add_f32_e32 v71, v70, v68
	v_lshlrev_b32_e32 v68, 16, v72
	v_sub_f32_e32 v68, v69, v68
	v_and_b32_e32 v69, 0xffff0000, v72
	v_sub_f32_e32 v69, v70, v69
	v_cvt_pk_bf16_f32 v68, v68, v69
	s_nop 0
	v_min_f32_e32 v94, 0x42c80000, v74
	s_nop 0
	s_nop 0
	v_exp_f32_e32 v69, v94
	s_nop 0
; DI unsigned pk_bf16(float lo, float hi) { f32x2 v = {lo, hi}; bf2_t b = __builtin_convertvector(v, bf2_t); return __builtin_bit_cast(unsigned, b); }
; DI float bf_lo(unsigned u) { return __uint_as_float(u << 16); }
; DI float bf_hi(unsigned u) { return __uint_as_float(u & 0xffff0000u); }
; DI int crow(int i, int h) { return (i & 3) + 8 * (i >> 2) + 4 * h; }
; DI float fast_exp2(float x) { return __builtin_amdgcn_exp2f(x); }
; DI float fast_log2(float x) { return __builtin_amdgcn_logf(x); }
; template <int DQK, bool SB, bool SMAX>
; DI void attn_item(const Params& p, char* smem, int bh, int qb, float Mb) {
;     ...
; #pragma unroll
;         for (int kb = 0; kb < 2; ++kb)
; #pragma unroll
;           for (int i2 = 0; i2 < 8; ++i2) {
;             float lk[2];
; #pragma unroll
;             for (int e = 0; e < 2; ++e) {
;               const int i = 2 * i2 + e;
;               const float z = fminf(st[kb][i], 100.f);
;               const int key = kb0 + kb * 32 + crow(i, h);
;               const bool valid = !diag || (key < query);
;               float l = -fast_log2(1.f + fast_exp2(z));
;               l = valid ? l : 0.f;
;               lk[e] = l;
;               tsum += l;
;               ca[kb][i] = z + carry;
;             }
;             const unsigned hp = pk_bf16(lk[0], lk[1]);
;             const unsigned lp = pk_bf16(lk[0] - bf_lo(hp), lk[1] - bf_hi(hp));
;             const int kk = kb * 2 + (i2 >> 2), w = i2 & 3;
;             hi[kk][2 * w] = (short)(hp & 0xffffu); hi[kk][2 * w + 1] = (short)(hp >> 16);
;             lo[kk][2 * w] = (short)(lp & 0xffffu); lo[kk][2 * w + 1] = (short)(lp >> 16);
;           }
	v_add_f32_e32 v69, 1.0, v69
	v_log_f32_e32 v69, v69
	s_nop 0
	v_xor_b32_e32 v69, 0x80000000, v69
	v_add_f32_e32 v70, v69, v71
	s_nop 0
	v_min_f32_e32 v95, 0x42c80000, v75
	s_nop 0
	s_nop 0
	v_exp_f32_e32 v71, v95
	s_nop 0
	v_add_f32_e32 v71, 1.0, v71
	v_log_f32_e32 v71, v71
	s_nop 0
	v_xor_b32_e32 v71, 0x80000000, v71
	v_cvt_pk_bf16_f32 v73, v69, v71
	v_lshlrev_b32_e32 v74, 16, v73
	v_sub_f32_e32 v69, v69, v74
	v_and_b32_e32 v74, 0xffff0000, v73
	v_add_f32_e32 v70, v71, v70
	v_sub_f32_e32 v71, v71, v74
	v_cvt_pk_bf16_f32 v69, v69, v71
	s_nop 0
	v_min_f32_e32 v154, 0x42c80000, v76
	s_nop 0
	s_nop 0
	s_nop 0
	v_min_f32_e32 v155, 0x42c80000, v77
	s_nop 0
	s_nop 0
	v_exp_f32_e32 v71, v154
	s_nop 0
	v_exp_f32_e32 v74, v155
	s_nop 0
	v_add_f32_e32 v71, 1.0, v71
	v_log_f32_e32 v71, v71
	v_add_f32_e32 v74, 1.0, v74
	v_log_f32_e32 v74, v74
	v_xor_b32_e32 v71, 0x80000000, v71
	v_add_f32_e32 v70, v71, v70
	v_xor_b32_e32 v75, 0x80000000, v74
	v_cvt_pk_bf16_f32 v74, v71, v75
	v_add_f32_e32 v76, v75, v70
	v_lshlrev_b32_e32 v70, 16, v74
	v_sub_f32_e32 v70, v71, v70
	v_and_b32_e32 v71, 0xffff0000, v74
	v_sub_f32_e32 v71, v75, v71
	v_cvt_pk_bf16_f32 v70, v70, v71
	s_nop 0
	v_min_f32_e32 v158, 0x42c80000, v78
	s_nop 0
	s_nop 0
	v_exp_f32_e32 v71, v158
	s_nop 0
	v_add_f32_e32 v71, 1.0, v71
	v_log_f32_e32 v71, v71
	s_nop 0
	v_xor_b32_e32 v71, 0x80000000, v71
	v_add_f32_e32 v75, v71, v76
	s_nop 0
	v_min_f32_e32 v159, 0x42c80000, v79
	s_nop 0
	s_nop 0
	v_exp_f32_e32 v76, v159
	s_nop 0
	v_add_f32_e32 v76, 1.0, v76
	v_log_f32_e32 v76, v76
	s_nop 0
	v_xor_b32_e32 v76, 0x80000000, v76
	v_add_f32_e32 v77, v76, v75
	v_cvt_pk_bf16_f32 v75, v71, v76
	v_lshlrev_b32_e32 v78, 16, v75
	v_sub_f32_e32 v71, v71, v78
	v_and_b32_e32 v78, 0xffff0000, v75
	v_sub_f32_e32 v76, v76, v78
	v_cvt_pk_bf16_f32 v71, v71, v76
	s_nop 0
	s_nop 0
	s_nop 0
	s_nop 0
	v_exp_f32_e32 v49, v157
	s_nop 0
	v_xor_b32_e32 v48, 0x80000000, v48
	v_add_f32_e32 v76, v48, v77
	v_add_f32_e32 v49, 1.0, v49
	v_log_f32_e32 v49, v49
	s_nop 0
	v_xor_b32_e32 v49, 0x80000000, v49
	v_cvt_pk_bf16_f32 v136, v48, v49
	v_add_f32_e32 v77, v49, v76
	v_lshlrev_b32_e32 v76, 16, v136
	v_sub_f32_e32 v48, v48, v76
	v_and_b32_e32 v76, 0xffff0000, v136
	v_sub_f32_e32 v49, v49, v76
	v_cvt_pk_bf16_f32 v76, v48, v49
	s_nop 0
	v_min_f32_e32 v160, 0x42c80000, v50
	s_nop 0
	s_nop 0
	s_nop 0
	v_min_f32_e32 v161, 0x42c80000, v51
	s_nop 0
	s_nop 0
	v_exp_f32_e32 v48, v160
	s_nop 0
	v_exp_f32_e32 v50, v161
	s_nop 0
	v_add_f32_e32 v48, 1.0, v48
	v_log_f32_e32 v48, v48
	v_add_f32_e32 v50, 1.0, v50
	v_log_f32_e32 v50, v50
	v_xor_b32_e32 v48, 0x80000000, v48
	v_add_f32_e32 v49, v48, v77
	v_xor_b32_e32 v50, 0x80000000, v50
	v_cvt_pk_bf16_f32 v137, v48, v50
	v_lshlrev_b32_e32 v51, 16, v137
	v_sub_f32_e32 v48, v48, v51
	v_and_b32_e32 v51, 0xffff0000, v137
	v_add_f32_e32 v49, v50, v49
	v_sub_f32_e32 v50, v50, v51
	v_cvt_pk_bf16_f32 v77, v48, v50
	s_nop 0
	v_min_f32_e32 v162, 0x42c80000, v52
	s_nop 0
	s_nop 0
	s_nop 0
	v_min_f32_e32 v163, 0x42c80000, v53
	s_nop 0
	s_nop 0
	v_exp_f32_e32 v48, v162
	s_nop 0
	v_exp_f32_e32 v50, v163
	s_nop 0
	v_add_f32_e32 v48, 1.0, v48
	v_log_f32_e32 v48, v48
	v_add_f32_e32 v50, 1.0, v50
	v_log_f32_e32 v50, v50
	v_add_f32_e64 v52, v152, v88
	v_add_f32_e64 v53, v152, v89
	v_xor_b32_e32 v48, 0x80000000, v48
	v_add_f32_e32 v49, v48, v49
	v_xor_b32_e32 v50, 0x80000000, v50
	v_cvt_pk_bf16_f32 v138, v48, v50
	v_lshlrev_b32_e32 v51, 16, v138
	v_sub_f32_e32 v48, v48, v51
	v_and_b32_e32 v51, 0xffff0000, v138
	v_add_f32_e32 v49, v50, v49
	v_sub_f32_e32 v50, v50, v51
	v_cvt_pk_bf16_f32 v78, v48, v50
	s_nop 0
	v_min_f32_e32 v164, 0x42c80000, v54
	s_nop 0
	s_nop 0
	s_nop 0
	v_min_f32_e32 v165, 0x42c80000, v55
	s_nop 0
	s_nop 0
	v_exp_f32_e32 v48, v164
	s_nop 0
	v_exp_f32_e32 v50, v165
	s_nop 0
	v_add_f32_e32 v48, 1.0, v48
	v_log_f32_e32 v48, v48
	v_add_f32_e32 v50, 1.0, v50
	v_log_f32_e32 v50, v50
	v_add_f32_e64 v54, v152, v90
	v_add_f32_e64 v55, v152, v91
	v_xor_b32_e32 v48, 0x80000000, v48
	v_add_f32_e32 v49, v48, v49
	v_xor_b32_e32 v50, 0x80000000, v50
	v_cvt_pk_bf16_f32 v139, v48, v50
	v_lshlrev_b32_e32 v51, 16, v139
	v_sub_f32_e32 v48, v48, v51
	v_and_b32_e32 v51, 0xffff0000, v139
	v_add_f32_e32 v49, v50, v49
	v_sub_f32_e32 v50, v50, v51
	v_cvt_pk_bf16_f32 v79, v48, v50
	s_nop 0
	v_min_f32_e32 v166, 0x42c80000, v56
	s_nop 0
	s_nop 0
	s_nop 0
	v_min_f32_e32 v167, 0x42c80000, v57
	s_nop 0
	s_nop 0
	v_exp_f32_e32 v48, v166
	s_nop 0
	v_exp_f32_e32 v50, v167
	s_nop 0
	v_add_f32_e32 v48, 1.0, v48
	v_log_f32_e32 v48, v48
	v_add_f32_e32 v50, 1.0, v50
	v_log_f32_e32 v50, v50
	v_add_f32_e64 v56, v152, v92
	v_add_f32_e64 v57, v152, v93
	v_xor_b32_e32 v48, 0x80000000, v48
	v_add_f32_e32 v49, v48, v49
	v_xor_b32_e32 v50, 0x80000000, v50
	v_cvt_pk_bf16_f32 v140, v48, v50
	v_lshlrev_b32_e32 v51, 16, v140
	v_sub_f32_e32 v48, v48, v51
	v_and_b32_e32 v51, 0xffff0000, v140
	v_add_f32_e32 v49, v50, v49
	v_sub_f32_e32 v50, v50, v51
	v_cvt_pk_bf16_f32 v144, v48, v50
	s_nop 0
	v_min_f32_e32 v168, 0x42c80000, v58
	s_nop 0
	s_nop 0
	s_nop 0
	v_min_f32_e32 v169, 0x42c80000, v59
	s_nop 0
	s_nop 0
	v_exp_f32_e32 v48, v168
	s_nop 0
	v_exp_f32_e32 v50, v169
	s_nop 0
	v_add_f32_e32 v48, 1.0, v48
	v_log_f32_e32 v48, v48
	v_add_f32_e32 v50, 1.0, v50
	v_log_f32_e32 v50, v50
	v_add_f32_e64 v58, v152, v94
	v_add_f32_e64 v59, v152, v95
	v_xor_b32_e32 v48, 0x80000000, v48
	v_add_f32_e32 v49, v48, v49
	v_xor_b32_e32 v50, 0x80000000, v50
	v_cvt_pk_bf16_f32 v141, v48, v50
	v_lshlrev_b32_e32 v51, 16, v141
	v_sub_f32_e32 v48, v48, v51
	v_and_b32_e32 v51, 0xffff0000, v141
	v_add_f32_e32 v49, v50, v49
	v_sub_f32_e32 v50, v50, v51
	v_cvt_pk_bf16_f32 v145, v48, v50
; template <int DQK, bool SB, bool SMAX>
; DI void attn_item(const Params& p, char* smem, int bh, int qb, float Mb) {
;     ...
;           for (int i2 = 0; i2 < 8; ++i2) {
;             float lk[2];
; #pragma unroll
;             for (int e = 0; e < 2; ++e) {
;               const int i = 2 * i2 + e;
;               const float z = fminf(st[kb][i], 100.f);
;               const int key = kb0 + kb * 32 + crow(i, h);
;               const bool valid = !diag || (key < query);
;               float l = -fast_log2(1.f + fast_exp2(z));
;               l = valid ? l : 0.f;
;               lk[e] = l;
;               tsum += l;
;               ca[kb][i] = z + carry;
;             }
;             const unsigned hp = pk_bf16(lk[0], lk[1]);
;             const unsigned lp = pk_bf16(lk[0] - bf_lo(hp), lk[1] - bf_hi(hp));
;             const int kk = kb * 2 + (i2 >> 2), w = i2 & 3;
;             hi[kk][2 * w] = (short)(hp & 0xffffu); hi[kk][2 * w + 1] = (short)(hp >> 16);
;             lo[kk][2 * w] = (short)(lp & 0xffffu); lo[kk][2 * w + 1] = (short)(lp >> 16);
;           }
;         tsum += other_half(tsum);
; #pragma unroll
;         for (int s = 0; s < 2; ++s) {
;           ca[0] = MFMA32(tri[s], hi[s], ca[0]);
;           ca[0] = MFMA32(tri[s], lo[s], ca[0]);
;           ca[0] = MFMA32(ones, hi[2 + s], ca[0]);
;           ca[0] = MFMA32(ones, lo[2 + s], ca[0]);
;           ca[1] = MFMA32(tri[s], hi[2 + s], ca[1]);
;           ca[1] = MFMA32(tri[s], lo[2 + s], ca[1]);
;         }
; #pragma unroll
;         for (int kb = 0; kb < 2; ++kb)
; #pragma unroll
;           for (int i = 0; i < 16; ++i) {
;             const int key = kb0 + kb * 32 + crow(i, h);
;             const bool valid = !diag || (key < query);
;             st[kb][i] = valid ? fast_exp2(ca[kb][i]) : 0.f;
;           }
;         carry += tsum;
;       }
; #pragma unroll
;       for (int kb = 0; kb < 2; ++kb)
; #pragma unroll
;         for (int s = 0; s < 2; ++s) {
;           u32x4 w;
; #pragma unroll
;           for (int e = 0; e < 4; ++e) w[e] = pk_bf16(st[kb][8 * s + 2 * e], st[kb][8 * s + 2 * e + 1]);
;           pk[kb * 2 + s] = __builtin_bit_cast(bf16x8, w);
;         }
; #pragma unroll
;       for (int kk = 0; kk < 4; ++kk)
; #pragma unroll
;         for (int db = 0; db < 2; ++db) {
;           const s16x4 v0 = __builtin_amdgcn_ds_read_tr16_b64_v4i16((lds_s16x4*)(vc + voff + (16 * kk) * VSTR + 32 * db));
	s_nop 0
	v_min_f32_e32 v170, 0x42c80000, v60
	s_nop 0
	s_nop 0
	s_nop 0
	v_min_f32_e32 v171, 0x42c80000, v61
	s_nop 0
	s_nop 0
	v_exp_f32_e32 v48, v170
	s_nop 0
	v_exp_f32_e32 v50, v171
	s_nop 0
	v_add_f32_e32 v48, 1.0, v48
	v_log_f32_e32 v48, v48
	v_add_f32_e32 v50, 1.0, v50
	v_log_f32_e32 v50, v50
	v_add_f32_e64 v60, v152, v154
	v_add_f32_e64 v61, v152, v155
	v_xor_b32_e32 v48, 0x80000000, v48
	v_add_f32_e32 v49, v48, v49
	v_xor_b32_e32 v50, 0x80000000, v50
	v_cvt_pk_bf16_f32 v142, v48, v50
	v_lshlrev_b32_e32 v51, 16, v142
	v_sub_f32_e32 v48, v48, v51
	v_and_b32_e32 v51, 0xffff0000, v142
	v_add_f32_e32 v49, v50, v49
	v_sub_f32_e32 v50, v50, v51
	v_cvt_pk_bf16_f32 v146, v48, v50
	s_nop 0
	v_min_f32_e32 v182, 0x42c80000, v62
	s_nop 0
	s_nop 0
	s_nop 0
	v_min_f32_e32 v183, 0x42c80000, v63
	s_nop 0
	s_nop 0
	v_exp_f32_e32 v48, v182
	s_nop 0
	v_exp_f32_e32 v50, v183
	s_nop 0
	v_add_f32_e32 v48, 1.0, v48
	v_log_f32_e32 v48, v48
	v_add_f32_e32 v50, 1.0, v50
	v_log_f32_e32 v50, v50
	v_add_f32_e64 v62, v152, v158
	v_add_f32_e64 v63, v152, v159
	v_xor_b32_e32 v48, 0x80000000, v48
	v_add_f32_e32 v49, v48, v49
	v_xor_b32_e32 v50, 0x80000000, v50
	v_cvt_pk_bf16_f32 v143, v48, v50
	v_add_f32_e32 v184, v50, v49
	v_lshlrev_b32_e32 v49, 16, v143
	v_sub_f32_e32 v48, v48, v49
	v_and_b32_e32 v49, 0xffff0000, v143
	v_sub_f32_e32 v49, v50, v49
	v_cvt_pk_bf16_f32 v147, v48, v49
	v_mov_b32_e32 v48, v184
	v_mov_b32_e32 v49, v184
	s_nop 1
	v_permlane32_swap_b32_e32 v48, v49
	v_cndmask_b32_e64 v185, v48, v49, s[8:9]
	v_add_f32_e64 v50, v152, v86
	v_add_f32_e64 v51, v152, v87
	v_add_f32_e64 v48, v152, v84
	v_add_f32_e64 v49, v152, v85
	v_add_f32_e64 v94, v152, v182
	v_add_f32_e64 v95, v152, v183
	v_add_f32_e64 v92, v152, v170
	v_add_f32_e64 v93, v152, v171
	v_mfma_f32_32x32x16_bf16 v[48:63], v[96:99], v[80:83], v[48:63]
	v_add_f32_e64 v90, v152, v168
	v_add_f32_e64 v91, v152, v169
	v_add_f32_e64 v88, v152, v166
	v_add_f32_e64 v89, v152, v167
	v_add_f32_e64 v86, v152, v164
	v_add_f32_e64 v87, v152, v165
	v_add_f32_e64 v84, v152, v162
	v_add_f32_e64 v85, v152, v163
	v_add_f32_e64 v82, v152, v160
	v_add_f32_e64 v83, v152, v161
	v_add_f32_e64 v80, v152, v156
	v_add_f32_e64 v81, v152, v157
	v_mfma_f32_32x32x16_bf16 v[48:63], v[96:99], v[64:67], v[48:63]
	v_mov_b64_e32 v[64:65], s[96:97]
	v_mov_b64_e32 v[66:67], s[98:99]
	s_nop 1
	v_mfma_f32_32x32x16_bf16 v[48:63], v[64:67], v[136:139], v[48:63]
	v_mfma_f32_32x32x16_bf16 v[48:63], v[64:67], v[76:79], v[48:63]
	v_mfma_f32_32x32x16_bf16 v[48:63], v[100:103], v[72:75], v[48:63]
	v_mfma_f32_32x32x16_bf16 v[48:63], v[100:103], v[68:71], v[48:63]
	v_mfma_f32_32x32x16_bf16 v[48:63], v[64:67], v[140:143], v[48:63]
	v_mfma_f32_32x32x16_bf16 v[48:63], v[64:67], v[144:147], v[48:63]
	v_mfma_f32_32x32x16_bf16 v[80:95], v[96:99], v[136:139], v[80:95]
	s_nop 10
	v_exp_f32_e32 v64, v48
	s_nop 0
	s_nop 0
	v_exp_f32_e32 v65, v49
	v_mfma_f32_32x32x16_bf16 v[80:95], v[96:99], v[76:79], v[80:95]
	s_nop 0
	v_exp_f32_e32 v66, v50
	s_nop 0
	s_nop 0
	v_exp_f32_e32 v67, v51
	v_mfma_f32_32x32x16_bf16 v[80:95], v[100:103], v[140:143], v[80:95]
	v_add_u32_e32 v141, v198, v200
	ds_read_b64_tr_b16 v[136:137], v141 offset:18432
	ds_read_b64_tr_b16 v[138:139], v141 offset:19584
	s_nop 0
	v_exp_f32_e32 v68, v52
	v_add_f32_e32 v140, v184, v185
	v_add_f32_e32 v152, v152, v140
	s_nop 0
	v_exp_f32_e32 v69, v53
	v_mfma_f32_32x32x16_bf16 v[80:95], v[100:103], v[144:147], v[80:95]
	s_nop 0
	v_exp_f32_e32 v70, v54
	s_nop 0
	s_nop 0
	v_exp_f32_e32 v71, v55
	s_nop 6
	v_exp_f32_e32 v49, v81
	v_exp_f32_e32 v50, v82
	v_exp_f32_e32 v51, v83
	s_nop 0
	v_exp_f32_e32 v72, v56
	v_exp_f32_e32 v56, v88
	v_exp_f32_e32 v52, v84
	v_exp_f32_e32 v53, v85
	s_nop 0
	v_exp_f32_e32 v73, v57
	v_exp_f32_e32 v57, v89
	v_exp_f32_e32 v54, v86
	v_exp_f32_e32 v55, v87
	s_nop 0
	v_exp_f32_e32 v74, v58
	v_exp_f32_e32 v58, v90
	v_cvt_pk_bf16_f32 v88, v72, v73
	s_nop 0
	s_nop 0
	v_exp_f32_e32 v75, v59
	v_exp_f32_e32 v59, v91
	s_nop 0
	s_nop 0
	s_nop 0
	v_exp_f32_e32 v76, v60
	v_exp_f32_e32 v60, v92
	v_cvt_pk_bf16_f32 v92, v64, v65
	v_cvt_pk_bf16_f32 v89, v74, v75
	s_nop 0
	v_exp_f32_e32 v77, v61
	v_exp_f32_e32 v61, v93
	v_cvt_pk_bf16_f32 v93, v66, v67
	s_nop 0
	s_nop 0
	v_exp_f32_e32 v78, v62
	v_exp_f32_e32 v62, v94
	v_cvt_pk_bf16_f32 v94, v68, v69
	v_cvt_pk_bf16_f32 v90, v76, v77
	s_nop 0
	v_exp_f32_e32 v79, v63
	v_exp_f32_e32 v63, v95
	v_cvt_pk_bf16_f32 v95, v70, v71
	s_nop 0
	s_nop 0
	s_waitcnt lgkmcnt(0)
	v_mfma_f32_32x32x16_bf16 v[32:47], v[136:139], v[92:95], v[32:47]
	ds_read_b64_tr_b16 v[136:137], v141 offset:18496
	ds_read_b64_tr_b16 v[138:139], v141 offset:19648
	v_cvt_pk_bf16_f32 v91, v78, v79
	v_exp_f32_e32 v48, v80
	s_nop 0
	s_nop 0
	v_cvt_pk_bf16_f32 v85, v50, v51
	s_nop 0
	s_waitcnt lgkmcnt(0)
	v_mfma_f32_32x32x16_bf16 v[16:31], v[136:139], v[92:95], v[16:31]
	ds_read_b64_tr_b16 v[92:93], v141 offset:20736
	ds_read_b64_tr_b16 v[94:95], v141 offset:21888
	v_cvt_pk_bf16_f32 v84, v48, v49
	v_cvt_pk_bf16_f32 v86, v52, v53
	v_cvt_pk_bf16_f32 v87, v54, v55
	s_nop 0
	s_nop 0
	s_nop 0
	s_waitcnt lgkmcnt(0)
	v_mfma_f32_32x32x16_bf16 v[32:47], v[92:95], v[88:91], v[32:47]
	ds_read_b64_tr_b16 v[92:93], v141 offset:20800
	ds_read_b64_tr_b16 v[94:95], v141 offset:21952
	s_nop 0
	s_nop 0
	s_nop 0
	s_nop 0
	s_nop 0
	v_cvt_pk_bf16_f32 v80, v56, v57
	s_waitcnt lgkmcnt(0)
	v_mfma_f32_32x32x16_bf16 v[16:31], v[92:95], v[88:91], v[16:31]
	ds_read_b64_tr_b16 v[88:89], v141 offset:23040
	ds_read_b64_tr_b16 v[90:91], v141 offset:24192
	v_cvt_pk_bf16_f32 v81, v58, v59
	v_cvt_pk_bf16_f32 v82, v60, v61
	v_cvt_pk_bf16_f32 v83, v62, v63
	s_waitcnt lgkmcnt(0)
	v_mfma_f32_32x32x16_bf16 v[32:47], v[88:91], v[84:87], v[32:47]
	ds_read_b64_tr_b16 v[88:89], v141 offset:23104
	ds_read_b64_tr_b16 v[90:91], v141 offset:24256
	s_waitcnt lgkmcnt(0)
	v_mfma_f32_32x32x16_bf16 v[16:31], v[88:91], v[84:87], v[16:31]
	ds_read_b64_tr_b16 v[84:85], v141 offset:25344
	ds_read_b64_tr_b16 v[86:87], v141 offset:26496
	s_waitcnt lgkmcnt(0)
	v_mfma_f32_32x32x16_bf16 v[32:47], v[84:87], v[80:83], v[32:47]
	ds_read_b64_tr_b16 v[84:85], v141 offset:25408
	ds_read_b64_tr_b16 v[86:87], v141 offset:26560
	s_waitcnt lgkmcnt(0)
	v_mfma_f32_32x32x16_bf16 v[16:31], v[84:87], v[80:83], v[16:31]

; template <int DQK, bool SB, bool SMAX>
; DI void attn_item(const Params& p, char* smem, int bh, int qb, float Mb) {
;     ...
;     AT_WRITE(0, st2 ^ 1)
;     AT_LOAD(0, (it + 2 < nt) ? it + 2 : nt - 1)
;     if (active) {
;       const bool diag = (kb0 + 64 > qw0);
;       bf16x8 pk[4];
;       if (!SB) {
;         if (diag) {
; #pragma unroll
;           for (int kb = 0; kb < 2; ++kb)
; #pragma unroll
;             for (int i = 0; i < 16; ++i) { const int key = kb0 + kb * 32 + crow(i, h); if (key > query) st[kb][i] = -__builtin_huge_valf(); }
;         }
;         if (SMAX) {
;           float ps = 0.f;
; #pragma unroll
;           for (int kb = 0; kb < 2; ++kb)
; #pragma unroll
;             for (int i = 0; i < 16; ++i) { const float pv = fast_exp2(st[kb][i]); st[kb][i] = pv; ps += pv; }
;           lsum += ps;
;         } else {
;         float mx = st[0][0];
; #pragma unroll
;         for (int kb = 0; kb < 2; ++kb)
; #pragma unroll
;           for (int i = 0; i < 16; ++i) mx = fmaxf(mx, st[kb][i]);
;         mx = fmaxf(mx, other_half(mx));
;         const float mnew = fmaxf(m, mx);
;         const float alpha = fast_exp2(m - mnew);
;         m = mnew;
;         float ps = 0.f;
; #pragma unroll
;         for (int kb = 0; kb < 2; ++kb)
; #pragma unroll
;           for (int i = 0; i < 16; ++i) { const float pv = fast_exp2(st[kb][i] - mnew); st[kb][i] = pv; ps += pv; }
;         lsum = lsum * alpha + ps;
; #pragma unroll
;         for (int db = 0; db < 2; ++db)
; #pragma unroll
;           for (int i = 0; i < 16; ++i) O[db][i] *= alpha;
;         }
;       } else {
;         f32x16 ca[2];
;         bf16x8 hi[4], lo[4];
;         float tsum = 0.f;
; #pragma unroll
;         for (int kb = 0; kb < 2; ++kb)
; #pragma unroll
;           for (int i2 = 0; i2 < 8; ++i2) {
;             float lk[2];
; #pragma unroll
;             for (int e = 0; e < 2; ++e) {
;               const int i = 2 * i2 + e;
;               const float z = fminf(st[kb][i], 100.f);
;               const int key = kb0 + kb * 32 + crow(i, h);
;               const bool valid = !diag || (key < query);
;               float l = -fast_log2(1.f + fast_exp2(z));
;               l = valid ? l : 0.f;
;               lk[e] = l;
;               tsum += l;
;               ca[kb][i] = z + carry;
;             }
;             const unsigned hp = pk_bf16(lk[0], lk[1]);
.LBB0_442:
	s_or_b64 exec, exec, s[2:3]
	s_add_i32 s2, s4, 1
	s_xor_b32 s3, s4, 0x3fffffe
	s_add_i32 s3, s3, s1
	s_lshl_b32 s3, s3, 6
	s_cmp_lt_u32 s2, s1
	s_cselect_b32 s2, s3, 0
	s_ashr_i32 s3, s2, 31
	s_lshl_b64 s[2:3], s[2:3], 7
	v_lshl_add_u64 v[80:81], v[148:149], 0, s[2:3]
	s_waitcnt vmcnt(3)
	ds_write_b128 v203, v[120:123]
	s_waitcnt vmcnt(2)
	ds_write_b128 v204, v[124:127]
	s_waitcnt vmcnt(1)
	ds_write_b128 v203, v[128:131] offset:18432
	s_waitcnt vmcnt(0)
	ds_write_b128 v204, v[132:135] offset:18432
	v_add_co_u32_e32 v82, vcc, s7, v80
	s_nop 1
	v_addc_co_u32_e32 v83, vcc, 0, v81, vcc
	global_load_dwordx4 v[120:123], v[80:81], off
	global_load_dwordx4 v[124:127], v[82:83], off
	v_lshl_add_u64 v[80:81], v[150:151], 0, s[2:3]
	v_add_co_u32_e32 v82, vcc, 0x1000, v80
	s_nop 1
	v_addc_co_u32_e32 v83, vcc, 0, v81, vcc
	global_load_dwordx4 v[128:131], v[80:81], off
	global_load_dwordx4 v[132:135], v[82:83], off
	s_and_saveexec_b64 s[80:81], s[12:13]
	s_cbranch_execz .LBB0_444
	v_cmp_le_i32_e64 s[44:45], s14, v181
	s_nop 0
	s_cmp_eq_u64 s[44:45], exec
	s_cbranch_scc1 .Lsbf_2
	s_nop 0
	v_add_u32_e32 v143, s78, v197
	v_min_f32_e32 v84, 0x42c80000, v64
	s_nop 0
	v_exp_f32_e32 v64, v84
	v_min_f32_e32 v85, 0x42c80000, v65
	v_add_u32_e32 v65, 0x41, v143
	v_cmp_lt_i32_e64 s[2:3], v65, v176
	v_exp_f32_e32 v65, v85
	v_add_f32_e32 v64, 1.0, v64
	v_log_f32_e32 v64, v64
	v_add_u32_e32 v80, 64, v143
	v_add_f32_e32 v65, 1.0, v65
	v_log_f32_e32 v65, v65
	v_cmp_le_i32_e64 s[44:45], s14, v181
	v_cmp_lt_i32_e32 vcc, v80, v176
	s_or_b64 vcc, s[44:45], vcc
	s_or_b64 s[12:13], s[44:45], s[2:3]
	v_cndmask_b32_e64 v64, 0, -v64, vcc
	v_add_f32_e32 v80, 0, v64
	v_cndmask_b32_e64 v65, 0, -v65, s[12:13]
	v_add_f32_e32 v81, v65, v80
	v_cvt_pk_bf16_f32 v80, v64, v65
	v_lshlrev_b32_e32 v82, 16, v80
	v_sub_f32_e32 v64, v64, v82
	v_and_b32_e32 v82, 0xffff0000, v80
	v_sub_f32_e32 v65, v65, v82
	v_cvt_pk_bf16_f32 v64, v64, v65
	s_nop 0
	v_min_f32_e32 v86, 0x42c80000, v66
	v_add_u32_e32 v65, 0x42, v143
	s_nop 0
	v_cmp_lt_i32_e64 s[2:3], v65, v176
	v_min_f32_e32 v87, 0x42c80000, v67
	v_add_u32_e32 v67, 0x43, v143
	s_or_b64 s[14:15], s[44:45], s[2:3]
	v_exp_f32_e32 v65, v86
	v_cmp_lt_i32_e64 s[2:3], v67, v176
	v_exp_f32_e32 v67, v87
	s_or_b64 s[16:17], s[44:45], s[2:3]
	v_add_f32_e32 v65, 1.0, v65
	v_log_f32_e32 v65, v65
	v_add_f32_e32 v67, 1.0, v67
	v_log_f32_e32 v67, v67
	s_nop 0
	v_cndmask_b32_e64 v65, 0, -v65, s[14:15]
	v_add_f32_e32 v66, v65, v81
	v_cndmask_b32_e64 v67, 0, -v67, s[16:17]
	v_cvt_pk_bf16_f32 v81, v65, v67
	v_lshlrev_b32_e32 v82, 16, v81
	v_sub_f32_e32 v65, v65, v82
	v_and_b32_e32 v82, 0xffff0000, v81
	v_add_f32_e32 v66, v67, v66
	v_sub_f32_e32 v67, v67, v82
	v_cvt_pk_bf16_f32 v65, v65, v67
	s_nop 0
	v_min_f32_e32 v88, 0x42c80000, v68
	v_add_u32_e32 v67, 0x48, v143
	s_nop 0
	v_cmp_lt_i32_e64 s[2:3], v67, v176
	v_min_f32_e32 v89, 0x42c80000, v69
	v_add_u32_e32 v68, 0x49, v143
	s_or_b64 s[18:19], s[44:45], s[2:3]
	v_exp_f32_e32 v67, v88
	v_cmp_lt_i32_e64 s[2:3], v68, v176
	v_exp_f32_e32 v68, v89
	s_or_b64 s[20:21], s[44:45], s[2:3]
	v_add_f32_e32 v67, 1.0, v67
	v_log_f32_e32 v67, v67
	v_add_f32_e32 v68, 1.0, v68
	v_log_f32_e32 v68, v68
	s_nop 0
	v_cndmask_b32_e64 v67, 0, -v67, s[18:19]
	v_add_f32_e32 v66, v67, v66
	v_cndmask_b32_e64 v68, 0, -v68, s[20:21]
	v_cvt_pk_bf16_f32 v82, v67, v68
	v_add_f32_e32 v69, v68, v66
	v_lshlrev_b32_e32 v66, 16, v82
	v_sub_f32_e32 v66, v67, v66
	v_and_b32_e32 v67, 0xffff0000, v82
	v_sub_f32_e32 v67, v68, v67
	v_cvt_pk_bf16_f32 v66, v66, v67
	s_nop 0
	v_min_f32_e32 v90, 0x42c80000, v70
	v_add_u32_e32 v67, 0x4a, v143
	v_cmp_lt_i32_e64 s[2:3], v67, v176
	v_exp_f32_e32 v67, v90
	s_or_b64 s[22:23], s[44:45], s[2:3]
	v_min_f32_e32 v156, 0x42c80000, v48
	v_min_f32_e32 v157, 0x42c80000, v49
	v_add_f32_e32 v67, 1.0, v67
	v_log_f32_e32 v67, v67
	v_add_u32_e32 v49, 0x61, v143
	v_exp_f32_e32 v48, v156
	s_mov_b32 s97, s96
	v_cndmask_b32_e64 v67, 0, -v67, s[22:23]
	v_add_f32_e32 v68, v67, v69
	s_nop 0
	v_min_f32_e32 v91, 0x42c80000, v71
	v_add_u32_e32 v69, 0x4b, v143
	v_cmp_lt_i32_e64 s[2:3], v69, v176
	v_exp_f32_e32 v69, v91
	s_or_b64 s[24:25], s[44:45], s[2:3]
	v_add_f32_e32 v48, 1.0, v48
	v_log_f32_e32 v48, v48
	v_add_f32_e32 v69, 1.0, v69
	v_log_f32_e32 v69, v69
	s_mov_b32 s98, s96
	s_mov_b32 s99, s96
	v_cndmask_b32_e64 v69, 0, -v69, s[24:25]
	v_cvt_pk_bf16_f32 v83, v67, v69
	v_lshlrev_b32_e32 v70, 16, v83
	v_sub_f32_e32 v67, v67, v70
	v_and_b32_e32 v70, 0xffff0000, v83
	v_add_f32_e32 v68, v69, v68
	v_sub_f32_e32 v69, v69, v70
	v_cvt_pk_bf16_f32 v67, v67, v69
	s_nop 0
	v_min_f32_e32 v92, 0x42c80000, v72
	v_add_u32_e32 v69, 0x50, v143
	s_nop 0
	v_cmp_lt_i32_e64 s[2:3], v69, v176
	v_min_f32_e32 v93, 0x42c80000, v73
	v_add_u32_e32 v70, 0x51, v143
	s_or_b64 s[26:27], s[44:45], s[2:3]
	v_exp_f32_e32 v69, v92
	v_cmp_lt_i32_e64 s[2:3], v70, v176
	v_exp_f32_e32 v70, v93
	s_or_b64 s[28:29], s[44:45], s[2:3]
	v_add_f32_e32 v69, 1.0, v69
	v_log_f32_e32 v69, v69
	v_add_f32_e32 v70, 1.0, v70
	v_log_f32_e32 v70, v70
	v_cndmask_b32_e64 v69, 0, -v69, s[26:27]
	v_add_f32_e32 v68, v69, v68
	v_cndmask_b32_e64 v70, 0, -v70, s[28:29]
	v_cvt_pk_bf16_f32 v72, v69, v70
	v_add_f32_e32 v71, v70, v68
	v_lshlrev_b32_e32 v68, 16, v72
	v_sub_f32_e32 v68, v69, v68
	v_and_b32_e32 v69, 0xffff0000, v72
	v_sub_f32_e32 v69, v70, v69
	v_cvt_pk_bf16_f32 v68, v68, v69
	s_nop 0
	v_min_f32_e32 v94, 0x42c80000, v74
	v_add_u32_e32 v69, 0x52, v143
	v_cmp_lt_i32_e64 s[2:3], v69, v176
	v_exp_f32_e32 v69, v94
	s_or_b64 s[30:31], s[44:45], s[2:3]
	v_add_f32_e32 v69, 1.0, v69
	v_log_f32_e32 v69, v69
	s_nop 0
	v_cndmask_b32_e64 v69, 0, -v69, s[30:31]
	v_add_f32_e32 v70, v69, v71
; DI unsigned pk_bf16(float lo, float hi) { f32x2 v = {lo, hi}; bf2_t b = __builtin_convertvector(v, bf2_t); return __builtin_bit_cast(unsigned, b); }
; DI float bf_lo(unsigned u) { return __uint_as_float(u << 16); }
; DI float bf_hi(unsigned u) { return __uint_as_float(u & 0xffff0000u); }
; DI int crow(int i, int h) { return (i & 3) + 8 * (i >> 2) + 4 * h; }
; DI float fast_exp2(float x) { return __builtin_amdgcn_exp2f(x); }
; DI float fast_log2(float x) { return __builtin_amdgcn_logf(x); }
; template <int DQK, bool SB, bool SMAX>
; DI void attn_item(const Params& p, char* smem, int bh, int qb, float Mb) {
;     ...
;           for (int i2 = 0; i2 < 8; ++i2) {
;             float lk[2];
; #pragma unroll
;             for (int e = 0; e < 2; ++e) {
;               const int i = 2 * i2 + e;
;               const float z = fminf(st[kb][i], 100.f);
;               const int key = kb0 + kb * 32 + crow(i, h);
;               const bool valid = !diag || (key < query);
;               float l = -fast_log2(1.f + fast_exp2(z));
;               l = valid ? l : 0.f;
;               lk[e] = l;
;               tsum += l;
;               ca[kb][i] = z + carry;
;             }
;             const unsigned hp = pk_bf16(lk[0], lk[1]);
;             const unsigned lp = pk_bf16(lk[0] - bf_lo(hp), lk[1] - bf_hi(hp));
;             const int kk = kb * 2 + (i2 >> 2), w = i2 & 3;
;             hi[kk][2 * w] = (short)(hp & 0xffffu); hi[kk][2 * w + 1] = (short)(hp >> 16);
;             lo[kk][2 * w] = (short)(lp & 0xffffu); lo[kk][2 * w + 1] = (short)(lp >> 16);
;           }
	s_nop 0
	v_min_f32_e32 v95, 0x42c80000, v75
	v_add_u32_e32 v71, 0x53, v143
	v_cmp_lt_i32_e64 s[2:3], v71, v176
	v_exp_f32_e32 v71, v95
	s_or_b64 s[34:35], s[44:45], s[2:3]
	v_add_f32_e32 v71, 1.0, v71
	v_log_f32_e32 v71, v71
	s_nop 0
	v_cndmask_b32_e64 v71, 0, -v71, s[34:35]
	v_cvt_pk_bf16_f32 v73, v69, v71
	v_lshlrev_b32_e32 v74, 16, v73
	v_sub_f32_e32 v69, v69, v74
	v_and_b32_e32 v74, 0xffff0000, v73
	v_add_f32_e32 v70, v71, v70
	v_sub_f32_e32 v71, v71, v74
	v_cvt_pk_bf16_f32 v69, v69, v71
	s_nop 0
	v_min_f32_e32 v154, 0x42c80000, v76
	v_add_u32_e32 v71, 0x58, v143
	s_nop 0
	v_cmp_lt_i32_e64 s[2:3], v71, v176
	v_min_f32_e32 v155, 0x42c80000, v77
	v_add_u32_e32 v74, 0x59, v143
	s_or_b64 s[36:37], s[44:45], s[2:3]
	v_exp_f32_e32 v71, v154
	v_cmp_lt_i32_e64 s[2:3], v74, v176
	v_exp_f32_e32 v74, v155
	s_or_b64 s[38:39], s[44:45], s[2:3]
	v_add_f32_e32 v71, 1.0, v71
	v_log_f32_e32 v71, v71
	v_add_f32_e32 v74, 1.0, v74
	v_log_f32_e32 v74, v74
	v_cndmask_b32_e64 v71, 0, -v71, s[36:37]
	v_add_f32_e32 v70, v71, v70
	v_cndmask_b32_e64 v75, 0, -v74, s[38:39]
	v_cvt_pk_bf16_f32 v74, v71, v75
	v_add_f32_e32 v76, v75, v70
	v_lshlrev_b32_e32 v70, 16, v74
	v_sub_f32_e32 v70, v71, v70
	v_and_b32_e32 v71, 0xffff0000, v74
	v_sub_f32_e32 v71, v75, v71
	v_cvt_pk_bf16_f32 v70, v70, v71
	s_nop 0
	v_min_f32_e32 v158, 0x42c80000, v78
	v_add_u32_e32 v71, 0x5a, v143
	v_cmp_lt_i32_e64 s[2:3], v71, v176
	v_exp_f32_e32 v71, v158
	s_or_b64 s[40:41], s[44:45], s[2:3]
	v_add_f32_e32 v71, 1.0, v71
	v_log_f32_e32 v71, v71
	s_nop 0
	v_cndmask_b32_e64 v71, 0, -v71, s[40:41]
	v_add_f32_e32 v75, v71, v76
	s_nop 0
	v_min_f32_e32 v159, 0x42c80000, v79
	v_add_u32_e32 v76, 0x5b, v143
	v_cmp_lt_i32_e64 s[2:3], v76, v176
	v_exp_f32_e32 v76, v159
	s_or_b64 s[42:43], s[44:45], s[2:3]
	v_add_f32_e32 v76, 1.0, v76
	v_log_f32_e32 v76, v76
	s_nop 0
	v_cndmask_b32_e64 v76, 0, -v76, s[42:43]
	v_add_f32_e32 v77, v76, v75
	v_cvt_pk_bf16_f32 v75, v71, v76
	v_lshlrev_b32_e32 v78, 16, v75
	v_sub_f32_e32 v71, v71, v78
	v_and_b32_e32 v78, 0xffff0000, v75
	v_sub_f32_e32 v76, v76, v78
	v_cvt_pk_bf16_f32 v71, v71, v76
	v_add_u32_e32 v76, 0x60, v143
	v_cmp_lt_i32_e64 s[2:3], v76, v176
	s_or_b64 s[46:47], s[44:45], s[2:3]
	v_cmp_lt_i32_e64 s[2:3], v49, v176
	v_exp_f32_e32 v49, v157
	s_or_b64 s[48:49], s[44:45], s[2:3]
	v_cndmask_b32_e64 v48, 0, -v48, s[46:47]
	v_add_f32_e32 v76, v48, v77
	v_add_f32_e32 v49, 1.0, v49
	v_log_f32_e32 v49, v49
	s_nop 0
	v_cndmask_b32_e64 v49, 0, -v49, s[48:49]
	v_cvt_pk_bf16_f32 v136, v48, v49
	v_add_f32_e32 v77, v49, v76
	v_lshlrev_b32_e32 v76, 16, v136
	v_sub_f32_e32 v48, v48, v76
	v_and_b32_e32 v76, 0xffff0000, v136
	v_sub_f32_e32 v49, v49, v76
	v_cvt_pk_bf16_f32 v76, v48, v49
	s_nop 0
	v_min_f32_e32 v160, 0x42c80000, v50
	v_add_u32_e32 v48, 0x62, v143
	s_nop 0
	v_cmp_lt_i32_e64 s[2:3], v48, v176
	v_min_f32_e32 v161, 0x42c80000, v51
	v_add_u32_e32 v50, 0x63, v143
	s_or_b64 s[50:51], s[44:45], s[2:3]
	v_exp_f32_e32 v48, v160
	v_cmp_lt_i32_e64 s[2:3], v50, v176
	v_exp_f32_e32 v50, v161
	s_or_b64 s[52:53], s[44:45], s[2:3]
	v_add_f32_e32 v48, 1.0, v48
	v_log_f32_e32 v48, v48
	v_add_f32_e32 v50, 1.0, v50
	v_log_f32_e32 v50, v50
	v_cndmask_b32_e64 v48, 0, -v48, s[50:51]
	v_add_f32_e32 v49, v48, v77
	v_cndmask_b32_e64 v50, 0, -v50, s[52:53]
	v_cvt_pk_bf16_f32 v137, v48, v50
	v_lshlrev_b32_e32 v51, 16, v137
	v_sub_f32_e32 v48, v48, v51
	v_and_b32_e32 v51, 0xffff0000, v137
	v_add_f32_e32 v49, v50, v49
	v_sub_f32_e32 v50, v50, v51
	v_cvt_pk_bf16_f32 v77, v48, v50
	s_nop 0
	v_min_f32_e32 v162, 0x42c80000, v52
	v_add_u32_e32 v48, 0x68, v143
	s_nop 0
	v_cmp_lt_i32_e64 s[2:3], v48, v176
	v_min_f32_e32 v163, 0x42c80000, v53
	v_add_u32_e32 v50, 0x69, v143
	s_or_b64 s[54:55], s[44:45], s[2:3]
	v_exp_f32_e32 v48, v162
	v_cmp_lt_i32_e64 s[2:3], v50, v176
	v_exp_f32_e32 v50, v163
	s_or_b64 s[56:57], s[44:45], s[2:3]
	v_add_f32_e32 v48, 1.0, v48
	v_log_f32_e32 v48, v48
	v_add_f32_e32 v50, 1.0, v50
	v_log_f32_e32 v50, v50
	v_add_f32_e64 v52, v152, v88
	v_add_f32_e64 v53, v152, v89
	v_cndmask_b32_e64 v48, 0, -v48, s[54:55]
	v_add_f32_e32 v49, v48, v49
	v_cndmask_b32_e64 v50, 0, -v50, s[56:57]
	v_cvt_pk_bf16_f32 v138, v48, v50
	v_lshlrev_b32_e32 v51, 16, v138
	v_sub_f32_e32 v48, v48, v51
	v_and_b32_e32 v51, 0xffff0000, v138
	v_add_f32_e32 v49, v50, v49
	v_sub_f32_e32 v50, v50, v51
	v_cvt_pk_bf16_f32 v78, v48, v50
	s_nop 0
	v_min_f32_e32 v164, 0x42c80000, v54
	v_add_u32_e32 v48, 0x6a, v143
	s_nop 0
	v_cmp_lt_i32_e64 s[2:3], v48, v176
	v_min_f32_e32 v165, 0x42c80000, v55
	v_add_u32_e32 v50, 0x6b, v143
	s_or_b64 s[58:59], s[44:45], s[2:3]
	v_exp_f32_e32 v48, v164
	v_cmp_lt_i32_e64 s[2:3], v50, v176
	v_exp_f32_e32 v50, v165
	s_or_b64 s[60:61], s[44:45], s[2:3]
	v_add_f32_e32 v48, 1.0, v48
	v_log_f32_e32 v48, v48
	v_add_f32_e32 v50, 1.0, v50
	v_log_f32_e32 v50, v50
	v_add_f32_e64 v54, v152, v90
	v_add_f32_e64 v55, v152, v91
	v_cndmask_b32_e64 v48, 0, -v48, s[58:59]
	v_add_f32_e32 v49, v48, v49
	v_cndmask_b32_e64 v50, 0, -v50, s[60:61]
	v_cvt_pk_bf16_f32 v139, v48, v50
	v_lshlrev_b32_e32 v51, 16, v139
	v_sub_f32_e32 v48, v48, v51
	v_and_b32_e32 v51, 0xffff0000, v139
	v_add_f32_e32 v49, v50, v49
	v_sub_f32_e32 v50, v50, v51
	v_cvt_pk_bf16_f32 v79, v48, v50
	s_nop 0
	v_min_f32_e32 v166, 0x42c80000, v56
	v_add_u32_e32 v48, 0x70, v143
	s_nop 0
	v_cmp_lt_i32_e64 s[2:3], v48, v176
	v_min_f32_e32 v167, 0x42c80000, v57
	v_add_u32_e32 v50, 0x71, v143
	s_or_b64 s[62:63], s[44:45], s[2:3]
	v_exp_f32_e32 v48, v166
	v_cmp_lt_i32_e64 s[2:3], v50, v176
	v_exp_f32_e32 v50, v167
	s_or_b64 s[64:65], s[44:45], s[2:3]
	v_add_f32_e32 v48, 1.0, v48
	v_log_f32_e32 v48, v48
	v_add_f32_e32 v50, 1.0, v50
; template <int DQK, bool SB, bool SMAX>
; DI void attn_item(const Params& p, char* smem, int bh, int qb, float Mb) {
;     ...
;           for (int i2 = 0; i2 < 8; ++i2) {
;             float lk[2];
; #pragma unroll
;             for (int e = 0; e < 2; ++e) {
;               const int i = 2 * i2 + e;
;               const float z = fminf(st[kb][i], 100.f);
;               const int key = kb0 + kb * 32 + crow(i, h);
;               const bool valid = !diag || (key < query);
;               float l = -fast_log2(1.f + fast_exp2(z));
;               l = valid ? l : 0.f;
;               lk[e] = l;
;               tsum += l;
;               ca[kb][i] = z + carry;
;             }
;             const unsigned hp = pk_bf16(lk[0], lk[1]);
;             const unsigned lp = pk_bf16(lk[0] - bf_lo(hp), lk[1] - bf_hi(hp));
;             const int kk = kb * 2 + (i2 >> 2), w = i2 & 3;
;             hi[kk][2 * w] = (short)(hp & 0xffffu); hi[kk][2 * w + 1] = (short)(hp >> 16);
;             lo[kk][2 * w] = (short)(lp & 0xffffu); lo[kk][2 * w + 1] = (short)(lp >> 16);
;           }
;         tsum += other_half(tsum);
; #pragma unroll
;         for (int s = 0; s < 2; ++s) {
;           ca[0] = MFMA32(tri[s], hi[s], ca[0]);
;           ca[0] = MFMA32(tri[s], lo[s], ca[0]);
;           ca[0] = MFMA32(ones, hi[2 + s], ca[0]);
;           ca[0] = MFMA32(ones, lo[2 + s], ca[0]);
;           ca[1] = MFMA32(tri[s], hi[2 + s], ca[1]);
;           ca[1] = MFMA32(tri[s], lo[2 + s], ca[1]);
;         }
; #pragma unroll
;         for (int kb = 0; kb < 2; ++kb)
; #pragma unroll
;           for (int i = 0; i < 16; ++i) {
;             const int key = kb0 + kb * 32 + crow(i, h);
;             const bool valid = !diag || (key < query);
;             st[kb][i] = valid ? fast_exp2(ca[kb][i]) : 0.f;
;           }
;         carry += tsum;
;       }
; #pragma unroll
;       for (int kb = 0; kb < 2; ++kb)
; #pragma unroll
;         for (int s = 0; s < 2; ++s) {
;           u32x4 w;
; #pragma unroll
;           for (int e = 0; e < 4; ++e) w[e] = pk_bf16(st[kb][8 * s + 2 * e], st[kb][8 * s + 2 * e + 1]);
;           pk[kb * 2 + s] = __builtin_bit_cast(bf16x8, w);
;         }
; #pragma unroll
;       for (int kk = 0; kk < 4; ++kk)
; #pragma unroll
;         for (int db = 0; db < 2; ++db) {
;           const s16x4 v0 = __builtin_amdgcn_ds_read_tr16_b64_v4i16((lds_s16x4*)(vc + voff + (16 * kk) * VSTR + 32 * db));
	v_log_f32_e32 v50, v50
	v_add_f32_e64 v56, v152, v92
	v_add_f32_e64 v57, v152, v93
	v_cndmask_b32_e64 v48, 0, -v48, s[62:63]
	v_add_f32_e32 v49, v48, v49
	v_cndmask_b32_e64 v50, 0, -v50, s[64:65]
	v_cvt_pk_bf16_f32 v140, v48, v50
	v_lshlrev_b32_e32 v51, 16, v140
	v_sub_f32_e32 v48, v48, v51
	v_and_b32_e32 v51, 0xffff0000, v140
	v_add_f32_e32 v49, v50, v49
	v_sub_f32_e32 v50, v50, v51
	v_cvt_pk_bf16_f32 v144, v48, v50
	s_nop 0
	v_min_f32_e32 v168, 0x42c80000, v58
	v_add_u32_e32 v48, 0x72, v143
	s_nop 0
	v_cmp_lt_i32_e64 s[2:3], v48, v176
	v_min_f32_e32 v169, 0x42c80000, v59
	v_add_u32_e32 v50, 0x73, v143
	s_or_b64 s[66:67], s[44:45], s[2:3]
	v_exp_f32_e32 v48, v168
	v_cmp_lt_i32_e64 s[2:3], v50, v176
	v_exp_f32_e32 v50, v169
	s_or_b64 s[68:69], s[44:45], s[2:3]
	v_add_f32_e32 v48, 1.0, v48
	v_log_f32_e32 v48, v48
	v_add_f32_e32 v50, 1.0, v50
	v_log_f32_e32 v50, v50
	v_add_f32_e64 v58, v152, v94
	v_add_f32_e64 v59, v152, v95
	v_cndmask_b32_e64 v48, 0, -v48, s[66:67]
	v_add_f32_e32 v49, v48, v49
	v_cndmask_b32_e64 v50, 0, -v50, s[68:69]
	v_cvt_pk_bf16_f32 v141, v48, v50
	v_lshlrev_b32_e32 v51, 16, v141
	v_sub_f32_e32 v48, v48, v51
	v_and_b32_e32 v51, 0xffff0000, v141
	v_add_f32_e32 v49, v50, v49
	v_sub_f32_e32 v50, v50, v51
	v_cvt_pk_bf16_f32 v145, v48, v50
	s_nop 0
	v_min_f32_e32 v170, 0x42c80000, v60
	v_add_u32_e32 v48, 0x78, v143
	s_nop 0
	v_cmp_lt_i32_e64 s[2:3], v48, v176
	v_min_f32_e32 v171, 0x42c80000, v61
	v_add_u32_e32 v50, 0x79, v143
	s_or_b64 s[70:71], s[44:45], s[2:3]
	v_exp_f32_e32 v48, v170
	v_cmp_lt_i32_e64 s[2:3], v50, v176
	v_exp_f32_e32 v50, v171
	s_or_b64 s[72:73], s[44:45], s[2:3]
	v_add_f32_e32 v48, 1.0, v48
	v_log_f32_e32 v48, v48
	v_add_f32_e32 v50, 1.0, v50
	v_log_f32_e32 v50, v50
	v_add_f32_e64 v60, v152, v154
	v_add_f32_e64 v61, v152, v155
	v_cndmask_b32_e64 v48, 0, -v48, s[70:71]
	v_add_f32_e32 v49, v48, v49
	v_cndmask_b32_e64 v50, 0, -v50, s[72:73]
	v_cvt_pk_bf16_f32 v142, v48, v50
	v_lshlrev_b32_e32 v51, 16, v142
	v_sub_f32_e32 v48, v48, v51
	v_and_b32_e32 v51, 0xffff0000, v142
	v_add_f32_e32 v49, v50, v49
	v_sub_f32_e32 v50, v50, v51
	v_cvt_pk_bf16_f32 v146, v48, v50
	s_nop 0
	v_min_f32_e32 v182, 0x42c80000, v62
	v_add_u32_e32 v48, 0x7a, v143
	s_nop 0
	v_cmp_lt_i32_e64 s[2:3], v48, v176
	v_min_f32_e32 v183, 0x42c80000, v63
	v_add_u32_e32 v50, 0x7b, v143
	s_or_b64 s[74:75], s[44:45], s[2:3]
	v_exp_f32_e32 v48, v182
	v_cmp_lt_i32_e64 s[2:3], v50, v176
	v_exp_f32_e32 v50, v183
	s_or_b64 s[44:45], s[44:45], s[2:3]
	v_add_f32_e32 v48, 1.0, v48
	v_log_f32_e32 v48, v48
	v_add_f32_e32 v50, 1.0, v50
	v_log_f32_e32 v50, v50
	v_add_f32_e64 v62, v152, v158
	v_add_f32_e64 v63, v152, v159
	v_cndmask_b32_e64 v48, 0, -v48, s[74:75]
	v_add_f32_e32 v49, v48, v49
	v_cndmask_b32_e64 v50, 0, -v50, s[44:45]
	v_cvt_pk_bf16_f32 v143, v48, v50
	v_add_f32_e32 v184, v50, v49
	v_lshlrev_b32_e32 v49, 16, v143
	v_sub_f32_e32 v48, v48, v49
	v_and_b32_e32 v49, 0xffff0000, v143
	v_sub_f32_e32 v49, v50, v49
	v_cvt_pk_bf16_f32 v147, v48, v49
	v_mov_b32_e32 v48, v184
	v_mov_b32_e32 v49, v184
	s_nop 1
	v_permlane32_swap_b32_e32 v48, v49
	v_cndmask_b32_e64 v185, v48, v49, s[8:9]
	v_add_f32_e64 v50, v152, v86
	v_add_f32_e64 v51, v152, v87
	v_add_f32_e64 v48, v152, v84
	v_add_f32_e64 v49, v152, v85
	v_add_f32_e64 v94, v152, v182
	v_add_f32_e64 v95, v152, v183
	v_add_f32_e64 v92, v152, v170
	v_add_f32_e64 v93, v152, v171
	v_mfma_f32_32x32x16_bf16 v[48:63], v[96:99], v[80:83], v[48:63]
	v_add_f32_e64 v90, v152, v168
	v_add_f32_e64 v91, v152, v169
	v_add_f32_e64 v88, v152, v166
	v_add_f32_e64 v89, v152, v167
	v_add_f32_e64 v86, v152, v164
	v_add_f32_e64 v87, v152, v165
	v_add_f32_e64 v84, v152, v162
	v_add_f32_e64 v85, v152, v163
	v_add_f32_e64 v82, v152, v160
	v_add_f32_e64 v83, v152, v161
	v_add_f32_e64 v80, v152, v156
	v_add_f32_e64 v81, v152, v157
	v_mfma_f32_32x32x16_bf16 v[48:63], v[96:99], v[64:67], v[48:63]
	v_mov_b64_e32 v[64:65], s[96:97]
	v_mov_b64_e32 v[66:67], s[98:99]
	s_nop 1
	v_mfma_f32_32x32x16_bf16 v[48:63], v[64:67], v[136:139], v[48:63]
	v_mfma_f32_32x32x16_bf16 v[48:63], v[64:67], v[76:79], v[48:63]
	v_mfma_f32_32x32x16_bf16 v[48:63], v[100:103], v[72:75], v[48:63]
	v_mfma_f32_32x32x16_bf16 v[48:63], v[100:103], v[68:71], v[48:63]
	v_mfma_f32_32x32x16_bf16 v[48:63], v[64:67], v[140:143], v[48:63]
	v_mfma_f32_32x32x16_bf16 v[48:63], v[64:67], v[144:147], v[48:63]
	v_mfma_f32_32x32x16_bf16 v[80:95], v[96:99], v[136:139], v[80:95]
	s_nop 10
	v_exp_f32_e32 v48, v48
	s_nop 0
	v_cndmask_b32_e32 v64, 0, v48, vcc
	v_exp_f32_e32 v48, v49
	v_mfma_f32_32x32x16_bf16 v[80:95], v[96:99], v[76:79], v[80:95]
	v_cndmask_b32_e64 v65, 0, v48, s[12:13]
	v_exp_f32_e32 v48, v50
	s_nop 0
	v_cndmask_b32_e64 v66, 0, v48, s[14:15]
	v_exp_f32_e32 v48, v51
	v_mfma_f32_32x32x16_bf16 v[80:95], v[100:103], v[140:143], v[80:95]
	v_cndmask_b32_e64 v67, 0, v48, s[16:17]
	v_exp_f32_e32 v48, v52
	s_nop 0
	v_cndmask_b32_e64 v68, 0, v48, s[18:19]
	v_exp_f32_e32 v48, v53
	v_mfma_f32_32x32x16_bf16 v[80:95], v[100:103], v[144:147], v[80:95]
	v_cndmask_b32_e64 v69, 0, v48, s[20:21]
	v_exp_f32_e32 v48, v54
	s_nop 0
	v_cndmask_b32_e64 v70, 0, v48, s[22:23]
	v_exp_f32_e32 v48, v55
	s_nop 6
	v_exp_f32_e32 v53, v85
	v_add_u32_e32 v85, v198, v200
	ds_read_b64_tr_b16 v[140:141], v85 offset:27648
	ds_read_b64_tr_b16 v[142:143], v85 offset:28800
	v_cndmask_b32_e64 v71, 0, v48, s[24:25]
	v_exp_f32_e32 v48, v56
	v_exp_f32_e32 v54, v86
	v_exp_f32_e32 v55, v87
	v_exp_f32_e32 v56, v88
	v_cndmask_b32_e64 v72, 0, v48, s[26:27]
	v_exp_f32_e32 v48, v57
	v_exp_f32_e32 v57, v89
	v_cvt_pk_bf16_f32 v86, v64, v65
	v_cvt_pk_bf16_f32 v87, v66, v67
	v_cndmask_b32_e64 v73, 0, v48, s[28:29]
	v_exp_f32_e32 v48, v58
	v_cvt_pk_bf16_f32 v88, v68, v69
	v_cvt_pk_bf16_f32 v89, v70, v71
	v_exp_f32_e32 v58, v90
	v_cndmask_b32_e64 v74, 0, v48, s[30:31]
	v_exp_f32_e32 v48, v59
	s_waitcnt lgkmcnt(0)
; #define MFMA32(a, b, c) __builtin_amdgcn_mfma_f32_32x32x16_bf16((a), (b), (c), 0, 0, 0)
; DI float bf_lo(unsigned u) { return __uint_as_float(u << 16); }
; template <int DQK, bool SB, bool SMAX>
; DI void attn_item(const Params& p, char* smem, int bh, int qb, float Mb) {
;     ...
;           for (int i2 = 0; i2 < 8; ++i2) {
;             float lk[2];
; #pragma unroll
;             for (int e = 0; e < 2; ++e) {
;               const int i = 2 * i2 + e;
;               const float z = fminf(st[kb][i], 100.f);
;               const int key = kb0 + kb * 32 + crow(i, h);
;               const bool valid = !diag || (key < query);
;               float l = -fast_log2(1.f + fast_exp2(z));
;               l = valid ? l : 0.f;
;               lk[e] = l;
;               tsum += l;
;               ca[kb][i] = z + carry;
;             }
;             const unsigned hp = pk_bf16(lk[0], lk[1]);
;             const unsigned lp = pk_bf16(lk[0] - bf_lo(hp), lk[1] - bf_hi(hp));
;             const int kk = kb * 2 + (i2 >> 2), w = i2 & 3;
;             hi[kk][2 * w] = (short)(hp & 0xffffu); hi[kk][2 * w + 1] = (short)(hp >> 16);
;             lo[kk][2 * w] = (short)(lp & 0xffffu); lo[kk][2 * w + 1] = (short)(lp >> 16);
;           }
;     ...
;         for (int kb = 0; kb < 2; ++kb)
; #pragma unroll
;           for (int i = 0; i < 16; ++i) {
;             const int key = kb0 + kb * 32 + crow(i, h);
;             const bool valid = !diag || (key < query);
;             st[kb][i] = valid ? fast_exp2(ca[kb][i]) : 0.f;
;           }
;         carry += tsum;
;       }
; #pragma unroll
;       for (int kb = 0; kb < 2; ++kb)
; #pragma unroll
;         for (int s = 0; s < 2; ++s) {
;           u32x4 w;
; #pragma unroll
;           for (int e = 0; e < 4; ++e) w[e] = pk_bf16(st[kb][8 * s + 2 * e], st[kb][8 * s + 2 * e + 1]);
;           pk[kb * 2 + s] = __builtin_bit_cast(bf16x8, w);
;         }
; #pragma unroll
;       for (int kk = 0; kk < 4; ++kk)
; #pragma unroll
;         for (int db = 0; db < 2; ++db) {
;           const s16x4 v0 = __builtin_amdgcn_ds_read_tr16_b64_v4i16((lds_s16x4*)(vc + voff + (16 * kk) * VSTR + 32 * db));
;           const s16x4 v1 = __builtin_amdgcn_ds_read_tr16_b64_v4i16((lds_s16x4*)(vc + voff + (16 * kk + 8) * VSTR + 32 * db));
;           const bf16x8 vf = __builtin_shufflevector(v0, v1, 0, 1, 2, 3, 4, 5, 6, 7);
;           O[db] = MFMA32(vf, pk[kk], O[db]);
;         }
	v_mfma_f32_32x32x16_bf16 v[32:47], v[140:143], v[86:89], v[32:47]
	ds_read_b64_tr_b16 v[140:141], v85 offset:27712
	ds_read_b64_tr_b16 v[142:143], v85 offset:28864
	v_exp_f32_e32 v59, v91
	v_cndmask_b32_e64 v75, 0, v48, s[34:35]
	v_exp_f32_e32 v48, v60
	v_exp_f32_e32 v60, v92
	v_cvt_pk_bf16_f32 v90, v72, v73
	v_cvt_pk_bf16_f32 v91, v74, v75
	v_cndmask_b32_e64 v76, 0, v48, s[36:37]
	v_exp_f32_e32 v48, v61
	s_waitcnt lgkmcnt(0)
	v_mfma_f32_32x32x16_bf16 v[16:31], v[140:143], v[86:89], v[16:31]
	ds_read_b64_tr_b16 v[86:87], v85 offset:29952
	ds_read_b64_tr_b16 v[88:89], v85 offset:31104
	v_exp_f32_e32 v61, v93
	v_cndmask_b32_e64 v77, 0, v48, s[38:39]
	v_exp_f32_e32 v48, v62
	v_cvt_pk_bf16_f32 v92, v76, v77
	v_exp_f32_e32 v49, v81
	v_exp_f32_e32 v50, v82
	v_cndmask_b32_e64 v78, 0, v48, s[40:41]
	v_exp_f32_e32 v48, v63
	v_exp_f32_e32 v51, v83
	v_exp_f32_e32 v52, v84
	v_cndmask_b32_e64 v49, 0, v49, s[48:49]
	v_cndmask_b32_e64 v79, 0, v48, s[42:43]
	v_cvt_pk_bf16_f32 v93, v78, v79
	v_exp_f32_e32 v48, v80
	v_cndmask_b32_e64 v50, 0, v50, s[50:51]
	s_waitcnt lgkmcnt(0)
	v_mfma_f32_32x32x16_bf16 v[32:47], v[86:89], v[90:93], v[32:47]
	ds_read_b64_tr_b16 v[86:87], v85 offset:30016
	ds_read_b64_tr_b16 v[88:89], v85 offset:31168
	v_cndmask_b32_e64 v48, 0, v48, s[46:47]
	v_cndmask_b32_e64 v51, 0, v51, s[52:53]
	v_cndmask_b32_e64 v52, 0, v52, s[54:55]
	v_cndmask_b32_e64 v53, 0, v53, s[56:57]
	v_cndmask_b32_e64 v54, 0, v54, s[58:59]
	v_cndmask_b32_e64 v55, 0, v55, s[60:61]
	s_waitcnt lgkmcnt(0)
	v_mfma_f32_32x32x16_bf16 v[16:31], v[86:89], v[90:93], v[16:31]
	ds_read_b64_tr_b16 v[86:87], v85 offset:32256
	ds_read_b64_tr_b16 v[88:89], v85 offset:33408
	v_cvt_pk_bf16_f32 v136, v48, v49
	v_cvt_pk_bf16_f32 v137, v50, v51
	v_cvt_pk_bf16_f32 v138, v52, v53
	v_cvt_pk_bf16_f32 v139, v54, v55
	v_exp_f32_e32 v62, v94
	v_exp_f32_e32 v63, v95
	s_waitcnt lgkmcnt(0)
	v_mfma_f32_32x32x16_bf16 v[32:47], v[86:89], v[136:139], v[32:47]
	ds_read_b64_tr_b16 v[86:87], v85 offset:32320
	ds_read_b64_tr_b16 v[88:89], v85 offset:33472
	v_cndmask_b32_e64 v56, 0, v56, s[62:63]
	v_cndmask_b32_e64 v57, 0, v57, s[64:65]
	v_cndmask_b32_e64 v58, 0, v58, s[66:67]
	v_cndmask_b32_e64 v59, 0, v59, s[68:69]
	v_cndmask_b32_e64 v60, 0, v60, s[70:71]
	v_cndmask_b32_e64 v61, 0, v61, s[72:73]
	s_waitcnt lgkmcnt(0)
	v_mfma_f32_32x32x16_bf16 v[16:31], v[86:89], v[136:139], v[16:31]
	ds_read_b64_tr_b16 v[86:87], v85 offset:34560
	ds_read_b64_tr_b16 v[88:89], v85 offset:35712
	v_cndmask_b32_e64 v62, 0, v62, s[74:75]
	v_cndmask_b32_e64 v63, 0, v63, s[44:45]
	v_cvt_pk_bf16_f32 v80, v56, v57
	v_cvt_pk_bf16_f32 v81, v58, v59
	v_cvt_pk_bf16_f32 v82, v60, v61
	v_cvt_pk_bf16_f32 v83, v62, v63
	v_add_f32_e32 v84, v184, v185
	v_add_f32_e32 v152, v152, v84
	s_waitcnt lgkmcnt(0)
	v_mfma_f32_32x32x16_bf16 v[32:47], v[86:89], v[80:83], v[32:47]
	ds_read_b64_tr_b16 v[86:87], v85 offset:34624
	ds_read_b64_tr_b16 v[88:89], v85 offset:35776
	s_waitcnt lgkmcnt(0)
	v_mfma_f32_32x32x16_bf16 v[16:31], v[86:89], v[80:83], v[16:31]
	s_branch .LBB0_444
.Lsbf_2:
	s_nop 0
	v_add_u32_e32 v143, s78, v197
	v_min_f32_e32 v84, 0x42c80000, v64
	s_nop 0
	v_exp_f32_e32 v64, v84
	v_min_f32_e32 v85, 0x42c80000, v65
	s_nop 0
	s_nop 0
	v_exp_f32_e32 v65, v85
	v_add_f32_e32 v64, 1.0, v64
	v_log_f32_e32 v64, v64
	s_nop 0
	v_add_f32_e32 v65, 1.0, v65
	v_log_f32_e32 v65, v65
	s_nop 0
	s_nop 0
	s_nop 0
	s_nop 0
	v_xor_b32_e32 v64, 0x80000000, v64
	v_add_f32_e32 v80, 0, v64
	v_xor_b32_e32 v65, 0x80000000, v65
	v_add_f32_e32 v81, v65, v80
	v_cvt_pk_bf16_f32 v80, v64, v65
	v_lshlrev_b32_e32 v82, 16, v80
	v_sub_f32_e32 v64, v64, v82
	v_and_b32_e32 v82, 0xffff0000, v80
	v_sub_f32_e32 v65, v65, v82
	v_cvt_pk_bf16_f32 v64, v64, v65
	s_nop 0
	v_min_f32_e32 v86, 0x42c80000, v66
	s_nop 0
	s_nop 0
	s_nop 0
	v_min_f32_e32 v87, 0x42c80000, v67
	s_nop 0
	s_nop 0
	v_exp_f32_e32 v65, v86
	s_nop 0
	v_exp_f32_e32 v67, v87
	s_nop 0
	v_add_f32_e32 v65, 1.0, v65
	v_log_f32_e32 v65, v65
	v_add_f32_e32 v67, 1.0, v67
	v_log_f32_e32 v67, v67
	s_nop 0
	v_xor_b32_e32 v65, 0x80000000, v65
	v_add_f32_e32 v66, v65, v81
	v_xor_b32_e32 v67, 0x80000000, v67
	v_cvt_pk_bf16_f32 v81, v65, v67
	v_lshlrev_b32_e32 v82, 16, v81
	v_sub_f32_e32 v65, v65, v82
	v_and_b32_e32 v82, 0xffff0000, v81
	v_add_f32_e32 v66, v67, v66
	v_sub_f32_e32 v67, v67, v82
	v_cvt_pk_bf16_f32 v65, v65, v67
	s_nop 0
	v_min_f32_e32 v88, 0x42c80000, v68
	s_nop 0
	s_nop 0
	s_nop 0
	v_min_f32_e32 v89, 0x42c80000, v69
	s_nop 0
	s_nop 0
	v_exp_f32_e32 v67, v88
	s_nop 0
	v_exp_f32_e32 v68, v89
	s_nop 0
	v_add_f32_e32 v67, 1.0, v67
	v_log_f32_e32 v67, v67
	v_add_f32_e32 v68, 1.0, v68
	v_log_f32_e32 v68, v68
	s_nop 0
	v_xor_b32_e32 v67, 0x80000000, v67
	v_add_f32_e32 v66, v67, v66
	v_xor_b32_e32 v68, 0x80000000, v68
	v_cvt_pk_bf16_f32 v82, v67, v68
	v_add_f32_e32 v69, v68, v66
	v_lshlrev_b32_e32 v66, 16, v82
	v_sub_f32_e32 v66, v67, v66
	v_and_b32_e32 v67, 0xffff0000, v82
	v_sub_f32_e32 v67, v68, v67
	v_cvt_pk_bf16_f32 v66, v66, v67
	s_nop 0
	v_min_f32_e32 v90, 0x42c80000, v70
	s_nop 0
	s_nop 0
	v_exp_f32_e32 v67, v90
	s_nop 0
	v_min_f32_e32 v156, 0x42c80000, v48
	v_min_f32_e32 v157, 0x42c80000, v49
	v_add_f32_e32 v67, 1.0, v67
	v_log_f32_e32 v67, v67
	s_nop 0
	v_exp_f32_e32 v48, v156
	s_mov_b32 s97, s96
	v_xor_b32_e32 v67, 0x80000000, v67
	v_add_f32_e32 v68, v67, v69
	s_nop 0
	v_min_f32_e32 v91, 0x42c80000, v71
	s_nop 0
	s_nop 0
	v_exp_f32_e32 v69, v91
	s_nop 0
	v_add_f32_e32 v48, 1.0, v48
	v_log_f32_e32 v48, v48
	v_add_f32_e32 v69, 1.0, v69
	v_log_f32_e32 v69, v69
	s_mov_b32 s98, s96
	s_mov_b32 s99, s96
	v_xor_b32_e32 v69, 0x80000000, v69
	v_cvt_pk_bf16_f32 v83, v67, v69
	v_lshlrev_b32_e32 v70, 16, v83
; DI unsigned pk_bf16(float lo, float hi) { f32x2 v = {lo, hi}; bf2_t b = __builtin_convertvector(v, bf2_t); return __builtin_bit_cast(unsigned, b); }
; DI float bf_lo(unsigned u) { return __uint_as_float(u << 16); }
; DI float bf_hi(unsigned u) { return __uint_as_float(u & 0xffff0000u); }
; DI int crow(int i, int h) { return (i & 3) + 8 * (i >> 2) + 4 * h; }
; DI float fast_exp2(float x) { return __builtin_amdgcn_exp2f(x); }
; DI float fast_log2(float x) { return __builtin_amdgcn_logf(x); }
; template <int DQK, bool SB, bool SMAX>
; DI void attn_item(const Params& p, char* smem, int bh, int qb, float Mb) {
;     ...
;           for (int i2 = 0; i2 < 8; ++i2) {
;             float lk[2];
; #pragma unroll
;             for (int e = 0; e < 2; ++e) {
;               const int i = 2 * i2 + e;
;               const float z = fminf(st[kb][i], 100.f);
;               const int key = kb0 + kb * 32 + crow(i, h);
;               const bool valid = !diag || (key < query);
;               float l = -fast_log2(1.f + fast_exp2(z));
;               l = valid ? l : 0.f;
;               lk[e] = l;
;               tsum += l;
;               ca[kb][i] = z + carry;
;             }
;             const unsigned hp = pk_bf16(lk[0], lk[1]);
;             const unsigned lp = pk_bf16(lk[0] - bf_lo(hp), lk[1] - bf_hi(hp));
;             const int kk = kb * 2 + (i2 >> 2), w = i2 & 3;
;             hi[kk][2 * w] = (short)(hp & 0xffffu); hi[kk][2 * w + 1] = (short)(hp >> 16);
;             lo[kk][2 * w] = (short)(lp & 0xffffu); lo[kk][2 * w + 1] = (short)(lp >> 16);
;           }
	v_sub_f32_e32 v67, v67, v70
	v_and_b32_e32 v70, 0xffff0000, v83
	v_add_f32_e32 v68, v69, v68
	v_sub_f32_e32 v69, v69, v70
	v_cvt_pk_bf16_f32 v67, v67, v69
	s_nop 0
	v_min_f32_e32 v92, 0x42c80000, v72
	s_nop 0
	s_nop 0
	s_nop 0
	v_min_f32_e32 v93, 0x42c80000, v73
	s_nop 0
	s_nop 0
	v_exp_f32_e32 v69, v92
	s_nop 0
	v_exp_f32_e32 v70, v93
	s_nop 0
	v_add_f32_e32 v69, 1.0, v69
	v_log_f32_e32 v69, v69
	v_add_f32_e32 v70, 1.0, v70
	v_log_f32_e32 v70, v70
	v_xor_b32_e32 v69, 0x80000000, v69
	v_add_f32_e32 v68, v69, v68
	v_xor_b32_e32 v70, 0x80000000, v70
	v_cvt_pk_bf16_f32 v72, v69, v70
	v_add_f32_e32 v71, v70, v68
	v_lshlrev_b32_e32 v68, 16, v72
	v_sub_f32_e32 v68, v69, v68
	v_and_b32_e32 v69, 0xffff0000, v72
	v_sub_f32_e32 v69, v70, v69
	v_cvt_pk_bf16_f32 v68, v68, v69
	s_nop 0
	v_min_f32_e32 v94, 0x42c80000, v74
	s_nop 0
	s_nop 0
	v_exp_f32_e32 v69, v94
	s_nop 0
	v_add_f32_e32 v69, 1.0, v69
	v_log_f32_e32 v69, v69
	s_nop 0
	v_xor_b32_e32 v69, 0x80000000, v69
	v_add_f32_e32 v70, v69, v71
	s_nop 0
	v_min_f32_e32 v95, 0x42c80000, v75
	s_nop 0
	s_nop 0
	v_exp_f32_e32 v71, v95
	s_nop 0
	v_add_f32_e32 v71, 1.0, v71
	v_log_f32_e32 v71, v71
	s_nop 0
	v_xor_b32_e32 v71, 0x80000000, v71
	v_cvt_pk_bf16_f32 v73, v69, v71
	v_lshlrev_b32_e32 v74, 16, v73
	v_sub_f32_e32 v69, v69, v74
	v_and_b32_e32 v74, 0xffff0000, v73
	v_add_f32_e32 v70, v71, v70
	v_sub_f32_e32 v71, v71, v74
	v_cvt_pk_bf16_f32 v69, v69, v71
	s_nop 0
	v_min_f32_e32 v154, 0x42c80000, v76
	s_nop 0
	s_nop 0
	s_nop 0
	v_min_f32_e32 v155, 0x42c80000, v77
	s_nop 0
	s_nop 0
	v_exp_f32_e32 v71, v154
	s_nop 0
	v_exp_f32_e32 v74, v155
	s_nop 0
	v_add_f32_e32 v71, 1.0, v71
	v_log_f32_e32 v71, v71
	v_add_f32_e32 v74, 1.0, v74
	v_log_f32_e32 v74, v74
	v_xor_b32_e32 v71, 0x80000000, v71
	v_add_f32_e32 v70, v71, v70
	v_xor_b32_e32 v75, 0x80000000, v74
	v_cvt_pk_bf16_f32 v74, v71, v75
	v_add_f32_e32 v76, v75, v70
	v_lshlrev_b32_e32 v70, 16, v74
	v_sub_f32_e32 v70, v71, v70
	v_and_b32_e32 v71, 0xffff0000, v74
	v_sub_f32_e32 v71, v75, v71
	v_cvt_pk_bf16_f32 v70, v70, v71
	s_nop 0
	v_min_f32_e32 v158, 0x42c80000, v78
	s_nop 0
	s_nop 0
	v_exp_f32_e32 v71, v158
	s_nop 0
	v_add_f32_e32 v71, 1.0, v71
	v_log_f32_e32 v71, v71
	s_nop 0
	v_xor_b32_e32 v71, 0x80000000, v71
	v_add_f32_e32 v75, v71, v76
	s_nop 0
	v_min_f32_e32 v159, 0x42c80000, v79
	s_nop 0
	s_nop 0
	v_exp_f32_e32 v76, v159
	s_nop 0
	v_add_f32_e32 v76, 1.0, v76
	v_log_f32_e32 v76, v76
	s_nop 0
	v_xor_b32_e32 v76, 0x80000000, v76
	v_add_f32_e32 v77, v76, v75
	v_cvt_pk_bf16_f32 v75, v71, v76
	v_lshlrev_b32_e32 v78, 16, v75
	v_sub_f32_e32 v71, v71, v78
	v_and_b32_e32 v78, 0xffff0000, v75
	v_sub_f32_e32 v76, v76, v78
	v_cvt_pk_bf16_f32 v71, v71, v76
	s_nop 0
	s_nop 0
	s_nop 0
	s_nop 0
	v_exp_f32_e32 v49, v157
	s_nop 0
	v_xor_b32_e32 v48, 0x80000000, v48
	v_add_f32_e32 v76, v48, v77
	v_add_f32_e32 v49, 1.0, v49
	v_log_f32_e32 v49, v49
	s_nop 0
	v_xor_b32_e32 v49, 0x80000000, v49
	v_cvt_pk_bf16_f32 v136, v48, v49
	v_add_f32_e32 v77, v49, v76
	v_lshlrev_b32_e32 v76, 16, v136
	v_sub_f32_e32 v48, v48, v76
	v_and_b32_e32 v76, 0xffff0000, v136
	v_sub_f32_e32 v49, v49, v76
	v_cvt_pk_bf16_f32 v76, v48, v49
	s_nop 0
	v_min_f32_e32 v160, 0x42c80000, v50
	s_nop 0
	s_nop 0
	s_nop 0
	v_min_f32_e32 v161, 0x42c80000, v51
	s_nop 0
	s_nop 0
	v_exp_f32_e32 v48, v160
	s_nop 0
	v_exp_f32_e32 v50, v161
	s_nop 0
	v_add_f32_e32 v48, 1.0, v48
	v_log_f32_e32 v48, v48
	v_add_f32_e32 v50, 1.0, v50
	v_log_f32_e32 v50, v50
	v_xor_b32_e32 v48, 0x80000000, v48
	v_add_f32_e32 v49, v48, v77
	v_xor_b32_e32 v50, 0x80000000, v50
	v_cvt_pk_bf16_f32 v137, v48, v50
	v_lshlrev_b32_e32 v51, 16, v137
	v_sub_f32_e32 v48, v48, v51
	v_and_b32_e32 v51, 0xffff0000, v137
	v_add_f32_e32 v49, v50, v49
	v_sub_f32_e32 v50, v50, v51
	v_cvt_pk_bf16_f32 v77, v48, v50
	s_nop 0
	v_min_f32_e32 v162, 0x42c80000, v52
	s_nop 0
	s_nop 0
	s_nop 0
	v_min_f32_e32 v163, 0x42c80000, v53
	s_nop 0
	s_nop 0
	v_exp_f32_e32 v48, v162
	s_nop 0
	v_exp_f32_e32 v50, v163
	s_nop 0
	v_add_f32_e32 v48, 1.0, v48
	v_log_f32_e32 v48, v48
	v_add_f32_e32 v50, 1.0, v50
	v_log_f32_e32 v50, v50
	v_add_f32_e64 v52, v152, v88
	v_add_f32_e64 v53, v152, v89
	v_xor_b32_e32 v48, 0x80000000, v48
	v_add_f32_e32 v49, v48, v49
	v_xor_b32_e32 v50, 0x80000000, v50
	v_cvt_pk_bf16_f32 v138, v48, v50
	v_lshlrev_b32_e32 v51, 16, v138
	v_sub_f32_e32 v48, v48, v51
	v_and_b32_e32 v51, 0xffff0000, v138
	v_add_f32_e32 v49, v50, v49
	v_sub_f32_e32 v50, v50, v51
	v_cvt_pk_bf16_f32 v78, v48, v50
	s_nop 0
	v_min_f32_e32 v164, 0x42c80000, v54
	s_nop 0
	s_nop 0
	s_nop 0
	v_min_f32_e32 v165, 0x42c80000, v55
	s_nop 0
	s_nop 0
	v_exp_f32_e32 v48, v164
	s_nop 0
	v_exp_f32_e32 v50, v165
	s_nop 0
	v_add_f32_e32 v48, 1.0, v48
	v_log_f32_e32 v48, v48
	v_add_f32_e32 v50, 1.0, v50
	v_log_f32_e32 v50, v50
	v_add_f32_e64 v54, v152, v90
	v_add_f32_e64 v55, v152, v91
	v_xor_b32_e32 v48, 0x80000000, v48
	v_add_f32_e32 v49, v48, v49
	v_xor_b32_e32 v50, 0x80000000, v50
	v_cvt_pk_bf16_f32 v139, v48, v50
	v_lshlrev_b32_e32 v51, 16, v139
	v_sub_f32_e32 v48, v48, v51
	v_and_b32_e32 v51, 0xffff0000, v139
	v_add_f32_e32 v49, v50, v49
	v_sub_f32_e32 v50, v50, v51
	v_cvt_pk_bf16_f32 v79, v48, v50
	s_nop 0
	v_min_f32_e32 v166, 0x42c80000, v56
	s_nop 0
	s_nop 0
	s_nop 0
	v_min_f32_e32 v167, 0x42c80000, v57
	s_nop 0
	s_nop 0
	v_exp_f32_e32 v48, v166
	s_nop 0
	v_exp_f32_e32 v50, v167
	s_nop 0
	v_add_f32_e32 v48, 1.0, v48
	v_log_f32_e32 v48, v48
	v_add_f32_e32 v50, 1.0, v50
	v_log_f32_e32 v50, v50
	v_add_f32_e64 v56, v152, v92
	v_add_f32_e64 v57, v152, v93
	v_xor_b32_e32 v48, 0x80000000, v48
	v_add_f32_e32 v49, v48, v49
	v_xor_b32_e32 v50, 0x80000000, v50
	v_cvt_pk_bf16_f32 v140, v48, v50
; template <int DQK, bool SB, bool SMAX>
; DI void attn_item(const Params& p, char* smem, int bh, int qb, float Mb) {
;     ...
;           for (int i2 = 0; i2 < 8; ++i2) {
;             float lk[2];
; #pragma unroll
;             for (int e = 0; e < 2; ++e) {
;               const int i = 2 * i2 + e;
;               const float z = fminf(st[kb][i], 100.f);
;               const int key = kb0 + kb * 32 + crow(i, h);
;               const bool valid = !diag || (key < query);
;               float l = -fast_log2(1.f + fast_exp2(z));
;               l = valid ? l : 0.f;
;               lk[e] = l;
;               tsum += l;
;               ca[kb][i] = z + carry;
;             }
;             const unsigned hp = pk_bf16(lk[0], lk[1]);
;             const unsigned lp = pk_bf16(lk[0] - bf_lo(hp), lk[1] - bf_hi(hp));
;             const int kk = kb * 2 + (i2 >> 2), w = i2 & 3;
;             hi[kk][2 * w] = (short)(hp & 0xffffu); hi[kk][2 * w + 1] = (short)(hp >> 16);
;             lo[kk][2 * w] = (short)(lp & 0xffffu); lo[kk][2 * w + 1] = (short)(lp >> 16);
;           }
;         tsum += other_half(tsum);
; #pragma unroll
;         for (int s = 0; s < 2; ++s) {
;           ca[0] = MFMA32(tri[s], hi[s], ca[0]);
;           ca[0] = MFMA32(tri[s], lo[s], ca[0]);
;           ca[0] = MFMA32(ones, hi[2 + s], ca[0]);
;           ca[0] = MFMA32(ones, lo[2 + s], ca[0]);
;           ca[1] = MFMA32(tri[s], hi[2 + s], ca[1]);
;           ca[1] = MFMA32(tri[s], lo[2 + s], ca[1]);
;         }
; #pragma unroll
;         for (int kb = 0; kb < 2; ++kb)
; #pragma unroll
;           for (int i = 0; i < 16; ++i) {
;             const int key = kb0 + kb * 32 + crow(i, h);
;             const bool valid = !diag || (key < query);
;             st[kb][i] = valid ? fast_exp2(ca[kb][i]) : 0.f;
;           }
;         carry += tsum;
;       }
; #pragma unroll
;       for (int kb = 0; kb < 2; ++kb)
; #pragma unroll
;         for (int s = 0; s < 2; ++s) {
;           u32x4 w;
; #pragma unroll
;           for (int e = 0; e < 4; ++e) w[e] = pk_bf16(st[kb][8 * s + 2 * e], st[kb][8 * s + 2 * e + 1]);
;           pk[kb * 2 + s] = __builtin_bit_cast(bf16x8, w);
;         }
; #pragma unroll
;       for (int kk = 0; kk < 4; ++kk)
; #pragma unroll
;         for (int db = 0; db < 2; ++db) {
;           const s16x4 v0 = __builtin_amdgcn_ds_read_tr16_b64_v4i16((lds_s16x4*)(vc + voff + (16 * kk) * VSTR + 32 * db));
	v_lshlrev_b32_e32 v51, 16, v140
	v_sub_f32_e32 v48, v48, v51
	v_and_b32_e32 v51, 0xffff0000, v140
	v_add_f32_e32 v49, v50, v49
	v_sub_f32_e32 v50, v50, v51
	v_cvt_pk_bf16_f32 v144, v48, v50
	s_nop 0
	v_min_f32_e32 v168, 0x42c80000, v58
	s_nop 0
	s_nop 0
	s_nop 0
	v_min_f32_e32 v169, 0x42c80000, v59
	s_nop 0
	s_nop 0
	v_exp_f32_e32 v48, v168
	s_nop 0
	v_exp_f32_e32 v50, v169
	s_nop 0
	v_add_f32_e32 v48, 1.0, v48
	v_log_f32_e32 v48, v48
	v_add_f32_e32 v50, 1.0, v50
	v_log_f32_e32 v50, v50
	v_add_f32_e64 v58, v152, v94
	v_add_f32_e64 v59, v152, v95
	v_xor_b32_e32 v48, 0x80000000, v48
	v_add_f32_e32 v49, v48, v49
	v_xor_b32_e32 v50, 0x80000000, v50
	v_cvt_pk_bf16_f32 v141, v48, v50
	v_lshlrev_b32_e32 v51, 16, v141
	v_sub_f32_e32 v48, v48, v51
	v_and_b32_e32 v51, 0xffff0000, v141
	v_add_f32_e32 v49, v50, v49
	v_sub_f32_e32 v50, v50, v51
	v_cvt_pk_bf16_f32 v145, v48, v50
	s_nop 0
	v_min_f32_e32 v170, 0x42c80000, v60
	s_nop 0
	s_nop 0
	s_nop 0
	v_min_f32_e32 v171, 0x42c80000, v61
	s_nop 0
	s_nop 0
	v_exp_f32_e32 v48, v170
	s_nop 0
	v_exp_f32_e32 v50, v171
	s_nop 0
	v_add_f32_e32 v48, 1.0, v48
	v_log_f32_e32 v48, v48
	v_add_f32_e32 v50, 1.0, v50
	v_log_f32_e32 v50, v50
	v_add_f32_e64 v60, v152, v154
	v_add_f32_e64 v61, v152, v155
	v_xor_b32_e32 v48, 0x80000000, v48
	v_add_f32_e32 v49, v48, v49
	v_xor_b32_e32 v50, 0x80000000, v50
	v_cvt_pk_bf16_f32 v142, v48, v50
	v_lshlrev_b32_e32 v51, 16, v142
	v_sub_f32_e32 v48, v48, v51
	v_and_b32_e32 v51, 0xffff0000, v142
	v_add_f32_e32 v49, v50, v49
	v_sub_f32_e32 v50, v50, v51
	v_cvt_pk_bf16_f32 v146, v48, v50
	s_nop 0
	v_min_f32_e32 v182, 0x42c80000, v62
	s_nop 0
	s_nop 0
	s_nop 0
	v_min_f32_e32 v183, 0x42c80000, v63
	s_nop 0
	s_nop 0
	v_exp_f32_e32 v48, v182
	s_nop 0
	v_exp_f32_e32 v50, v183
	s_nop 0
	v_add_f32_e32 v48, 1.0, v48
	v_log_f32_e32 v48, v48
	v_add_f32_e32 v50, 1.0, v50
	v_log_f32_e32 v50, v50
	v_add_f32_e64 v62, v152, v158
	v_add_f32_e64 v63, v152, v159
	v_xor_b32_e32 v48, 0x80000000, v48
	v_add_f32_e32 v49, v48, v49
	v_xor_b32_e32 v50, 0x80000000, v50
	v_cvt_pk_bf16_f32 v143, v48, v50
	v_add_f32_e32 v184, v50, v49
	v_lshlrev_b32_e32 v49, 16, v143
	v_sub_f32_e32 v48, v48, v49
	v_and_b32_e32 v49, 0xffff0000, v143
	v_sub_f32_e32 v49, v50, v49
	v_cvt_pk_bf16_f32 v147, v48, v49
	v_mov_b32_e32 v48, v184
	v_mov_b32_e32 v49, v184
	s_nop 1
	v_permlane32_swap_b32_e32 v48, v49
	v_cndmask_b32_e64 v185, v48, v49, s[8:9]
	v_add_f32_e64 v50, v152, v86
	v_add_f32_e64 v51, v152, v87
	v_add_f32_e64 v48, v152, v84
	v_add_f32_e64 v49, v152, v85
	v_add_f32_e64 v94, v152, v182
	v_add_f32_e64 v95, v152, v183
	v_add_f32_e64 v92, v152, v170
	v_add_f32_e64 v93, v152, v171
	v_mfma_f32_32x32x16_bf16 v[48:63], v[96:99], v[80:83], v[48:63]
	v_add_f32_e64 v90, v152, v168
	v_add_f32_e64 v91, v152, v169
	v_add_f32_e64 v88, v152, v166
	v_add_f32_e64 v89, v152, v167
	v_add_f32_e64 v86, v152, v164
	v_add_f32_e64 v87, v152, v165
	v_add_f32_e64 v84, v152, v162
	v_add_f32_e64 v85, v152, v163
	v_add_f32_e64 v82, v152, v160
	v_add_f32_e64 v83, v152, v161
	v_add_f32_e64 v80, v152, v156
	v_add_f32_e64 v81, v152, v157
	v_mfma_f32_32x32x16_bf16 v[48:63], v[96:99], v[64:67], v[48:63]
	v_mov_b64_e32 v[64:65], s[96:97]
	v_mov_b64_e32 v[66:67], s[98:99]
	s_nop 1
	v_mfma_f32_32x32x16_bf16 v[48:63], v[64:67], v[136:139], v[48:63]
	v_mfma_f32_32x32x16_bf16 v[48:63], v[64:67], v[76:79], v[48:63]
	v_mfma_f32_32x32x16_bf16 v[48:63], v[100:103], v[72:75], v[48:63]
	v_mfma_f32_32x32x16_bf16 v[48:63], v[100:103], v[68:71], v[48:63]
	v_mfma_f32_32x32x16_bf16 v[48:63], v[64:67], v[140:143], v[48:63]
	v_mfma_f32_32x32x16_bf16 v[48:63], v[64:67], v[144:147], v[48:63]
	v_mfma_f32_32x32x16_bf16 v[80:95], v[96:99], v[136:139], v[80:95]
	s_nop 10
	v_exp_f32_e32 v64, v48
	s_nop 0
	s_nop 0
	v_exp_f32_e32 v65, v49
	v_mfma_f32_32x32x16_bf16 v[80:95], v[96:99], v[76:79], v[80:95]
	s_nop 0
	v_exp_f32_e32 v66, v50
	s_nop 0
	s_nop 0
	v_exp_f32_e32 v67, v51
	v_mfma_f32_32x32x16_bf16 v[80:95], v[100:103], v[140:143], v[80:95]
	s_nop 0
	v_exp_f32_e32 v68, v52
	s_nop 0
	s_nop 0
	v_exp_f32_e32 v69, v53
	v_mfma_f32_32x32x16_bf16 v[80:95], v[100:103], v[144:147], v[80:95]
	s_nop 0
	v_exp_f32_e32 v70, v54
	s_nop 0
	s_nop 0
	v_exp_f32_e32 v71, v55
	s_nop 6
	v_exp_f32_e32 v53, v85
	v_add_u32_e32 v85, v198, v200
	ds_read_b64_tr_b16 v[140:141], v85 offset:27648
	ds_read_b64_tr_b16 v[142:143], v85 offset:28800
	s_nop 0
	v_exp_f32_e32 v72, v56
	v_exp_f32_e32 v54, v86
	v_exp_f32_e32 v55, v87
	v_exp_f32_e32 v56, v88
	s_nop 0
	v_exp_f32_e32 v73, v57
	v_exp_f32_e32 v57, v89
	v_cvt_pk_bf16_f32 v86, v64, v65
	v_cvt_pk_bf16_f32 v87, v66, v67
	s_nop 0
	v_exp_f32_e32 v74, v58
	v_cvt_pk_bf16_f32 v88, v68, v69
	v_cvt_pk_bf16_f32 v89, v70, v71
	v_exp_f32_e32 v58, v90
	s_nop 0
	v_exp_f32_e32 v75, v59
	s_waitcnt lgkmcnt(0)
; #define MFMA32(a, b, c) __builtin_amdgcn_mfma_f32_32x32x16_bf16((a), (b), (c), 0, 0, 0)
; DI unsigned pk_bf16(float lo, float hi) { f32x2 v = {lo, hi}; bf2_t b = __builtin_convertvector(v, bf2_t); return __builtin_bit_cast(unsigned, b); }
; DI float fast_exp2(float x) { return __builtin_amdgcn_exp2f(x); }
; template <int DQK, bool SB, bool SMAX>
; DI void attn_item(const Params& p, char* smem, int bh, int qb, float Mb) {
;     ...
;             st[kb][i] = valid ? fast_exp2(ca[kb][i]) : 0.f;
;           }
;         carry += tsum;
;       }
; #pragma unroll
;       for (int kb = 0; kb < 2; ++kb)
; #pragma unroll
;         for (int s = 0; s < 2; ++s) {
;           u32x4 w;
; #pragma unroll
;           for (int e = 0; e < 4; ++e) w[e] = pk_bf16(st[kb][8 * s + 2 * e], st[kb][8 * s + 2 * e + 1]);
;           pk[kb * 2 + s] = __builtin_bit_cast(bf16x8, w);
;         }
; #pragma unroll
;       for (int kk = 0; kk < 4; ++kk)
; #pragma unroll
;         for (int db = 0; db < 2; ++db) {
;           const s16x4 v0 = __builtin_amdgcn_ds_read_tr16_b64_v4i16((lds_s16x4*)(vc + voff + (16 * kk) * VSTR + 32 * db));
;           const s16x4 v1 = __builtin_amdgcn_ds_read_tr16_b64_v4i16((lds_s16x4*)(vc + voff + (16 * kk + 8) * VSTR + 32 * db));
;           const bf16x8 vf = __builtin_shufflevector(v0, v1, 0, 1, 2, 3, 4, 5, 6, 7);
;           O[db] = MFMA32(vf, pk[kk], O[db]);
;         }
	v_mfma_f32_32x32x16_bf16 v[32:47], v[140:143], v[86:89], v[32:47]
	ds_read_b64_tr_b16 v[140:141], v85 offset:27712
	ds_read_b64_tr_b16 v[142:143], v85 offset:28864
	v_exp_f32_e32 v59, v91
	s_nop 0
	v_exp_f32_e32 v76, v60
	v_exp_f32_e32 v60, v92
	v_cvt_pk_bf16_f32 v90, v72, v73
	v_cvt_pk_bf16_f32 v91, v74, v75
	s_nop 0
	v_exp_f32_e32 v77, v61
	s_waitcnt lgkmcnt(0)
	v_mfma_f32_32x32x16_bf16 v[16:31], v[140:143], v[86:89], v[16:31]
	ds_read_b64_tr_b16 v[86:87], v85 offset:29952
	ds_read_b64_tr_b16 v[88:89], v85 offset:31104
	v_exp_f32_e32 v61, v93
	s_nop 0
	v_exp_f32_e32 v78, v62
	v_cvt_pk_bf16_f32 v92, v76, v77
	v_exp_f32_e32 v49, v81
	v_exp_f32_e32 v50, v82
	s_nop 0
	v_exp_f32_e32 v79, v63
	v_exp_f32_e32 v51, v83
	v_exp_f32_e32 v52, v84
	s_nop 0
	s_nop 0
	v_cvt_pk_bf16_f32 v93, v78, v79
	v_exp_f32_e32 v48, v80
	s_nop 0
	s_waitcnt lgkmcnt(0)
	v_mfma_f32_32x32x16_bf16 v[32:47], v[86:89], v[90:93], v[32:47]
	ds_read_b64_tr_b16 v[86:87], v85 offset:30016
	ds_read_b64_tr_b16 v[88:89], v85 offset:31168
	s_nop 0
	s_nop 0
	s_nop 0
	s_nop 0
	s_nop 0
	s_nop 0
	s_waitcnt lgkmcnt(0)
	v_mfma_f32_32x32x16_bf16 v[16:31], v[86:89], v[90:93], v[16:31]
	ds_read_b64_tr_b16 v[86:87], v85 offset:32256
	ds_read_b64_tr_b16 v[88:89], v85 offset:33408
	v_cvt_pk_bf16_f32 v136, v48, v49
	v_cvt_pk_bf16_f32 v137, v50, v51
	v_cvt_pk_bf16_f32 v138, v52, v53
	v_cvt_pk_bf16_f32 v139, v54, v55
	v_exp_f32_e32 v62, v94
	v_exp_f32_e32 v63, v95
	s_waitcnt lgkmcnt(0)
	v_mfma_f32_32x32x16_bf16 v[32:47], v[86:89], v[136:139], v[32:47]
	ds_read_b64_tr_b16 v[86:87], v85 offset:32320
	ds_read_b64_tr_b16 v[88:89], v85 offset:33472
	s_nop 0
	s_nop 0
	s_nop 0
	s_nop 0
	s_nop 0
	s_nop 0
	s_waitcnt lgkmcnt(0)
	v_mfma_f32_32x32x16_bf16 v[16:31], v[86:89], v[136:139], v[16:31]
	ds_read_b64_tr_b16 v[86:87], v85 offset:34560
	ds_read_b64_tr_b16 v[88:89], v85 offset:35712
	s_nop 0
	s_nop 0
	v_cvt_pk_bf16_f32 v80, v56, v57
	v_cvt_pk_bf16_f32 v81, v58, v59
	v_cvt_pk_bf16_f32 v82, v60, v61
	v_cvt_pk_bf16_f32 v83, v62, v63
	v_add_f32_e32 v84, v184, v185
	v_add_f32_e32 v152, v152, v84
	s_waitcnt lgkmcnt(0)
	v_mfma_f32_32x32x16_bf16 v[32:47], v[86:89], v[80:83], v[32:47]
	ds_read_b64_tr_b16 v[86:87], v85 offset:34624
	ds_read_b64_tr_b16 v[88:89], v85 offset:35776
	s_waitcnt lgkmcnt(0)
	v_mfma_f32_32x32x16_bf16 v[16:31], v[86:89], v[80:83], v[16:31]

; DI unsigned pk_bf16(float lo, float hi) { f32x2 v = {lo, hi}; bf2_t b = __builtin_convertvector(v, bf2_t); return __builtin_bit_cast(unsigned, b); }
; DI float bf_lo(unsigned u) { return __uint_as_float(u << 16); }
; DI float bf_hi(unsigned u) { return __uint_as_float(u & 0xffff0000u); }
; template <int DQK, bool SB, bool SMAX>
; DI void attn_item(const Params& p, char* smem, int bh, int qb, float Mb) {
;     ...
;   float inv = 1.f;
;   if (!SB) { const float lt = lsum + other_half(lsum); inv = 1.f / lt; }
;   const size_t token = (size_t)(bh >> 3) * S_ + query;
;   const int colbase = (SB ? 0 : 512) + (bh & 7) * 64;
; #pragma unroll
;   for (int db = 0; db < 2; ++db) {
;     u32x2 w[4];
; #pragma unroll
;     for (int g = 0; g < 4; ++g) {
;       const int col = colbase + db * 32 + 8 * g + 4 * h;
;       const u32x2 gt = *(const u32x2*)(p.Gate + token * 1024 + col);
;       w[g].x = pk_bf16(O[db][4 * g] * inv * bf_lo(gt.x), O[db][4 * g + 1] * inv * bf_hi(gt.x));
;       w[g].y = pk_bf16(O[db][4 * g + 2] * inv * bf_lo(gt.y), O[db][4 * g + 3] * inv * bf_hi(gt.y));
;     }
; #pragma unroll
;     for (int q = 0; q < 2; ++q) *(u32x4*)(p.Mixed + token * 1024 + colbase + db * 32 + 16 * q + 8 * h) = widen_pair(w[2 * q], w[2 * q + 1]);
;   }
.LBB0_450:
	s_lshl_b32 s0, s0, 6
	v_readlane_b32 s2, v255, 15
	s_and_b32 s0, s0, 0x1c0
	v_lshlrev_b64 v[48:49], 11, v[176:177]
	v_readlane_b32 s3, v255, 16
	v_or_b32_e32 v52, s0, v197
	v_lshlrev_b32_e32 v176, 1, v52
	v_lshl_add_u64 v[48:49], v[48:49], 0, s[2:3]
	v_lshl_add_u64 v[50:51], s[94:95], 0, v[48:49]
	v_lshl_add_u64 v[50:51], v[50:51], 0, v[176:177]
	global_load_dwordx2 v[52:53], v[50:51], off
	global_load_dwordx2 v[54:55], v[50:51], off offset:16
	global_load_dwordx2 v[56:57], v[50:51], off offset:32
	global_load_dwordx2 v[58:59], v[50:51], off offset:48
	v_lshl_add_u64 v[48:49], s[86:87], 0, v[48:49]
	s_lshl_b32 s4, s0, 1
	v_mov_b32_e32 v181, v177
	v_lshl_add_u64 v[48:49], v[48:49], 0, s[4:5]
	v_lshl_add_u64 v[48:49], v[48:49], 0, v[180:181]
	v_readlane_b32 s72, v255, 2
	s_mov_b64 s[0:1], 0
	v_readlane_b32 s73, v255, 3
	s_mov_b32 s24, s79
	s_waitcnt vmcnt(3)
	v_lshlrev_b32_e32 v60, 16, v52
	v_and_b32_e32 v61, 0xffff0000, v52
	v_lshlrev_b32_e32 v52, 16, v53
	v_and_b32_e32 v53, 0xffff0000, v53
	s_waitcnt vmcnt(2)
	v_lshlrev_b32_e32 v62, 16, v54
	v_and_b32_e32 v63, 0xffff0000, v54
	v_lshlrev_b32_e32 v54, 16, v55
	v_and_b32_e32 v55, 0xffff0000, v55
	s_waitcnt vmcnt(1)
	v_lshlrev_b32_e32 v64, 16, v56
	v_and_b32_e32 v65, 0xffff0000, v56
	v_lshlrev_b32_e32 v56, 16, v57
	v_and_b32_e32 v57, 0xffff0000, v57
	s_waitcnt vmcnt(0)
	v_lshlrev_b32_e32 v66, 16, v58
	v_and_b32_e32 v67, 0xffff0000, v58
	v_lshlrev_b32_e32 v58, 16, v59
	v_and_b32_e32 v59, 0xffff0000, v59
	v_mul_f32_e64 v32, v32, v60
	v_mul_f32_e64 v33, v33, v61
	v_mul_f32_e64 v34, v34, v52
	v_mul_f32_e64 v35, v35, v53
	v_mul_f32_e64 v36, v36, v62
	v_mul_f32_e64 v37, v37, v63
	v_mul_f32_e64 v38, v38, v54
	v_mul_f32_e64 v39, v39, v55
	v_mul_f32_e64 v40, v40, v64
	v_mul_f32_e64 v41, v41, v65
	v_mul_f32_e64 v42, v42, v56
	v_mul_f32_e64 v43, v43, v57
	v_mul_f32_e64 v44, v44, v66
	v_mul_f32_e64 v45, v45, v67
	v_mul_f32_e64 v46, v46, v58
	v_mul_f32_e64 v47, v47, v59
	v_cvt_pk_bf16_f32 v32, v32, v33
	v_cvt_pk_bf16_f32 v33, v34, v35
	v_cvt_pk_bf16_f32 v34, v36, v37
	v_cvt_pk_bf16_f32 v35, v38, v39
	v_cvt_pk_bf16_f32 v36, v40, v41
	v_cvt_pk_bf16_f32 v37, v42, v43
	v_cvt_pk_bf16_f32 v38, v44, v45
	v_cvt_pk_bf16_f32 v39, v46, v47
	v_permlane32_swap_b32_e32 v32, v34
	v_permlane32_swap_b32_e32 v33, v35
	v_permlane32_swap_b32_e32 v36, v38
	v_permlane32_swap_b32_e32 v37, v39
	global_store_dwordx4 v[48:49], v[32:35], off
	global_store_dwordx4 v[48:49], v[36:39], off offset:32
	global_load_dwordx2 v[32:33], v[50:51], off offset:64
	s_nop 0
	global_load_dwordx2 v[34:35], v[50:51], off offset:80
	global_load_dwordx2 v[36:37], v[50:51], off offset:96
	global_load_dwordx2 v[38:39], v[50:51], off offset:112
	s_waitcnt vmcnt(3)
	v_lshlrev_b32_e32 v40, 16, v32
	v_and_b32_e32 v41, 0xffff0000, v32
	v_lshlrev_b32_e32 v32, 16, v33
	v_and_b32_e32 v33, 0xffff0000, v33
	s_waitcnt vmcnt(2)
	v_lshlrev_b32_e32 v42, 16, v34
	v_and_b32_e32 v43, 0xffff0000, v34
	v_lshlrev_b32_e32 v34, 16, v35
	v_and_b32_e32 v35, 0xffff0000, v35
	s_waitcnt vmcnt(1)
	v_lshlrev_b32_e32 v44, 16, v36
	v_and_b32_e32 v45, 0xffff0000, v36
	v_lshlrev_b32_e32 v36, 16, v37
	v_and_b32_e32 v37, 0xffff0000, v37
	s_waitcnt vmcnt(0)
	v_lshlrev_b32_e32 v46, 16, v38
	v_and_b32_e32 v47, 0xffff0000, v38
	v_lshlrev_b32_e32 v38, 16, v39
	v_and_b32_e32 v39, 0xffff0000, v39
	v_mul_f32_e64 v16, v16, v40
	v_mul_f32_e64 v17, v17, v41
	v_mul_f32_e64 v18, v18, v32
	v_mul_f32_e64 v19, v19, v33
	v_mul_f32_e64 v20, v20, v42
	v_mul_f32_e64 v21, v21, v43
	v_mul_f32_e64 v22, v22, v34
	v_mul_f32_e64 v23, v23, v35
	v_mul_f32_e64 v24, v24, v44
	v_mul_f32_e64 v25, v25, v45
	v_mul_f32_e64 v26, v26, v36
	v_mul_f32_e64 v27, v27, v37
	v_mul_f32_e64 v28, v28, v46
	v_mul_f32_e64 v29, v29, v47
	v_mul_f32_e64 v30, v30, v38
	v_mul_f32_e64 v31, v31, v39
	v_cvt_pk_bf16_f32 v16, v16, v17
	v_cvt_pk_bf16_f32 v17, v18, v19
	v_cvt_pk_bf16_f32 v18, v20, v21
	v_cvt_pk_bf16_f32 v19, v22, v23
	v_cvt_pk_bf16_f32 v20, v24, v25
	v_cvt_pk_bf16_f32 v21, v26, v27
	v_cvt_pk_bf16_f32 v22, v28, v29
	v_cvt_pk_bf16_f32 v23, v30, v31
	v_permlane32_swap_b32_e32 v16, v18
	v_permlane32_swap_b32_e32 v17, v19
	v_permlane32_swap_b32_e32 v20, v22
	v_permlane32_swap_b32_e32 v21, v23
	global_store_dwordx4 v[48:49], v[16:19], off offset:64
	global_store_dwordx4 v[48:49], v[20:23], off offset:96
	s_barrier

; #define MFMA32(a, b, c) __builtin_amdgcn_mfma_f32_32x32x16_bf16((a), (b), (c), 0, 0, 0)
; DI unsigned pk_bf16(float lo, float hi) { f32x2 v = {lo, hi}; bf2_t b = __builtin_convertvector(v, bf2_t); return __builtin_bit_cast(unsigned, b); }
; DI float fast_exp2(float x) { return __builtin_amdgcn_exp2f(x); }
; template <int DQK, bool SB, bool SMAX>
; DI void attn_item(const Params& p, char* smem, int bh, int qb, float Mb) {
;     ...
;         float mx = st[0][0];
; #pragma unroll
;         for (int kb = 0; kb < 2; ++kb)
; #pragma unroll
;           for (int i = 0; i < 16; ++i) mx = fmaxf(mx, st[kb][i]);
;         mx = fmaxf(mx, other_half(mx));
;         const float mnew = fmaxf(m, mx);
;         const float alpha = fast_exp2(m - mnew);
;         m = mnew;
;         float ps = 0.f;
; #pragma unroll
;         for (int kb = 0; kb < 2; ++kb)
; #pragma unroll
;           for (int i = 0; i < 16; ++i) { const float pv = fast_exp2(st[kb][i] - mnew); st[kb][i] = pv; ps += pv; }
;         lsum = lsum * alpha + ps;
; #pragma unroll
;         for (int db = 0; db < 2; ++db)
; #pragma unroll
;           for (int i = 0; i < 16; ++i) O[db][i] *= alpha;
;     ...
; #pragma unroll
;       for (int kb = 0; kb < 2; ++kb)
; #pragma unroll
;         for (int s = 0; s < 2; ++s) {
;           u32x4 w;
; #pragma unroll
;           for (int e = 0; e < 4; ++e) w[e] = pk_bf16(st[kb][8 * s + 2 * e], st[kb][8 * s + 2 * e + 1]);
;           pk[kb * 2 + s] = __builtin_bit_cast(bf16x8, w);
;         }
; #pragma unroll
;       for (int kk = 0; kk < 4; ++kk)
; #pragma unroll
;         for (int db = 0; db < 2; ++db) {
;           const s16x4 v0 = __builtin_amdgcn_ds_read_tr16_b64_v4i16((lds_s16x4*)(vc + voff + (16 * kk) * VSTR + 32 * db));
;           const s16x4 v1 = __builtin_amdgcn_ds_read_tr16_b64_v4i16((lds_s16x4*)(vc + voff + (16 * kk + 8) * VSTR + 32 * db));
;           const bf16x8 vf = __builtin_shufflevector(v0, v1, 0, 1, 2, 3, 4, 5, 6, 7);
;           O[db] = MFMA32(vf, pk[kk], O[db]);
;         }
.LBB0_455:
	s_or_b64 exec, exec, s[14:15]
	v_max_f32_e32 v152, v49, v49
	v_max_f32_e32 v153, v48, v48
	v_max_f32_e32 v152, v153, v152
	v_max3_f32 v152, v152, v50, v51
	v_max3_f32 v152, v152, v52, v53
	v_max3_f32 v152, v152, v54, v55
	v_max3_f32 v152, v152, v56, v57
	v_max3_f32 v152, v152, v58, v59
	v_max3_f32 v152, v152, v60, v61
	v_max3_f32 v152, v152, v62, v63
	v_max3_f32 v152, v152, v64, v65
	v_max3_f32 v152, v152, v66, v67
	v_max3_f32 v152, v152, v68, v69
	v_max3_f32 v152, v152, v70, v71
	v_max3_f32 v152, v152, v72, v73
	v_max3_f32 v152, v152, v74, v75
	v_max3_f32 v152, v152, v76, v77
	v_max3_f32 v152, v152, v78, v79
	v_mov_b32_e32 v153, v152
	v_mov_b32_e32 v154, v152
	s_nop 1
	v_permlane32_swap_b32_e32 v153, v154
	v_cndmask_b32_e64 v153, v153, v154, s[8:9]
	v_max3_f32 v165, v181, v152, v153
	v_sub_f32_e32 v48, v48, v165
	v_exp_f32_e32 v48, v48
	v_sub_f32_e32 v49, v49, v165
	v_exp_f32_e32 v49, v49
	v_sub_f32_e32 v50, v50, v165
	v_exp_f32_e32 v50, v50
	v_sub_f32_e32 v51, v51, v165
	v_exp_f32_e32 v51, v51
	v_sub_f32_e32 v52, v52, v165
	v_add_f32_e32 v153, 0, v48
	v_exp_f32_e32 v52, v52
	v_sub_f32_e32 v53, v53, v165
	v_add_f32_e32 v153, v49, v153
	v_exp_f32_e32 v53, v53
	v_sub_f32_e32 v54, v54, v165
	v_add_f32_e32 v153, v50, v153
	v_exp_f32_e32 v54, v54
	v_sub_f32_e32 v55, v55, v165
	v_add_f32_e32 v153, v51, v153
	v_exp_f32_e32 v55, v55
	v_sub_f32_e32 v56, v56, v165
	v_add_f32_e32 v153, v52, v153
	v_exp_f32_e32 v56, v56
	v_sub_f32_e32 v57, v57, v165
	v_add_f32_e32 v153, v53, v153
	v_exp_f32_e32 v57, v57
	v_sub_f32_e32 v58, v58, v165
	v_add_f32_e32 v153, v54, v153
	v_exp_f32_e32 v58, v58
	v_sub_f32_e32 v59, v59, v165
	v_add_f32_e32 v153, v55, v153
	v_exp_f32_e32 v59, v59
	v_sub_f32_e32 v60, v60, v165
	v_add_f32_e32 v153, v56, v153
	v_exp_f32_e32 v60, v60
	v_sub_f32_e32 v61, v61, v165
	v_add_f32_e32 v153, v57, v153
	v_exp_f32_e32 v61, v61
	v_sub_f32_e32 v62, v62, v165
	v_add_f32_e32 v153, v58, v153
	v_exp_f32_e32 v62, v62
	v_sub_f32_e32 v63, v63, v165
	v_add_f32_e32 v153, v59, v153
	v_exp_f32_e32 v63, v63
	v_add_f32_e32 v153, v60, v153
	v_add_f32_e32 v153, v61, v153
	v_sub_f32_e32 v152, v181, v165
	v_add_f32_e32 v153, v62, v153
	v_add_u32_e32 v167, v198, v200
	v_add_f32_e32 v166, v63, v153
	v_exp_f32_e32 v164, v152
	ds_read_b64_tr_b16 v[152:153], v167 offset:35840
	ds_read_b64_tr_b16 v[154:155], v167 offset:36992
	ds_read_b64_tr_b16 v[162:163], v167 offset:37056
	ds_read_b64_tr_b16 v[160:161], v167 offset:35904
	v_cvt_pk_bf16_f32 v156, v48, v49
	v_mul_f32_e64 v46, v46, v164
	v_mul_f32_e64 v47, v47, v164
	v_mul_f32_e64 v44, v44, v164
	v_mul_f32_e64 v45, v45, v164
	v_mul_f32_e64 v42, v42, v164
	v_mul_f32_e64 v43, v43, v164
	v_mul_f32_e64 v40, v40, v164
	v_mul_f32_e64 v41, v41, v164
	v_mul_f32_e64 v38, v38, v164
	v_mul_f32_e64 v39, v39, v164
	v_mul_f32_e64 v36, v36, v164
	v_mul_f32_e64 v37, v37, v164
	v_mul_f32_e64 v34, v34, v164
	v_mul_f32_e64 v35, v35, v164
	v_mul_f32_e64 v32, v32, v164
	v_mul_f32_e64 v33, v33, v164
	v_cvt_pk_bf16_f32 v157, v50, v51
	v_cvt_pk_bf16_f32 v158, v52, v53
	v_cvt_pk_bf16_f32 v159, v54, v55
	v_mul_f32_e64 v30, v30, v164
	v_mul_f32_e64 v31, v31, v164
	v_mul_f32_e64 v28, v28, v164
	v_mul_f32_e64 v29, v29, v164
	s_waitcnt lgkmcnt(2)
	v_mfma_f32_32x32x16_bf16 v[32:47], v[152:155], v[156:159], v[32:47]
	v_mul_f32_e64 v26, v26, v164
	v_mul_f32_e64 v27, v27, v164
	v_mul_f32_e64 v24, v24, v164
	v_mul_f32_e64 v25, v25, v164
	v_mul_f32_e64 v22, v22, v164
	v_mul_f32_e64 v23, v23, v164
	v_mul_f32_e64 v20, v20, v164
	v_mul_f32_e64 v21, v21, v164
	v_mul_f32_e64 v18, v18, v164
	v_mul_f32_e64 v19, v19, v164
	v_mul_f32_e64 v16, v16, v164
	v_mul_f32_e64 v17, v17, v164
	ds_read_b64_tr_b16 v[152:153], v167 offset:38144
	ds_read_b64_tr_b16 v[154:155], v167 offset:39296
	s_waitcnt lgkmcnt(2)
	v_mfma_f32_32x32x16_bf16 v[16:31], v[160:163], v[156:159], v[16:31]
	v_sub_f32_e32 v64, v64, v165
	ds_read_b64_tr_b16 v[162:163], v167 offset:39360
	ds_read_b64_tr_b16 v[160:161], v167 offset:38208
	v_exp_f32_e32 v64, v64
	v_sub_f32_e32 v65, v65, v165
	v_exp_f32_e32 v65, v65
	v_cvt_pk_bf16_f32 v156, v56, v57
	v_cvt_pk_bf16_f32 v157, v58, v59
	v_cvt_pk_bf16_f32 v158, v60, v61
	v_cvt_pk_bf16_f32 v159, v62, v63
	v_sub_f32_e32 v66, v66, v165
	v_sub_f32_e32 v67, v67, v165
	s_waitcnt lgkmcnt(2)
	v_mfma_f32_32x32x16_bf16 v[32:47], v[152:155], v[156:159], v[32:47]
	v_sub_f32_e32 v68, v68, v165
	v_sub_f32_e32 v69, v69, v165
	v_sub_f32_e32 v70, v70, v165
	v_sub_f32_e32 v71, v71, v165
	v_add_f32_e32 v152, v64, v166
	v_exp_f32_e32 v66, v66
	v_exp_f32_e32 v67, v67
	s_waitcnt lgkmcnt(0)
	v_mfma_f32_32x32x16_bf16 v[16:31], v[160:163], v[156:159], v[16:31]
	v_exp_f32_e32 v68, v68
	v_exp_f32_e32 v69, v69
	v_exp_f32_e32 v70, v70
	v_exp_f32_e32 v71, v71
	v_add_f32_e32 v166, v65, v152
	ds_read_b64_tr_b16 v[152:153], v167 offset:40448
	ds_read_b64_tr_b16 v[154:155], v167 offset:41600
	ds_read_b64_tr_b16 v[162:163], v167 offset:41664
	ds_read_b64_tr_b16 v[160:161], v167 offset:40512
	v_add_f32_e32 v166, v66, v166
	v_cvt_pk_bf16_f32 v156, v64, v65
	v_cvt_pk_bf16_f32 v157, v66, v67
	v_cvt_pk_bf16_f32 v158, v68, v69
	v_cvt_pk_bf16_f32 v159, v70, v71
	v_sub_f32_e32 v72, v72, v165
	v_sub_f32_e32 v73, v73, v165
	s_waitcnt lgkmcnt(2)
	v_mfma_f32_32x32x16_bf16 v[32:47], v[152:155], v[156:159], v[32:47]
	v_add_f32_e32 v152, v67, v166
	v_add_f32_e32 v152, v68, v152
	v_add_f32_e32 v152, v69, v152
	v_sub_f32_e32 v74, v74, v165
	v_sub_f32_e32 v75, v75, v165
	v_sub_f32_e32 v76, v76, v165
	v_sub_f32_e32 v77, v77, v165
	s_waitcnt lgkmcnt(0)
	v_mfma_f32_32x32x16_bf16 v[16:31], v[160:163], v[156:159], v[16:31]
	v_sub_f32_e32 v78, v78, v165
	v_sub_f32_e32 v79, v79, v165
	v_add_f32_e32 v152, v70, v152
	v_exp_f32_e32 v72, v72
	v_exp_f32_e32 v73, v73
	v_exp_f32_e32 v74, v74
	v_exp_f32_e32 v75, v75
	v_exp_f32_e32 v76, v76
	v_exp_f32_e32 v77, v77
	v_exp_f32_e32 v78, v78
	v_exp_f32_e32 v79, v79
	v_add_f32_e32 v166, v71, v152
	ds_read_b64_tr_b16 v[152:153], v167 offset:42752
	ds_read_b64_tr_b16 v[154:155], v167 offset:43904
	ds_read_b64_tr_b16 v[162:163], v167 offset:43968
	ds_read_b64_tr_b16 v[160:161], v167 offset:42816
	v_add_f32_e32 v166, v72, v166
	v_cvt_pk_bf16_f32 v156, v72, v73
	v_cvt_pk_bf16_f32 v157, v74, v75
	v_cvt_pk_bf16_f32 v158, v76, v77
	v_cvt_pk_bf16_f32 v159, v78, v79
	v_mov_b32_e32 v181, v165
	s_waitcnt lgkmcnt(2)
	v_mfma_f32_32x32x16_bf16 v[32:47], v[152:155], v[156:159], v[32:47]
	v_add_f32_e32 v152, v73, v166
	v_add_f32_e32 v152, v74, v152
	v_add_f32_e32 v152, v75, v152
	v_add_f32_e32 v152, v76, v152
	v_add_f32_e32 v152, v77, v152
	v_add_f32_e32 v152, v78, v152
	v_add_f32_e32 v152, v79, v152
	s_waitcnt lgkmcnt(0)
	v_mfma_f32_32x32x16_bf16 v[16:31], v[160:163], v[156:159], v[16:31]
	v_fmac_f32_e32 v152, v212, v164
	v_mov_b32_e32 v212, v152

; #define MFMA32(a, b, c) __builtin_amdgcn_mfma_f32_32x32x16_bf16((a), (b), (c), 0, 0, 0)
; DI unsigned pk_bf16(float lo, float hi) { f32x2 v = {lo, hi}; bf2_t b = __builtin_convertvector(v, bf2_t); return __builtin_bit_cast(unsigned, b); }
; DI float fast_exp2(float x) { return __builtin_amdgcn_exp2f(x); }
; template <int DQK, bool SB, bool SMAX>
; DI void attn_item(const Params& p, char* smem, int bh, int qb, float Mb) {
;     ...
;         float mx = st[0][0];
; #pragma unroll
;         for (int kb = 0; kb < 2; ++kb)
; #pragma unroll
;           for (int i = 0; i < 16; ++i) mx = fmaxf(mx, st[kb][i]);
;         mx = fmaxf(mx, other_half(mx));
;         const float mnew = fmaxf(m, mx);
;         const float alpha = fast_exp2(m - mnew);
;         m = mnew;
;         float ps = 0.f;
; #pragma unroll
;         for (int kb = 0; kb < 2; ++kb)
; #pragma unroll
;           for (int i = 0; i < 16; ++i) { const float pv = fast_exp2(st[kb][i] - mnew); st[kb][i] = pv; ps += pv; }
;         lsum = lsum * alpha + ps;
; #pragma unroll
;         for (int db = 0; db < 2; ++db)
; #pragma unroll
;           for (int i = 0; i < 16; ++i) O[db][i] *= alpha;
;     ...
; #pragma unroll
;       for (int kb = 0; kb < 2; ++kb)
; #pragma unroll
;         for (int s = 0; s < 2; ++s) {
;           u32x4 w;
; #pragma unroll
;           for (int e = 0; e < 4; ++e) w[e] = pk_bf16(st[kb][8 * s + 2 * e], st[kb][8 * s + 2 * e + 1]);
;           pk[kb * 2 + s] = __builtin_bit_cast(bf16x8, w);
;         }
; #pragma unroll
;       for (int kk = 0; kk < 4; ++kk)
; #pragma unroll
;         for (int db = 0; db < 2; ++db) {
;           const s16x4 v0 = __builtin_amdgcn_ds_read_tr16_b64_v4i16((lds_s16x4*)(vc + voff + (16 * kk) * VSTR + 32 * db));
;           const s16x4 v1 = __builtin_amdgcn_ds_read_tr16_b64_v4i16((lds_s16x4*)(vc + voff + (16 * kk + 8) * VSTR + 32 * db));
;           const bf16x8 vf = __builtin_shufflevector(v0, v1, 0, 1, 2, 3, 4, 5, 6, 7);
;           O[db] = MFMA32(vf, pk[kk], O[db]);
;         }
.LBB0_462:
	s_or_b64 exec, exec, s[14:15]
	v_max_f32_e32 v132, v49, v49
	v_max_f32_e32 v133, v48, v48
	v_max_f32_e32 v132, v133, v132
	v_max3_f32 v132, v132, v50, v51
	v_max3_f32 v132, v132, v52, v53
	v_max3_f32 v132, v132, v54, v55
	v_max3_f32 v132, v132, v56, v57
	v_max3_f32 v132, v132, v58, v59
	v_max3_f32 v132, v132, v60, v61
	v_max3_f32 v132, v132, v62, v63
	v_max3_f32 v132, v132, v64, v65
	v_max3_f32 v132, v132, v66, v67
	v_max3_f32 v132, v132, v68, v69
	v_max3_f32 v132, v132, v70, v71
	v_max3_f32 v132, v132, v72, v73
	v_max3_f32 v132, v132, v74, v75
	v_max3_f32 v132, v132, v76, v77
	v_max3_f32 v132, v132, v78, v79
	v_mov_b32_e32 v133, v132
	v_mov_b32_e32 v134, v132
	s_nop 1
	v_permlane32_swap_b32_e32 v133, v134
	v_cndmask_b32_e64 v133, v133, v134, s[8:9]
	v_max3_f32 v145, v181, v132, v133
	v_sub_f32_e32 v48, v48, v145
	v_exp_f32_e32 v48, v48
	v_sub_f32_e32 v49, v49, v145
	v_exp_f32_e32 v49, v49
	v_sub_f32_e32 v50, v50, v145
	v_exp_f32_e32 v50, v50
	v_sub_f32_e32 v51, v51, v145
	v_exp_f32_e32 v51, v51
	v_sub_f32_e32 v52, v52, v145
	v_add_f32_e32 v133, 0, v48
	v_exp_f32_e32 v52, v52
	v_sub_f32_e32 v53, v53, v145
	v_add_f32_e32 v133, v49, v133
	v_exp_f32_e32 v53, v53
	v_sub_f32_e32 v54, v54, v145
	v_add_f32_e32 v133, v50, v133
	v_exp_f32_e32 v54, v54
	v_sub_f32_e32 v55, v55, v145
	v_add_f32_e32 v133, v51, v133
	v_exp_f32_e32 v55, v55
	v_sub_f32_e32 v56, v56, v145
	v_add_f32_e32 v133, v52, v133
	v_exp_f32_e32 v56, v56
	v_sub_f32_e32 v57, v57, v145
	v_add_f32_e32 v133, v53, v133
	v_exp_f32_e32 v57, v57
	v_sub_f32_e32 v58, v58, v145
	v_add_f32_e32 v133, v54, v133
	v_exp_f32_e32 v58, v58
	v_sub_f32_e32 v59, v59, v145
	v_add_f32_e32 v133, v55, v133
	v_exp_f32_e32 v59, v59
	v_sub_f32_e32 v60, v60, v145
	v_add_f32_e32 v133, v56, v133
	v_exp_f32_e32 v60, v60
	v_sub_f32_e32 v61, v61, v145
	v_add_f32_e32 v133, v57, v133
	v_exp_f32_e32 v61, v61
	v_sub_f32_e32 v62, v62, v145
	v_add_f32_e32 v133, v58, v133
	v_exp_f32_e32 v62, v62
	v_sub_f32_e32 v63, v63, v145
	v_add_f32_e32 v133, v59, v133
	v_exp_f32_e32 v63, v63
	v_add_f32_e32 v133, v60, v133
	v_add_f32_e32 v133, v61, v133
	v_sub_f32_e32 v132, v181, v145
	v_add_f32_e32 v133, v62, v133
	v_add_u32_e32 v147, v198, v200
	v_add_f32_e32 v146, v63, v133
	v_exp_f32_e32 v144, v132
	ds_read_b64_tr_b16 v[132:133], v147 offset:26624
	ds_read_b64_tr_b16 v[134:135], v147 offset:27776
	ds_read_b64_tr_b16 v[142:143], v147 offset:27840
	ds_read_b64_tr_b16 v[140:141], v147 offset:26688
	v_cvt_pk_bf16_f32 v136, v48, v49
	v_mul_f32_e64 v46, v46, v144
	v_mul_f32_e64 v47, v47, v144
	v_mul_f32_e64 v44, v44, v144
	v_mul_f32_e64 v45, v45, v144
	v_mul_f32_e64 v42, v42, v144
	v_mul_f32_e64 v43, v43, v144
	v_mul_f32_e64 v40, v40, v144
	v_mul_f32_e64 v41, v41, v144
	v_mul_f32_e64 v38, v38, v144
	v_mul_f32_e64 v39, v39, v144
	v_mul_f32_e64 v36, v36, v144
	v_mul_f32_e64 v37, v37, v144
	v_mul_f32_e64 v34, v34, v144
	v_mul_f32_e64 v35, v35, v144
	v_mul_f32_e64 v32, v32, v144
	v_mul_f32_e64 v33, v33, v144
	v_cvt_pk_bf16_f32 v137, v50, v51
	v_cvt_pk_bf16_f32 v138, v52, v53
	v_cvt_pk_bf16_f32 v139, v54, v55
	v_mul_f32_e64 v30, v30, v144
	v_mul_f32_e64 v31, v31, v144
	v_mul_f32_e64 v28, v28, v144
	v_mul_f32_e64 v29, v29, v144
	s_waitcnt lgkmcnt(2)
	v_mfma_f32_32x32x16_bf16 v[32:47], v[132:135], v[136:139], v[32:47]
	v_mul_f32_e64 v26, v26, v144
	v_mul_f32_e64 v27, v27, v144
	v_mul_f32_e64 v24, v24, v144
	v_mul_f32_e64 v25, v25, v144
	v_mul_f32_e64 v22, v22, v144
	v_mul_f32_e64 v23, v23, v144
	v_mul_f32_e64 v20, v20, v144
	v_mul_f32_e64 v21, v21, v144
	v_mul_f32_e64 v18, v18, v144
	v_mul_f32_e64 v19, v19, v144
	v_mul_f32_e64 v16, v16, v144
	v_mul_f32_e64 v17, v17, v144
	ds_read_b64_tr_b16 v[132:133], v147 offset:28928
	ds_read_b64_tr_b16 v[134:135], v147 offset:30080
	s_waitcnt lgkmcnt(2)
	v_mfma_f32_32x32x16_bf16 v[16:31], v[140:143], v[136:139], v[16:31]
	v_sub_f32_e32 v64, v64, v145
	ds_read_b64_tr_b16 v[142:143], v147 offset:30144
	ds_read_b64_tr_b16 v[140:141], v147 offset:28992
	v_exp_f32_e32 v64, v64
	v_sub_f32_e32 v65, v65, v145
	v_exp_f32_e32 v65, v65
	v_cvt_pk_bf16_f32 v136, v56, v57
	v_cvt_pk_bf16_f32 v137, v58, v59
	v_cvt_pk_bf16_f32 v138, v60, v61
	v_cvt_pk_bf16_f32 v139, v62, v63
	v_sub_f32_e32 v66, v66, v145
	v_sub_f32_e32 v67, v67, v145
	s_waitcnt lgkmcnt(2)
	v_mfma_f32_32x32x16_bf16 v[32:47], v[132:135], v[136:139], v[32:47]
	v_sub_f32_e32 v68, v68, v145
	v_sub_f32_e32 v69, v69, v145
	v_sub_f32_e32 v70, v70, v145
	v_sub_f32_e32 v71, v71, v145
	v_add_f32_e32 v132, v64, v146
	v_exp_f32_e32 v66, v66
	v_exp_f32_e32 v67, v67
	s_waitcnt lgkmcnt(0)
	v_mfma_f32_32x32x16_bf16 v[16:31], v[140:143], v[136:139], v[16:31]
	v_exp_f32_e32 v68, v68
	v_exp_f32_e32 v69, v69
	v_exp_f32_e32 v70, v70
	v_exp_f32_e32 v71, v71
	v_add_f32_e32 v146, v65, v132
	ds_read_b64_tr_b16 v[132:133], v147 offset:31232
	ds_read_b64_tr_b16 v[134:135], v147 offset:32384
	ds_read_b64_tr_b16 v[142:143], v147 offset:32448
	ds_read_b64_tr_b16 v[140:141], v147 offset:31296
	v_add_f32_e32 v146, v66, v146
	v_cvt_pk_bf16_f32 v136, v64, v65
	v_cvt_pk_bf16_f32 v137, v66, v67
	v_cvt_pk_bf16_f32 v138, v68, v69
	v_cvt_pk_bf16_f32 v139, v70, v71
	v_sub_f32_e32 v72, v72, v145
	v_sub_f32_e32 v73, v73, v145
	s_waitcnt lgkmcnt(2)
	v_mfma_f32_32x32x16_bf16 v[32:47], v[132:135], v[136:139], v[32:47]
	v_add_f32_e32 v132, v67, v146
	v_add_f32_e32 v132, v68, v132
	v_add_f32_e32 v132, v69, v132
	v_sub_f32_e32 v74, v74, v145
	v_sub_f32_e32 v75, v75, v145
	v_sub_f32_e32 v76, v76, v145
	v_sub_f32_e32 v77, v77, v145
	s_waitcnt lgkmcnt(0)
	v_mfma_f32_32x32x16_bf16 v[16:31], v[140:143], v[136:139], v[16:31]
	v_sub_f32_e32 v78, v78, v145
	v_sub_f32_e32 v79, v79, v145
	v_add_f32_e32 v132, v70, v132
	v_exp_f32_e32 v72, v72
	v_exp_f32_e32 v73, v73
	v_exp_f32_e32 v74, v74
	v_exp_f32_e32 v75, v75
	v_exp_f32_e32 v76, v76
	v_exp_f32_e32 v77, v77
	v_exp_f32_e32 v78, v78
	v_exp_f32_e32 v79, v79
	v_add_f32_e32 v146, v71, v132
	ds_read_b64_tr_b16 v[132:133], v147 offset:33536
	ds_read_b64_tr_b16 v[134:135], v147 offset:34688
	ds_read_b64_tr_b16 v[142:143], v147 offset:34752
	ds_read_b64_tr_b16 v[140:141], v147 offset:33600
	v_add_f32_e32 v146, v72, v146
	v_cvt_pk_bf16_f32 v136, v72, v73
	v_cvt_pk_bf16_f32 v137, v74, v75
	v_cvt_pk_bf16_f32 v138, v76, v77
	v_cvt_pk_bf16_f32 v139, v78, v79
	v_mov_b32_e32 v181, v145
	s_waitcnt lgkmcnt(2)
	v_mfma_f32_32x32x16_bf16 v[32:47], v[132:135], v[136:139], v[32:47]
	v_add_f32_e32 v132, v73, v146
	v_add_f32_e32 v132, v74, v132
	v_add_f32_e32 v132, v75, v132
	v_add_f32_e32 v132, v76, v132
	v_add_f32_e32 v132, v77, v132
	v_add_f32_e32 v132, v78, v132
	v_add_f32_e32 v132, v79, v132
	s_waitcnt lgkmcnt(0)
	v_mfma_f32_32x32x16_bf16 v[16:31], v[140:143], v[136:139], v[16:31]
	v_fmac_f32_e32 v132, v212, v144
	v_mov_b32_e32 v212, v132

; DI unsigned pk_bf16(float lo, float hi) { f32x2 v = {lo, hi}; bf2_t b = __builtin_convertvector(v, bf2_t); return __builtin_bit_cast(unsigned, b); }
; DI float bf_lo(unsigned u) { return __uint_as_float(u << 16); }
; DI float bf_hi(unsigned u) { return __uint_as_float(u & 0xffff0000u); }
; template <int DQK, bool SB, bool SMAX>
; DI void attn_item(const Params& p, char* smem, int bh, int qb, float Mb) {
;     ...
;   float inv = 1.f;
;   if (!SB) { const float lt = lsum + other_half(lsum); inv = 1.f / lt; }
;   const size_t token = (size_t)(bh >> 3) * S_ + query;
;   const int colbase = (SB ? 0 : 512) + (bh & 7) * 64;
; #pragma unroll
;   for (int db = 0; db < 2; ++db) {
;     u32x2 w[4];
; #pragma unroll
;     for (int g = 0; g < 4; ++g) {
;       const int col = colbase + db * 32 + 8 * g + 4 * h;
;       const u32x2 gt = *(const u32x2*)(p.Gate + token * 1024 + col);
;       w[g].x = pk_bf16(O[db][4 * g] * inv * bf_lo(gt.x), O[db][4 * g + 1] * inv * bf_hi(gt.x));
;       w[g].y = pk_bf16(O[db][4 * g + 2] * inv * bf_lo(gt.y), O[db][4 * g + 3] * inv * bf_hi(gt.y));
;     }
; #pragma unroll
;     for (int q = 0; q < 2; ++q) *(u32x4*)(p.Mixed + token * 1024 + colbase + db * 32 + 16 * q + 8 * h) = widen_pair(w[2 * q], w[2 * q + 1]);
;   }
.LBB0_469:
	s_lshl_b32 s2, s0, 6
	v_readlane_b32 s14, v255, 15
	s_and_b32 s2, s2, 0x1c0
	v_lshlrev_b64 v[48:49], 11, v[176:177]
	v_readlane_b32 s15, v255, 16
	v_or_b32_e32 v52, s2, v197
	v_lshlrev_b32_e32 v52, 1, v52
	v_lshl_add_u64 v[48:49], v[48:49], 0, s[14:15]
	v_lshl_add_u64 v[50:51], s[94:95], 0, v[48:49]
	v_mov_b32_e32 v53, v177
	v_lshl_add_u64 v[50:51], v[50:51], 0, v[52:53]
	global_load_dwordx2 v[52:53], v[50:51], off offset:1024
	global_load_dwordx2 v[54:55], v[50:51], off offset:1040
	global_load_dwordx2 v[56:57], v[50:51], off offset:1056
	global_load_dwordx2 v[58:59], v[50:51], off offset:1072
	v_mov_b32_e32 v60, v212
	v_mov_b32_e32 v61, v212
	s_nop 1
	v_permlane32_swap_b32_e32 v60, v61
	v_cndmask_b32_e64 v60, v60, v61, s[8:9]
	v_add_f32_e32 v60, v212, v60
	s_lshl_b32 s4, s2, 1
	v_div_scale_f32 v61, s[2:3], v60, v60, 1.0
	v_rcp_f32_e32 v62, v61
	v_div_scale_f32 v63, vcc, 1.0, v60, 1.0
	v_lshl_add_u64 v[48:49], s[86:87], 0, v[48:49]
	v_fma_f32 v64, -v61, v62, 1.0
	v_fmac_f32_e32 v62, v64, v62
	v_mul_f32_e32 v64, v63, v62
	v_fma_f32 v65, -v61, v64, v63
	v_fmac_f32_e32 v64, v65, v62
	v_fma_f32 v61, -v61, v64, v63
	v_div_fmas_f32 v61, v61, v62, v64
	v_div_fixup_f32 v60, v61, v60, 1.0
	v_mul_f32_e64 v32, v32, v60
	v_mul_f32_e64 v33, v33, v60
	v_mul_f32_e64 v34, v34, v60
	v_mul_f32_e64 v35, v35, v60
	v_mul_f32_e64 v36, v36, v60
	v_mul_f32_e64 v37, v37, v60
	v_mul_f32_e64 v38, v38, v60
	v_mul_f32_e64 v39, v39, v60
	v_mul_f32_e64 v40, v40, v60
	v_mul_f32_e64 v41, v41, v60
	v_mul_f32_e64 v42, v42, v60
	v_mul_f32_e64 v43, v43, v60
	v_mul_f32_e64 v44, v44, v60
	v_mul_f32_e64 v45, v45, v60
	v_mul_f32_e64 v46, v46, v60
	v_mul_f32_e64 v47, v47, v60
	v_mov_b32_e32 v181, v177
	v_lshl_add_u64 v[48:49], v[48:49], 0, s[4:5]
	v_lshl_add_u64 v[48:49], v[48:49], 0, v[180:181]
	v_mul_f32_e64 v16, v16, v60
	v_mul_f32_e64 v17, v17, v60
	v_mul_f32_e64 v18, v18, v60
	v_mul_f32_e64 v19, v19, v60
	v_mul_f32_e64 v20, v20, v60
	v_mul_f32_e64 v21, v21, v60
	v_mul_f32_e64 v22, v22, v60
	v_mul_f32_e64 v23, v23, v60
	v_mul_f32_e64 v24, v24, v60
	v_mul_f32_e64 v25, v25, v60
	v_mul_f32_e64 v26, v26, v60
	v_mul_f32_e64 v27, v27, v60
	v_mul_f32_e64 v28, v28, v60
	v_mul_f32_e64 v29, v29, v60
	v_mul_f32_e64 v30, v30, v60
	v_mul_f32_e64 v31, v31, v60
	s_mov_b64 s[2:3], 0
	s_waitcnt vmcnt(3)
	v_lshlrev_b32_e32 v62, 16, v52
	v_and_b32_e32 v63, 0xffff0000, v52
	v_lshlrev_b32_e32 v52, 16, v53
	v_and_b32_e32 v53, 0xffff0000, v53
	s_waitcnt vmcnt(2)
	v_lshlrev_b32_e32 v64, 16, v54
	v_and_b32_e32 v65, 0xffff0000, v54
	v_lshlrev_b32_e32 v54, 16, v55
	v_and_b32_e32 v55, 0xffff0000, v55
	s_waitcnt vmcnt(1)
	v_lshlrev_b32_e32 v66, 16, v56
	v_and_b32_e32 v67, 0xffff0000, v56
	v_lshlrev_b32_e32 v56, 16, v57
	v_and_b32_e32 v57, 0xffff0000, v57
	s_waitcnt vmcnt(0)
	v_lshlrev_b32_e32 v68, 16, v58
	v_and_b32_e32 v69, 0xffff0000, v58
	v_lshlrev_b32_e32 v58, 16, v59
	v_and_b32_e32 v59, 0xffff0000, v59
	v_mul_f32_e64 v32, v32, v62
	v_mul_f32_e64 v33, v33, v63
	v_mul_f32_e64 v34, v34, v52
	v_mul_f32_e64 v35, v35, v53
	v_mul_f32_e64 v36, v36, v64
	v_mul_f32_e64 v37, v37, v65
	v_mul_f32_e64 v38, v38, v54
	v_mul_f32_e64 v39, v39, v55
	v_mul_f32_e64 v40, v40, v66
	v_mul_f32_e64 v41, v41, v67
	v_mul_f32_e64 v42, v42, v56
	v_mul_f32_e64 v43, v43, v57
	v_mul_f32_e64 v44, v44, v68
	v_mul_f32_e64 v45, v45, v69
	v_mul_f32_e64 v46, v46, v58
	v_mul_f32_e64 v47, v47, v59
	v_cvt_pk_bf16_f32 v32, v32, v33
	v_cvt_pk_bf16_f32 v33, v34, v35
	v_cvt_pk_bf16_f32 v34, v36, v37
	v_cvt_pk_bf16_f32 v35, v38, v39
	v_cvt_pk_bf16_f32 v36, v40, v41
	v_cvt_pk_bf16_f32 v37, v42, v43
	v_cvt_pk_bf16_f32 v38, v44, v45
	v_cvt_pk_bf16_f32 v39, v46, v47
	v_permlane32_swap_b32_e32 v32, v34
	v_permlane32_swap_b32_e32 v33, v35
	v_permlane32_swap_b32_e32 v36, v38
	v_permlane32_swap_b32_e32 v37, v39
	global_store_dwordx4 v[48:49], v[32:35], off offset:1024
	global_store_dwordx4 v[48:49], v[36:39], off offset:1056
	global_load_dwordx2 v[32:33], v[50:51], off offset:1088
	s_nop 0
	global_load_dwordx2 v[34:35], v[50:51], off offset:1104
	global_load_dwordx2 v[36:37], v[50:51], off offset:1120
	global_load_dwordx2 v[38:39], v[50:51], off offset:1136
	s_waitcnt vmcnt(3)
	v_lshlrev_b32_e32 v40, 16, v32
	v_and_b32_e32 v41, 0xffff0000, v32
	v_lshlrev_b32_e32 v32, 16, v33
	v_and_b32_e32 v33, 0xffff0000, v33
	s_waitcnt vmcnt(2)
	v_lshlrev_b32_e32 v42, 16, v34
	v_and_b32_e32 v43, 0xffff0000, v34
	v_lshlrev_b32_e32 v34, 16, v35
	v_and_b32_e32 v35, 0xffff0000, v35
	s_waitcnt vmcnt(1)
	v_lshlrev_b32_e32 v44, 16, v36
	v_and_b32_e32 v45, 0xffff0000, v36
	v_lshlrev_b32_e32 v36, 16, v37
	v_and_b32_e32 v37, 0xffff0000, v37
	s_waitcnt vmcnt(0)
	v_lshlrev_b32_e32 v46, 16, v38
	v_and_b32_e32 v47, 0xffff0000, v38
	v_lshlrev_b32_e32 v38, 16, v39
	v_and_b32_e32 v39, 0xffff0000, v39
	v_mul_f32_e64 v16, v16, v40
	v_mul_f32_e64 v17, v17, v41
	v_mul_f32_e64 v18, v18, v32
	v_mul_f32_e64 v19, v19, v33
	v_mul_f32_e64 v20, v20, v42
	v_mul_f32_e64 v21, v21, v43
	v_mul_f32_e64 v22, v22, v34
	v_mul_f32_e64 v23, v23, v35
	v_mul_f32_e64 v24, v24, v44
	v_mul_f32_e64 v25, v25, v45
	v_mul_f32_e64 v26, v26, v36
	v_mul_f32_e64 v27, v27, v37
	v_mul_f32_e64 v28, v28, v46
	v_mul_f32_e64 v29, v29, v47
	v_mul_f32_e64 v30, v30, v38
	v_mul_f32_e64 v31, v31, v39
	v_cvt_pk_bf16_f32 v16, v16, v17
	v_cvt_pk_bf16_f32 v17, v18, v19
	v_cvt_pk_bf16_f32 v18, v20, v21
	v_cvt_pk_bf16_f32 v19, v22, v23
	v_cvt_pk_bf16_f32 v20, v24, v25
	v_cvt_pk_bf16_f32 v21, v26, v27
	v_cvt_pk_bf16_f32 v22, v28, v29
	v_cvt_pk_bf16_f32 v23, v30, v31
	v_permlane32_swap_b32_e32 v16, v18
	v_permlane32_swap_b32_e32 v17, v19
	v_permlane32_swap_b32_e32 v20, v22
	v_permlane32_swap_b32_e32 v21, v23
	global_store_dwordx4 v[48:49], v[16:19], off offset:1088
	global_store_dwordx4 v[48:49], v[20:23], off offset:1120
	s_barrier

; DI float bf_lo(unsigned u) { return __uint_as_float(u << 16); }
;     ...
;   if (cold) {
;     GT_LOAD(0, 0)
;     GT_LOAD(1, 1)
;     GT_WRITE(0, lds, true)
;     GT_LOAD(0, (2 < nk) ? 2 : nk - 1)
;     __syncthreads();
;   }
;   for (int kt2 = 0; kt2 < nk; kt2 += 2) {
; #pragma unroll
;     for (int st = 0; st < 2; ++st) {
;       const int kt = kt2 + st;
;       const bf16_t* cur = lds + st * BUFE;
;       bf16_t* oth = lds + (st ^ 1) * BUFE;
;       const long k0r = (kt + 3 < nk) ? (long)(kt + 3) * BK : dR + (long)(kt + 3 - nk) * BK;
;       const long k0c = (kt + 3 < nk) ? (long)(kt + 3) * BK : dC + (long)(kt + 3 - nk) * BK;
;       const bool cnt = kt + 1 < nk;
;       const bf16_t* abase = cur + (wr * (RM / WR) + r) * STR + h * 8;
;       const bf16_t* bbase = cur + (RM + wc * (CN / WC) + r) * STR + h * 8;
;       bf16x8 af[2][MI], bfr[2][NI];
;       if (FDB) {
; #pragma unroll
;         for (int mi = 0; mi < MI; ++mi) af[0][mi] = *(const bf16x8*)(abase + mi * 32 * STR);
; #pragma unroll
;         for (int ni = 0; ni < NI; ++ni) bfr[0][ni] = *(const bf16x8*)(bbase + ni * 32 * STR);
;       }
; #pragma unroll
;       for (int ks = 0; ks < KS; ++ks) {
;         if (!FDB) {
; #pragma unroll
;           for (int mi = 0; mi < MI; ++mi) af[ks & 1][mi] = *(const bf16x8*)(abase + mi * 32 * STR + ks * 16);
; #pragma unroll
;           for (int ni = 0; ni < NI; ++ni) bfr[ks & 1][ni] = *(const bf16x8*)(bbase + ni * 32 * STR + ks * 16);
;         }
; #pragma unroll
;         for (int c = ks; c < RCH; c += KS) *(u32x4*)(oth + (srow + RPP * c) * STR + skc) = rr[st ^ 1][c];
; #pragma unroll
;         for (int c = ks; c < CCH; c += KS) {
;           *(u32x4*)(oth + (RM + srow + RPP * c) * STR + skc) = cr[st ^ 1][c];
;           if (SUMSQ && cnt) {
; #pragma unroll
;             for (int e = 0; e < 4; ++e) { const float a_ = bf_lo(cr[st ^ 1][c][e]), b_ = bf_hi(cr[st ^ 1][c][e]); ss[c] += a_ * a_ + b_ * b_; }
;           }
;         }
; #pragma unroll
; DI void phase5(const Params& p, char* smem, const Sched sc) {
;     ...
;   for (int l = sc.rank; l < 16 * 8; l += sc.nloc) {
;     const int g8 = l >> 6, rem = l & 63, nt = rem >> 3, mt = 16 * v + 8 * g8 + (rem & 7), m0 = mt * 128, n0 = nt * 128;
;     f32x16 acc[2][2];
;     gemm_tile<128, 128, 2, 2, false, true>(p.WoutT + (size_t)n0 * DM, DM, p.Mixed + (size_t)m0 * DM, DM, DM, smem, acc, nullptr);
.LBB0_529:
	s_ashr_i32 s2, s25, 3
	s_and_b32 s27, s2, -8
	s_add_i32 s27, s27, s23
	s_and_b32 s2, s25, 7
	s_or_b32 s2, s27, s2
	s_and_b32 s26, s24, 0x380
	s_lshl_b32 s8, s2, 7
	s_lshl_b32 s2, s26, 11
	v_lshl_add_u64 v[116:117], v[98:99], 0, s[2:3]
	v_add_co_u32_e32 v112, vcc, s12, v116
	s_ashr_i32 s9, s8, 31
	s_nop 0
	v_addc_co_u32_e32 v113, vcc, 0, v117, vcc
	v_add_co_u32_e32 v108, vcc, s13, v116
	s_lshl_b64 s[28:29], s[8:9], 11
	s_nop 0
	v_addc_co_u32_e32 v109, vcc, 0, v117, vcc
	v_add_co_u32_e32 v104, vcc, s14, v116
	v_lshl_add_u64 v[118:119], v[100:101], 0, s[28:29]
	s_nop 0
	v_addc_co_u32_e32 v105, vcc, 0, v117, vcc
	v_add_co_u32_e32 v114, vcc, s12, v118
	global_load_dwordx4 v[84:87], v[116:117], off
	s_nop 0
	v_addc_co_u32_e32 v115, vcc, 0, v119, vcc
	v_add_co_u32_e32 v110, vcc, s13, v118
	global_load_dwordx4 v[80:83], v[112:113], off
	global_load_dwordx4 v[68:71], v[108:109], off
	v_addc_co_u32_e32 v111, vcc, 0, v119, vcc
	v_add_co_u32_e32 v106, vcc, s14, v118
	global_load_dwordx4 v[64:67], v[104:105], off
	global_load_dwordx4 v[92:95], v[118:119], off
	global_load_dwordx4 v[88:91], v[114:115], off
	global_load_dwordx4 v[76:79], v[110:111], off
	v_addc_co_u32_e32 v107, vcc, 0, v119, vcc
	global_load_dwordx4 v[72:75], v[106:107], off
	global_load_dwordx4 v[0:3], v[116:117], off offset:128
	global_load_dwordx4 v[4:7], v[112:113], off offset:128
	global_load_dwordx4 v[142:145], v[108:109], off offset:128
	global_load_dwordx4 v[146:149], v[104:105], off offset:128
	global_load_dwordx4 v[8:11], v[118:119], off offset:128
	global_load_dwordx4 v[12:15], v[114:115], off offset:128
	global_load_dwordx4 v[150:153], v[110:111], off offset:128
	global_load_dwordx4 v[154:157], v[106:107], off offset:128
	global_load_dwordx4 v[158:161], v[116:117], off offset:256
	global_load_dwordx4 v[162:165], v[112:113], off offset:256
	global_load_dwordx4 v[166:169], v[108:109], off offset:256
	global_load_dwordx4 v[170:173], v[104:105], off offset:256
	global_load_dwordx4 v[174:177], v[118:119], off offset:256
	global_load_dwordx4 v[178:181], v[114:115], off offset:256
	global_load_dwordx4 v[182:185], v[110:111], off offset:256
	global_load_dwordx4 v[186:189], v[106:107], off offset:256
	s_waitcnt vmcnt(23)
	ds_write_b128 v120, v[84:87]
	s_waitcnt vmcnt(22)
	ds_write_b128 v120, v[80:83] offset:4608
	s_waitcnt vmcnt(21)
	ds_write_b128 v120, v[68:71] offset:9216
	s_waitcnt vmcnt(20)
	ds_write_b128 v120, v[64:67] offset:13824
	s_waitcnt vmcnt(19)
	ds_write_b128 v120, v[92:95] offset:18432
	s_waitcnt vmcnt(18)
	ds_write_b128 v120, v[88:91] offset:23040
	s_waitcnt vmcnt(17)
	ds_write_b128 v120, v[76:79] offset:27648
	s_waitcnt vmcnt(16)
	ds_write_b128 v120, v[72:75] offset:32256
	s_waitcnt lgkmcnt(0)
	s_barrier
	global_load_dwordx4 v[190:193], v[116:117], off offset:384
	global_load_dwordx4 v[194:197], v[118:119], off offset:384
	ds_read_b128 v[16:19], v121
	ds_read_b128 v[198:201], v121 offset:4608
	ds_read_b128 v[20:23], v122 offset:18432
	ds_read_b128 v[202:205], v122 offset:23040
	s_waitcnt vmcnt(17)
	ds_write_b128 v120, v[0:3] offset:36864
	s_waitcnt vmcnt(13)
	ds_write_b128 v120, v[8:11] offset:55296
	global_load_dwordx4 v[206:209], v[112:113], off offset:384
	global_load_dwordx4 v[210:213], v[114:115], off offset:384
	ds_read_b128 v[214:217], v121 offset:32
	ds_read_b128 v[218:221], v121 offset:4640
	ds_read_b128 v[222:225], v122 offset:18464
	ds_read_b128 v[226:229], v122 offset:23072
	s_waitcnt lgkmcnt(7)
	v_mfma_f32_32x32x16_bf16 v[48:63], v[16:19], v[20:23], 0
	ds_write_b128 v120, v[4:7] offset:41472
	s_waitcnt vmcnt(14)
	ds_write_b128 v120, v[12:15] offset:59904
	s_waitcnt lgkmcnt(8)
	v_mfma_f32_32x32x16_bf16 v[32:47], v[16:19], v[202:205], 0
	v_mfma_f32_32x32x16_bf16 v[16:31], v[198:201], v[20:23], 0
	v_mfma_f32_32x32x16_bf16 v[0:15], v[198:201], v[202:205], 0
	global_load_dwordx4 v[198:201], v[108:109], off offset:384
	global_load_dwordx4 v[202:205], v[110:111], off offset:384
	s_waitcnt lgkmcnt(3)
	v_mfma_f32_32x32x16_bf16 v[48:63], v[214:217], v[222:225], v[48:63]
	s_waitcnt lgkmcnt(2)
	v_mfma_f32_32x32x16_bf16 v[32:47], v[214:217], v[226:229], v[32:47]
	v_mfma_f32_32x32x16_bf16 v[16:31], v[218:221], v[222:225], v[16:31]
	ds_read_b128 v[214:217], v121 offset:64
	ds_read_b128 v[222:225], v121 offset:4672
	ds_read_b128 v[230:233], v122 offset:18496
	ds_read_b128 v[234:237], v122 offset:23104
	ds_write_b128 v120, v[142:145] offset:46080
	s_waitcnt vmcnt(15)
	ds_write_b128 v120, v[150:153] offset:64512
	v_mfma_f32_32x32x16_bf16 v[0:15], v[218:221], v[226:229], v[0:15]
	global_load_dwordx4 v[142:145], v[104:105], off offset:384
	global_load_dwordx4 v[150:153], v[106:107], off offset:384
	s_waitcnt lgkmcnt(3)
	v_mfma_f32_32x32x16_bf16 v[48:63], v[214:217], v[230:233], v[48:63]
	s_waitcnt lgkmcnt(2)
	v_mfma_f32_32x32x16_bf16 v[32:47], v[214:217], v[234:237], v[32:47]
	v_mfma_f32_32x32x16_bf16 v[16:31], v[222:225], v[230:233], v[16:31]
	ds_read_b128 v[214:217], v121 offset:96
	ds_read_b128 v[218:221], v121 offset:4704
	ds_read_b128 v[226:229], v122 offset:18528
	ds_read_b128 v[230:233], v122 offset:23136
	ds_write_b128 v120, v[146:149] offset:50688
	s_waitcnt vmcnt(16)
	ds_write_b128 v123, v[154:157] offset:13824
	v_mfma_f32_32x32x16_bf16 v[0:15], v[222:225], v[234:237], v[0:15]
	s_waitcnt lgkmcnt(0)
	s_barrier
;     ...
;   for (int kt2 = 0; kt2 < nk; kt2 += 2) {
; #pragma unroll
;     for (int st = 0; st < 2; ++st) {
;       const int kt = kt2 + st;
;       const bf16_t* cur = lds + st * BUFE;
;       bf16_t* oth = lds + (st ^ 1) * BUFE;
;       const long k0r = (kt + 3 < nk) ? (long)(kt + 3) * BK : dR + (long)(kt + 3 - nk) * BK;
;       const long k0c = (kt + 3 < nk) ? (long)(kt + 3) * BK : dC + (long)(kt + 3 - nk) * BK;
;       const bool cnt = kt + 1 < nk;
;       const bf16_t* abase = cur + (wr * (RM / WR) + r) * STR + h * 8;
;       const bf16_t* bbase = cur + (RM + wc * (CN / WC) + r) * STR + h * 8;
;       bf16x8 af[2][MI], bfr[2][NI];
;       if (FDB) {
; #pragma unroll
;         for (int mi = 0; mi < MI; ++mi) af[0][mi] = *(const bf16x8*)(abase + mi * 32 * STR);
; #pragma unroll
;         for (int ni = 0; ni < NI; ++ni) bfr[0][ni] = *(const bf16x8*)(bbase + ni * 32 * STR);
;       }
; #pragma unroll
;       for (int ks = 0; ks < KS; ++ks) {
;         if (!FDB) {
; #pragma unroll
;           for (int mi = 0; mi < MI; ++mi) af[ks & 1][mi] = *(const bf16x8*)(abase + mi * 32 * STR + ks * 16);
; #pragma unroll
;           for (int ni = 0; ni < NI; ++ni) bfr[ks & 1][ni] = *(const bf16x8*)(bbase + ni * 32 * STR + ks * 16);
;         }
; #pragma unroll
;         for (int c = ks; c < RCH; c += KS) *(u32x4*)(oth + (srow + RPP * c) * STR + skc) = rr[st ^ 1][c];
; #pragma unroll
;         for (int c = ks; c < CCH; c += KS) {
;           *(u32x4*)(oth + (RM + srow + RPP * c) * STR + skc) = cr[st ^ 1][c];
;           if (SUMSQ && cnt) {
; #pragma unroll
;             for (int e = 0; e < 4; ++e) { const float a_ = bf_lo(cr[st ^ 1][c][e]), b_ = bf_hi(cr[st ^ 1][c][e]); ss[c] += a_ * a_ + b_ * b_; }
;           }
;         }
; #pragma unroll
;         for (int c = ks; c < RCH; c += KS) rr[st ^ 1][c] = *(const u32x4*)(rp + (size_t)(RPP * c) * ldr + k0r);
; #pragma unroll
;         for (int c = ks; c < CCH; c += KS) cr[st ^ 1][c] = *(const u32x4*)(cp + (size_t)(RPP * c) * ldc + k0c);
;         __builtin_amdgcn_sched_barrier(0);
;         if (FDB && ks + 1 < KS) {
; #pragma unroll
;           for (int mi = 0; mi < MI; ++mi) af[(ks + 1) & 1][mi] = *(const bf16x8*)(abase + mi * 32 * STR + (ks + 1) * 16);
; #pragma unroll
;           for (int ni = 0; ni < NI; ++ni) bfr[(ks + 1) & 1][ni] = *(const bf16x8*)(bbase + ni * 32 * STR + (ks + 1) * 16);
;         }
; #pragma unroll
	global_load_dwordx4 v[146:149], v[116:117], off offset:512
	global_load_dwordx4 v[154:157], v[118:119], off offset:512
	v_mfma_f32_32x32x16_bf16 v[48:63], v[214:217], v[226:229], v[48:63]
	v_mfma_f32_32x32x16_bf16 v[32:47], v[214:217], v[230:233], v[32:47]
	v_mfma_f32_32x32x16_bf16 v[16:31], v[218:221], v[226:229], v[16:31]
	ds_read_b128 v[214:217], v121 offset:36864
	ds_read_b128 v[222:225], v121 offset:41472
	ds_read_b128 v[226:229], v122 offset:55296
	ds_read_b128 v[234:237], v122 offset:59904
	s_waitcnt vmcnt(17)
	ds_write_b128 v120, v[158:161]
	s_waitcnt vmcnt(13)
	ds_write_b128 v120, v[174:177] offset:18432
	v_mfma_f32_32x32x16_bf16 v[0:15], v[218:221], v[230:233], v[0:15]
	global_load_dwordx4 v[158:161], v[112:113], off offset:512
	global_load_dwordx4 v[174:177], v[114:115], off offset:512
	s_waitcnt lgkmcnt(3)
	v_mfma_f32_32x32x16_bf16 v[48:63], v[214:217], v[226:229], v[48:63]
	s_waitcnt lgkmcnt(2)
	v_mfma_f32_32x32x16_bf16 v[32:47], v[214:217], v[234:237], v[32:47]
	v_mfma_f32_32x32x16_bf16 v[16:31], v[222:225], v[226:229], v[16:31]
	ds_read_b128 v[214:217], v121 offset:36896
	ds_read_b128 v[218:221], v121 offset:41504
	ds_read_b128 v[226:229], v122 offset:55328
	ds_read_b128 v[230:233], v122 offset:59936
	ds_write_b128 v120, v[162:165] offset:4608
	s_waitcnt vmcnt(14)
	ds_write_b128 v120, v[178:181] offset:23040
	v_mfma_f32_32x32x16_bf16 v[0:15], v[222:225], v[234:237], v[0:15]
	global_load_dwordx4 v[162:165], v[108:109], off offset:512
	global_load_dwordx4 v[178:181], v[110:111], off offset:512
	s_waitcnt lgkmcnt(3)
	v_mfma_f32_32x32x16_bf16 v[48:63], v[214:217], v[226:229], v[48:63]
	s_waitcnt lgkmcnt(2)
	v_mfma_f32_32x32x16_bf16 v[32:47], v[214:217], v[230:233], v[32:47]
	v_mfma_f32_32x32x16_bf16 v[16:31], v[218:221], v[226:229], v[16:31]
	ds_read_b128 v[214:217], v121 offset:36928
	ds_read_b128 v[222:225], v121 offset:41536
	ds_read_b128 v[226:229], v122 offset:55360
	ds_read_b128 v[234:237], v122 offset:59968
	ds_write_b128 v120, v[166:169] offset:9216
	s_waitcnt vmcnt(15)
	ds_write_b128 v120, v[182:185] offset:27648
	v_mfma_f32_32x32x16_bf16 v[0:15], v[218:221], v[230:233], v[0:15]
	global_load_dwordx4 v[166:169], v[104:105], off offset:512
	global_load_dwordx4 v[182:185], v[106:107], off offset:512
	s_waitcnt lgkmcnt(3)
	v_mfma_f32_32x32x16_bf16 v[48:63], v[214:217], v[226:229], v[48:63]
	s_waitcnt lgkmcnt(2)
	v_mfma_f32_32x32x16_bf16 v[32:47], v[214:217], v[234:237], v[32:47]
	v_mfma_f32_32x32x16_bf16 v[16:31], v[222:225], v[226:229], v[16:31]
	ds_read_b128 v[214:217], v121 offset:36960
	ds_read_b128 v[218:221], v121 offset:41568
	ds_read_b128 v[226:229], v122 offset:55392
	ds_read_b128 v[230:233], v122 offset:60000
	ds_write_b128 v120, v[170:173] offset:13824
	s_waitcnt vmcnt(16)
	ds_write_b128 v120, v[186:189] offset:32256
	v_mfma_f32_32x32x16_bf16 v[0:15], v[222:225], v[234:237], v[0:15]
	s_waitcnt lgkmcnt(0)
	s_barrier
	global_load_dwordx4 v[170:173], v[116:117], off offset:640
	global_load_dwordx4 v[186:189], v[118:119], off offset:640
	v_mfma_f32_32x32x16_bf16 v[48:63], v[214:217], v[226:229], v[48:63]
	v_mfma_f32_32x32x16_bf16 v[32:47], v[214:217], v[230:233], v[32:47]
	v_mfma_f32_32x32x16_bf16 v[16:31], v[218:221], v[226:229], v[16:31]
	ds_read_b128 v[214:217], v121
	ds_read_b128 v[222:225], v121 offset:4608
	ds_read_b128 v[226:229], v122 offset:18432
	ds_read_b128 v[234:237], v122 offset:23040
	s_waitcnt vmcnt(17)
	ds_write_b128 v120, v[190:193] offset:36864
	s_waitcnt vmcnt(16)
	ds_write_b128 v120, v[194:197] offset:55296
	v_mfma_f32_32x32x16_bf16 v[0:15], v[218:221], v[230:233], v[0:15]
	global_load_dwordx4 v[190:193], v[112:113], off offset:640
	global_load_dwordx4 v[194:197], v[114:115], off offset:640
	s_waitcnt lgkmcnt(3)
	v_mfma_f32_32x32x16_bf16 v[48:63], v[214:217], v[226:229], v[48:63]
	s_waitcnt lgkmcnt(2)
	v_mfma_f32_32x32x16_bf16 v[32:47], v[214:217], v[234:237], v[32:47]
	v_mfma_f32_32x32x16_bf16 v[16:31], v[222:225], v[226:229], v[16:31]
	ds_read_b128 v[214:217], v121 offset:32
	ds_read_b128 v[218:221], v121 offset:4640
	ds_read_b128 v[226:229], v122 offset:18464
	ds_read_b128 v[230:233], v122 offset:23072
	s_waitcnt vmcnt(17)
	ds_write_b128 v120, v[206:209] offset:41472
	s_waitcnt vmcnt(16)
	ds_write_b128 v120, v[210:213] offset:59904
	v_mfma_f32_32x32x16_bf16 v[0:15], v[222:225], v[234:237], v[0:15]
	global_load_dwordx4 v[206:209], v[108:109], off offset:640
	global_load_dwordx4 v[210:213], v[110:111], off offset:640
	s_waitcnt lgkmcnt(3)
	v_mfma_f32_32x32x16_bf16 v[48:63], v[214:217], v[226:229], v[48:63]
	s_waitcnt lgkmcnt(2)
	v_mfma_f32_32x32x16_bf16 v[32:47], v[214:217], v[230:233], v[32:47]
	v_mfma_f32_32x32x16_bf16 v[16:31], v[218:221], v[226:229], v[16:31]
	ds_read_b128 v[214:217], v121 offset:64
	ds_read_b128 v[222:225], v121 offset:4672
	ds_read_b128 v[226:229], v122 offset:18496
	ds_read_b128 v[234:237], v122 offset:23104
	s_waitcnt vmcnt(17)
	ds_write_b128 v120, v[198:201] offset:46080
	s_waitcnt vmcnt(16)
	ds_write_b128 v120, v[202:205] offset:64512
	v_mfma_f32_32x32x16_bf16 v[0:15], v[218:221], v[230:233], v[0:15]
	global_load_dwordx4 v[198:201], v[104:105], off offset:640
	global_load_dwordx4 v[202:205], v[106:107], off offset:640
	s_waitcnt lgkmcnt(3)
	v_mfma_f32_32x32x16_bf16 v[48:63], v[214:217], v[226:229], v[48:63]
	s_waitcnt lgkmcnt(2)
	v_mfma_f32_32x32x16_bf16 v[32:47], v[214:217], v[234:237], v[32:47]
	v_mfma_f32_32x32x16_bf16 v[16:31], v[222:225], v[226:229], v[16:31]
	ds_read_b128 v[214:217], v121 offset:96
	ds_read_b128 v[218:221], v121 offset:4704
	ds_read_b128 v[226:229], v122 offset:18528
	ds_read_b128 v[230:233], v122 offset:23136
	s_waitcnt vmcnt(17)
	ds_write_b128 v120, v[142:145] offset:50688
	s_waitcnt vmcnt(16)
	ds_write_b128 v123, v[150:153] offset:13824
	v_mfma_f32_32x32x16_bf16 v[0:15], v[222:225], v[234:237], v[0:15]
	s_waitcnt lgkmcnt(0)
	s_barrier
;     ...
;   for (int kt2 = 0; kt2 < nk; kt2 += 2) {
; #pragma unroll
;     for (int st = 0; st < 2; ++st) {
;       const int kt = kt2 + st;
;       const bf16_t* cur = lds + st * BUFE;
;       bf16_t* oth = lds + (st ^ 1) * BUFE;
;       const long k0r = (kt + 3 < nk) ? (long)(kt + 3) * BK : dR + (long)(kt + 3 - nk) * BK;
;       const long k0c = (kt + 3 < nk) ? (long)(kt + 3) * BK : dC + (long)(kt + 3 - nk) * BK;
;       const bool cnt = kt + 1 < nk;
;       const bf16_t* abase = cur + (wr * (RM / WR) + r) * STR + h * 8;
;       const bf16_t* bbase = cur + (RM + wc * (CN / WC) + r) * STR + h * 8;
;       bf16x8 af[2][MI], bfr[2][NI];
;       if (FDB) {
; #pragma unroll
;         for (int mi = 0; mi < MI; ++mi) af[0][mi] = *(const bf16x8*)(abase + mi * 32 * STR);
; #pragma unroll
;         for (int ni = 0; ni < NI; ++ni) bfr[0][ni] = *(const bf16x8*)(bbase + ni * 32 * STR);
;       }
; #pragma unroll
;       for (int ks = 0; ks < KS; ++ks) {
;         if (!FDB) {
; #pragma unroll
;           for (int mi = 0; mi < MI; ++mi) af[ks & 1][mi] = *(const bf16x8*)(abase + mi * 32 * STR + ks * 16);
; #pragma unroll
;           for (int ni = 0; ni < NI; ++ni) bfr[ks & 1][ni] = *(const bf16x8*)(bbase + ni * 32 * STR + ks * 16);
;         }
; #pragma unroll
;         for (int c = ks; c < RCH; c += KS) *(u32x4*)(oth + (srow + RPP * c) * STR + skc) = rr[st ^ 1][c];
; #pragma unroll
;         for (int c = ks; c < CCH; c += KS) {
;           *(u32x4*)(oth + (RM + srow + RPP * c) * STR + skc) = cr[st ^ 1][c];
;           if (SUMSQ && cnt) {
; #pragma unroll
;             for (int e = 0; e < 4; ++e) { const float a_ = bf_lo(cr[st ^ 1][c][e]), b_ = bf_hi(cr[st ^ 1][c][e]); ss[c] += a_ * a_ + b_ * b_; }
;           }
;         }
; #pragma unroll
;         for (int c = ks; c < RCH; c += KS) rr[st ^ 1][c] = *(const u32x4*)(rp + (size_t)(RPP * c) * ldr + k0r);
; #pragma unroll
;         for (int c = ks; c < CCH; c += KS) cr[st ^ 1][c] = *(const u32x4*)(cp + (size_t)(RPP * c) * ldc + k0c);
;         __builtin_amdgcn_sched_barrier(0);
;         if (FDB && ks + 1 < KS) {
; #pragma unroll
;           for (int mi = 0; mi < MI; ++mi) af[(ks + 1) & 1][mi] = *(const bf16x8*)(abase + mi * 32 * STR + (ks + 1) * 16);
; #pragma unroll
;           for (int ni = 0; ni < NI; ++ni) bfr[(ks + 1) & 1][ni] = *(const bf16x8*)(bbase + ni * 32 * STR + (ks + 1) * 16);
;         }
; #pragma unroll
	global_load_dwordx4 v[142:145], v[116:117], off offset:768
	global_load_dwordx4 v[150:153], v[118:119], off offset:768
	v_mfma_f32_32x32x16_bf16 v[48:63], v[214:217], v[226:229], v[48:63]
	v_mfma_f32_32x32x16_bf16 v[32:47], v[214:217], v[230:233], v[32:47]
	v_mfma_f32_32x32x16_bf16 v[16:31], v[218:221], v[226:229], v[16:31]
	ds_read_b128 v[214:217], v121 offset:36864
	ds_read_b128 v[222:225], v121 offset:41472
	ds_read_b128 v[226:229], v122 offset:55296
	ds_read_b128 v[234:237], v122 offset:59904
	s_waitcnt vmcnt(17)
	ds_write_b128 v120, v[146:149]
	s_waitcnt vmcnt(16)
	ds_write_b128 v120, v[154:157] offset:18432
	v_mfma_f32_32x32x16_bf16 v[0:15], v[218:221], v[230:233], v[0:15]
	global_load_dwordx4 v[146:149], v[112:113], off offset:768
	global_load_dwordx4 v[154:157], v[114:115], off offset:768
	s_waitcnt lgkmcnt(3)
	v_mfma_f32_32x32x16_bf16 v[48:63], v[214:217], v[226:229], v[48:63]
	s_waitcnt lgkmcnt(2)
	v_mfma_f32_32x32x16_bf16 v[32:47], v[214:217], v[234:237], v[32:47]
	v_mfma_f32_32x32x16_bf16 v[16:31], v[222:225], v[226:229], v[16:31]
	ds_read_b128 v[214:217], v121 offset:36896
	ds_read_b128 v[218:221], v121 offset:41504
	ds_read_b128 v[226:229], v122 offset:55328
	ds_read_b128 v[230:233], v122 offset:59936
	s_waitcnt vmcnt(17)
	ds_write_b128 v120, v[158:161] offset:4608
	s_waitcnt vmcnt(16)
	ds_write_b128 v120, v[174:177] offset:23040
	v_mfma_f32_32x32x16_bf16 v[0:15], v[222:225], v[234:237], v[0:15]
	global_load_dwordx4 v[158:161], v[108:109], off offset:768
	global_load_dwordx4 v[174:177], v[110:111], off offset:768
	s_waitcnt lgkmcnt(3)
	v_mfma_f32_32x32x16_bf16 v[48:63], v[214:217], v[226:229], v[48:63]
	s_waitcnt lgkmcnt(2)
	v_mfma_f32_32x32x16_bf16 v[32:47], v[214:217], v[230:233], v[32:47]
	v_mfma_f32_32x32x16_bf16 v[16:31], v[218:221], v[226:229], v[16:31]
	ds_read_b128 v[214:217], v121 offset:36928
	ds_read_b128 v[222:225], v121 offset:41536
	ds_read_b128 v[226:229], v122 offset:55360
	ds_read_b128 v[234:237], v122 offset:59968
	s_waitcnt vmcnt(17)
	ds_write_b128 v120, v[162:165] offset:9216
	s_waitcnt vmcnt(16)
	ds_write_b128 v120, v[178:181] offset:27648
	v_mfma_f32_32x32x16_bf16 v[0:15], v[218:221], v[230:233], v[0:15]
	global_load_dwordx4 v[162:165], v[104:105], off offset:768
	global_load_dwordx4 v[178:181], v[106:107], off offset:768
	s_waitcnt lgkmcnt(3)
	v_mfma_f32_32x32x16_bf16 v[48:63], v[214:217], v[226:229], v[48:63]
	s_waitcnt lgkmcnt(2)
	v_mfma_f32_32x32x16_bf16 v[32:47], v[214:217], v[234:237], v[32:47]
	v_mfma_f32_32x32x16_bf16 v[16:31], v[222:225], v[226:229], v[16:31]
	ds_read_b128 v[214:217], v121 offset:36960
	ds_read_b128 v[218:221], v121 offset:41568
	ds_read_b128 v[226:229], v122 offset:55392
	ds_read_b128 v[230:233], v122 offset:60000
	s_waitcnt vmcnt(17)
	ds_write_b128 v120, v[166:169] offset:13824
	s_waitcnt vmcnt(16)
	ds_write_b128 v120, v[182:185] offset:32256
	v_mfma_f32_32x32x16_bf16 v[0:15], v[222:225], v[234:237], v[0:15]
	s_waitcnt lgkmcnt(0)
	s_barrier
	global_load_dwordx4 v[166:169], v[116:117], off offset:896
	global_load_dwordx4 v[182:185], v[118:119], off offset:896
	v_mfma_f32_32x32x16_bf16 v[48:63], v[214:217], v[226:229], v[48:63]
	v_mfma_f32_32x32x16_bf16 v[32:47], v[214:217], v[230:233], v[32:47]
	v_mfma_f32_32x32x16_bf16 v[16:31], v[218:221], v[226:229], v[16:31]
	ds_read_b128 v[214:217], v121
	ds_read_b128 v[222:225], v121 offset:4608
	ds_read_b128 v[226:229], v122 offset:18432
	ds_read_b128 v[234:237], v122 offset:23040
	s_waitcnt vmcnt(17)
	ds_write_b128 v120, v[170:173] offset:36864
	s_waitcnt vmcnt(16)
	ds_write_b128 v120, v[186:189] offset:55296
	v_mfma_f32_32x32x16_bf16 v[0:15], v[218:221], v[230:233], v[0:15]
	global_load_dwordx4 v[170:173], v[112:113], off offset:896
	global_load_dwordx4 v[186:189], v[114:115], off offset:896
	s_waitcnt lgkmcnt(3)
	v_mfma_f32_32x32x16_bf16 v[48:63], v[214:217], v[226:229], v[48:63]
	s_waitcnt lgkmcnt(2)
	v_mfma_f32_32x32x16_bf16 v[32:47], v[214:217], v[234:237], v[32:47]
	v_mfma_f32_32x32x16_bf16 v[16:31], v[222:225], v[226:229], v[16:31]
	ds_read_b128 v[214:217], v121 offset:32
	ds_read_b128 v[218:221], v121 offset:4640
	ds_read_b128 v[226:229], v122 offset:18464
	ds_read_b128 v[230:233], v122 offset:23072
	s_waitcnt vmcnt(17)
	ds_write_b128 v120, v[190:193] offset:41472
	s_waitcnt vmcnt(16)
	ds_write_b128 v120, v[194:197] offset:59904
	v_mfma_f32_32x32x16_bf16 v[0:15], v[222:225], v[234:237], v[0:15]
	global_load_dwordx4 v[190:193], v[108:109], off offset:896
	global_load_dwordx4 v[194:197], v[110:111], off offset:896
	s_waitcnt lgkmcnt(3)
	v_mfma_f32_32x32x16_bf16 v[48:63], v[214:217], v[226:229], v[48:63]
	s_waitcnt lgkmcnt(2)
	v_mfma_f32_32x32x16_bf16 v[32:47], v[214:217], v[230:233], v[32:47]
	v_mfma_f32_32x32x16_bf16 v[16:31], v[218:221], v[226:229], v[16:31]
	ds_read_b128 v[214:217], v121 offset:64
	ds_read_b128 v[222:225], v121 offset:4672
	ds_read_b128 v[226:229], v122 offset:18496
	ds_read_b128 v[234:237], v122 offset:23104
	s_waitcnt vmcnt(17)
	ds_write_b128 v120, v[206:209] offset:46080
	s_waitcnt vmcnt(16)
	ds_write_b128 v120, v[210:213] offset:64512
	v_mfma_f32_32x32x16_bf16 v[0:15], v[218:221], v[230:233], v[0:15]
	global_load_dwordx4 v[206:209], v[104:105], off offset:896
	global_load_dwordx4 v[210:213], v[106:107], off offset:896
	s_waitcnt lgkmcnt(3)
	v_mfma_f32_32x32x16_bf16 v[48:63], v[214:217], v[226:229], v[48:63]
	s_waitcnt lgkmcnt(2)
	v_mfma_f32_32x32x16_bf16 v[32:47], v[214:217], v[234:237], v[32:47]
	v_mfma_f32_32x32x16_bf16 v[16:31], v[222:225], v[226:229], v[16:31]
	ds_read_b128 v[214:217], v121 offset:96
	ds_read_b128 v[218:221], v121 offset:4704
	ds_read_b128 v[226:229], v122 offset:18528
	ds_read_b128 v[230:233], v122 offset:23136
	s_waitcnt vmcnt(17)
	ds_write_b128 v120, v[198:201] offset:50688
	s_waitcnt vmcnt(16)
	ds_write_b128 v123, v[202:205] offset:13824
	v_mfma_f32_32x32x16_bf16 v[0:15], v[222:225], v[234:237], v[0:15]
	s_waitcnt lgkmcnt(0)
	s_barrier
;     ...
;   for (int kt2 = 0; kt2 < nk; kt2 += 2) {
; #pragma unroll
;     for (int st = 0; st < 2; ++st) {
;       const int kt = kt2 + st;
;       const bf16_t* cur = lds + st * BUFE;
;       bf16_t* oth = lds + (st ^ 1) * BUFE;
;       const long k0r = (kt + 3 < nk) ? (long)(kt + 3) * BK : dR + (long)(kt + 3 - nk) * BK;
;       const long k0c = (kt + 3 < nk) ? (long)(kt + 3) * BK : dC + (long)(kt + 3 - nk) * BK;
;       const bool cnt = kt + 1 < nk;
;       const bf16_t* abase = cur + (wr * (RM / WR) + r) * STR + h * 8;
;       const bf16_t* bbase = cur + (RM + wc * (CN / WC) + r) * STR + h * 8;
;       bf16x8 af[2][MI], bfr[2][NI];
;       if (FDB) {
; #pragma unroll
;         for (int mi = 0; mi < MI; ++mi) af[0][mi] = *(const bf16x8*)(abase + mi * 32 * STR);
; #pragma unroll
;         for (int ni = 0; ni < NI; ++ni) bfr[0][ni] = *(const bf16x8*)(bbase + ni * 32 * STR);
;       }
; #pragma unroll
;       for (int ks = 0; ks < KS; ++ks) {
;         if (!FDB) {
; #pragma unroll
;           for (int mi = 0; mi < MI; ++mi) af[ks & 1][mi] = *(const bf16x8*)(abase + mi * 32 * STR + ks * 16);
; #pragma unroll
;           for (int ni = 0; ni < NI; ++ni) bfr[ks & 1][ni] = *(const bf16x8*)(bbase + ni * 32 * STR + ks * 16);
;         }
; #pragma unroll
;         for (int c = ks; c < RCH; c += KS) *(u32x4*)(oth + (srow + RPP * c) * STR + skc) = rr[st ^ 1][c];
; #pragma unroll
;         for (int c = ks; c < CCH; c += KS) {
;           *(u32x4*)(oth + (RM + srow + RPP * c) * STR + skc) = cr[st ^ 1][c];
;           if (SUMSQ && cnt) {
; #pragma unroll
;             for (int e = 0; e < 4; ++e) { const float a_ = bf_lo(cr[st ^ 1][c][e]), b_ = bf_hi(cr[st ^ 1][c][e]); ss[c] += a_ * a_ + b_ * b_; }
;           }
;         }
; #pragma unroll
;         for (int c = ks; c < RCH; c += KS) rr[st ^ 1][c] = *(const u32x4*)(rp + (size_t)(RPP * c) * ldr + k0r);
; #pragma unroll
;         for (int c = ks; c < CCH; c += KS) cr[st ^ 1][c] = *(const u32x4*)(cp + (size_t)(RPP * c) * ldc + k0c);
;         __builtin_amdgcn_sched_barrier(0);
;         if (FDB && ks + 1 < KS) {
; #pragma unroll
;           for (int mi = 0; mi < MI; ++mi) af[(ks + 1) & 1][mi] = *(const bf16x8*)(abase + mi * 32 * STR + (ks + 1) * 16);
; #pragma unroll
;           for (int ni = 0; ni < NI; ++ni) bfr[(ks + 1) & 1][ni] = *(const bf16x8*)(bbase + ni * 32 * STR + (ks + 1) * 16);
;         }
; #pragma unroll
	global_load_dwordx4 v[198:201], v[116:117], off offset:1024
	global_load_dwordx4 v[202:205], v[118:119], off offset:1024
	v_mfma_f32_32x32x16_bf16 v[48:63], v[214:217], v[226:229], v[48:63]
	v_mfma_f32_32x32x16_bf16 v[32:47], v[214:217], v[230:233], v[32:47]
	v_mfma_f32_32x32x16_bf16 v[16:31], v[218:221], v[226:229], v[16:31]
	ds_read_b128 v[214:217], v121 offset:36864
	ds_read_b128 v[222:225], v121 offset:41472
	ds_read_b128 v[226:229], v122 offset:55296
	ds_read_b128 v[234:237], v122 offset:59904
	s_waitcnt vmcnt(17)
	ds_write_b128 v120, v[142:145]
	s_waitcnt vmcnt(16)
	ds_write_b128 v120, v[150:153] offset:18432
	v_mfma_f32_32x32x16_bf16 v[0:15], v[218:221], v[230:233], v[0:15]
	global_load_dwordx4 v[142:145], v[112:113], off offset:1024
	global_load_dwordx4 v[150:153], v[114:115], off offset:1024
	s_waitcnt lgkmcnt(3)
	v_mfma_f32_32x32x16_bf16 v[48:63], v[214:217], v[226:229], v[48:63]
	s_waitcnt lgkmcnt(2)
	v_mfma_f32_32x32x16_bf16 v[32:47], v[214:217], v[234:237], v[32:47]
	v_mfma_f32_32x32x16_bf16 v[16:31], v[222:225], v[226:229], v[16:31]
	ds_read_b128 v[214:217], v121 offset:36896
	ds_read_b128 v[218:221], v121 offset:41504
	ds_read_b128 v[226:229], v122 offset:55328
	ds_read_b128 v[230:233], v122 offset:59936
	s_waitcnt vmcnt(17)
	ds_write_b128 v120, v[146:149] offset:4608
	s_waitcnt vmcnt(16)
	ds_write_b128 v120, v[154:157] offset:23040
	v_mfma_f32_32x32x16_bf16 v[0:15], v[222:225], v[234:237], v[0:15]
	global_load_dwordx4 v[146:149], v[108:109], off offset:1024
	global_load_dwordx4 v[154:157], v[110:111], off offset:1024
	s_waitcnt lgkmcnt(3)
	v_mfma_f32_32x32x16_bf16 v[48:63], v[214:217], v[226:229], v[48:63]
	s_waitcnt lgkmcnt(2)
	v_mfma_f32_32x32x16_bf16 v[32:47], v[214:217], v[230:233], v[32:47]
	v_mfma_f32_32x32x16_bf16 v[16:31], v[218:221], v[226:229], v[16:31]
	ds_read_b128 v[214:217], v121 offset:36928
	ds_read_b128 v[222:225], v121 offset:41536
	ds_read_b128 v[226:229], v122 offset:55360
	ds_read_b128 v[234:237], v122 offset:59968
	s_waitcnt vmcnt(17)
	ds_write_b128 v120, v[158:161] offset:9216
	s_waitcnt vmcnt(16)
	ds_write_b128 v120, v[174:177] offset:27648
	v_mfma_f32_32x32x16_bf16 v[0:15], v[218:221], v[230:233], v[0:15]
	global_load_dwordx4 v[158:161], v[104:105], off offset:1024
	global_load_dwordx4 v[174:177], v[106:107], off offset:1024
	s_waitcnt lgkmcnt(3)
	v_mfma_f32_32x32x16_bf16 v[48:63], v[214:217], v[226:229], v[48:63]
	s_waitcnt lgkmcnt(2)
	v_mfma_f32_32x32x16_bf16 v[32:47], v[214:217], v[234:237], v[32:47]
	v_mfma_f32_32x32x16_bf16 v[16:31], v[222:225], v[226:229], v[16:31]
	ds_read_b128 v[214:217], v121 offset:36960
	ds_read_b128 v[218:221], v121 offset:41568
	ds_read_b128 v[226:229], v122 offset:55392
	ds_read_b128 v[230:233], v122 offset:60000
	s_waitcnt vmcnt(17)
	ds_write_b128 v120, v[162:165] offset:13824
	s_waitcnt vmcnt(16)
	ds_write_b128 v120, v[178:181] offset:32256
	v_mfma_f32_32x32x16_bf16 v[0:15], v[222:225], v[234:237], v[0:15]
	s_waitcnt lgkmcnt(0)
	s_barrier
	global_load_dwordx4 v[162:165], v[116:117], off offset:1152
	global_load_dwordx4 v[178:181], v[118:119], off offset:1152
	v_mfma_f32_32x32x16_bf16 v[48:63], v[214:217], v[226:229], v[48:63]
	v_mfma_f32_32x32x16_bf16 v[32:47], v[214:217], v[230:233], v[32:47]
	v_mfma_f32_32x32x16_bf16 v[16:31], v[218:221], v[226:229], v[16:31]
	ds_read_b128 v[214:217], v121
	ds_read_b128 v[222:225], v121 offset:4608
	ds_read_b128 v[226:229], v122 offset:18432
	ds_read_b128 v[234:237], v122 offset:23040
	s_waitcnt vmcnt(17)
	ds_write_b128 v120, v[166:169] offset:36864
	s_waitcnt vmcnt(16)
	ds_write_b128 v120, v[182:185] offset:55296
	v_mfma_f32_32x32x16_bf16 v[0:15], v[218:221], v[230:233], v[0:15]
	global_load_dwordx4 v[166:169], v[112:113], off offset:1152
	global_load_dwordx4 v[182:185], v[114:115], off offset:1152
	s_waitcnt lgkmcnt(3)
	v_mfma_f32_32x32x16_bf16 v[48:63], v[214:217], v[226:229], v[48:63]
	s_waitcnt lgkmcnt(2)
	v_mfma_f32_32x32x16_bf16 v[32:47], v[214:217], v[234:237], v[32:47]
	v_mfma_f32_32x32x16_bf16 v[16:31], v[222:225], v[226:229], v[16:31]
	ds_read_b128 v[214:217], v121 offset:32
	ds_read_b128 v[218:221], v121 offset:4640
	ds_read_b128 v[226:229], v122 offset:18464
	ds_read_b128 v[230:233], v122 offset:23072
	s_waitcnt vmcnt(17)
	ds_write_b128 v120, v[170:173] offset:41472
	s_waitcnt vmcnt(16)
	ds_write_b128 v120, v[186:189] offset:59904
	v_mfma_f32_32x32x16_bf16 v[0:15], v[222:225], v[234:237], v[0:15]
	global_load_dwordx4 v[170:173], v[108:109], off offset:1152
	global_load_dwordx4 v[186:189], v[110:111], off offset:1152
	s_waitcnt lgkmcnt(3)
	v_mfma_f32_32x32x16_bf16 v[48:63], v[214:217], v[226:229], v[48:63]
	s_waitcnt lgkmcnt(2)
	v_mfma_f32_32x32x16_bf16 v[32:47], v[214:217], v[230:233], v[32:47]
	v_mfma_f32_32x32x16_bf16 v[16:31], v[218:221], v[226:229], v[16:31]
	ds_read_b128 v[214:217], v121 offset:64
	ds_read_b128 v[222:225], v121 offset:4672
	ds_read_b128 v[226:229], v122 offset:18496
	ds_read_b128 v[234:237], v122 offset:23104
	s_waitcnt vmcnt(17)
	ds_write_b128 v120, v[190:193] offset:46080
	s_waitcnt vmcnt(16)
	ds_write_b128 v120, v[194:197] offset:64512
	v_mfma_f32_32x32x16_bf16 v[0:15], v[218:221], v[230:233], v[0:15]
	global_load_dwordx4 v[190:193], v[104:105], off offset:1152
	global_load_dwordx4 v[194:197], v[106:107], off offset:1152
	s_waitcnt lgkmcnt(3)
	v_mfma_f32_32x32x16_bf16 v[48:63], v[214:217], v[226:229], v[48:63]
	s_waitcnt lgkmcnt(2)
	v_mfma_f32_32x32x16_bf16 v[32:47], v[214:217], v[234:237], v[32:47]
	v_mfma_f32_32x32x16_bf16 v[16:31], v[222:225], v[226:229], v[16:31]
	ds_read_b128 v[214:217], v121 offset:96
	ds_read_b128 v[218:221], v121 offset:4704
	ds_read_b128 v[226:229], v122 offset:18528
	ds_read_b128 v[230:233], v122 offset:23136
	s_waitcnt vmcnt(17)
	ds_write_b128 v120, v[206:209] offset:50688
	s_waitcnt vmcnt(16)
	ds_write_b128 v123, v[210:213] offset:13824
	v_mfma_f32_32x32x16_bf16 v[0:15], v[222:225], v[234:237], v[0:15]
	s_waitcnt lgkmcnt(0)
	s_barrier
;     ...
;   for (int kt2 = 0; kt2 < nk; kt2 += 2) {
; #pragma unroll
;     for (int st = 0; st < 2; ++st) {
;       const int kt = kt2 + st;
;       const bf16_t* cur = lds + st * BUFE;
;       bf16_t* oth = lds + (st ^ 1) * BUFE;
;       const long k0r = (kt + 3 < nk) ? (long)(kt + 3) * BK : dR + (long)(kt + 3 - nk) * BK;
;       const long k0c = (kt + 3 < nk) ? (long)(kt + 3) * BK : dC + (long)(kt + 3 - nk) * BK;
;       const bool cnt = kt + 1 < nk;
;       const bf16_t* abase = cur + (wr * (RM / WR) + r) * STR + h * 8;
;       const bf16_t* bbase = cur + (RM + wc * (CN / WC) + r) * STR + h * 8;
;       bf16x8 af[2][MI], bfr[2][NI];
;       if (FDB) {
; #pragma unroll
;         for (int mi = 0; mi < MI; ++mi) af[0][mi] = *(const bf16x8*)(abase + mi * 32 * STR);
; #pragma unroll
;         for (int ni = 0; ni < NI; ++ni) bfr[0][ni] = *(const bf16x8*)(bbase + ni * 32 * STR);
;       }
; #pragma unroll
;       for (int ks = 0; ks < KS; ++ks) {
;         if (!FDB) {
; #pragma unroll
;           for (int mi = 0; mi < MI; ++mi) af[ks & 1][mi] = *(const bf16x8*)(abase + mi * 32 * STR + ks * 16);
; #pragma unroll
;           for (int ni = 0; ni < NI; ++ni) bfr[ks & 1][ni] = *(const bf16x8*)(bbase + ni * 32 * STR + ks * 16);
;         }
; #pragma unroll
;         for (int c = ks; c < RCH; c += KS) *(u32x4*)(oth + (srow + RPP * c) * STR + skc) = rr[st ^ 1][c];
; #pragma unroll
;         for (int c = ks; c < CCH; c += KS) {
;           *(u32x4*)(oth + (RM + srow + RPP * c) * STR + skc) = cr[st ^ 1][c];
;           if (SUMSQ && cnt) {
; #pragma unroll
;             for (int e = 0; e < 4; ++e) { const float a_ = bf_lo(cr[st ^ 1][c][e]), b_ = bf_hi(cr[st ^ 1][c][e]); ss[c] += a_ * a_ + b_ * b_; }
;           }
;         }
; #pragma unroll
;         for (int c = ks; c < RCH; c += KS) rr[st ^ 1][c] = *(const u32x4*)(rp + (size_t)(RPP * c) * ldr + k0r);
; #pragma unroll
;         for (int c = ks; c < CCH; c += KS) cr[st ^ 1][c] = *(const u32x4*)(cp + (size_t)(RPP * c) * ldc + k0c);
;         __builtin_amdgcn_sched_barrier(0);
;         if (FDB && ks + 1 < KS) {
; #pragma unroll
;           for (int mi = 0; mi < MI; ++mi) af[(ks + 1) & 1][mi] = *(const bf16x8*)(abase + mi * 32 * STR + (ks + 1) * 16);
; #pragma unroll
;           for (int ni = 0; ni < NI; ++ni) bfr[(ks + 1) & 1][ni] = *(const bf16x8*)(bbase + ni * 32 * STR + (ks + 1) * 16);
;         }
; #pragma unroll
	global_load_dwordx4 v[206:209], v[116:117], off offset:1280
	global_load_dwordx4 v[210:213], v[118:119], off offset:1280
	v_mfma_f32_32x32x16_bf16 v[48:63], v[214:217], v[226:229], v[48:63]
	v_mfma_f32_32x32x16_bf16 v[32:47], v[214:217], v[230:233], v[32:47]
	v_mfma_f32_32x32x16_bf16 v[16:31], v[218:221], v[226:229], v[16:31]
	ds_read_b128 v[214:217], v121 offset:36864
	ds_read_b128 v[222:225], v121 offset:41472
	ds_read_b128 v[226:229], v122 offset:55296
	ds_read_b128 v[234:237], v122 offset:59904
	s_waitcnt vmcnt(17)
	ds_write_b128 v120, v[198:201]
	s_waitcnt vmcnt(16)
	ds_write_b128 v120, v[202:205] offset:18432
	v_mfma_f32_32x32x16_bf16 v[0:15], v[218:221], v[230:233], v[0:15]
	global_load_dwordx4 v[198:201], v[112:113], off offset:1280
	global_load_dwordx4 v[202:205], v[114:115], off offset:1280
	s_waitcnt lgkmcnt(3)
	v_mfma_f32_32x32x16_bf16 v[48:63], v[214:217], v[226:229], v[48:63]
	s_waitcnt lgkmcnt(2)
	v_mfma_f32_32x32x16_bf16 v[32:47], v[214:217], v[234:237], v[32:47]
	v_mfma_f32_32x32x16_bf16 v[16:31], v[222:225], v[226:229], v[16:31]
	ds_read_b128 v[214:217], v121 offset:36896
	ds_read_b128 v[218:221], v121 offset:41504
	ds_read_b128 v[226:229], v122 offset:55328
	ds_read_b128 v[230:233], v122 offset:59936
	s_waitcnt vmcnt(17)
	ds_write_b128 v120, v[142:145] offset:4608
	s_waitcnt vmcnt(16)
	ds_write_b128 v120, v[150:153] offset:23040
	v_mfma_f32_32x32x16_bf16 v[0:15], v[222:225], v[234:237], v[0:15]
	global_load_dwordx4 v[142:145], v[108:109], off offset:1280
	global_load_dwordx4 v[150:153], v[110:111], off offset:1280
	s_waitcnt lgkmcnt(3)
	v_mfma_f32_32x32x16_bf16 v[48:63], v[214:217], v[226:229], v[48:63]
	s_waitcnt lgkmcnt(2)
	v_mfma_f32_32x32x16_bf16 v[32:47], v[214:217], v[230:233], v[32:47]
	v_mfma_f32_32x32x16_bf16 v[16:31], v[218:221], v[226:229], v[16:31]
	ds_read_b128 v[214:217], v121 offset:36928
	ds_read_b128 v[222:225], v121 offset:41536
	ds_read_b128 v[226:229], v122 offset:55360
	ds_read_b128 v[234:237], v122 offset:59968
	s_waitcnt vmcnt(17)
	ds_write_b128 v120, v[146:149] offset:9216
	s_waitcnt vmcnt(16)
	ds_write_b128 v120, v[154:157] offset:27648
	v_mfma_f32_32x32x16_bf16 v[0:15], v[218:221], v[230:233], v[0:15]
	global_load_dwordx4 v[146:149], v[104:105], off offset:1280
	global_load_dwordx4 v[154:157], v[106:107], off offset:1280
	s_waitcnt lgkmcnt(3)
	v_mfma_f32_32x32x16_bf16 v[48:63], v[214:217], v[226:229], v[48:63]
	s_waitcnt lgkmcnt(2)
	v_mfma_f32_32x32x16_bf16 v[32:47], v[214:217], v[234:237], v[32:47]
	v_mfma_f32_32x32x16_bf16 v[16:31], v[222:225], v[226:229], v[16:31]
	ds_read_b128 v[214:217], v121 offset:36960
	ds_read_b128 v[218:221], v121 offset:41568
	ds_read_b128 v[226:229], v122 offset:55392
	ds_read_b128 v[230:233], v122 offset:60000
	s_waitcnt vmcnt(17)
	ds_write_b128 v120, v[158:161] offset:13824
	s_waitcnt vmcnt(16)
	ds_write_b128 v120, v[174:177] offset:32256
	v_mfma_f32_32x32x16_bf16 v[0:15], v[222:225], v[234:237], v[0:15]
	s_waitcnt lgkmcnt(0)
	s_barrier
	global_load_dwordx4 v[158:161], v[116:117], off offset:1408
	global_load_dwordx4 v[174:177], v[118:119], off offset:1408
	v_mfma_f32_32x32x16_bf16 v[48:63], v[214:217], v[226:229], v[48:63]
	v_mfma_f32_32x32x16_bf16 v[32:47], v[214:217], v[230:233], v[32:47]
	v_mfma_f32_32x32x16_bf16 v[16:31], v[218:221], v[226:229], v[16:31]
	ds_read_b128 v[214:217], v121
	ds_read_b128 v[222:225], v121 offset:4608
	ds_read_b128 v[226:229], v122 offset:18432
	ds_read_b128 v[234:237], v122 offset:23040
	s_waitcnt vmcnt(17)
	ds_write_b128 v120, v[162:165] offset:36864
	s_waitcnt vmcnt(16)
	ds_write_b128 v120, v[178:181] offset:55296
	v_mfma_f32_32x32x16_bf16 v[0:15], v[218:221], v[230:233], v[0:15]
	global_load_dwordx4 v[162:165], v[112:113], off offset:1408
	global_load_dwordx4 v[178:181], v[114:115], off offset:1408
	s_waitcnt lgkmcnt(3)
	v_mfma_f32_32x32x16_bf16 v[48:63], v[214:217], v[226:229], v[48:63]
	s_waitcnt lgkmcnt(2)
	v_mfma_f32_32x32x16_bf16 v[32:47], v[214:217], v[234:237], v[32:47]
	v_mfma_f32_32x32x16_bf16 v[16:31], v[222:225], v[226:229], v[16:31]
	ds_read_b128 v[214:217], v121 offset:32
	ds_read_b128 v[218:221], v121 offset:4640
	ds_read_b128 v[226:229], v122 offset:18464
	ds_read_b128 v[230:233], v122 offset:23072
	s_waitcnt vmcnt(17)
	ds_write_b128 v120, v[166:169] offset:41472
	s_waitcnt vmcnt(16)
	ds_write_b128 v120, v[182:185] offset:59904
	v_mfma_f32_32x32x16_bf16 v[0:15], v[222:225], v[234:237], v[0:15]
	global_load_dwordx4 v[166:169], v[108:109], off offset:1408
	global_load_dwordx4 v[182:185], v[110:111], off offset:1408
	s_waitcnt lgkmcnt(3)
	v_mfma_f32_32x32x16_bf16 v[48:63], v[214:217], v[226:229], v[48:63]
	s_waitcnt lgkmcnt(2)
	v_mfma_f32_32x32x16_bf16 v[32:47], v[214:217], v[230:233], v[32:47]
	v_mfma_f32_32x32x16_bf16 v[16:31], v[218:221], v[226:229], v[16:31]
	ds_read_b128 v[214:217], v121 offset:64
	ds_read_b128 v[222:225], v121 offset:4672
	ds_read_b128 v[226:229], v122 offset:18496
	ds_read_b128 v[234:237], v122 offset:23104
	s_waitcnt vmcnt(17)
	ds_write_b128 v120, v[170:173] offset:46080
	s_waitcnt vmcnt(16)
	ds_write_b128 v120, v[186:189] offset:64512
	v_mfma_f32_32x32x16_bf16 v[0:15], v[218:221], v[230:233], v[0:15]
	global_load_dwordx4 v[170:173], v[104:105], off offset:1408
	global_load_dwordx4 v[186:189], v[106:107], off offset:1408
	s_waitcnt lgkmcnt(3)
	v_mfma_f32_32x32x16_bf16 v[48:63], v[214:217], v[226:229], v[48:63]
	s_waitcnt lgkmcnt(2)
	v_mfma_f32_32x32x16_bf16 v[32:47], v[214:217], v[234:237], v[32:47]
	v_mfma_f32_32x32x16_bf16 v[16:31], v[222:225], v[226:229], v[16:31]
	ds_read_b128 v[214:217], v121 offset:96
	ds_read_b128 v[218:221], v121 offset:4704
	ds_read_b128 v[226:229], v122 offset:18528
	ds_read_b128 v[230:233], v122 offset:23136
	s_waitcnt vmcnt(17)
	ds_write_b128 v120, v[190:193] offset:50688
	s_waitcnt vmcnt(16)
	ds_write_b128 v123, v[194:197] offset:13824
	v_mfma_f32_32x32x16_bf16 v[0:15], v[222:225], v[234:237], v[0:15]
	s_waitcnt lgkmcnt(0)
	s_barrier
;     ...
;   for (int kt2 = 0; kt2 < nk; kt2 += 2) {
; #pragma unroll
;     for (int st = 0; st < 2; ++st) {
;       const int kt = kt2 + st;
;       const bf16_t* cur = lds + st * BUFE;
;       bf16_t* oth = lds + (st ^ 1) * BUFE;
;       const long k0r = (kt + 3 < nk) ? (long)(kt + 3) * BK : dR + (long)(kt + 3 - nk) * BK;
;       const long k0c = (kt + 3 < nk) ? (long)(kt + 3) * BK : dC + (long)(kt + 3 - nk) * BK;
;       const bool cnt = kt + 1 < nk;
;       const bf16_t* abase = cur + (wr * (RM / WR) + r) * STR + h * 8;
;       const bf16_t* bbase = cur + (RM + wc * (CN / WC) + r) * STR + h * 8;
;       bf16x8 af[2][MI], bfr[2][NI];
;       if (FDB) {
; #pragma unroll
;         for (int mi = 0; mi < MI; ++mi) af[0][mi] = *(const bf16x8*)(abase + mi * 32 * STR);
; #pragma unroll
;         for (int ni = 0; ni < NI; ++ni) bfr[0][ni] = *(const bf16x8*)(bbase + ni * 32 * STR);
;       }
; #pragma unroll
;       for (int ks = 0; ks < KS; ++ks) {
;         if (!FDB) {
; #pragma unroll
;           for (int mi = 0; mi < MI; ++mi) af[ks & 1][mi] = *(const bf16x8*)(abase + mi * 32 * STR + ks * 16);
; #pragma unroll
;           for (int ni = 0; ni < NI; ++ni) bfr[ks & 1][ni] = *(const bf16x8*)(bbase + ni * 32 * STR + ks * 16);
;         }
; #pragma unroll
;         for (int c = ks; c < RCH; c += KS) *(u32x4*)(oth + (srow + RPP * c) * STR + skc) = rr[st ^ 1][c];
; #pragma unroll
;         for (int c = ks; c < CCH; c += KS) {
;           *(u32x4*)(oth + (RM + srow + RPP * c) * STR + skc) = cr[st ^ 1][c];
;           if (SUMSQ && cnt) {
; #pragma unroll
;             for (int e = 0; e < 4; ++e) { const float a_ = bf_lo(cr[st ^ 1][c][e]), b_ = bf_hi(cr[st ^ 1][c][e]); ss[c] += a_ * a_ + b_ * b_; }
;           }
;         }
; #pragma unroll
;         for (int c = ks; c < RCH; c += KS) rr[st ^ 1][c] = *(const u32x4*)(rp + (size_t)(RPP * c) * ldr + k0r);
; #pragma unroll
;         for (int c = ks; c < CCH; c += KS) cr[st ^ 1][c] = *(const u32x4*)(cp + (size_t)(RPP * c) * ldc + k0c);
;         __builtin_amdgcn_sched_barrier(0);
;         if (FDB && ks + 1 < KS) {
; #pragma unroll
;           for (int mi = 0; mi < MI; ++mi) af[(ks + 1) & 1][mi] = *(const bf16x8*)(abase + mi * 32 * STR + (ks + 1) * 16);
; #pragma unroll
;           for (int ni = 0; ni < NI; ++ni) bfr[(ks + 1) & 1][ni] = *(const bf16x8*)(bbase + ni * 32 * STR + (ks + 1) * 16);
;         }
; #pragma unroll
	global_load_dwordx4 v[190:193], v[116:117], off offset:1536
	global_load_dwordx4 v[194:197], v[118:119], off offset:1536
	v_mfma_f32_32x32x16_bf16 v[48:63], v[214:217], v[226:229], v[48:63]
	v_mfma_f32_32x32x16_bf16 v[32:47], v[214:217], v[230:233], v[32:47]
	v_mfma_f32_32x32x16_bf16 v[16:31], v[218:221], v[226:229], v[16:31]
	ds_read_b128 v[214:217], v121 offset:36864
	ds_read_b128 v[222:225], v121 offset:41472
	ds_read_b128 v[226:229], v122 offset:55296
	ds_read_b128 v[234:237], v122 offset:59904
	s_waitcnt vmcnt(17)
	ds_write_b128 v120, v[206:209]
	s_waitcnt vmcnt(16)
	ds_write_b128 v120, v[210:213] offset:18432
	v_mfma_f32_32x32x16_bf16 v[0:15], v[218:221], v[230:233], v[0:15]
	global_load_dwordx4 v[206:209], v[112:113], off offset:1536
	global_load_dwordx4 v[210:213], v[114:115], off offset:1536
	s_waitcnt lgkmcnt(3)
	v_mfma_f32_32x32x16_bf16 v[48:63], v[214:217], v[226:229], v[48:63]
	s_waitcnt lgkmcnt(2)
	v_mfma_f32_32x32x16_bf16 v[32:47], v[214:217], v[234:237], v[32:47]
	v_mfma_f32_32x32x16_bf16 v[16:31], v[222:225], v[226:229], v[16:31]
	ds_read_b128 v[214:217], v121 offset:36896
	ds_read_b128 v[218:221], v121 offset:41504
	ds_read_b128 v[226:229], v122 offset:55328
	ds_read_b128 v[230:233], v122 offset:59936
	s_waitcnt vmcnt(17)
	ds_write_b128 v120, v[198:201] offset:4608
	s_waitcnt vmcnt(16)
	ds_write_b128 v120, v[202:205] offset:23040
	v_mfma_f32_32x32x16_bf16 v[0:15], v[222:225], v[234:237], v[0:15]
	global_load_dwordx4 v[198:201], v[108:109], off offset:1536
	global_load_dwordx4 v[202:205], v[110:111], off offset:1536
	s_waitcnt lgkmcnt(3)
	v_mfma_f32_32x32x16_bf16 v[48:63], v[214:217], v[226:229], v[48:63]
	s_waitcnt lgkmcnt(2)
	v_mfma_f32_32x32x16_bf16 v[32:47], v[214:217], v[230:233], v[32:47]
	v_mfma_f32_32x32x16_bf16 v[16:31], v[218:221], v[226:229], v[16:31]
	ds_read_b128 v[214:217], v121 offset:36928
	ds_read_b128 v[222:225], v121 offset:41536
	ds_read_b128 v[226:229], v122 offset:55360
	ds_read_b128 v[234:237], v122 offset:59968
	s_waitcnt vmcnt(17)
	ds_write_b128 v120, v[142:145] offset:9216
	s_waitcnt vmcnt(16)
	ds_write_b128 v120, v[150:153] offset:27648
	v_mfma_f32_32x32x16_bf16 v[0:15], v[218:221], v[230:233], v[0:15]
	global_load_dwordx4 v[142:145], v[104:105], off offset:1536
	global_load_dwordx4 v[150:153], v[106:107], off offset:1536
	s_waitcnt lgkmcnt(3)
	v_mfma_f32_32x32x16_bf16 v[48:63], v[214:217], v[226:229], v[48:63]
	s_waitcnt lgkmcnt(2)
	v_mfma_f32_32x32x16_bf16 v[32:47], v[214:217], v[234:237], v[32:47]
	v_mfma_f32_32x32x16_bf16 v[16:31], v[222:225], v[226:229], v[16:31]
	ds_read_b128 v[214:217], v121 offset:36960
	ds_read_b128 v[218:221], v121 offset:41568
	ds_read_b128 v[226:229], v122 offset:55392
	ds_read_b128 v[230:233], v122 offset:60000
	s_waitcnt vmcnt(17)
	ds_write_b128 v120, v[146:149] offset:13824
	s_waitcnt vmcnt(16)
	ds_write_b128 v120, v[154:157] offset:32256
	v_mfma_f32_32x32x16_bf16 v[0:15], v[222:225], v[234:237], v[0:15]
	s_waitcnt lgkmcnt(0)
	s_barrier
	global_load_dwordx4 v[146:149], v[116:117], off offset:1664
	global_load_dwordx4 v[154:157], v[118:119], off offset:1664
	v_mfma_f32_32x32x16_bf16 v[48:63], v[214:217], v[226:229], v[48:63]
	v_mfma_f32_32x32x16_bf16 v[32:47], v[214:217], v[230:233], v[32:47]
	v_mfma_f32_32x32x16_bf16 v[16:31], v[218:221], v[226:229], v[16:31]
	ds_read_b128 v[214:217], v121
	ds_read_b128 v[222:225], v121 offset:4608
	ds_read_b128 v[226:229], v122 offset:18432
	ds_read_b128 v[234:237], v122 offset:23040
	s_waitcnt vmcnt(17)
	ds_write_b128 v120, v[158:161] offset:36864
	s_waitcnt vmcnt(16)
	ds_write_b128 v120, v[174:177] offset:55296
	v_mfma_f32_32x32x16_bf16 v[0:15], v[218:221], v[230:233], v[0:15]
	global_load_dwordx4 v[158:161], v[112:113], off offset:1664
	global_load_dwordx4 v[174:177], v[114:115], off offset:1664
	s_waitcnt lgkmcnt(3)
	v_mfma_f32_32x32x16_bf16 v[48:63], v[214:217], v[226:229], v[48:63]
	s_waitcnt lgkmcnt(2)
	v_mfma_f32_32x32x16_bf16 v[32:47], v[214:217], v[234:237], v[32:47]
	v_mfma_f32_32x32x16_bf16 v[16:31], v[222:225], v[226:229], v[16:31]
	ds_read_b128 v[214:217], v121 offset:32
	ds_read_b128 v[218:221], v121 offset:4640
	ds_read_b128 v[226:229], v122 offset:18464
	ds_read_b128 v[230:233], v122 offset:23072
	s_waitcnt vmcnt(17)
	ds_write_b128 v120, v[162:165] offset:41472
	s_waitcnt vmcnt(16)
	ds_write_b128 v120, v[178:181] offset:59904
	v_mfma_f32_32x32x16_bf16 v[0:15], v[222:225], v[234:237], v[0:15]
	global_load_dwordx4 v[162:165], v[108:109], off offset:1664
	global_load_dwordx4 v[178:181], v[110:111], off offset:1664
	s_waitcnt lgkmcnt(3)
	v_mfma_f32_32x32x16_bf16 v[48:63], v[214:217], v[226:229], v[48:63]
	s_waitcnt lgkmcnt(2)
	v_mfma_f32_32x32x16_bf16 v[32:47], v[214:217], v[230:233], v[32:47]
	v_mfma_f32_32x32x16_bf16 v[16:31], v[218:221], v[226:229], v[16:31]
	ds_read_b128 v[214:217], v121 offset:64
	ds_read_b128 v[222:225], v121 offset:4672
	ds_read_b128 v[226:229], v122 offset:18496
	ds_read_b128 v[234:237], v122 offset:23104
	s_waitcnt vmcnt(17)
	ds_write_b128 v120, v[166:169] offset:46080
	s_waitcnt vmcnt(16)
	ds_write_b128 v120, v[182:185] offset:64512
	v_mfma_f32_32x32x16_bf16 v[0:15], v[218:221], v[230:233], v[0:15]
	global_load_dwordx4 v[166:169], v[104:105], off offset:1664
	global_load_dwordx4 v[182:185], v[106:107], off offset:1664
	s_waitcnt lgkmcnt(3)
	v_mfma_f32_32x32x16_bf16 v[48:63], v[214:217], v[226:229], v[48:63]
	s_waitcnt lgkmcnt(2)
	v_mfma_f32_32x32x16_bf16 v[32:47], v[214:217], v[234:237], v[32:47]
	v_mfma_f32_32x32x16_bf16 v[16:31], v[222:225], v[226:229], v[16:31]
	ds_read_b128 v[214:217], v121 offset:96
	ds_read_b128 v[218:221], v121 offset:4704
	ds_read_b128 v[226:229], v122 offset:18528
	ds_read_b128 v[230:233], v122 offset:23136
	s_waitcnt vmcnt(17)
	ds_write_b128 v120, v[170:173] offset:50688
	s_waitcnt vmcnt(16)
	ds_write_b128 v123, v[186:189] offset:13824
	v_mfma_f32_32x32x16_bf16 v[0:15], v[222:225], v[234:237], v[0:15]
	s_waitcnt lgkmcnt(0)
	s_barrier
;     ...
;   for (int kt2 = 0; kt2 < nk; kt2 += 2) {
; #pragma unroll
;     for (int st = 0; st < 2; ++st) {
;       const int kt = kt2 + st;
;       const bf16_t* cur = lds + st * BUFE;
;       bf16_t* oth = lds + (st ^ 1) * BUFE;
;       const long k0r = (kt + 3 < nk) ? (long)(kt + 3) * BK : dR + (long)(kt + 3 - nk) * BK;
;       const long k0c = (kt + 3 < nk) ? (long)(kt + 3) * BK : dC + (long)(kt + 3 - nk) * BK;
;       const bool cnt = kt + 1 < nk;
;       const bf16_t* abase = cur + (wr * (RM / WR) + r) * STR + h * 8;
;       const bf16_t* bbase = cur + (RM + wc * (CN / WC) + r) * STR + h * 8;
;       bf16x8 af[2][MI], bfr[2][NI];
;       if (FDB) {
; #pragma unroll
;         for (int mi = 0; mi < MI; ++mi) af[0][mi] = *(const bf16x8*)(abase + mi * 32 * STR);
; #pragma unroll
;         for (int ni = 0; ni < NI; ++ni) bfr[0][ni] = *(const bf16x8*)(bbase + ni * 32 * STR);
;       }
; #pragma unroll
;       for (int ks = 0; ks < KS; ++ks) {
;         if (!FDB) {
; #pragma unroll
;           for (int mi = 0; mi < MI; ++mi) af[ks & 1][mi] = *(const bf16x8*)(abase + mi * 32 * STR + ks * 16);
; #pragma unroll
;           for (int ni = 0; ni < NI; ++ni) bfr[ks & 1][ni] = *(const bf16x8*)(bbase + ni * 32 * STR + ks * 16);
;         }
; #pragma unroll
;         for (int c = ks; c < RCH; c += KS) *(u32x4*)(oth + (srow + RPP * c) * STR + skc) = rr[st ^ 1][c];
; #pragma unroll
;         for (int c = ks; c < CCH; c += KS) {
;           *(u32x4*)(oth + (RM + srow + RPP * c) * STR + skc) = cr[st ^ 1][c];
;           if (SUMSQ && cnt) {
; #pragma unroll
;             for (int e = 0; e < 4; ++e) { const float a_ = bf_lo(cr[st ^ 1][c][e]), b_ = bf_hi(cr[st ^ 1][c][e]); ss[c] += a_ * a_ + b_ * b_; }
;           }
;         }
; #pragma unroll
;         for (int c = ks; c < RCH; c += KS) rr[st ^ 1][c] = *(const u32x4*)(rp + (size_t)(RPP * c) * ldr + k0r);
; #pragma unroll
;         for (int c = ks; c < CCH; c += KS) cr[st ^ 1][c] = *(const u32x4*)(cp + (size_t)(RPP * c) * ldc + k0c);
;         __builtin_amdgcn_sched_barrier(0);
;         if (FDB && ks + 1 < KS) {
; #pragma unroll
;           for (int mi = 0; mi < MI; ++mi) af[(ks + 1) & 1][mi] = *(const bf16x8*)(abase + mi * 32 * STR + (ks + 1) * 16);
; #pragma unroll
;           for (int ni = 0; ni < NI; ++ni) bfr[(ks + 1) & 1][ni] = *(const bf16x8*)(bbase + ni * 32 * STR + (ks + 1) * 16);
;         }
; #pragma unroll
	global_load_dwordx4 v[170:173], v[116:117], off offset:1792
	global_load_dwordx4 v[186:189], v[118:119], off offset:1792
	v_mfma_f32_32x32x16_bf16 v[48:63], v[214:217], v[226:229], v[48:63]
	v_mfma_f32_32x32x16_bf16 v[32:47], v[214:217], v[230:233], v[32:47]
	v_mfma_f32_32x32x16_bf16 v[16:31], v[218:221], v[226:229], v[16:31]
	ds_read_b128 v[214:217], v121 offset:36864
	ds_read_b128 v[222:225], v121 offset:41472
	ds_read_b128 v[226:229], v122 offset:55296
	ds_read_b128 v[234:237], v122 offset:59904
	s_waitcnt vmcnt(17)
	ds_write_b128 v120, v[190:193]
	s_waitcnt vmcnt(16)
	ds_write_b128 v120, v[194:197] offset:18432
	v_mfma_f32_32x32x16_bf16 v[0:15], v[218:221], v[230:233], v[0:15]
	global_load_dwordx4 v[190:193], v[112:113], off offset:1792
	global_load_dwordx4 v[194:197], v[114:115], off offset:1792
	s_waitcnt lgkmcnt(3)
	v_mfma_f32_32x32x16_bf16 v[48:63], v[214:217], v[226:229], v[48:63]
	s_waitcnt lgkmcnt(2)
	v_mfma_f32_32x32x16_bf16 v[32:47], v[214:217], v[234:237], v[32:47]
	v_mfma_f32_32x32x16_bf16 v[16:31], v[222:225], v[226:229], v[16:31]
	ds_read_b128 v[214:217], v121 offset:36896
	ds_read_b128 v[218:221], v121 offset:41504
	ds_read_b128 v[226:229], v122 offset:55328
	ds_read_b128 v[230:233], v122 offset:59936
	s_waitcnt vmcnt(17)
	ds_write_b128 v120, v[206:209] offset:4608
	s_waitcnt vmcnt(16)
	ds_write_b128 v120, v[210:213] offset:23040
	v_mfma_f32_32x32x16_bf16 v[0:15], v[222:225], v[234:237], v[0:15]
	global_load_dwordx4 v[206:209], v[108:109], off offset:1792
	global_load_dwordx4 v[210:213], v[110:111], off offset:1792
	s_waitcnt lgkmcnt(3)
	v_mfma_f32_32x32x16_bf16 v[48:63], v[214:217], v[226:229], v[48:63]
	s_waitcnt lgkmcnt(2)
	v_mfma_f32_32x32x16_bf16 v[32:47], v[214:217], v[230:233], v[32:47]
	v_mfma_f32_32x32x16_bf16 v[16:31], v[218:221], v[226:229], v[16:31]
	ds_read_b128 v[214:217], v121 offset:36928
	ds_read_b128 v[222:225], v121 offset:41536
	ds_read_b128 v[226:229], v122 offset:55360
	ds_read_b128 v[234:237], v122 offset:59968
	s_waitcnt vmcnt(17)
	ds_write_b128 v120, v[198:201] offset:9216
	s_waitcnt vmcnt(16)
	ds_write_b128 v120, v[202:205] offset:27648
	v_mfma_f32_32x32x16_bf16 v[0:15], v[218:221], v[230:233], v[0:15]
	global_load_dwordx4 v[198:201], v[104:105], off offset:1792
	global_load_dwordx4 v[202:205], v[106:107], off offset:1792
	s_waitcnt lgkmcnt(3)
	v_mfma_f32_32x32x16_bf16 v[48:63], v[214:217], v[226:229], v[48:63]
	s_waitcnt lgkmcnt(2)
	v_mfma_f32_32x32x16_bf16 v[32:47], v[214:217], v[234:237], v[32:47]
	v_mfma_f32_32x32x16_bf16 v[16:31], v[222:225], v[226:229], v[16:31]
	ds_read_b128 v[214:217], v121 offset:36960
	ds_read_b128 v[218:221], v121 offset:41568
	ds_read_b128 v[226:229], v122 offset:55392
	ds_read_b128 v[230:233], v122 offset:60000
	s_waitcnt vmcnt(17)
	ds_write_b128 v120, v[142:145] offset:13824
	s_waitcnt vmcnt(16)
	ds_write_b128 v120, v[150:153] offset:32256
	v_mfma_f32_32x32x16_bf16 v[0:15], v[222:225], v[234:237], v[0:15]
	s_waitcnt lgkmcnt(0)
	s_barrier
	global_load_dwordx4 v[142:145], v[116:117], off offset:1920
	s_nop 0
	global_load_dwordx4 v[116:119], v[118:119], off offset:1920
	v_mfma_f32_32x32x16_bf16 v[48:63], v[214:217], v[226:229], v[48:63]
	v_mfma_f32_32x32x16_bf16 v[32:47], v[214:217], v[230:233], v[32:47]
	v_mfma_f32_32x32x16_bf16 v[16:31], v[218:221], v[226:229], v[16:31]
	ds_read_b128 v[150:153], v121
	ds_read_b128 v[214:217], v121 offset:4608
	ds_read_b128 v[222:225], v122 offset:18432
	ds_read_b128 v[226:229], v122 offset:23040
	s_waitcnt vmcnt(17)
	ds_write_b128 v120, v[146:149] offset:36864
	s_waitcnt vmcnt(16)
	ds_write_b128 v120, v[154:157] offset:55296
	v_mfma_f32_32x32x16_bf16 v[0:15], v[218:221], v[230:233], v[0:15]
	global_load_dwordx4 v[146:149], v[112:113], off offset:1920
	s_nop 0
	global_load_dwordx4 v[112:115], v[114:115], off offset:1920
	s_waitcnt lgkmcnt(3)
	v_mfma_f32_32x32x16_bf16 v[48:63], v[150:153], v[222:225], v[48:63]
	s_waitcnt lgkmcnt(2)
	v_mfma_f32_32x32x16_bf16 v[32:47], v[150:153], v[226:229], v[32:47]
	v_mfma_f32_32x32x16_bf16 v[16:31], v[214:217], v[222:225], v[16:31]
	ds_read_b128 v[150:153], v121 offset:32
	ds_read_b128 v[154:157], v121 offset:4640
	ds_read_b128 v[218:221], v122 offset:18464
	ds_read_b128 v[222:225], v122 offset:23072
	s_waitcnt vmcnt(17)
	ds_write_b128 v120, v[158:161] offset:41472
	s_waitcnt vmcnt(16)
	ds_write_b128 v120, v[174:177] offset:59904
	v_mfma_f32_32x32x16_bf16 v[0:15], v[214:217], v[226:229], v[0:15]
	s_waitcnt lgkmcnt(3)
	v_mfma_f32_32x32x16_bf16 v[48:63], v[150:153], v[218:221], v[48:63]
	s_waitcnt lgkmcnt(2)
	v_mfma_f32_32x32x16_bf16 v[32:47], v[150:153], v[222:225], v[32:47]
	global_load_dwordx4 v[150:153], v[108:109], off offset:1920
	s_nop 0
	global_load_dwordx4 v[108:111], v[110:111], off offset:1920
	v_mfma_f32_32x32x16_bf16 v[16:31], v[154:157], v[218:221], v[16:31]
	ds_read_b128 v[158:161], v121 offset:64
	ds_read_b128 v[174:177], v121 offset:4672
	ds_read_b128 v[214:217], v122 offset:18496
	ds_read_b128 v[218:221], v122 offset:23104
	s_waitcnt vmcnt(17)
	ds_write_b128 v120, v[162:165] offset:46080
	s_waitcnt vmcnt(16)
	ds_write_b128 v120, v[178:181] offset:64512
	v_mfma_f32_32x32x16_bf16 v[0:15], v[154:157], v[222:225], v[0:15]
	global_load_dwordx4 v[154:157], v[104:105], off offset:1920
	s_nop 0
	global_load_dwordx4 v[104:107], v[106:107], off offset:1920
	s_waitcnt lgkmcnt(3)
	v_mfma_f32_32x32x16_bf16 v[48:63], v[158:161], v[214:217], v[48:63]
	s_waitcnt lgkmcnt(2)
	v_mfma_f32_32x32x16_bf16 v[32:47], v[158:161], v[218:221], v[32:47]
	v_mfma_f32_32x32x16_bf16 v[16:31], v[174:177], v[214:217], v[16:31]
	ds_read_b128 v[158:161], v121 offset:96
	ds_read_b128 v[162:165], v121 offset:4704
	ds_read_b128 v[178:181], v122 offset:18528
	ds_read_b128 v[214:217], v122 offset:23136
	s_waitcnt vmcnt(17)
	ds_write_b128 v120, v[166:169] offset:50688
	s_waitcnt vmcnt(16)
	ds_write_b128 v123, v[182:185] offset:13824
	v_mfma_f32_32x32x16_bf16 v[0:15], v[174:177], v[218:221], v[0:15]
	s_waitcnt lgkmcnt(3)
	v_mfma_f32_32x32x16_bf16 v[48:63], v[158:161], v[178:181], v[48:63]
	s_waitcnt lgkmcnt(0)
	s_barrier
;     ...
;   for (int kt2 = 0; kt2 < nk; kt2 += 2) {
; #pragma unroll
;     for (int st = 0; st < 2; ++st) {
;       const int kt = kt2 + st;
;       const bf16_t* cur = lds + st * BUFE;
;       bf16_t* oth = lds + (st ^ 1) * BUFE;
;       const long k0r = (kt + 3 < nk) ? (long)(kt + 3) * BK : dR + (long)(kt + 3 - nk) * BK;
;       const long k0c = (kt + 3 < nk) ? (long)(kt + 3) * BK : dC + (long)(kt + 3 - nk) * BK;
;       const bool cnt = kt + 1 < nk;
;       const bf16_t* abase = cur + (wr * (RM / WR) + r) * STR + h * 8;
;       const bf16_t* bbase = cur + (RM + wc * (CN / WC) + r) * STR + h * 8;
;       bf16x8 af[2][MI], bfr[2][NI];
;       if (FDB) {
; #pragma unroll
;         for (int mi = 0; mi < MI; ++mi) af[0][mi] = *(const bf16x8*)(abase + mi * 32 * STR);
; #pragma unroll
;         for (int ni = 0; ni < NI; ++ni) bfr[0][ni] = *(const bf16x8*)(bbase + ni * 32 * STR);
;       }
; #pragma unroll
;       for (int ks = 0; ks < KS; ++ks) {
;         if (!FDB) {
; #pragma unroll
;           for (int mi = 0; mi < MI; ++mi) af[ks & 1][mi] = *(const bf16x8*)(abase + mi * 32 * STR + ks * 16);
; #pragma unroll
;           for (int ni = 0; ni < NI; ++ni) bfr[ks & 1][ni] = *(const bf16x8*)(bbase + ni * 32 * STR + ks * 16);
;         }
; #pragma unroll
;         for (int c = ks; c < RCH; c += KS) *(u32x4*)(oth + (srow + RPP * c) * STR + skc) = rr[st ^ 1][c];
; #pragma unroll
;         for (int c = ks; c < CCH; c += KS) {
;           *(u32x4*)(oth + (RM + srow + RPP * c) * STR + skc) = cr[st ^ 1][c];
;           if (SUMSQ && cnt) {
; #pragma unroll
;             for (int e = 0; e < 4; ++e) { const float a_ = bf_lo(cr[st ^ 1][c][e]), b_ = bf_hi(cr[st ^ 1][c][e]); ss[c] += a_ * a_ + b_ * b_; }
;           }
;         }
; #pragma unroll
;         for (int c = ks; c < RCH; c += KS) rr[st ^ 1][c] = *(const u32x4*)(rp + (size_t)(RPP * c) * ldr + k0r);
; #pragma unroll
;         for (int c = ks; c < CCH; c += KS) cr[st ^ 1][c] = *(const u32x4*)(cp + (size_t)(RPP * c) * ldc + k0c);
;         __builtin_amdgcn_sched_barrier(0);
;         if (FDB && ks + 1 < KS) {
; #pragma unroll
;           for (int mi = 0; mi < MI; ++mi) af[(ks + 1) & 1][mi] = *(const bf16x8*)(abase + mi * 32 * STR + (ks + 1) * 16);
; #pragma unroll
;           for (int ni = 0; ni < NI; ++ni) bfr[(ks + 1) & 1][ni] = *(const bf16x8*)(bbase + ni * 32 * STR + (ks + 1) * 16);
;         }
; #pragma unroll
	v_mfma_f32_32x32x16_bf16 v[32:47], v[158:161], v[214:217], v[32:47]
	v_mfma_f32_32x32x16_bf16 v[16:31], v[162:165], v[178:181], v[16:31]
	ds_read_b128 v[158:161], v121 offset:36864
	ds_read_b128 v[166:169], v121 offset:41472
	ds_read_b128 v[174:177], v122 offset:55296
	ds_read_b128 v[178:181], v122 offset:59904
	s_waitcnt vmcnt(15)
	ds_write_b128 v120, v[170:173]
	s_waitcnt vmcnt(14)
	ds_write_b128 v120, v[186:189] offset:18432
	v_mfma_f32_32x32x16_bf16 v[0:15], v[162:165], v[214:217], v[0:15]
	s_waitcnt lgkmcnt(3)
	v_mfma_f32_32x32x16_bf16 v[48:63], v[158:161], v[174:177], v[48:63]
	s_waitcnt lgkmcnt(2)
	v_mfma_f32_32x32x16_bf16 v[32:47], v[158:161], v[178:181], v[32:47]
	v_mfma_f32_32x32x16_bf16 v[16:31], v[166:169], v[174:177], v[16:31]
	ds_read_b128 v[158:161], v121 offset:36896
	ds_read_b128 v[162:165], v121 offset:41504
	ds_read_b128 v[170:173], v122 offset:55328
	ds_read_b128 v[174:177], v122 offset:59936
	s_waitcnt vmcnt(13)
	ds_write_b128 v120, v[190:193] offset:4608
	s_waitcnt vmcnt(12)
	ds_write_b128 v120, v[194:197] offset:23040
	v_mfma_f32_32x32x16_bf16 v[0:15], v[166:169], v[178:181], v[0:15]
	s_waitcnt lgkmcnt(3)
	v_mfma_f32_32x32x16_bf16 v[48:63], v[158:161], v[170:173], v[48:63]
	s_waitcnt lgkmcnt(2)
	v_mfma_f32_32x32x16_bf16 v[32:47], v[158:161], v[174:177], v[32:47]
	v_mfma_f32_32x32x16_bf16 v[16:31], v[162:165], v[170:173], v[16:31]
	ds_read_b128 v[158:161], v121 offset:36928
	ds_read_b128 v[166:169], v121 offset:41536
	ds_read_b128 v[170:173], v122 offset:55360
	ds_read_b128 v[178:181], v122 offset:59968
	s_waitcnt vmcnt(11)
	ds_write_b128 v120, v[206:209] offset:9216
	s_waitcnt vmcnt(10)
	ds_write_b128 v120, v[210:213] offset:27648
	v_mfma_f32_32x32x16_bf16 v[0:15], v[162:165], v[174:177], v[0:15]
	s_waitcnt lgkmcnt(3)
	v_mfma_f32_32x32x16_bf16 v[48:63], v[158:161], v[170:173], v[48:63]
	s_waitcnt lgkmcnt(2)
	v_mfma_f32_32x32x16_bf16 v[32:47], v[158:161], v[178:181], v[32:47]
	v_mfma_f32_32x32x16_bf16 v[16:31], v[166:169], v[170:173], v[16:31]
	ds_read_b128 v[158:161], v121 offset:36960
	ds_read_b128 v[162:165], v121 offset:41568
	ds_read_b128 v[170:173], v122 offset:55392
	ds_read_b128 v[174:177], v122 offset:60000
	s_waitcnt vmcnt(9)
	ds_write_b128 v120, v[198:201] offset:13824
	s_waitcnt vmcnt(8)
	ds_write_b128 v120, v[202:205] offset:32256
	v_mfma_f32_32x32x16_bf16 v[0:15], v[166:169], v[178:181], v[0:15]
	s_waitcnt lgkmcnt(3)
	v_mfma_f32_32x32x16_bf16 v[48:63], v[158:161], v[170:173], v[48:63]
	s_waitcnt lgkmcnt(0)
	s_barrier
	v_mfma_f32_32x32x16_bf16 v[32:47], v[158:161], v[174:177], v[32:47]
	v_mfma_f32_32x32x16_bf16 v[16:31], v[162:165], v[170:173], v[16:31]
	ds_read_b128 v[158:161], v121
	ds_read_b128 v[166:169], v121 offset:4608
	ds_read_b128 v[170:173], v122 offset:18432
	ds_read_b128 v[178:181], v122 offset:23040
	s_waitcnt vmcnt(7)
	ds_write_b128 v120, v[142:145] offset:36864
	s_waitcnt vmcnt(6)
	ds_write_b128 v120, v[116:119] offset:55296
	v_mfma_f32_32x32x16_bf16 v[0:15], v[162:165], v[174:177], v[0:15]
	s_waitcnt lgkmcnt(3)
	v_mfma_f32_32x32x16_bf16 v[48:63], v[158:161], v[170:173], v[48:63]
	s_waitcnt lgkmcnt(2)
	v_mfma_f32_32x32x16_bf16 v[32:47], v[158:161], v[178:181], v[32:47]
	ds_read_b128 v[116:119], v121 offset:32
	ds_read_b128 v[142:145], v121 offset:4640
	ds_read_b128 v[158:161], v122 offset:18464
	ds_read_b128 v[162:165], v122 offset:23072
	s_waitcnt vmcnt(5)
	ds_write_b128 v120, v[146:149] offset:41472
	s_waitcnt vmcnt(4)
	ds_write_b128 v120, v[112:115] offset:59904
	v_mfma_f32_32x32x16_bf16 v[16:31], v[166:169], v[170:173], v[16:31]
	v_mfma_f32_32x32x16_bf16 v[0:15], v[166:169], v[178:181], v[0:15]
	s_waitcnt lgkmcnt(3)
	v_mfma_f32_32x32x16_bf16 v[48:63], v[116:119], v[158:161], v[48:63]
	s_waitcnt lgkmcnt(2)
	v_mfma_f32_32x32x16_bf16 v[32:47], v[116:119], v[162:165], v[32:47]
	v_mfma_f32_32x32x16_bf16 v[16:31], v[142:145], v[158:161], v[16:31]
	ds_read_b128 v[112:115], v121 offset:64
	ds_read_b128 v[116:119], v121 offset:4672
	ds_read_b128 v[146:149], v122 offset:18496
	ds_read_b128 v[158:161], v122 offset:23104
	s_waitcnt vmcnt(3)
	ds_write_b128 v120, v[150:153] offset:46080
	s_waitcnt vmcnt(2)
	ds_write_b128 v120, v[108:111] offset:64512
	v_mfma_f32_32x32x16_bf16 v[0:15], v[142:145], v[162:165], v[0:15]
	s_waitcnt lgkmcnt(3)
	v_mfma_f32_32x32x16_bf16 v[48:63], v[112:115], v[146:149], v[48:63]
	s_waitcnt lgkmcnt(2)
	v_mfma_f32_32x32x16_bf16 v[32:47], v[112:115], v[158:161], v[32:47]
	v_mfma_f32_32x32x16_bf16 v[16:31], v[116:119], v[146:149], v[16:31]
	ds_read_b128 v[108:111], v121 offset:96
	ds_read_b128 v[112:115], v121 offset:4704
	ds_read_b128 v[142:145], v122 offset:18528
	ds_read_b128 v[146:149], v122 offset:23136
	s_waitcnt vmcnt(1)
	ds_write_b128 v120, v[154:157] offset:50688
	s_waitcnt vmcnt(0)
	ds_write_b128 v123, v[104:107] offset:13824
	v_mfma_f32_32x32x16_bf16 v[0:15], v[116:119], v[158:161], v[0:15]
	s_waitcnt lgkmcnt(3)
	v_mfma_f32_32x32x16_bf16 v[48:63], v[108:111], v[142:145], v[48:63]
	s_waitcnt lgkmcnt(0)
	s_barrier
;     ...
;       for (int ks = 0; ks < KS; ++ks) {
;         if (!FDB) {
; #pragma unroll
;           for (int mi = 0; mi < MI; ++mi) af[ks & 1][mi] = *(const bf16x8*)(abase + mi * 32 * STR + ks * 16);
; #pragma unroll
;           for (int ni = 0; ni < NI; ++ni) bfr[ks & 1][ni] = *(const bf16x8*)(bbase + ni * 32 * STR + ks * 16);
;         }
; #pragma unroll
;         for (int c = ks; c < RCH; c += KS) *(u32x4*)(oth + (srow + RPP * c) * STR + skc) = rr[st ^ 1][c];
; #pragma unroll
;         for (int c = ks; c < CCH; c += KS) {
;           *(u32x4*)(oth + (RM + srow + RPP * c) * STR + skc) = cr[st ^ 1][c];
;           if (SUMSQ && cnt) {
; #pragma unroll
;             for (int e = 0; e < 4; ++e) { const float a_ = bf_lo(cr[st ^ 1][c][e]), b_ = bf_hi(cr[st ^ 1][c][e]); ss[c] += a_ * a_ + b_ * b_; }
;           }
;         }
; #pragma unroll
;         for (int c = ks; c < RCH; c += KS) rr[st ^ 1][c] = *(const u32x4*)(rp + (size_t)(RPP * c) * ldr + k0r);
; #pragma unroll
;         for (int c = ks; c < CCH; c += KS) cr[st ^ 1][c] = *(const u32x4*)(cp + (size_t)(RPP * c) * ldc + k0c);
;         __builtin_amdgcn_sched_barrier(0);
;         if (FDB && ks + 1 < KS) {
; #pragma unroll
;           for (int mi = 0; mi < MI; ++mi) af[(ks + 1) & 1][mi] = *(const bf16x8*)(abase + mi * 32 * STR + (ks + 1) * 16);
; #pragma unroll
;           for (int ni = 0; ni < NI; ++ni) bfr[(ks + 1) & 1][ni] = *(const bf16x8*)(bbase + ni * 32 * STR + (ks + 1) * 16);
;         }
; #pragma unroll
;         for (int mi = 0; mi < MI; ++mi)
; #pragma unroll
;           for (int ni = 0; ni < NI; ++ni) acc[mi][ni] = MFMA32(af[ks & 1][mi], bfr[ks & 1][ni], acc[mi][ni]);
;       }
;       __syncthreads();
; DI void phase5(const Params& p, char* smem, const Sched sc) {
;     ...
;     const int b = m0 >> 13;
; #pragma unroll
;     for (int mi = 0; mi < 2; ++mi)
; #pragma unroll
;       for (int ni = 0; ni < 2; ++ni)
; #pragma unroll
;         for (int g = 0; g < 4; ++g) {
;           const f32x4 vv = {acc[mi][ni][4 * g], acc[mi][ni][4 * g + 1], acc[mi][ni][4 * g + 2], acc[mi][ni][4 * g + 3]};
;           *(f32x4*)(ct + (wc * 64 + ni * 32 + r) * CST + wr * 64 + mi * 32 + 8 * g + 4 * h) = vv;
;         }
;     __syncthreads();
;     const int c4 = (tid & 31) * 4, row0 = tid >> 5;
;     const f32x4 gt = *(const f32x4*)(p.ada + b * 3072 + 2048 + n0 + c4);
; #pragma unroll
;     for (int half = 0; half < 2; ++half) {
	v_mfma_f32_32x32x16_bf16 v[32:47], v[108:111], v[146:149], v[32:47]
	v_mfma_f32_32x32x16_bf16 v[16:31], v[112:115], v[142:145], v[16:31]
	ds_read_b128 v[104:107], v121 offset:36864
	ds_read_b128 v[108:111], v121 offset:41472
	ds_read_b128 v[116:119], v122 offset:55296
	ds_read_b128 v[142:145], v122 offset:59904
	ds_write_b128 v120, v[84:87]
	ds_write_b128 v120, v[92:95] offset:18432
	v_mfma_f32_32x32x16_bf16 v[0:15], v[112:115], v[146:149], v[0:15]
	s_waitcnt lgkmcnt(3)
	v_mfma_f32_32x32x16_bf16 v[48:63], v[104:107], v[116:119], v[48:63]
	s_waitcnt lgkmcnt(2)
	v_mfma_f32_32x32x16_bf16 v[32:47], v[104:107], v[142:145], v[32:47]
	ds_read_b128 v[84:87], v121 offset:36896
	ds_read_b128 v[92:95], v121 offset:41504
	ds_read_b128 v[104:107], v122 offset:55328
	ds_read_b128 v[112:115], v122 offset:59936
	ds_write_b128 v120, v[80:83] offset:4608
	ds_write_b128 v120, v[88:91] offset:23040
	v_mfma_f32_32x32x16_bf16 v[16:31], v[108:111], v[116:119], v[16:31]
	v_mfma_f32_32x32x16_bf16 v[0:15], v[108:111], v[142:145], v[0:15]
	s_waitcnt lgkmcnt(3)
	v_mfma_f32_32x32x16_bf16 v[48:63], v[84:87], v[104:107], v[48:63]
	s_waitcnt lgkmcnt(2)
	v_mfma_f32_32x32x16_bf16 v[32:47], v[84:87], v[112:115], v[32:47]
	v_mfma_f32_32x32x16_bf16 v[16:31], v[92:95], v[104:107], v[16:31]
	ds_read_b128 v[80:83], v121 offset:36928
	ds_read_b128 v[84:87], v121 offset:41536
	ds_read_b128 v[88:91], v122 offset:55360
	ds_read_b128 v[104:107], v122 offset:59968
	ds_write_b128 v120, v[68:71] offset:9216
	ds_write_b128 v120, v[76:79] offset:27648
	v_mfma_f32_32x32x16_bf16 v[0:15], v[92:95], v[112:115], v[0:15]
	s_waitcnt lgkmcnt(3)
	v_mfma_f32_32x32x16_bf16 v[48:63], v[80:83], v[88:91], v[48:63]
	s_waitcnt lgkmcnt(2)
	v_mfma_f32_32x32x16_bf16 v[32:47], v[80:83], v[104:107], v[32:47]
	v_mfma_f32_32x32x16_bf16 v[16:31], v[84:87], v[88:91], v[16:31]
	ds_read_b128 v[68:71], v121 offset:36960
	ds_read_b128 v[76:79], v121 offset:41568
	ds_read_b128 v[80:83], v122 offset:55392
	ds_read_b128 v[88:91], v122 offset:60000
	ds_write_b128 v120, v[64:67] offset:13824
	ds_write_b128 v120, v[72:75] offset:32256
	v_mfma_f32_32x32x16_bf16 v[0:15], v[84:87], v[104:107], v[0:15]
	s_waitcnt lgkmcnt(3)
	v_mfma_f32_32x32x16_bf16 v[48:63], v[68:71], v[80:83], v[48:63]
	s_lshr_b32 s2, s27, 6
	s_mul_i32 s28, s2, 0xc00
	s_ashr_i32 s29, s28, 31
	s_lshl_b64 s[28:29], s[28:29], 2
	s_add_u32 s9, s6, s28
	s_addc_u32 s27, s7, s29
	s_lshl_b32 s2, s26, 2
	s_waitcnt lgkmcnt(2)
	v_mfma_f32_32x32x16_bf16 v[32:47], v[68:71], v[88:91], v[32:47]
	s_add_u32 s26, s9, s2
	s_waitcnt lgkmcnt(0)
	s_barrier
	s_barrier
	v_mfma_f32_32x32x16_bf16 v[0:15], v[76:79], v[88:91], v[0:15]
	ds_write_b128 v140, v[48:51]
	ds_write_b128 v140, v[52:55] offset:32
	ds_write_b128 v140, v[56:59] offset:64
	ds_write_b128 v140, v[60:63] offset:96
	s_nop 2
	ds_write_b128 v140, v[32:35] offset:16896
	s_addc_u32 s27, s27, 0
	s_add_i32 s25, s25, s33
	s_add_i32 s24, s24, s11
	s_cmpk_gt_i32 s25, 0x7f
	v_mfma_f32_32x32x16_bf16 v[16:31], v[76:79], v[80:83], v[16:31]
	ds_write_b128 v140, v[36:39] offset:16928
	ds_write_b128 v140, v[40:43] offset:16960
	ds_write_b128 v140, v[44:47] offset:16992
	s_nop 8
	ds_write_b128 v140, v[16:19] offset:128
	ds_write_b128 v140, v[20:23] offset:160
	ds_write_b128 v140, v[24:27] offset:192
	ds_write_b128 v140, v[28:31] offset:224
	ds_write_b128 v140, v[0:3] offset:17024
	ds_write_b128 v140, v[4:7] offset:17056
	ds_write_b128 v140, v[8:11] offset:17088
	ds_write_b128 v140, v[12:15] offset:17120
	v_or_b32_e32 v6, s8, v124
	v_lshl_add_u64 v[0:1], s[26:27], 0, v[96:97]
	v_ashrrev_i32_e32 v7, 31, v6
	v_add_co_u32_e32 v0, vcc, s15, v0
	v_lshl_add_u64 v[4:5], v[102:103], 0, s[2:3]
	v_lshlrev_b64 v[44:45], 12, v[6:7]
	v_addc_co_u32_e32 v1, vcc, 0, v1, vcc
	v_lshl_add_u64 v[48:49], v[4:5], 0, v[44:45]
	v_add_co_u32_e32 v12, vcc, s16, v48
	s_waitcnt lgkmcnt(0)
	s_barrier
	global_load_dwordx4 v[0:3], v[0:1], off
	v_addc_co_u32_e32 v13, vcc, 0, v49, vcc
	global_load_dwordx4 v[8:11], v[48:49], off
	v_add_co_u32_e32 v16, vcc, s12, v48
	global_load_dwordx4 v[12:15], v[12:13], off
	s_nop 0
	v_addc_co_u32_e32 v17, vcc, 0, v49, vcc
	global_load_dwordx4 v[16:19], v[16:17], off
	v_add_co_u32_e32 v20, vcc, s17, v48
	v_or_b32_e32 v24, 32, v6
	s_nop 0
	v_addc_co_u32_e32 v21, vcc, 0, v49, vcc
	global_load_dwordx4 v[20:23], v[20:21], off
	v_ashrrev_i32_e32 v25, 31, v24
	v_lshlrev_b64 v[24:25], 12, v[24:25]
	v_lshl_add_u64 v[24:25], v[4:5], 0, v[24:25]
	global_load_dwordx4 v[24:27], v[24:25], off
	v_add_co_u32_e32 v28, vcc, s18, v48
	ds_read_b128 v[40:43], v141
	s_nop 0
	v_addc_co_u32_e32 v29, vcc, 0, v49, vcc
	global_load_dwordx4 v[28:31], v[28:29], off
	v_add_co_u32_e32 v32, vcc, s14, v48
	v_lshl_add_u64 v[44:45], s[4:5], 0, v[44:45]
	s_nop 0
	v_addc_co_u32_e32 v33, vcc, 0, v49, vcc
	global_load_dwordx4 v[32:35], v[32:33], off
	v_add_co_u32_e32 v36, vcc, s19, v48
	v_lshl_add_u64 v[50:51], v[44:45], 0, s[2:3]
	s_nop 0
	v_addc_co_u32_e32 v37, vcc, 0, v49, vcc
	global_load_dwordx4 v[36:39], v[36:37], off
	ds_read_b128 v[44:47], v141 offset:4224
	s_waitcnt vmcnt(7) lgkmcnt(1)
	v_fma_f32 v10, v2, v42, v10
	v_fma_f32 v11, v3, v43, v11
	v_fma_f32 v8, v0, v40, v8
	v_fma_f32 v9, v1, v41, v9
	v_lshl_add_u64 v[40:41], v[50:51], 0, v[96:97]
	global_store_dwordx4 v[40:41], v[8:11], off
	s_waitcnt vmcnt(7) lgkmcnt(0)
	s_nop 0
	v_fma_f32 v8, v0, v44, v12
	v_fma_f32 v9, v1, v45, v13
	v_or_b32_e32 v12, s8, v125
	v_ashrrev_i32_e32 v13, 31, v12
	v_lshlrev_b64 v[12:13], 12, v[12:13]
	v_fma_f32 v10, v2, v46, v14
	v_fma_f32 v11, v3, v47, v15
	v_lshl_add_u64 v[40:41], s[4:5], 0, v[12:13]
	ds_read_b128 v[12:15], v141 offset:8448
	v_lshl_add_u64 v[40:41], v[40:41], 0, s[2:3]
	v_lshl_add_u64 v[40:41], v[40:41], 0, v[96:97]
	global_store_dwordx4 v[40:41], v[8:11], off
	ds_read_b128 v[8:11], v141 offset:12672
	s_waitcnt vmcnt(7) lgkmcnt(1)
; DI void phase5(const Params& p, char* smem, const Sched sc) {
;     ...
;     const int c4 = (tid & 31) * 4, row0 = tid >> 5;
;     const f32x4 gt = *(const f32x4*)(p.ada + b * 3072 + 2048 + n0 + c4);
; #pragma unroll
;     for (int half = 0; half < 2; ++half) {
;       f32x4 xv[8];
; #pragma unroll
;       for (int j = 0; j < 8; ++j) xv[j] = *(const f32x4*)(p.x + (size_t)(m0 + row0 + 8 * (half * 8 + j)) * DM + n0 + c4);
; #pragma unroll
;       for (int j = 0; j < 8; ++j) {
;         const int row = row0 + 8 * (half * 8 + j);
;         const f32x4 cv = *(const f32x4*)(ct + row * CST + c4);
;         f32x4 o;
; #pragma unroll
;         for (int e = 0; e < 4; ++e) o[e] = xv[j][e] + gt[e] * cv[e];
;         *(f32x4*)(p.out + (size_t)(m0 + row) * DM + n0 + c4) = o;
;       }
	v_fma_f32 v12, v0, v12, v16
	v_fma_f32 v13, v1, v13, v17
	v_or_b32_e32 v16, s8, v126
	v_ashrrev_i32_e32 v17, 31, v16
	v_lshlrev_b64 v[16:17], 12, v[16:17]
	v_lshl_add_u64 v[16:17], s[4:5], 0, v[16:17]
	v_lshl_add_u64 v[16:17], v[16:17], 0, s[2:3]
	v_fma_f32 v14, v2, v14, v18
	v_fma_f32 v15, v3, v15, v19
	v_lshl_add_u64 v[16:17], v[16:17], 0, v[96:97]
	global_store_dwordx4 v[16:17], v[12:15], off
	s_waitcnt vmcnt(7) lgkmcnt(0)
	v_fma_f32 v10, v2, v10, v22
	v_fma_f32 v11, v3, v11, v23
	v_fma_f32 v8, v0, v8, v20
	v_fma_f32 v9, v1, v9, v21
	v_or_b32_e32 v12, s8, v127
	v_ashrrev_i32_e32 v13, 31, v12
	v_lshlrev_b64 v[12:13], 12, v[12:13]
	v_lshl_add_u64 v[16:17], s[4:5], 0, v[12:13]
	v_lshl_add_u64 v[16:17], v[16:17], 0, s[2:3]
	v_lshl_add_u64 v[16:17], v[16:17], 0, v[96:97]
	ds_read_b128 v[12:15], v141 offset:16896
	global_store_dwordx4 v[16:17], v[8:11], off
	v_or_b32_e32 v16, s8, v128
	v_ashrrev_i32_e32 v17, 31, v16
	v_lshlrev_b64 v[16:17], 12, v[16:17]
	v_lshl_add_u64 v[16:17], s[4:5], 0, v[16:17]
	v_lshl_add_u64 v[16:17], v[16:17], 0, s[2:3]
	ds_read_b128 v[8:11], v141 offset:21120
	s_waitcnt vmcnt(7) lgkmcnt(1)
	v_fma_f32 v14, v2, v14, v26
	v_fma_f32 v15, v3, v15, v27
	v_fma_f32 v12, v0, v12, v24
	v_fma_f32 v13, v1, v13, v25
	v_lshl_add_u64 v[16:17], v[16:17], 0, v[96:97]
	global_store_dwordx4 v[16:17], v[12:15], off
	s_waitcnt vmcnt(7) lgkmcnt(0)
	v_fma_f32 v10, v2, v10, v30
	v_fma_f32 v11, v3, v11, v31
	v_fma_f32 v8, v0, v8, v28
	v_fma_f32 v9, v1, v9, v29
	v_or_b32_e32 v12, s8, v129
	v_ashrrev_i32_e32 v13, 31, v12
	v_lshlrev_b64 v[12:13], 12, v[12:13]
	v_lshl_add_u64 v[16:17], s[4:5], 0, v[12:13]
	v_lshl_add_u64 v[16:17], v[16:17], 0, s[2:3]
	v_lshl_add_u64 v[16:17], v[16:17], 0, v[96:97]
	ds_read_b128 v[12:15], v141 offset:25344
	global_store_dwordx4 v[16:17], v[8:11], off
	v_or_b32_e32 v16, s8, v130
	v_ashrrev_i32_e32 v17, 31, v16
	v_lshlrev_b64 v[16:17], 12, v[16:17]
	v_lshl_add_u64 v[16:17], s[4:5], 0, v[16:17]
	v_lshl_add_u64 v[16:17], v[16:17], 0, s[2:3]
	ds_read_b128 v[8:11], v141 offset:29568
	s_waitcnt vmcnt(7) lgkmcnt(1)
	v_fma_f32 v14, v2, v14, v34
	v_fma_f32 v15, v3, v15, v35
	v_fma_f32 v12, v0, v12, v32
	v_fma_f32 v13, v1, v13, v33
	v_lshl_add_u64 v[16:17], v[16:17], 0, v[96:97]
	global_store_dwordx4 v[16:17], v[12:15], off
	s_waitcnt vmcnt(7) lgkmcnt(0)
	v_fma_f32 v10, v2, v10, v38
	v_fma_f32 v11, v3, v11, v39
	v_fma_f32 v8, v0, v8, v36
	v_fma_f32 v9, v1, v9, v37
	v_or_b32_e32 v12, s8, v131
	v_ashrrev_i32_e32 v13, 31, v12
	v_lshlrev_b64 v[12:13], 12, v[12:13]
	v_lshl_add_u64 v[12:13], s[4:5], 0, v[12:13]
	v_lshl_add_u64 v[12:13], v[12:13], 0, s[2:3]
	v_lshl_add_u64 v[12:13], v[12:13], 0, v[96:97]
	global_store_dwordx4 v[12:13], v[8:11], off
	v_add_co_u32_e32 v12, vcc, s20, v48
	s_nop 0
	v_or_b32_e32 v8, 64, v6
	v_ashrrev_i32_e32 v9, 31, v8
	v_lshlrev_b64 v[8:9], 12, v[8:9]
	v_lshl_add_u64 v[8:9], v[4:5], 0, v[8:9]
	global_load_dwordx4 v[8:11], v[8:9], off
	v_addc_co_u32_e32 v13, vcc, 0, v49, vcc
	global_load_dwordx4 v[12:15], v[12:13], off
	v_add_co_u32_e32 v16, vcc, s21, v48
	v_or_b32_e32 v24, 0x60, v6
	s_nop 0
	v_addc_co_u32_e32 v17, vcc, 0, v49, vcc
	global_load_dwordx4 v[16:19], v[16:17], off
	v_add_co_u32_e32 v20, vcc, s22, v48
	v_ashrrev_i32_e32 v25, 31, v24
	s_nop 0
	v_addc_co_u32_e32 v21, vcc, 0, v49, vcc
	global_load_dwordx4 v[20:23], v[20:21], off
	v_lshlrev_b64 v[24:25], 12, v[24:25]
	v_lshl_add_u64 v[24:25], v[4:5], 0, v[24:25]
	global_load_dwordx4 v[24:27], v[24:25], off
	v_add_u32_e32 v28, 0x68, v6
	v_ashrrev_i32_e32 v29, 31, v28
	v_lshlrev_b64 v[28:29], 12, v[28:29]
	v_lshl_add_u64 v[28:29], v[4:5], 0, v[28:29]
	global_load_dwordx4 v[28:31], v[28:29], off
	v_add_u32_e32 v32, 0x70, v6
	v_add_u32_e32 v6, 0x78, v6
	v_ashrrev_i32_e32 v33, 31, v32
	v_ashrrev_i32_e32 v7, 31, v6
	v_lshlrev_b64 v[32:33], 12, v[32:33]
	v_lshlrev_b64 v[6:7], 12, v[6:7]
	v_lshl_add_u64 v[32:33], v[4:5], 0, v[32:33]
	v_lshl_add_u64 v[4:5], v[4:5], 0, v[6:7]
	global_load_dwordx4 v[32:35], v[32:33], off
	s_nop 0
	global_load_dwordx4 v[4:7], v[4:5], off
	ds_read_b128 v[36:39], v141 offset:33792
	ds_read_b128 v[40:43], v141 offset:38016
	s_waitcnt vmcnt(7) lgkmcnt(1)
; DI void phase5(const Params& p, char* smem, const Sched sc) {
;     ...
;     const int c4 = (tid & 31) * 4, row0 = tid >> 5;
;     const f32x4 gt = *(const f32x4*)(p.ada + b * 3072 + 2048 + n0 + c4);
; #pragma unroll
;     for (int half = 0; half < 2; ++half) {
;       f32x4 xv[8];
; #pragma unroll
;       for (int j = 0; j < 8; ++j) xv[j] = *(const f32x4*)(p.x + (size_t)(m0 + row0 + 8 * (half * 8 + j)) * DM + n0 + c4);
; #pragma unroll
;       for (int j = 0; j < 8; ++j) {
;         const int row = row0 + 8 * (half * 8 + j);
;         const f32x4 cv = *(const f32x4*)(ct + row * CST + c4);
;         f32x4 o;
; #pragma unroll
;         for (int e = 0; e < 4; ++e) o[e] = xv[j][e] + gt[e] * cv[e];
;         *(f32x4*)(p.out + (size_t)(m0 + row) * DM + n0 + c4) = o;
;       }
;     }
;     __syncthreads();
	v_fma_f32 v8, v0, v36, v8
	v_fma_f32 v9, v1, v37, v9
	v_or_b32_e32 v36, s8, v132
	v_ashrrev_i32_e32 v37, 31, v36
	v_lshlrev_b64 v[36:37], 12, v[36:37]
	v_lshl_add_u64 v[36:37], s[4:5], 0, v[36:37]
	v_lshl_add_u64 v[36:37], v[36:37], 0, s[2:3]
	v_fma_f32 v10, v2, v38, v10
	v_fma_f32 v11, v3, v39, v11
	v_lshl_add_u64 v[36:37], v[36:37], 0, v[96:97]
	global_store_dwordx4 v[36:37], v[8:11], off
	s_waitcnt vmcnt(7) lgkmcnt(0)
	s_nop 0
	v_fma_f32 v8, v0, v40, v12
	v_fma_f32 v9, v1, v41, v13
	v_or_b32_e32 v12, s8, v133
	v_ashrrev_i32_e32 v13, 31, v12
	v_lshlrev_b64 v[12:13], 12, v[12:13]
	v_fma_f32 v10, v2, v42, v14
	v_fma_f32 v11, v3, v43, v15
	v_lshl_add_u64 v[36:37], s[4:5], 0, v[12:13]
	ds_read_b128 v[12:15], v141 offset:42240
	v_lshl_add_u64 v[36:37], v[36:37], 0, s[2:3]
	v_lshl_add_u64 v[36:37], v[36:37], 0, v[96:97]
	global_store_dwordx4 v[36:37], v[8:11], off
	ds_read_b128 v[8:11], v141 offset:46464
	s_waitcnt vmcnt(7) lgkmcnt(1)
	v_fma_f32 v12, v0, v12, v16
	v_fma_f32 v13, v1, v13, v17
	v_or_b32_e32 v16, s8, v134
	v_ashrrev_i32_e32 v17, 31, v16
	v_lshlrev_b64 v[16:17], 12, v[16:17]
	v_lshl_add_u64 v[16:17], s[4:5], 0, v[16:17]
	v_lshl_add_u64 v[16:17], v[16:17], 0, s[2:3]
	v_fma_f32 v14, v2, v14, v18
	v_fma_f32 v15, v3, v15, v19
	v_lshl_add_u64 v[16:17], v[16:17], 0, v[96:97]
	global_store_dwordx4 v[16:17], v[12:15], off
	s_waitcnt vmcnt(7) lgkmcnt(0)
	v_fma_f32 v10, v2, v10, v22
	v_fma_f32 v11, v3, v11, v23
	v_fma_f32 v8, v0, v8, v20
	v_fma_f32 v9, v1, v9, v21
	v_or_b32_e32 v12, s8, v135
	v_ashrrev_i32_e32 v13, 31, v12
	v_lshlrev_b64 v[12:13], 12, v[12:13]
	v_lshl_add_u64 v[16:17], s[4:5], 0, v[12:13]
	v_lshl_add_u64 v[16:17], v[16:17], 0, s[2:3]
	v_lshl_add_u64 v[16:17], v[16:17], 0, v[96:97]
	ds_read_b128 v[12:15], v141 offset:50688
	global_store_dwordx4 v[16:17], v[8:11], off
	v_or_b32_e32 v16, s8, v136
	v_ashrrev_i32_e32 v17, 31, v16
	v_lshlrev_b64 v[16:17], 12, v[16:17]
	v_lshl_add_u64 v[16:17], s[4:5], 0, v[16:17]
	v_lshl_add_u64 v[16:17], v[16:17], 0, s[2:3]
	ds_read_b128 v[8:11], v141 offset:54912
	s_waitcnt vmcnt(7) lgkmcnt(1)
	v_fma_f32 v14, v2, v14, v26
	v_fma_f32 v15, v3, v15, v27
	v_fma_f32 v12, v0, v12, v24
	v_fma_f32 v13, v1, v13, v25
	v_lshl_add_u64 v[16:17], v[16:17], 0, v[96:97]
	global_store_dwordx4 v[16:17], v[12:15], off
	s_waitcnt vmcnt(7) lgkmcnt(0)
	v_fma_f32 v10, v2, v10, v30
	v_fma_f32 v11, v3, v11, v31
	v_fma_f32 v8, v0, v8, v28
	v_fma_f32 v9, v1, v9, v29
	v_add_u32_e32 v12, s8, v137
	v_ashrrev_i32_e32 v13, 31, v12
	v_lshlrev_b64 v[12:13], 12, v[12:13]
	v_lshl_add_u64 v[16:17], s[4:5], 0, v[12:13]
	v_lshl_add_u64 v[16:17], v[16:17], 0, s[2:3]
	v_lshl_add_u64 v[16:17], v[16:17], 0, v[96:97]
	ds_read_b128 v[12:15], v141 offset:59136
	global_store_dwordx4 v[16:17], v[8:11], off
	ds_read_b128 v[8:11], v141 offset:63360
	v_add_u32_e32 v16, s8, v138
	v_ashrrev_i32_e32 v17, 31, v16
	s_waitcnt vmcnt(7) lgkmcnt(1)
	v_fma_f32 v12, v0, v12, v32
	v_fma_f32 v13, v1, v13, v33
	v_lshlrev_b64 v[16:17], 12, v[16:17]
	s_waitcnt vmcnt(6) lgkmcnt(0)
	v_fma_f32 v0, v0, v8, v4
	v_fma_f32 v1, v1, v9, v5
	v_add_u32_e32 v4, s8, v139
	v_ashrrev_i32_e32 v5, 31, v4
	v_lshlrev_b64 v[4:5], 12, v[4:5]
	v_lshl_add_u64 v[16:17], s[4:5], 0, v[16:17]
	v_lshl_add_u64 v[4:5], s[4:5], 0, v[4:5]
	v_lshl_add_u64 v[16:17], v[16:17], 0, s[2:3]
	v_lshl_add_u64 v[4:5], v[4:5], 0, s[2:3]
	v_fma_f32 v14, v2, v14, v34
	v_fma_f32 v15, v3, v15, v35
	v_lshl_add_u64 v[16:17], v[16:17], 0, v[96:97]
	v_fma_f32 v2, v2, v10, v6
	v_fma_f32 v3, v3, v11, v7
	v_lshl_add_u64 v[4:5], v[4:5], 0, v[96:97]
	global_store_dwordx4 v[16:17], v[12:15], off
	global_store_dwordx4 v[4:5], v[0:3], off
	s_barrier
	s_cbranch_scc0 .LBB0_529
	s_branch .LBB0_526
